# final_norm: hoist loop-invariant gain loads + prefetch next row; GEMM tile prologue issues stage-1 loads before the first wait
# speedup vs baseline: 1.0244x; 1.0014x over previous
; template <int PIPE>
; DI void gemm_loop_g(const u16* __restrict__ Xp, long ldx_l, long ldx_i, long kxs,
;                     const u16* __restrict__ Yp, long ldy_l, long ldy_i, long kys, int K,
;                     f32x4 (&acc)[4][8], unsigned char* smem) {
;   const int t = tid_opaque(), l = t & 63, w = __builtin_amdgcn_readfirstlane(t >> 6), wx = w >> 1, wy = w & 1;
;   const int lrow = t >> 3, gch = (t & 7) ^ ((t >> 4) & 7);
;   const u16* xs = Xp + (long)lrow * ldx_l + gch * 8;
;   const u16* ys = Yp + (long)lrow * ldy_l + gch * 8;
; template <int MODE>
; DI void gemm_phase(const Params& p, const GP& g, unsigned char* smem) {
;     ...
;     int bsel = 0;
;     {
;       const int ml = e / g.ntn;
;       nt = e - ml * g.ntn;
;       mt = xcd + 8 * ml;
;     }
;     if (MODE == M_SEQ) { bsel = mt >> 4; mt &= 15; Wb = g.W + (long)bsel * 1024 * 8192; }
;     const int m0 = mt * 256, n0 = nt * 256;
;     f32x4 acc[4][8];
;     zero_acc(acc);
;     int transposed = 0;
;     if (MODE == M_FN_IN) transposed = nt < 8;
;     if (MODE == M_NA_IN) transposed = (nt >= 8 && nt < 12);
;     if (MODE == M_MLA_UKV) transposed = nt >= 4;
;     if (MODE == M_HG_IN) transposed = nt >= 12;
;     if (MODE == M_PLE) {
;       const u16* pb = (const u16*)g.d1;
;       gemm_loop(g.W2 + (long)n0 * 256, 256, pb + (long)m0 * 256, 256, 256, acc, smem);
;       u16* xb = (u16*)g.d0;
;       EPI_STD_BEGIN
;         *(u32x2*)(xb + (long)m * 1024 + n4) = pack4(v[0], v[1], v[2], v[3]);
;       EPI_END
;       zero_acc(acc);
;     }
;     if (MODE == M_FFT1) {
;       const int bt = mt >> 8, cg = mt & 255;
;       gemm_loop_g<0>(Ab + ((long)(bt * 1024 + cg * 4)) * 8192, 64, 8192, 4096, Wb, 128, 64 * 128, 64, 128, acc, smem);
;     } else if (MODE == M_FFT3) {
;       const int bt = mt >> 8, v = (mt >> 2) & 63, cq = mt & 3;
;       gemm_loop(Ab + (((long)(bt * 64 + v)) * 1024 + cq * 256) * 128, 128, Wb, 128, 128, acc, smem);
;     } else if (MODE == M_FN_IN && transposed) {
;       const u16* Ap = Ab + ((long)(mt >> 4) * 4096 + (mt & 15) * 4) * g.lda;
;       gemm_loop_g<1>(Ap, 64 * g.lda, g.lda, 64, Wb + (long)n0 * g.K, g.K, 64L * g.K, 64, g.K, acc, smem);
;     } else {
;       const u16* Ap = Ab + (long)m0 * g.lda; const u16* Wp = Wb + (long)n0 * g.K;
;       if (transposed) gemm_loop(Ap, g.lda, Wp, g.K, g.K, acc, smem);
;       else gemm_loop(Wp, g.K, Ap, g.lda, g.K, acc, smem);
.LBB0_80:
	s_mul_hi_u32 s6, s65, 0xaaaaaaab
	s_lshr_b32 s63, s6, 3
	s_mul_i32 s62, s63, -12
	s_and_b32 s6, s6, -8
	s_add_i32 s62, s62, s65
	s_or_b32 s66, s6, s53
	s_lshl_b32 s8, s66, 8
	s_lshl_b32 s6, s62, 8
	s_cmp_gt_i32 s62, 7
	s_cselect_b64 s[10:11], -1, 0
	s_mov_b64 s[60:61], -1
	s_and_b64 vcc, exec, s[10:11]
	s_cbranch_vccz .LBB0_86
	s_mov_b32 s7, s19
	s_lshl_b64 s[48:49], s[6:7], 11
	s_add_u32 s48, s22, s48
	s_mov_b32 s9, s19
	v_mov_b32_e32 v4, v182
	s_addc_u32 s49, s23, s49
	s_lshl_b64 s[60:61], s[8:9], 11
	s_waitcnt lgkmcnt(0)
	s_add_u32 s60, s12, s60
	v_ashrrev_i32_e32 v0, 3, v4
	v_lshrrev_b32_e32 v5, 4, v4
	v_xor_b32_e32 v6, v5, v4
	v_ashrrev_i32_e32 v1, 31, v0
	s_addc_u32 s61, s13, s61
	v_lshlrev_b64 v[0:1], 11, v[0:1]
	v_lshlrev_b32_e32 v6, 4, v6
	v_lshl_add_u64 v[2:3], s[48:49], 0, v[0:1]
	v_and_b32_e32 v128, 0x70, v6
	v_lshl_add_u64 v[0:1], s[60:61], 0, v[0:1]
	v_lshl_add_u64 v[132:133], v[2:3], 0, v[128:129]
	v_lshl_add_u64 v[134:135], v[0:1], 0, v[128:129]
	v_lshlrev_b32_e32 v128, 4, v4
	s_mov_b32 s59, s19
	v_readfirstlane_b32 s7, v128
	v_add_u32_e32 v2, 0x2000, v128
	v_lshl_add_u64 v[0:1], v[132:133], 0, s[58:59]
	s_mov_b32 m0, s7
	v_lshl_add_u64 v[136:137], v[132:133], 0, s[24:25]
	v_readfirstlane_b32 s7, v2
	v_add_u32_e32 v2, 0x4000, v128
	s_barrier
; #define LDS_PTR(p) ((__attribute__((address_space(3))) unsigned*)(p))
; template <int PIPE>
; DI void gemm_loop_g(const u16* __restrict__ Xp, long ldx_l, long ldx_i, long kxs,
;                     const u16* __restrict__ Yp, long ldy_l, long ldy_i, long kys, int K,
;                     f32x4 (&acc)[4][8], unsigned char* smem) {
;     ...
;   auto issue = [&](int kt0, int stage) {
;     int kt = kt0 + rot; if (kt >= nk) kt -= nk;
;     unsigned char* sb = smem + stage * 65536 + t * 16;
; #pragma unroll
;     for (int i = 0; i < 4; ++i)
;       __builtin_amdgcn_global_load_lds((const unsigned*)(xs + i * ldx_i + kt * kxs), LDS_PTR(sb + i * 8192), 16, 0, 0);
; #pragma unroll
;     for (int i = 0; i < 4; ++i)
;       __builtin_amdgcn_global_load_lds((const unsigned*)(ys + i * ldy_i + kt * kys), LDS_PTR(sb + 32768 + i * 8192), 16, 0, 0);
;   };
;   __syncthreads();
;   issue(0, 0);
;   asm volatile("s_waitcnt vmcnt(0)" ::: "memory");
;   __syncthreads();
; #pragma unroll 1
;   for (int kt = 0; kt < nk; ++kt) {
;     const unsigned char* cur = smem + (kt & 1) * 65536;
;     if (kt + 1 < nk) issue(kt + 1, (kt + 1) & 1);
; DI void zero_acc(f32x4 (&acc)[4][8]) {
; #pragma unroll
;   for (int i = 0; i < 4; ++i)
; #pragma unroll
;     for (int j = 0; j < 8; ++j) acc[i][j] = f32x4{0.f, 0.f, 0.f, 0.f};
	global_load_lds_dwordx4 v[0:1], off
	v_lshl_add_u64 v[0:1], v[136:137], 0, s[58:59]
	s_mov_b32 m0, s7
	v_lshl_add_u64 v[138:139], v[132:133], 0, s[26:27]
	v_readfirstlane_b32 s7, v2
	v_add_u32_e32 v2, 0x6000, v128
	global_load_lds_dwordx4 v[0:1], off
	v_lshl_add_u64 v[0:1], v[138:139], 0, s[58:59]
	s_mov_b32 m0, s7
	v_lshl_add_u64 v[140:141], v[132:133], 0, s[28:29]
	v_readfirstlane_b32 s7, v2
	v_add_u32_e32 v2, 0x8000, v128
	global_load_lds_dwordx4 v[0:1], off
	v_lshl_add_u64 v[0:1], v[140:141], 0, s[58:59]
	s_mov_b32 m0, s7
	v_readfirstlane_b32 s7, v2
	v_add_u32_e32 v2, 0xa000, v128
	global_load_lds_dwordx4 v[0:1], off
	v_lshl_add_u64 v[0:1], v[134:135], 0, s[58:59]
	s_mov_b32 m0, s7
	v_lshl_add_u64 v[142:143], v[134:135], 0, s[24:25]
	v_readfirstlane_b32 s7, v2
	v_add_u32_e32 v2, 0xc000, v128
	global_load_lds_dwordx4 v[0:1], off
	v_lshl_add_u64 v[0:1], v[142:143], 0, s[58:59]
	s_mov_b32 m0, s7
	v_lshl_add_u64 v[144:145], v[134:135], 0, s[26:27]
	v_readfirstlane_b32 s7, v2
	v_add_u32_e32 v2, 0xe000, v128
	global_load_lds_dwordx4 v[0:1], off
	v_lshl_add_u64 v[0:1], v[144:145], 0, s[58:59]
	s_mov_b32 m0, s7
	v_lshl_add_u64 v[146:147], v[134:135], 0, s[28:29]
	v_readfirstlane_b32 s7, v2
	global_load_lds_dwordx4 v[0:1], off
	v_lshl_add_u64 v[0:1], v[146:147], 0, s[58:59]
	s_mov_b32 m0, s7
	v_lshlrev_b32_e32 v2, 7, v4
	global_load_lds_dwordx4 v[0:1], off
	v_bfe_u32 v0, v4, 4, 2
	v_bfe_u32 v1, v4, 1, 3
	v_readfirstlane_b32 s9, v4
	s_nop 0
	v_bitop3_b32 v0, v0, v1, 4 bitop3:0x36
	v_and_b32_e32 v2, 0x780, v2
	s_lshl_b32 s7, s9, 8
	s_lshl_b32 s9, s9, 6
	v_lshl_or_b32 v131, v0, 4, v2
	v_bitop3_b32 v0, v5, v1, 3 bitop3:0x6c
	v_mov_b32_e32 v8, 0
	s_and_b32 s7, s7, 0x4000
	s_and_b32 s9, s9, 0xffffe000
	v_lshl_or_b32 v156, v0, 4, v2
	s_mov_b32 s18, 0
	s_mov_b32 s33, 0x10000
	v_mov_b32_e32 v9, v8
	v_mov_b32_e32 v10, v8
	v_mov_b32_e32 v11, v8
	v_mov_b32_e32 v12, v8
	v_mov_b32_e32 v13, v8
	v_mov_b32_e32 v14, v8
	v_mov_b32_e32 v15, v8
	v_mov_b32_e32 v28, v8
	v_mov_b32_e32 v29, v8
	v_mov_b32_e32 v30, v8
	v_mov_b32_e32 v31, v8
	v_mov_b32_e32 v44, v8
	v_mov_b32_e32 v45, v8
	v_mov_b32_e32 v46, v8
	v_mov_b32_e32 v47, v8
	v_mov_b32_e32 v60, v8
	v_mov_b32_e32 v61, v8
	v_mov_b32_e32 v62, v8
	v_mov_b32_e32 v63, v8
	v_mov_b32_e32 v76, v8
	v_mov_b32_e32 v77, v8
	v_mov_b32_e32 v78, v8
	v_mov_b32_e32 v79, v8
	v_mov_b32_e32 v92, v8
	v_mov_b32_e32 v93, v8
	v_mov_b32_e32 v94, v8
	v_mov_b32_e32 v95, v8
	v_mov_b32_e32 v108, v8
	v_mov_b32_e32 v109, v8
	v_mov_b32_e32 v110, v8
	v_mov_b32_e32 v111, v8
	v_mov_b32_e32 v0, v8
	v_mov_b32_e32 v1, v8
	v_mov_b32_e32 v2, v8
	v_mov_b32_e32 v3, v8
	v_mov_b32_e32 v20, v8
	v_mov_b32_e32 v21, v8
	v_mov_b32_e32 v22, v8
	v_mov_b32_e32 v23, v8
	v_mov_b32_e32 v36, v8
	v_mov_b32_e32 v37, v8
	v_mov_b32_e32 v38, v8
	v_mov_b32_e32 v39, v8
	v_mov_b32_e32 v52, v8
	v_mov_b32_e32 v53, v8
	v_mov_b32_e32 v54, v8
	v_mov_b32_e32 v55, v8
	v_mov_b32_e32 v68, v8
	v_mov_b32_e32 v69, v8
	v_mov_b32_e32 v70, v8
	v_mov_b32_e32 v71, v8
	v_mov_b32_e32 v84, v8
	v_mov_b32_e32 v85, v8
	v_mov_b32_e32 v86, v8
	v_mov_b32_e32 v87, v8
	v_mov_b32_e32 v100, v8
	v_mov_b32_e32 v101, v8
	v_mov_b32_e32 v102, v8
	v_mov_b32_e32 v103, v8
	v_mov_b32_e32 v116, v8
	v_mov_b32_e32 v117, v8
	v_mov_b32_e32 v118, v8
	v_mov_b32_e32 v119, v8
	v_mov_b32_e32 v4, v8
	v_mov_b32_e32 v5, v8
	v_mov_b32_e32 v6, v8
	v_mov_b32_e32 v7, v8
	v_mov_b32_e32 v24, v8
	v_mov_b32_e32 v25, v8
	v_mov_b32_e32 v26, v8
	v_mov_b32_e32 v27, v8
	v_mov_b32_e32 v40, v8
	v_mov_b32_e32 v41, v8
	v_mov_b32_e32 v42, v8
	v_mov_b32_e32 v43, v8
	v_mov_b32_e32 v56, v8
	v_mov_b32_e32 v57, v8
	v_mov_b32_e32 v58, v8
	v_mov_b32_e32 v59, v8
	v_mov_b32_e32 v72, v8
	v_mov_b32_e32 v73, v8
	v_mov_b32_e32 v74, v8
	v_mov_b32_e32 v75, v8
	v_mov_b32_e32 v88, v8
	v_mov_b32_e32 v89, v8
	v_mov_b32_e32 v90, v8
	v_mov_b32_e32 v91, v8
	v_mov_b32_e32 v104, v8
	v_mov_b32_e32 v105, v8
	v_mov_b32_e32 v106, v8
	v_mov_b32_e32 v107, v8
	v_mov_b32_e32 v120, v8
	v_mov_b32_e32 v121, v8
	v_mov_b32_e32 v122, v8
	v_mov_b32_e32 v123, v8
	v_mov_b32_e32 v16, v8
	v_mov_b32_e32 v17, v8
	v_mov_b32_e32 v18, v8
	v_mov_b32_e32 v19, v8
	v_mov_b32_e32 v32, v8
	v_mov_b32_e32 v33, v8
	v_mov_b32_e32 v34, v8
	v_mov_b32_e32 v35, v8
	v_mov_b32_e32 v48, v8
	v_mov_b32_e32 v49, v8
	v_mov_b32_e32 v50, v8
	v_mov_b32_e32 v51, v8
	v_mov_b32_e32 v64, v8
	v_mov_b32_e32 v65, v8
	v_mov_b32_e32 v66, v8
	v_mov_b32_e32 v67, v8
	v_mov_b32_e32 v80, v8
	v_mov_b32_e32 v81, v8
	v_mov_b32_e32 v82, v8
	v_mov_b32_e32 v83, v8
	v_mov_b32_e32 v96, v8
	v_mov_b32_e32 v97, v8
	v_mov_b32_e32 v98, v8
	v_mov_b32_e32 v99, v8
	v_mov_b32_e32 v112, v8
	v_mov_b32_e32 v113, v8
	v_mov_b32_e32 v114, v8
	v_mov_b32_e32 v115, v8
	v_mov_b32_e32 v124, v8
	v_mov_b32_e32 v125, v8
	v_mov_b32_e32 v126, v8
	v_mov_b32_e32 v127, v8
	s_add_i32 s40, s57, s18
	s_cmp_lt_u32 s40, 16
	s_cselect_b32 s41, 0, -16
	s_add_i32 s48, s40, s41
	s_and_b32 s40, s33, 0x10000
	v_add_u32_e32 v157, s40, v128
	s_ashr_i32 s49, s48, 31
	s_lshl_b64 s[48:49], s[48:49], 7
	v_readfirstlane_b32 s40, v157
	v_add_u32_e32 v160, 0x2000, v157
	v_lshl_add_u64 v[158:159], v[132:133], 0, s[48:49]
	s_mov_b32 m0, s40
	v_readfirstlane_b32 s40, v160
	v_add_u32_e32 v160, 0x4000, v157
	global_load_lds_dwordx4 v[158:159], off
	v_lshl_add_u64 v[158:159], v[136:137], 0, s[48:49]
	s_mov_b32 m0, s40
	v_readfirstlane_b32 s40, v160
	v_add_u32_e32 v160, 0x6000, v157
	global_load_lds_dwordx4 v[158:159], off
	v_lshl_add_u64 v[158:159], v[138:139], 0, s[48:49]
	s_mov_b32 m0, s40
	v_readfirstlane_b32 s40, v160
	v_add_u32_e32 v160, 0x8000, v157
	global_load_lds_dwordx4 v[158:159], off
	v_lshl_add_u64 v[158:159], v[140:141], 0, s[48:49]
	s_mov_b32 m0, s40
	v_readfirstlane_b32 s40, v160
	v_add_u32_e32 v160, 0xa000, v157
	global_load_lds_dwordx4 v[158:159], off
	v_lshl_add_u64 v[158:159], v[134:135], 0, s[48:49]
	s_mov_b32 m0, s40
	v_readfirstlane_b32 s40, v160
	v_add_u32_e32 v160, 0xc000, v157
	global_load_lds_dwordx4 v[158:159], off
	v_lshl_add_u64 v[158:159], v[142:143], 0, s[48:49]
	s_mov_b32 m0, s40
	v_readfirstlane_b32 s40, v160
	v_add_u32_e32 v157, 0xe000, v157
	global_load_lds_dwordx4 v[158:159], off
	v_lshl_add_u64 v[158:159], v[144:145], 0, s[48:49]
	s_mov_b32 m0, s40
	v_readfirstlane_b32 s40, v157
	global_load_lds_dwordx4 v[158:159], off
	v_lshl_add_u64 v[158:159], v[146:147], 0, s[48:49]
	s_mov_b32 m0, s40
	s_nop 0
	global_load_lds_dwordx4 v[158:159], off
	s_waitcnt vmcnt(8) lgkmcnt(0)
	s_barrier
	s_branch .LBB0_82

; DI int tid_opaque() { int t = threadIdx.x; asm volatile("" : "+v"(t)); return t; }
; #define LDS_PTR(p) ((__attribute__((address_space(3))) unsigned*)(p))
; template <int PIPE>
; DI void gemm_loop_g(const u16* __restrict__ Xp, long ldx_l, long ldx_i, long kxs,
;                     const u16* __restrict__ Yp, long ldy_l, long ldy_i, long kys, int K,
;                     f32x4 (&acc)[4][8], unsigned char* smem) {
;   const int t = tid_opaque(), l = t & 63, w = __builtin_amdgcn_readfirstlane(t >> 6), wx = w >> 1, wy = w & 1;
;   const int lrow = t >> 3, gch = (t & 7) ^ ((t >> 4) & 7);
;   const u16* xs = Xp + (long)lrow * ldx_l + gch * 8;
;   const u16* ys = Yp + (long)lrow * ldy_l + gch * 8;
;   const int fsw = (l >> 1) & 7, lg = l >> 4;
;   const unsigned fr0 = (l & 15) * 128 + ((lg ^ fsw) << 4);
;   const unsigned fr1 = (l & 15) * 128 + (((lg + 4) ^ fsw) << 4);
;   const unsigned ub = wx * 8192, vb = 32768 + wy * 16384;
;   const int nk = K >> 6;
;   const int rot = (int)((blockIdx.x >> 3) + (blockIdx.x & 7) * 5) % nk;
;   auto issue = [&](int kt0, int stage) {
;     int kt = kt0 + rot; if (kt >= nk) kt -= nk;
;     unsigned char* sb = smem + stage * 65536 + t * 16;
; #pragma unroll
;     for (int i = 0; i < 4; ++i)
;       __builtin_amdgcn_global_load_lds((const unsigned*)(xs + i * ldx_i + kt * kxs), LDS_PTR(sb + i * 8192), 16, 0, 0);
; #pragma unroll
;     for (int i = 0; i < 4; ++i)
;       __builtin_amdgcn_global_load_lds((const unsigned*)(ys + i * ldy_i + kt * kys), LDS_PTR(sb + 32768 + i * 8192), 16, 0, 0);
;   };
;   __syncthreads();
; template <int MODE>
; DI void gemm_phase(const Params& p, const GP& g, unsigned char* smem) {
;     ...
;     } else if (MODE == M_FN_IN && transposed) {
;       const u16* Ap = Ab + ((long)(mt >> 4) * 4096 + (mt & 15) * 4) * g.lda;
;       gemm_loop_g<1>(Ap, 64 * g.lda, g.lda, 64, Wb + (long)n0 * g.K, g.K, 64L * g.K, 64, g.K, acc, smem);
.LBB0_86:
	s_and_b64 vcc, exec, s[60:61]
	s_cbranch_vccz .LBB0_91
	s_lshr_b32 s18, s63, 1
	s_lshl_b64 s[48:49], s[18:19], 23
	s_waitcnt lgkmcnt(0)
	s_add_u32 s7, s12, s48
	s_addc_u32 s9, s13, s49
	s_lshl_b32 s18, s66, 13
	s_and_b32 s18, s18, 0x1e000
	s_add_u32 s48, s7, s18
	s_addc_u32 s49, s9, 0
	s_ashr_i32 s7, s6, 31
	v_mov_b32_e32 v4, v182
	s_lshl_b64 s[60:61], s[6:7], 11
	s_add_u32 s60, s22, s60
	v_ashrrev_i32_e32 v0, 3, v4
	v_lshrrev_b32_e32 v5, 4, v4
	v_xor_b32_e32 v6, v5, v4
	v_ashrrev_i32_e32 v1, 31, v0
	s_addc_u32 s61, s23, s61
	v_lshlrev_b64 v[2:3], 17, v[0:1]
	v_lshlrev_b32_e32 v6, 4, v6
	v_lshlrev_b64 v[0:1], 11, v[0:1]
	v_lshl_add_u64 v[2:3], s[48:49], 0, v[2:3]
	v_and_b32_e32 v128, 0x70, v6
	v_lshl_add_u64 v[0:1], s[60:61], 0, v[0:1]
	v_lshl_add_u64 v[132:133], v[2:3], 0, v[128:129]
	v_lshl_add_u64 v[134:135], v[0:1], 0, v[128:129]
	v_lshlrev_b32_e32 v128, 4, v4
	s_mov_b32 s59, s19
	v_readfirstlane_b32 s7, v128
	v_add_u32_e32 v2, 0x2000, v128
	v_lshl_add_u64 v[0:1], v[132:133], 0, s[58:59]
	s_mov_b32 m0, s7
	v_readfirstlane_b32 s7, v2
	v_add_u32_e32 v2, 0x4000, v128
	s_barrier
; #define LDS_PTR(p) ((__attribute__((address_space(3))) unsigned*)(p))
; template <int PIPE>
; DI void gemm_loop_g(const u16* __restrict__ Xp, long ldx_l, long ldx_i, long kxs,
;                     const u16* __restrict__ Yp, long ldy_l, long ldy_i, long kys, int K,
;                     f32x4 (&acc)[4][8], unsigned char* smem) {
;     ...
;   auto issue = [&](int kt0, int stage) {
;     int kt = kt0 + rot; if (kt >= nk) kt -= nk;
;     unsigned char* sb = smem + stage * 65536 + t * 16;
; #pragma unroll
;     for (int i = 0; i < 4; ++i)
;       __builtin_amdgcn_global_load_lds((const unsigned*)(xs + i * ldx_i + kt * kxs), LDS_PTR(sb + i * 8192), 16, 0, 0);
; #pragma unroll
;     for (int i = 0; i < 4; ++i)
;       __builtin_amdgcn_global_load_lds((const unsigned*)(ys + i * ldy_i + kt * kys), LDS_PTR(sb + 32768 + i * 8192), 16, 0, 0);
;   };
;   __syncthreads();
;   issue(0, 0);
;   asm volatile("s_waitcnt vmcnt(0)" ::: "memory");
;   __syncthreads();
; #pragma unroll 1
;   for (int kt = 0; kt < nk; ++kt) {
;     const unsigned char* cur = smem + (kt & 1) * 65536;
;     if (kt + 1 < nk) issue(kt + 1, (kt + 1) & 1);
; DI void zero_acc(f32x4 (&acc)[4][8]) {
; #pragma unroll
;   for (int i = 0; i < 4; ++i)
; #pragma unroll
;     for (int j = 0; j < 8; ++j) acc[i][j] = f32x4{0.f, 0.f, 0.f, 0.f};
	global_load_lds_dwordx4 v[0:1], off
	v_lshl_add_u64 v[0:1], v[0:1], 0, s[30:31]
	s_mov_b32 m0, s7
	v_lshl_add_u64 v[136:137], v[132:133], 0, s[36:37]
	v_readfirstlane_b32 s7, v2
	v_add_u32_e32 v2, 0x6000, v128
	global_load_lds_dwordx4 v[0:1], off
	v_lshl_add_u64 v[0:1], v[136:137], 0, s[58:59]
	s_mov_b32 m0, s7
	v_lshl_add_u64 v[138:139], v[132:133], 0, s[38:39]
	v_readfirstlane_b32 s7, v2
	v_add_u32_e32 v2, 0x8000, v128
	global_load_lds_dwordx4 v[0:1], off
	v_lshl_add_u64 v[0:1], v[138:139], 0, s[58:59]
	s_mov_b32 m0, s7
	v_readfirstlane_b32 s7, v2
	v_add_u32_e32 v2, 0xa000, v128
	global_load_lds_dwordx4 v[0:1], off
	v_lshl_add_u64 v[0:1], v[134:135], 0, s[58:59]
	s_mov_b32 m0, s7
	v_lshl_add_u64 v[140:141], v[134:135], 0, s[24:25]
	v_readfirstlane_b32 s7, v2
	v_add_u32_e32 v2, 0xc000, v128
	global_load_lds_dwordx4 v[0:1], off
	v_lshl_add_u64 v[0:1], v[140:141], 0, s[58:59]
	s_mov_b32 m0, s7
	v_lshl_add_u64 v[142:143], v[134:135], 0, s[26:27]
	v_readfirstlane_b32 s7, v2
	v_add_u32_e32 v2, 0xe000, v128
	global_load_lds_dwordx4 v[0:1], off
	v_lshl_add_u64 v[0:1], v[142:143], 0, s[58:59]
	s_mov_b32 m0, s7
	v_lshl_add_u64 v[144:145], v[134:135], 0, s[28:29]
	v_readfirstlane_b32 s7, v2
	global_load_lds_dwordx4 v[0:1], off
	v_lshl_add_u64 v[0:1], v[144:145], 0, s[58:59]
	s_mov_b32 m0, s7
	v_lshlrev_b32_e32 v2, 7, v4
	global_load_lds_dwordx4 v[0:1], off
	v_bfe_u32 v0, v4, 4, 2
	v_bfe_u32 v1, v4, 1, 3
	v_readfirstlane_b32 s9, v4
	s_nop 0
	v_bitop3_b32 v0, v0, v1, 4 bitop3:0x36
	v_and_b32_e32 v2, 0x780, v2
	s_lshl_b32 s7, s9, 8
	s_lshl_b32 s9, s9, 6
	v_lshl_or_b32 v131, v0, 4, v2
	v_bitop3_b32 v0, v5, v1, 3 bitop3:0x6c
	v_mov_b32_e32 v8, 0
	s_and_b32 s7, s7, 0x4000
	s_and_b32 s9, s9, 0xffffe000
	v_lshl_or_b32 v146, v0, 4, v2
	s_mov_b32 s18, 0
	s_mov_b32 s33, 0x10000
	v_mov_b32_e32 v9, v8
	v_mov_b32_e32 v10, v8
	v_mov_b32_e32 v11, v8
	v_mov_b32_e32 v12, v8
	v_mov_b32_e32 v13, v8
	v_mov_b32_e32 v14, v8
	v_mov_b32_e32 v15, v8
	v_mov_b32_e32 v28, v8
	v_mov_b32_e32 v29, v8
	v_mov_b32_e32 v30, v8
	v_mov_b32_e32 v31, v8
	v_mov_b32_e32 v44, v8
	v_mov_b32_e32 v45, v8
	v_mov_b32_e32 v46, v8
	v_mov_b32_e32 v47, v8
	v_mov_b32_e32 v60, v8
	v_mov_b32_e32 v61, v8
	v_mov_b32_e32 v62, v8
	v_mov_b32_e32 v63, v8
	v_mov_b32_e32 v76, v8
	v_mov_b32_e32 v77, v8
	v_mov_b32_e32 v78, v8
	v_mov_b32_e32 v79, v8
	v_mov_b32_e32 v92, v8
	v_mov_b32_e32 v93, v8
	v_mov_b32_e32 v94, v8
	v_mov_b32_e32 v95, v8
	v_mov_b32_e32 v108, v8
	v_mov_b32_e32 v109, v8
	v_mov_b32_e32 v110, v8
	v_mov_b32_e32 v111, v8
	v_mov_b32_e32 v0, v8
	v_mov_b32_e32 v1, v8
	v_mov_b32_e32 v2, v8
	v_mov_b32_e32 v3, v8
	v_mov_b32_e32 v20, v8
	v_mov_b32_e32 v21, v8
	v_mov_b32_e32 v22, v8
	v_mov_b32_e32 v23, v8
	v_mov_b32_e32 v36, v8
	v_mov_b32_e32 v37, v8
	v_mov_b32_e32 v38, v8
	v_mov_b32_e32 v39, v8
	v_mov_b32_e32 v52, v8
	v_mov_b32_e32 v53, v8
	v_mov_b32_e32 v54, v8
	v_mov_b32_e32 v55, v8
	v_mov_b32_e32 v68, v8
	v_mov_b32_e32 v69, v8
	v_mov_b32_e32 v70, v8
	v_mov_b32_e32 v71, v8
	v_mov_b32_e32 v84, v8
	v_mov_b32_e32 v85, v8
	v_mov_b32_e32 v86, v8
	v_mov_b32_e32 v87, v8
	v_mov_b32_e32 v100, v8
	v_mov_b32_e32 v101, v8
	v_mov_b32_e32 v102, v8
	v_mov_b32_e32 v103, v8
	v_mov_b32_e32 v116, v8
	v_mov_b32_e32 v117, v8
	v_mov_b32_e32 v118, v8
	v_mov_b32_e32 v119, v8
	v_mov_b32_e32 v4, v8
	v_mov_b32_e32 v5, v8
	v_mov_b32_e32 v6, v8
	v_mov_b32_e32 v7, v8
	v_mov_b32_e32 v24, v8
	v_mov_b32_e32 v25, v8
	v_mov_b32_e32 v26, v8
	v_mov_b32_e32 v27, v8
	v_mov_b32_e32 v40, v8
	v_mov_b32_e32 v41, v8
	v_mov_b32_e32 v42, v8
	v_mov_b32_e32 v43, v8
	v_mov_b32_e32 v56, v8
	v_mov_b32_e32 v57, v8
	v_mov_b32_e32 v58, v8
	v_mov_b32_e32 v59, v8
	v_mov_b32_e32 v72, v8
	v_mov_b32_e32 v73, v8
	v_mov_b32_e32 v74, v8
	v_mov_b32_e32 v75, v8
	v_mov_b32_e32 v88, v8
	v_mov_b32_e32 v89, v8
	v_mov_b32_e32 v90, v8
	v_mov_b32_e32 v91, v8
	v_mov_b32_e32 v104, v8
	v_mov_b32_e32 v105, v8
	v_mov_b32_e32 v106, v8
	v_mov_b32_e32 v107, v8
	v_mov_b32_e32 v120, v8
	v_mov_b32_e32 v121, v8
	v_mov_b32_e32 v122, v8
	v_mov_b32_e32 v123, v8
	v_mov_b32_e32 v16, v8
	v_mov_b32_e32 v17, v8
	v_mov_b32_e32 v18, v8
	v_mov_b32_e32 v19, v8
	v_mov_b32_e32 v32, v8
	v_mov_b32_e32 v33, v8
	v_mov_b32_e32 v34, v8
	v_mov_b32_e32 v35, v8
	v_mov_b32_e32 v48, v8
	v_mov_b32_e32 v49, v8
	v_mov_b32_e32 v50, v8
	v_mov_b32_e32 v51, v8
	v_mov_b32_e32 v64, v8
	v_mov_b32_e32 v65, v8
	v_mov_b32_e32 v66, v8
	v_mov_b32_e32 v67, v8
	v_mov_b32_e32 v80, v8
	v_mov_b32_e32 v81, v8
	v_mov_b32_e32 v82, v8
	v_mov_b32_e32 v83, v8
	v_mov_b32_e32 v96, v8
	v_mov_b32_e32 v97, v8
	v_mov_b32_e32 v98, v8
	v_mov_b32_e32 v99, v8
	v_mov_b32_e32 v112, v8
	v_mov_b32_e32 v113, v8
	v_mov_b32_e32 v114, v8
	v_mov_b32_e32 v115, v8
	v_mov_b32_e32 v124, v8
	v_mov_b32_e32 v125, v8
	v_mov_b32_e32 v126, v8
	v_mov_b32_e32 v127, v8
	s_add_i32 s40, s57, s18
	s_cmp_lt_u32 s40, 16
	s_cselect_b32 s41, 0, -16
	s_add_i32 s48, s40, s41
	s_and_b32 s40, s33, 0x10000
	v_add_u32_e32 v147, s40, v128
	s_ashr_i32 s49, s48, 31
	s_lshl_b64 s[48:49], s[48:49], 7
	v_readfirstlane_b32 s40, v147
	v_add_u32_e32 v158, 0x2000, v147
	v_lshl_add_u64 v[156:157], v[132:133], 0, s[48:49]
	s_mov_b32 m0, s40
	v_readfirstlane_b32 s40, v158
	v_add_u32_e32 v158, 0x4000, v147
	global_load_lds_dwordx4 v[156:157], off
	v_lshl_add_u64 v[156:157], v[156:157], 0, s[30:31]
	s_mov_b32 m0, s40
	v_readfirstlane_b32 s40, v158
	v_add_u32_e32 v158, 0x6000, v147
	global_load_lds_dwordx4 v[156:157], off
	v_lshl_add_u64 v[156:157], v[136:137], 0, s[48:49]
	s_mov_b32 m0, s40
	v_readfirstlane_b32 s40, v158
	v_add_u32_e32 v158, 0x8000, v147
	global_load_lds_dwordx4 v[156:157], off
	v_lshl_add_u64 v[156:157], v[138:139], 0, s[48:49]
	s_mov_b32 m0, s40
	v_readfirstlane_b32 s40, v158
	v_add_u32_e32 v158, 0xa000, v147
	global_load_lds_dwordx4 v[156:157], off
	v_lshl_add_u64 v[156:157], v[134:135], 0, s[48:49]
	s_mov_b32 m0, s40
	v_readfirstlane_b32 s40, v158
	v_add_u32_e32 v158, 0xc000, v147
	global_load_lds_dwordx4 v[156:157], off
	v_lshl_add_u64 v[156:157], v[140:141], 0, s[48:49]
	s_mov_b32 m0, s40
	v_readfirstlane_b32 s40, v158
	v_add_u32_e32 v147, 0xe000, v147
	global_load_lds_dwordx4 v[156:157], off
	v_lshl_add_u64 v[156:157], v[142:143], 0, s[48:49]
	s_mov_b32 m0, s40
	v_readfirstlane_b32 s40, v147
	global_load_lds_dwordx4 v[156:157], off
	v_lshl_add_u64 v[156:157], v[144:145], 0, s[48:49]
	s_mov_b32 m0, s40
	s_nop 0
	global_load_lds_dwordx4 v[156:157], off
	s_waitcnt vmcnt(8) lgkmcnt(0)
	s_barrier
	s_branch .LBB0_88

; template <int PIPE>
; DI void gemm_loop_g(const u16* __restrict__ Xp, long ldx_l, long ldx_i, long kxs,
;                     const u16* __restrict__ Yp, long ldy_l, long ldy_i, long kys, int K,
;                     f32x4 (&acc)[4][8], unsigned char* smem) {
;   const int t = tid_opaque(), l = t & 63, w = __builtin_amdgcn_readfirstlane(t >> 6), wx = w >> 1, wy = w & 1;
;   const int lrow = t >> 3, gch = (t & 7) ^ ((t >> 4) & 7);
;   const u16* xs = Xp + (long)lrow * ldx_l + gch * 8;
;   const u16* ys = Yp + (long)lrow * ldy_l + gch * 8;
; template <int MODE>
; DI void gemm_phase(const Params& p, const GP& g, unsigned char* smem) {
;     ...
;     int bsel = 0;
;     {
;       const int ml = e / g.ntn;
;       nt = e - ml * g.ntn;
;       mt = xcd + 8 * ml;
;     }
;     if (MODE == M_SEQ) { bsel = mt >> 4; mt &= 15; Wb = g.W + (long)bsel * 1024 * 8192; }
;     const int m0 = mt * 256, n0 = nt * 256;
;     f32x4 acc[4][8];
;     zero_acc(acc);
;     int transposed = 0;
;     if (MODE == M_FN_IN) transposed = nt < 8;
;     if (MODE == M_NA_IN) transposed = (nt >= 8 && nt < 12);
;     if (MODE == M_MLA_UKV) transposed = nt >= 4;
;     if (MODE == M_HG_IN) transposed = nt >= 12;
;     if (MODE == M_PLE) {
;       const u16* pb = (const u16*)g.d1;
;       gemm_loop(g.W2 + (long)n0 * 256, 256, pb + (long)m0 * 256, 256, 256, acc, smem);
;       u16* xb = (u16*)g.d0;
;       EPI_STD_BEGIN
;         *(u32x2*)(xb + (long)m * 1024 + n4) = pack4(v[0], v[1], v[2], v[3]);
;       EPI_END
;       zero_acc(acc);
;     }
;     if (MODE == M_FFT1) {
;       const int bt = mt >> 8, cg = mt & 255;
;       gemm_loop_g<0>(Ab + ((long)(bt * 1024 + cg * 4)) * 8192, 64, 8192, 4096, Wb, 128, 64 * 128, 64, 128, acc, smem);
;     } else if (MODE == M_FFT3) {
;       const int bt = mt >> 8, v = (mt >> 2) & 63, cq = mt & 3;
;       gemm_loop(Ab + (((long)(bt * 64 + v)) * 1024 + cq * 256) * 128, 128, Wb, 128, 128, acc, smem);
;     } else if (MODE == M_FN_IN && transposed) {
;       const u16* Ap = Ab + ((long)(mt >> 4) * 4096 + (mt & 15) * 4) * g.lda;
;       gemm_loop_g<1>(Ap, 64 * g.lda, g.lda, 64, Wb + (long)n0 * g.K, g.K, 64L * g.K, 64, g.K, acc, smem);
;     } else {
;       const u16* Ap = Ab + (long)m0 * g.lda; const u16* Wp = Wb + (long)n0 * g.K;
;       if (transposed) gemm_loop(Ap, g.lda, Wp, g.K, g.K, acc, smem);
;       else gemm_loop(Wp, g.K, Ap, g.lda, g.K, acc, smem);
.LBB0_146:
	s_lshl_b32 s10, s58, 9
	s_and_b32 s10, s10, 0xfffff800
	s_or_b32 s28, s10, s54
	s_lshl_b32 s10, s58, 8
	s_and_b32 s10, s10, 0x300
	s_lshl_b32 s11, s10, 11
	s_add_u32 s30, s6, s11
	s_addc_u32 s31, s7, 0
	s_ashr_i32 s29, s28, 31
	v_mov_b32_e32 v4, v182
	s_lshl_b64 s[48:49], s[28:29], 11
	s_add_u32 s48, s52, s48
	v_ashrrev_i32_e32 v0, 3, v4
	v_lshrrev_b32_e32 v5, 4, v4
	v_xor_b32_e32 v6, v5, v4
	v_ashrrev_i32_e32 v1, 31, v0
	s_addc_u32 s49, s53, s49
	v_lshlrev_b64 v[0:1], 11, v[0:1]
	v_lshlrev_b32_e32 v6, 4, v6
	v_lshl_add_u64 v[2:3], s[30:31], 0, v[0:1]
	v_and_b32_e32 v128, 0x70, v6
	v_lshl_add_u64 v[0:1], s[48:49], 0, v[0:1]
	v_lshl_add_u64 v[130:131], v[2:3], 0, v[128:129]
	v_lshl_add_u64 v[132:133], v[0:1], 0, v[128:129]
	v_lshlrev_b32_e32 v128, 4, v4
	v_add_u32_e32 v2, 0x2000, v128
	v_readfirstlane_b32 s11, v128
	v_lshl_add_u64 v[0:1], v[130:131], 0, s[8:9]
	s_mov_b32 m0, s11
	v_lshl_add_u64 v[134:135], v[130:131], 0, s[14:15]
	v_readfirstlane_b32 s11, v2
	v_add_u32_e32 v2, 0x4000, v128
	s_barrier
; #define LDS_PTR(p) ((__attribute__((address_space(3))) unsigned*)(p))
; template <int PIPE>
; DI void gemm_loop_g(const u16* __restrict__ Xp, long ldx_l, long ldx_i, long kxs,
;                     const u16* __restrict__ Yp, long ldy_l, long ldy_i, long kys, int K,
;                     f32x4 (&acc)[4][8], unsigned char* smem) {
;     ...
;   auto issue = [&](int kt0, int stage) {
;     int kt = kt0 + rot; if (kt >= nk) kt -= nk;
;     unsigned char* sb = smem + stage * 65536 + t * 16;
; #pragma unroll
;     for (int i = 0; i < 4; ++i)
;       __builtin_amdgcn_global_load_lds((const unsigned*)(xs + i * ldx_i + kt * kxs), LDS_PTR(sb + i * 8192), 16, 0, 0);
; #pragma unroll
;     for (int i = 0; i < 4; ++i)
;       __builtin_amdgcn_global_load_lds((const unsigned*)(ys + i * ldy_i + kt * kys), LDS_PTR(sb + 32768 + i * 8192), 16, 0, 0);
;   };
;   __syncthreads();
;   issue(0, 0);
;   asm volatile("s_waitcnt vmcnt(0)" ::: "memory");
;   __syncthreads();
; #pragma unroll 1
;   for (int kt = 0; kt < nk; ++kt) {
;     const unsigned char* cur = smem + (kt & 1) * 65536;
;     if (kt + 1 < nk) issue(kt + 1, (kt + 1) & 1);
; DI void zero_acc(f32x4 (&acc)[4][8]) {
; #pragma unroll
;   for (int i = 0; i < 4; ++i)
; #pragma unroll
;     for (int j = 0; j < 8; ++j) acc[i][j] = f32x4{0.f, 0.f, 0.f, 0.f};
	global_load_lds_dwordx4 v[0:1], off
	v_lshl_add_u64 v[0:1], v[134:135], 0, s[8:9]
	s_mov_b32 m0, s11
	v_lshl_add_u64 v[136:137], v[130:131], 0, s[24:25]
	v_readfirstlane_b32 s11, v2
	v_add_u32_e32 v2, 0x6000, v128
	global_load_lds_dwordx4 v[0:1], off
	v_lshl_add_u64 v[0:1], v[136:137], 0, s[8:9]
	s_mov_b32 m0, s11
	v_lshl_add_u64 v[138:139], v[130:131], 0, s[26:27]
	v_readfirstlane_b32 s11, v2
	v_add_u32_e32 v2, 0x8000, v128
	global_load_lds_dwordx4 v[0:1], off
	v_lshl_add_u64 v[0:1], v[138:139], 0, s[8:9]
	s_mov_b32 m0, s11
	v_readfirstlane_b32 s11, v2
	v_add_u32_e32 v2, 0xa000, v128
	global_load_lds_dwordx4 v[0:1], off
	v_lshl_add_u64 v[0:1], v[132:133], 0, s[8:9]
	s_mov_b32 m0, s11
	v_lshl_add_u64 v[140:141], v[132:133], 0, s[14:15]
	v_readfirstlane_b32 s11, v2
	v_add_u32_e32 v2, 0xc000, v128
	global_load_lds_dwordx4 v[0:1], off
	v_lshl_add_u64 v[0:1], v[140:141], 0, s[8:9]
	s_mov_b32 m0, s11
	v_lshl_add_u64 v[142:143], v[132:133], 0, s[24:25]
	v_readfirstlane_b32 s11, v2
	v_add_u32_e32 v2, 0xe000, v128
	global_load_lds_dwordx4 v[0:1], off
	v_lshl_add_u64 v[0:1], v[142:143], 0, s[8:9]
	s_mov_b32 m0, s11
	v_lshl_add_u64 v[144:145], v[132:133], 0, s[26:27]
	v_readfirstlane_b32 s11, v2
	global_load_lds_dwordx4 v[0:1], off
	v_lshl_add_u64 v[0:1], v[144:145], 0, s[8:9]
	s_mov_b32 m0, s11
	v_lshlrev_b32_e32 v2, 7, v4
	global_load_lds_dwordx4 v[0:1], off
	v_bfe_u32 v0, v4, 4, 2
	v_bfe_u32 v1, v4, 1, 3
	v_readfirstlane_b32 s29, v4
	s_nop 0
	v_bitop3_b32 v0, v0, v1, 4 bitop3:0x36
	v_and_b32_e32 v2, 0x780, v2
	s_lshl_b32 s11, s29, 8
	s_lshl_b32 s29, s29, 6
	v_lshl_or_b32 v148, v0, 4, v2
	v_bitop3_b32 v0, v5, v1, 3 bitop3:0x6c
	s_and_b32 s11, s11, 0x4000
	s_and_b32 s29, s29, 0xffffe000
	v_lshl_or_b32 v149, v0, 4, v2
	s_mov_b32 s30, 0x10000
	s_mov_b32 s31, 0
	v_mov_b32_e32 v12, 0
	v_mov_b32_e32 v13, v129
	v_mov_b32_e32 v14, v129
	v_mov_b32_e32 v15, v129
	v_mov_b32_e32 v4, 0
	v_mov_b32_e32 v5, v129
	v_mov_b32_e32 v6, v129
	v_mov_b32_e32 v7, v129
	v_mov_b32_e32 v24, 0
	v_mov_b32_e32 v25, v129
	v_mov_b32_e32 v26, v129
	v_mov_b32_e32 v27, v129
	v_mov_b32_e32 v40, 0
	v_mov_b32_e32 v41, v129
	v_mov_b32_e32 v42, v129
	v_mov_b32_e32 v43, v129
	v_mov_b32_e32 v56, 0
	v_mov_b32_e32 v57, v129
	v_mov_b32_e32 v58, v129
	v_mov_b32_e32 v59, v129
	v_mov_b32_e32 v72, 0
	v_mov_b32_e32 v73, v129
	v_mov_b32_e32 v74, v129
	v_mov_b32_e32 v75, v129
	v_mov_b32_e32 v88, 0
	v_mov_b32_e32 v89, v129
	v_mov_b32_e32 v90, v129
	v_mov_b32_e32 v91, v129
	v_mov_b32_e32 v104, 0
	v_mov_b32_e32 v105, v129
	v_mov_b32_e32 v106, v129
	v_mov_b32_e32 v107, v129
	v_mov_b32_e32 v0, 0
	v_mov_b32_e32 v1, v129
	v_mov_b32_e32 v2, v129
	v_mov_b32_e32 v3, v129
	v_mov_b32_e32 v20, 0
	v_mov_b32_e32 v21, v129
	v_mov_b32_e32 v22, v129
	v_mov_b32_e32 v23, v129
	v_mov_b32_e32 v36, 0
	v_mov_b32_e32 v37, v129
	v_mov_b32_e32 v38, v129
	v_mov_b32_e32 v39, v129
	v_mov_b32_e32 v52, 0
	v_mov_b32_e32 v53, v129
	v_mov_b32_e32 v54, v129
	v_mov_b32_e32 v55, v129
	v_mov_b32_e32 v68, 0
	v_mov_b32_e32 v69, v129
	v_mov_b32_e32 v70, v129
	v_mov_b32_e32 v71, v129
	v_mov_b32_e32 v84, 0
	v_mov_b32_e32 v85, v129
	v_mov_b32_e32 v86, v129
	v_mov_b32_e32 v87, v129
	v_mov_b32_e32 v100, 0
	v_mov_b32_e32 v101, v129
	v_mov_b32_e32 v102, v129
	v_mov_b32_e32 v103, v129
	v_mov_b32_e32 v116, 0
	v_mov_b32_e32 v117, v129
	v_mov_b32_e32 v118, v129
	v_mov_b32_e32 v119, v129
	v_mov_b32_e32 v8, 0
	v_mov_b32_e32 v9, v129
	v_mov_b32_e32 v10, v129
	v_mov_b32_e32 v11, v129
	v_mov_b32_e32 v28, 0
	v_mov_b32_e32 v29, v129
	v_mov_b32_e32 v30, v129
	v_mov_b32_e32 v31, v129
	v_mov_b32_e32 v44, 0
	v_mov_b32_e32 v45, v129
	v_mov_b32_e32 v46, v129
	v_mov_b32_e32 v47, v129
	v_mov_b32_e32 v60, 0
	v_mov_b32_e32 v61, v129
	v_mov_b32_e32 v62, v129
	v_mov_b32_e32 v63, v129
	v_mov_b32_e32 v76, 0
	v_mov_b32_e32 v77, v129
	v_mov_b32_e32 v78, v129
	v_mov_b32_e32 v79, v129
	v_mov_b32_e32 v92, 0
	v_mov_b32_e32 v93, v129
	v_mov_b32_e32 v94, v129
	v_mov_b32_e32 v95, v129
	v_mov_b32_e32 v108, 0
	v_mov_b32_e32 v109, v129
	v_mov_b32_e32 v110, v129
	v_mov_b32_e32 v111, v129
	v_mov_b32_e32 v120, 0
	v_mov_b32_e32 v121, v129
	v_mov_b32_e32 v122, v129
	v_mov_b32_e32 v123, v129
	v_mov_b32_e32 v16, 0
	v_mov_b32_e32 v17, v129
	v_mov_b32_e32 v18, v129
	v_mov_b32_e32 v19, v129
	v_mov_b32_e32 v32, 0
	v_mov_b32_e32 v33, v129
	v_mov_b32_e32 v34, v129
	v_mov_b32_e32 v35, v129
	v_mov_b32_e32 v48, 0
	v_mov_b32_e32 v49, v129
	v_mov_b32_e32 v50, v129
	v_mov_b32_e32 v51, v129
	v_mov_b32_e32 v64, 0
	v_mov_b32_e32 v65, v129
	v_mov_b32_e32 v66, v129
	v_mov_b32_e32 v67, v129
	v_mov_b32_e32 v80, 0
	v_mov_b32_e32 v81, v129
	v_mov_b32_e32 v82, v129
	v_mov_b32_e32 v83, v129
	v_mov_b32_e32 v96, 0
	v_mov_b32_e32 v97, v129
	v_mov_b32_e32 v98, v129
	v_mov_b32_e32 v99, v129
	v_mov_b32_e32 v112, 0
	v_mov_b32_e32 v113, v129
	v_mov_b32_e32 v114, v129
	v_mov_b32_e32 v115, v129
	v_mov_b32_e32 v124, 0
	v_mov_b32_e32 v125, v129
	v_mov_b32_e32 v126, v129
	v_mov_b32_e32 v127, v129
	s_add_i32 s33, s57, s31
	s_cmp_lt_u32 s33, 16
	s_cselect_b32 s40, 0, -16
	s_add_i32 s48, s33, s40
	s_and_b32 s33, s30, 0x10000
	v_add_u32_e32 v152, s33, v128
	s_ashr_i32 s49, s48, 31
	s_lshl_b64 s[48:49], s[48:49], 7
	v_readfirstlane_b32 s33, v152
	v_add_u32_e32 v153, 0x2000, v152
	v_lshl_add_u64 v[150:151], v[130:131], 0, s[48:49]
	s_mov_b32 m0, s33
	v_readfirstlane_b32 s33, v153
	v_add_u32_e32 v153, 0x4000, v152
	global_load_lds_dwordx4 v[150:151], off
	v_lshl_add_u64 v[150:151], v[134:135], 0, s[48:49]
	s_mov_b32 m0, s33
	v_readfirstlane_b32 s33, v153
	v_add_u32_e32 v153, 0x6000, v152
	global_load_lds_dwordx4 v[150:151], off
	v_lshl_add_u64 v[150:151], v[136:137], 0, s[48:49]
	s_mov_b32 m0, s33
	v_readfirstlane_b32 s33, v153
	v_add_u32_e32 v153, 0x8000, v152
	global_load_lds_dwordx4 v[150:151], off
	v_lshl_add_u64 v[150:151], v[138:139], 0, s[48:49]
	s_mov_b32 m0, s33
	v_readfirstlane_b32 s33, v153
	v_add_u32_e32 v153, 0xa000, v152
	global_load_lds_dwordx4 v[150:151], off
	v_lshl_add_u64 v[150:151], v[132:133], 0, s[48:49]
	s_mov_b32 m0, s33
	v_readfirstlane_b32 s33, v153
	v_add_u32_e32 v153, 0xc000, v152
	global_load_lds_dwordx4 v[150:151], off
	v_lshl_add_u64 v[150:151], v[140:141], 0, s[48:49]
	s_mov_b32 m0, s33
	v_readfirstlane_b32 s33, v153
	v_add_u32_e32 v152, 0xe000, v152
	global_load_lds_dwordx4 v[150:151], off
	v_lshl_add_u64 v[150:151], v[142:143], 0, s[48:49]
	s_mov_b32 m0, s33
	v_readfirstlane_b32 s33, v152
	global_load_lds_dwordx4 v[150:151], off
	v_lshl_add_u64 v[150:151], v[144:145], 0, s[48:49]
	s_mov_b32 m0, s33
	s_nop 0
	global_load_lds_dwordx4 v[150:151], off
	s_waitcnt vmcnt(8) lgkmcnt(0)
	s_barrier
	s_branch .LBB0_147

; DI int tid_opaque() { int t = threadIdx.x; asm volatile("" : "+v"(t)); return t; }
; #define LDS_PTR(p) ((__attribute__((address_space(3))) unsigned*)(p))
; template <int PIPE>
; DI void gemm_loop_g(const u16* __restrict__ Xp, long ldx_l, long ldx_i, long kxs,
;                     const u16* __restrict__ Yp, long ldy_l, long ldy_i, long kys, int K,
;                     f32x4 (&acc)[4][8], unsigned char* smem) {
;   const int t = tid_opaque(), l = t & 63, w = __builtin_amdgcn_readfirstlane(t >> 6), wx = w >> 1, wy = w & 1;
;   const int lrow = t >> 3, gch = (t & 7) ^ ((t >> 4) & 7);
;   const u16* xs = Xp + (long)lrow * ldx_l + gch * 8;
;   const u16* ys = Yp + (long)lrow * ldy_l + gch * 8;
;   const int fsw = (l >> 1) & 7, lg = l >> 4;
;   const unsigned fr0 = (l & 15) * 128 + ((lg ^ fsw) << 4);
;   const unsigned fr1 = (l & 15) * 128 + (((lg + 4) ^ fsw) << 4);
;   const unsigned ub = wx * 8192, vb = 32768 + wy * 16384;
;   const int nk = K >> 6;
;   const int rot = (int)((blockIdx.x >> 3) + (blockIdx.x & 7) * 5) % nk;
;   auto issue = [&](int kt0, int stage) {
;     int kt = kt0 + rot; if (kt >= nk) kt -= nk;
;     unsigned char* sb = smem + stage * 65536 + t * 16;
; #pragma unroll
;     for (int i = 0; i < 4; ++i)
;       __builtin_amdgcn_global_load_lds((const unsigned*)(xs + i * ldx_i + kt * kxs), LDS_PTR(sb + i * 8192), 16, 0, 0);
; #pragma unroll
;     for (int i = 0; i < 4; ++i)
;       __builtin_amdgcn_global_load_lds((const unsigned*)(ys + i * ldy_i + kt * kys), LDS_PTR(sb + 32768 + i * 8192), 16, 0, 0);
;   };
;   __syncthreads();
; template <int MODE>
; DI void gemm_phase(const Params& p, const GP& g, unsigned char* smem) {
;     ...
;       const u16* pb = (const u16*)g.d1;
;       gemm_loop(g.W2 + (long)n0 * 256, 256, pb + (long)m0 * 256, 256, 256, acc, smem);
.LBB0_166:
	s_lshl_b32 s6, s69, 9
	s_and_b32 s6, s6, 0xfffff800
	s_or_b32 s12, s6, s66
	s_lshl_b32 s6, s69, 8
	s_and_b32 s6, s6, 0x300
	s_lshl_b32 s7, s6, 9
	s_add_u32 s8, s16, s7
	v_mov_b32_e32 v6, v182
	s_addc_u32 s9, s17, 0
	s_ashr_i32 s13, s12, 31
	s_lshl_b64 s[10:11], s[12:13], 9
	v_ashrrev_i32_e32 v2, 3, v6
	v_lshrrev_b32_e32 v7, 4, v6
	v_xor_b32_e32 v8, v7, v6
	v_ashrrev_i32_e32 v3, 31, v2
	s_waitcnt lgkmcnt(0)
	v_lshl_add_u64 v[0:1], v[128:129], 0, s[10:11]
	v_lshlrev_b64 v[2:3], 9, v[2:3]
	v_lshlrev_b32_e32 v8, 4, v8
	v_lshl_add_u64 v[4:5], s[8:9], 0, v[2:3]
	v_and_b32_e32 v130, 0x70, v8
	v_lshl_add_u64 v[0:1], v[0:1], 0, v[2:3]
	v_lshl_add_u64 v[132:133], v[4:5], 0, v[130:131]
	v_lshl_add_u64 v[134:135], v[0:1], 0, v[130:131]
	v_lshlrev_b32_e32 v130, 4, v6
	v_add_u32_e32 v2, 0x2000, v130
	v_readfirstlane_b32 s7, v130
	v_lshl_add_u64 v[0:1], v[132:133], 0, s[24:25]
	s_mov_b32 m0, s7
	v_lshl_add_u64 v[136:137], v[132:133], 0, s[28:29]
	v_readfirstlane_b32 s7, v2
	v_add_u32_e32 v2, 0x4000, v130
	s_barrier
; #define LDS_PTR(p) ((__attribute__((address_space(3))) unsigned*)(p))
; template <int PIPE>
; DI void gemm_loop_g(const u16* __restrict__ Xp, long ldx_l, long ldx_i, long kxs,
;                     const u16* __restrict__ Yp, long ldy_l, long ldy_i, long kys, int K,
;                     f32x4 (&acc)[4][8], unsigned char* smem) {
;     ...
;   auto issue = [&](int kt0, int stage) {
;     int kt = kt0 + rot; if (kt >= nk) kt -= nk;
;     unsigned char* sb = smem + stage * 65536 + t * 16;
; #pragma unroll
;     for (int i = 0; i < 4; ++i)
;       __builtin_amdgcn_global_load_lds((const unsigned*)(xs + i * ldx_i + kt * kxs), LDS_PTR(sb + i * 8192), 16, 0, 0);
; #pragma unroll
;     for (int i = 0; i < 4; ++i)
;       __builtin_amdgcn_global_load_lds((const unsigned*)(ys + i * ldy_i + kt * kys), LDS_PTR(sb + 32768 + i * 8192), 16, 0, 0);
;   };
;   __syncthreads();
;   issue(0, 0);
;   asm volatile("s_waitcnt vmcnt(0)" ::: "memory");
;   __syncthreads();
; #pragma unroll 1
;   for (int kt = 0; kt < nk; ++kt) {
;     const unsigned char* cur = smem + (kt & 1) * 65536;
;     if (kt + 1 < nk) issue(kt + 1, (kt + 1) & 1);
; DI void zero_acc(f32x4 (&acc)[4][8]) {
; #pragma unroll
;   for (int i = 0; i < 4; ++i)
; #pragma unroll
;     for (int j = 0; j < 8; ++j) acc[i][j] = f32x4{0.f, 0.f, 0.f, 0.f};
	global_load_lds_dwordx4 v[0:1], off
	v_lshl_add_u64 v[0:1], v[136:137], 0, s[24:25]
	s_mov_b32 m0, s7
	v_lshl_add_u64 v[138:139], v[132:133], 0, s[30:31]
	v_readfirstlane_b32 s7, v2
	v_add_u32_e32 v2, 0x6000, v130
	global_load_lds_dwordx4 v[0:1], off
	v_lshl_add_u64 v[0:1], v[138:139], 0, s[24:25]
	s_mov_b32 m0, s7
	v_lshl_add_u64 v[140:141], v[132:133], 0, s[54:55]
	v_readfirstlane_b32 s7, v2
	v_add_u32_e32 v2, 0x8000, v130
	global_load_lds_dwordx4 v[0:1], off
	v_lshl_add_u64 v[0:1], v[140:141], 0, s[24:25]
	s_mov_b32 m0, s7
	v_readfirstlane_b32 s7, v2
	v_add_u32_e32 v2, 0xa000, v130
	global_load_lds_dwordx4 v[0:1], off
	v_lshl_add_u64 v[0:1], v[134:135], 0, s[24:25]
	s_mov_b32 m0, s7
	v_lshl_add_u64 v[142:143], v[134:135], 0, s[28:29]
	v_readfirstlane_b32 s7, v2
	v_add_u32_e32 v2, 0xc000, v130
	global_load_lds_dwordx4 v[0:1], off
	v_lshl_add_u64 v[0:1], v[142:143], 0, s[24:25]
	s_mov_b32 m0, s7
	v_lshl_add_u64 v[144:145], v[134:135], 0, s[30:31]
	v_readfirstlane_b32 s7, v2
	v_add_u32_e32 v2, 0xe000, v130
	global_load_lds_dwordx4 v[0:1], off
	v_lshl_add_u64 v[0:1], v[144:145], 0, s[24:25]
	s_mov_b32 m0, s7
	v_lshl_add_u64 v[146:147], v[134:135], 0, s[54:55]
	v_readfirstlane_b32 s7, v2
	global_load_lds_dwordx4 v[0:1], off
	v_lshl_add_u64 v[0:1], v[146:147], 0, s[24:25]
	s_mov_b32 m0, s7
	v_lshlrev_b32_e32 v2, 7, v6
	global_load_lds_dwordx4 v[0:1], off
	v_bfe_u32 v0, v6, 4, 2
	v_bfe_u32 v1, v6, 1, 3
	v_readfirstlane_b32 s10, v6
	s_nop 0
	v_bitop3_b32 v0, v0, v1, 4 bitop3:0x36
	v_and_b32_e32 v2, 0x780, v2
	s_lshl_b32 s7, s10, 8
	s_lshl_b32 s8, s10, 6
	v_lshl_or_b32 v148, v0, 4, v2
	v_bitop3_b32 v0, v7, v1, 3 bitop3:0x6c
	s_and_b32 s7, s7, 0x4000
	s_and_b32 s10, s8, 0xffffe000
	v_lshl_or_b32 v149, v0, 4, v2
	s_mov_b32 s11, 0x10000
	s_mov_b32 s33, 0
	v_mov_b32_e32 v40, 0
	v_mov_b32_e32 v41, v131
	v_mov_b32_e32 v42, v131
	v_mov_b32_e32 v43, v131
	v_mov_b32_e32 v0, 0
	v_mov_b32_e32 v1, v131
	v_mov_b32_e32 v2, v131
	v_mov_b32_e32 v3, v131
	v_mov_b32_e32 v8, 0
	v_mov_b32_e32 v9, v131
	v_mov_b32_e32 v10, v131
	v_mov_b32_e32 v11, v131
	v_mov_b32_e32 v20, 0
	v_mov_b32_e32 v21, v131
	v_mov_b32_e32 v22, v131
	v_mov_b32_e32 v23, v131
	v_mov_b32_e32 v36, 0
	v_mov_b32_e32 v37, v131
	v_mov_b32_e32 v38, v131
	v_mov_b32_e32 v39, v131
	v_mov_b32_e32 v56, 0
	v_mov_b32_e32 v57, v131
	v_mov_b32_e32 v58, v131
	v_mov_b32_e32 v59, v131
	v_mov_b32_e32 v72, 0
	v_mov_b32_e32 v73, v131
	v_mov_b32_e32 v74, v131
	v_mov_b32_e32 v75, v131
	v_mov_b32_e32 v96, 0
	v_mov_b32_e32 v97, v131
	v_mov_b32_e32 v98, v131
	v_mov_b32_e32 v99, v131
	v_mov_b32_e32 v4, 0
	v_mov_b32_e32 v5, v131
	v_mov_b32_e32 v6, v131
	v_mov_b32_e32 v7, v131
	v_mov_b32_e32 v12, 0
	v_mov_b32_e32 v13, v131
	v_mov_b32_e32 v14, v131
	v_mov_b32_e32 v15, v131
	v_mov_b32_e32 v24, 0
	v_mov_b32_e32 v25, v131
	v_mov_b32_e32 v26, v131
	v_mov_b32_e32 v27, v131
	v_mov_b32_e32 v44, 0
	v_mov_b32_e32 v45, v131
	v_mov_b32_e32 v46, v131
	v_mov_b32_e32 v47, v131
	v_mov_b32_e32 v64, 0
	v_mov_b32_e32 v65, v131
	v_mov_b32_e32 v66, v131
	v_mov_b32_e32 v67, v131
	v_mov_b32_e32 v76, 0
	v_mov_b32_e32 v77, v131
	v_mov_b32_e32 v78, v131
	v_mov_b32_e32 v79, v131
	v_mov_b32_e32 v88, 0
	v_mov_b32_e32 v89, v131
	v_mov_b32_e32 v90, v131
	v_mov_b32_e32 v91, v131
	v_mov_b32_e32 v112, 0
	v_mov_b32_e32 v113, v131
	v_mov_b32_e32 v114, v131
	v_mov_b32_e32 v115, v131
	v_mov_b32_e32 v16, 0
	v_mov_b32_e32 v17, v131
	v_mov_b32_e32 v18, v131
	v_mov_b32_e32 v19, v131
	v_mov_b32_e32 v28, 0
	v_mov_b32_e32 v29, v131
	v_mov_b32_e32 v30, v131
	v_mov_b32_e32 v31, v131
	v_mov_b32_e32 v48, 0
	v_mov_b32_e32 v49, v131
	v_mov_b32_e32 v50, v131
	v_mov_b32_e32 v51, v131
	v_mov_b32_e32 v60, 0
	v_mov_b32_e32 v61, v131
	v_mov_b32_e32 v62, v131
	v_mov_b32_e32 v63, v131
	v_mov_b32_e32 v80, 0
	v_mov_b32_e32 v81, v131
	v_mov_b32_e32 v82, v131
	v_mov_b32_e32 v83, v131
	v_mov_b32_e32 v92, 0
	v_mov_b32_e32 v93, v131
	v_mov_b32_e32 v94, v131
	v_mov_b32_e32 v95, v131
	v_mov_b32_e32 v108, 0
	v_mov_b32_e32 v109, v131
	v_mov_b32_e32 v110, v131
	v_mov_b32_e32 v111, v131
	v_mov_b32_e32 v116, 0
	v_mov_b32_e32 v117, v131
	v_mov_b32_e32 v118, v131
	v_mov_b32_e32 v119, v131
	v_mov_b32_e32 v32, 0
	v_mov_b32_e32 v33, v131
	v_mov_b32_e32 v34, v131
	v_mov_b32_e32 v35, v131
	v_mov_b32_e32 v52, 0
	v_mov_b32_e32 v53, v131
	v_mov_b32_e32 v54, v131
	v_mov_b32_e32 v55, v131
	v_mov_b32_e32 v68, 0
	v_mov_b32_e32 v69, v131
	v_mov_b32_e32 v70, v131
	v_mov_b32_e32 v71, v131
	v_mov_b32_e32 v84, 0
	v_mov_b32_e32 v85, v131
	v_mov_b32_e32 v86, v131
	v_mov_b32_e32 v87, v131
	v_mov_b32_e32 v100, 0
	v_mov_b32_e32 v101, v131
	v_mov_b32_e32 v102, v131
	v_mov_b32_e32 v103, v131
	v_mov_b32_e32 v104, 0
	v_mov_b32_e32 v105, v131
	v_mov_b32_e32 v106, v131
	v_mov_b32_e32 v107, v131
	v_mov_b32_e32 v120, 0
	v_mov_b32_e32 v121, v131
	v_mov_b32_e32 v122, v131
	v_mov_b32_e32 v123, v131
	v_mov_b32_e32 v124, 0
	v_mov_b32_e32 v125, v131
	v_mov_b32_e32 v126, v131
	v_mov_b32_e32 v127, v131
	s_add_i32 s8, s67, s33
	s_cmp_lt_u32 s8, 4
	s_cselect_b32 s9, 0, -4
	s_add_i32 s8, s8, s9
	s_and_b32 s9, s11, 0x10000
	v_add_u32_e32 v152, s9, v130
	s_ashr_i32 s9, s8, 31
	s_lshl_b64 s[8:9], s[8:9], 7
	v_readfirstlane_b32 s40, v152
	v_add_u32_e32 v153, 0x2000, v152
	v_lshl_add_u64 v[150:151], v[132:133], 0, s[8:9]
	s_mov_b32 m0, s40
	v_readfirstlane_b32 s40, v153
	v_add_u32_e32 v153, 0x4000, v152
	global_load_lds_dwordx4 v[150:151], off
	v_lshl_add_u64 v[150:151], v[136:137], 0, s[8:9]
	s_mov_b32 m0, s40
	v_readfirstlane_b32 s40, v153
	v_add_u32_e32 v153, 0x6000, v152
	global_load_lds_dwordx4 v[150:151], off
	v_lshl_add_u64 v[150:151], v[138:139], 0, s[8:9]
	s_mov_b32 m0, s40
	v_readfirstlane_b32 s40, v153
	v_add_u32_e32 v153, 0x8000, v152
	global_load_lds_dwordx4 v[150:151], off
	v_lshl_add_u64 v[150:151], v[140:141], 0, s[8:9]
	s_mov_b32 m0, s40
	v_readfirstlane_b32 s40, v153
	v_add_u32_e32 v153, 0xa000, v152
	global_load_lds_dwordx4 v[150:151], off
	v_lshl_add_u64 v[150:151], v[134:135], 0, s[8:9]
	s_mov_b32 m0, s40
	v_readfirstlane_b32 s40, v153
	v_add_u32_e32 v153, 0xc000, v152
	global_load_lds_dwordx4 v[150:151], off
	v_lshl_add_u64 v[150:151], v[142:143], 0, s[8:9]
	s_mov_b32 m0, s40
	v_readfirstlane_b32 s40, v153
	global_load_lds_dwordx4 v[150:151], off
	v_lshl_add_u64 v[150:151], v[144:145], 0, s[8:9]
	s_mov_b32 m0, s40
	v_add_u32_e32 v152, 0xe000, v152
	global_load_lds_dwordx4 v[150:151], off
	v_lshl_add_u64 v[150:151], v[146:147], 0, s[8:9]
	v_readfirstlane_b32 s8, v152
	s_mov_b32 m0, s8
	s_nop 0
	global_load_lds_dwordx4 v[150:151], off
	s_waitcnt vmcnt(8) lgkmcnt(0)
	s_barrier
	s_branch .LBB0_167

; template <int PIPE>
; DI void gemm_loop_g(const u16* __restrict__ Xp, long ldx_l, long ldx_i, long kxs,
;                     const u16* __restrict__ Yp, long ldy_l, long ldy_i, long kys, int K,
;                     f32x4 (&acc)[4][8], unsigned char* smem) {
;   const int t = tid_opaque(), l = t & 63, w = __builtin_amdgcn_readfirstlane(t >> 6), wx = w >> 1, wy = w & 1;
;   const int lrow = t >> 3, gch = (t & 7) ^ ((t >> 4) & 7);
;   const u16* xs = Xp + (long)lrow * ldx_l + gch * 8;
;   const u16* ys = Yp + (long)lrow * ldy_l + gch * 8;
;   const int fsw = (l >> 1) & 7, lg = l >> 4;
;   const unsigned fr0 = (l & 15) * 128 + ((lg ^ fsw) << 4);
;   const unsigned fr1 = (l & 15) * 128 + (((lg + 4) ^ fsw) << 4);
;   const unsigned ub = wx * 8192, vb = 32768 + wy * 16384;
;   const int nk = K >> 6;
;   const int rot = (int)((blockIdx.x >> 3) + (blockIdx.x & 7) * 5) % nk;
;   auto issue = [&](int kt0, int stage) {
;     int kt = kt0 + rot; if (kt >= nk) kt -= nk;
;     unsigned char* sb = smem + stage * 65536 + t * 16;
; #pragma unroll
;     for (int i = 0; i < 4; ++i)
;       __builtin_amdgcn_global_load_lds((const unsigned*)(xs + i * ldx_i + kt * kxs), LDS_PTR(sb + i * 8192), 16, 0, 0);
; #pragma unroll
;     for (int i = 0; i < 4; ++i)
; template <int MODE>
; DI void gemm_phase(const Params& p, const GP& g, unsigned char* smem) {
;     ...
;       u16* xb = (u16*)g.d0;
;       EPI_STD_BEGIN
;         *(u32x2*)(xb + (long)m * 1024 + n4) = pack4(v[0], v[1], v[2], v[3]);
;       EPI_END
;       zero_acc(acc);
;     }
;     if (MODE == M_FFT1) {
;       const int bt = mt >> 8, cg = mt & 255;
;       gemm_loop_g<0>(Ab + ((long)(bt * 1024 + cg * 4)) * 8192, 64, 8192, 4096, Wb, 128, 64 * 128, 64, 128, acc, smem);
;     } else if (MODE == M_FFT3) {
;       const int bt = mt >> 8, v = (mt >> 2) & 63, cq = mt & 3;
;       gemm_loop(Ab + (((long)(bt * 64 + v)) * 1024 + cq * 256) * 128, 128, Wb, 128, 128, acc, smem);
;     } else if (MODE == M_FN_IN && transposed) {
;       const u16* Ap = Ab + ((long)(mt >> 4) * 4096 + (mt & 15) * 4) * g.lda;
;       gemm_loop_g<1>(Ap, 64 * g.lda, g.lda, 64, Wb + (long)n0 * g.K, g.K, 64L * g.K, 64, g.K, acc, smem);
;     } else {
;       const u16* Ap = Ab + (long)m0 * g.lda; const u16* Wp = Wb + (long)n0 * g.K;
;       if (transposed) gemm_loop(Ap, g.lda, Wp, g.K, g.K, acc, smem);
;       else gemm_loop(Wp, g.K, Ap, g.lda, g.K, acc, smem);
.LBB0_170:
	v_or_b32_e32 v160, s12, v185
	v_add_u32_e32 v134, s6, v184
	v_ashrrev_i32_e32 v161, 31, v160
	v_lshlrev_b64 v[164:165], 11, v[160:161]
	v_ashrrev_i32_e32 v135, 31, v134
	v_or_b32_e32 v156, 16, v160
	v_lshl_add_u64 v[132:133], s[38:39], 0, v[164:165]
	v_cvt_pk_bf16_f32 v124, v124, v125
	v_cvt_pk_bf16_f32 v125, v126, v127
	v_lshlrev_b64 v[126:127], 1, v[134:135]
	v_ashrrev_i32_e32 v157, 31, v156
	v_lshl_add_u64 v[132:133], v[132:133], 0, v[126:127]
	v_cvt_pk_bf16_f32 v96, v96, v97
	v_cvt_pk_bf16_f32 v97, v98, v99
	v_lshlrev_b64 v[162:163], 11, v[156:157]
	v_or_b32_e32 v152, 32, v160
	global_store_dwordx2 v[132:133], v[96:97], off offset:96
	v_lshl_add_u64 v[96:97], s[38:39], 0, v[162:163]
	v_ashrrev_i32_e32 v153, 31, v152
	v_lshl_add_u64 v[96:97], v[96:97], 0, v[126:127]
	v_cvt_pk_bf16_f32 v72, v72, v73
	v_cvt_pk_bf16_f32 v73, v74, v75
	v_lshlrev_b64 v[158:159], 11, v[152:153]
	v_or_b32_e32 v148, 48, v160
	global_store_dwordx2 v[96:97], v[72:73], off offset:96
	v_lshl_add_u64 v[72:73], s[38:39], 0, v[158:159]
	v_ashrrev_i32_e32 v149, 31, v148
	v_lshl_add_u64 v[72:73], v[72:73], 0, v[126:127]
	v_cvt_pk_bf16_f32 v56, v56, v57
	v_cvt_pk_bf16_f32 v57, v58, v59
	v_lshlrev_b64 v[154:155], 11, v[148:149]
	global_store_dwordx2 v[72:73], v[56:57], off offset:96
	v_lshl_add_u64 v[56:57], s[38:39], 0, v[154:155]
	v_cvt_pk_bf16_f32 v74, v104, v105
	v_cvt_pk_bf16_f32 v75, v106, v107
	v_cvt_pk_bf16_f32 v58, v100, v101
	v_cvt_pk_bf16_f32 v59, v102, v103
	v_lshl_add_u64 v[56:57], v[56:57], 0, v[126:127]
	v_cvt_pk_bf16_f32 v98, v120, v121
	v_cvt_pk_bf16_f32 v99, v122, v123
	global_store_dwordx2 v[72:73], v[74:75], off
	v_cvt_pk_bf16_f32 v74, v92, v93
	v_cvt_pk_bf16_f32 v75, v94, v95
	global_store_dwordx2 v[56:57], v[58:59], off
	v_cvt_pk_bf16_f32 v58, v80, v81
	v_cvt_pk_bf16_f32 v59, v82, v83
	v_cvt_pk_bf16_f32 v116, v116, v117
	v_cvt_pk_bf16_f32 v117, v118, v119
	v_cvt_pk_bf16_f32 v112, v112, v113
	v_cvt_pk_bf16_f32 v113, v114, v115
	global_store_dwordx2 v[96:97], v[98:99], off
	v_cvt_pk_bf16_f32 v98, v108, v109
	v_cvt_pk_bf16_f32 v99, v110, v111
	v_cvt_pk_bf16_f32 v88, v88, v89
	v_cvt_pk_bf16_f32 v89, v90, v91
	global_store_dwordx2 v[72:73], v[74:75], off offset:32
	v_cvt_pk_bf16_f32 v74, v76, v77
	v_cvt_pk_bf16_f32 v75, v78, v79
	global_store_dwordx2 v[56:57], v[58:59], off offset:32
	v_cvt_pk_bf16_f32 v58, v64, v65
	v_cvt_pk_bf16_f32 v59, v66, v67
	v_cvt_pk_bf16_f32 v36, v36, v37
	v_cvt_pk_bf16_f32 v37, v38, v39
	global_store_dwordx2 v[132:133], v[124:125], off
	global_store_dwordx2 v[132:133], v[116:117], off offset:32
	global_store_dwordx2 v[132:133], v[112:113], off offset:64
	global_store_dwordx2 v[96:97], v[98:99], off offset:32
	global_store_dwordx2 v[96:97], v[88:89], off offset:64
	global_store_dwordx2 v[72:73], v[74:75], off offset:64
	global_store_dwordx2 v[56:57], v[58:59], off offset:64
	global_store_dwordx2 v[56:57], v[36:37], off offset:96
	v_or_b32_e32 v144, 64, v160
	v_ashrrev_i32_e32 v145, 31, v144
	v_lshlrev_b64 v[150:151], 11, v[144:145]
	v_or_b32_e32 v140, 0x50, v160
	v_lshl_add_u64 v[36:37], s[38:39], 0, v[150:151]
	v_ashrrev_i32_e32 v141, 31, v140
	v_lshl_add_u64 v[36:37], v[36:37], 0, v[126:127]
	v_cvt_pk_bf16_f32 v20, v20, v21
	v_cvt_pk_bf16_f32 v21, v22, v23
	v_lshlrev_b64 v[146:147], 11, v[140:141]
	v_or_b32_e32 v136, 0x60, v160
	global_store_dwordx2 v[36:37], v[20:21], off offset:96
	v_lshl_add_u64 v[20:21], s[38:39], 0, v[146:147]
	v_ashrrev_i32_e32 v137, 31, v136
	v_lshl_add_u64 v[20:21], v[20:21], 0, v[126:127]
	v_cvt_pk_bf16_f32 v8, v8, v9
	v_cvt_pk_bf16_f32 v9, v10, v11
	v_lshlrev_b64 v[142:143], 11, v[136:137]
	v_or_b32_e32 v132, 0x70, v160
	global_store_dwordx2 v[20:21], v[8:9], off offset:96
	v_lshl_add_u64 v[8:9], s[38:39], 0, v[142:143]
	v_ashrrev_i32_e32 v133, 31, v132
	v_lshl_add_u64 v[8:9], v[8:9], 0, v[126:127]
	v_cvt_pk_bf16_f32 v0, v0, v1
	v_cvt_pk_bf16_f32 v1, v2, v3
	v_lshlrev_b64 v[138:139], 11, v[132:133]
	global_store_dwordx2 v[8:9], v[0:1], off offset:96
	v_lshl_add_u64 v[0:1], s[38:39], 0, v[138:139]
	v_cvt_pk_bf16_f32 v2, v32, v33
	v_cvt_pk_bf16_f32 v3, v34, v35
	v_lshl_add_u64 v[0:1], v[0:1], 0, v[126:127]
	v_cvt_pk_bf16_f32 v38, v84, v85
	v_cvt_pk_bf16_f32 v39, v86, v87
	v_cvt_pk_bf16_f32 v22, v68, v69
	v_cvt_pk_bf16_f32 v23, v70, v71
	v_cvt_pk_bf16_f32 v10, v52, v53
	v_cvt_pk_bf16_f32 v11, v54, v55
	global_store_dwordx2 v[0:1], v[2:3], off
	v_cvt_pk_bf16_f32 v2, v16, v17
	v_cvt_pk_bf16_f32 v3, v18, v19
	global_store_dwordx2 v[36:37], v[38:39], off
	v_cvt_pk_bf16_f32 v38, v60, v61
	v_cvt_pk_bf16_f32 v39, v62, v63
	global_store_dwordx2 v[20:21], v[22:23], off
	v_cvt_pk_bf16_f32 v22, v48, v49
	v_cvt_pk_bf16_f32 v23, v50, v51
	global_store_dwordx2 v[8:9], v[10:11], off
	v_cvt_pk_bf16_f32 v10, v28, v29
	v_cvt_pk_bf16_f32 v11, v30, v31
	global_store_dwordx2 v[0:1], v[2:3], off offset:32
	v_cvt_pk_bf16_f32 v2, v4, v5
	v_cvt_pk_bf16_f32 v3, v6, v7
	global_store_dwordx2 v[36:37], v[38:39], off offset:32
	v_cvt_pk_bf16_f32 v38, v44, v45
	v_cvt_pk_bf16_f32 v39, v46, v47
	global_store_dwordx2 v[20:21], v[22:23], off offset:32
	v_cvt_pk_bf16_f32 v22, v24, v25
	v_cvt_pk_bf16_f32 v23, v26, v27
	global_store_dwordx2 v[8:9], v[10:11], off offset:32
	v_cvt_pk_bf16_f32 v10, v12, v13
	v_cvt_pk_bf16_f32 v11, v14, v15
	global_store_dwordx2 v[0:1], v[2:3], off offset:64
	v_cvt_pk_bf16_f32 v2, v40, v41
	v_cvt_pk_bf16_f32 v3, v42, v43
	global_store_dwordx2 v[36:37], v[38:39], off offset:64
	global_store_dwordx2 v[20:21], v[22:23], off offset:64
	global_store_dwordx2 v[8:9], v[10:11], off offset:64
	global_store_dwordx2 v[0:1], v[2:3], off offset:96
	s_lshl_b32 s6, s6, 11
	s_add_u32 s6, s18, s6
	v_mov_b32_e32 v4, v182
	s_addc_u32 s7, s19, 0
	s_lshl_b64 s[8:9], s[12:13], 11
	s_add_u32 s8, s36, s8
	v_ashrrev_i32_e32 v0, 3, v4
	v_lshrrev_b32_e32 v5, 4, v4
	v_xor_b32_e32 v6, v5, v4
	v_ashrrev_i32_e32 v1, 31, v0
	s_addc_u32 s9, s37, s9
	v_lshlrev_b64 v[0:1], 11, v[0:1]
	v_lshlrev_b32_e32 v6, 4, v6
	v_lshl_add_u64 v[2:3], s[6:7], 0, v[0:1]
	v_and_b32_e32 v130, 0x70, v6
	v_lshl_add_u64 v[0:1], s[8:9], 0, v[0:1]
	v_lshl_add_u64 v[166:167], v[2:3], 0, v[130:131]
	v_lshl_add_u64 v[168:169], v[0:1], 0, v[130:131]
	v_lshlrev_b32_e32 v130, 4, v4
	v_add_u32_e32 v2, 0x2000, v130
	v_readfirstlane_b32 s6, v130
	v_lshl_add_u64 v[0:1], v[166:167], 0, s[56:57]
	s_mov_b32 m0, s6
	v_lshl_add_u64 v[170:171], v[166:167], 0, s[58:59]
	v_readfirstlane_b32 s6, v2
	v_add_u32_e32 v2, 0x4000, v130
	s_barrier
; #define LDS_PTR(p) ((__attribute__((address_space(3))) unsigned*)(p))
; template <int PIPE>
; DI void gemm_loop_g(const u16* __restrict__ Xp, long ldx_l, long ldx_i, long kxs,
;                     const u16* __restrict__ Yp, long ldy_l, long ldy_i, long kys, int K,
;                     f32x4 (&acc)[4][8], unsigned char* smem) {
;     ...
;   auto issue = [&](int kt0, int stage) {
;     int kt = kt0 + rot; if (kt >= nk) kt -= nk;
;     unsigned char* sb = smem + stage * 65536 + t * 16;
; #pragma unroll
;     for (int i = 0; i < 4; ++i)
;       __builtin_amdgcn_global_load_lds((const unsigned*)(xs + i * ldx_i + kt * kxs), LDS_PTR(sb + i * 8192), 16, 0, 0);
; #pragma unroll
;     for (int i = 0; i < 4; ++i)
;       __builtin_amdgcn_global_load_lds((const unsigned*)(ys + i * ldy_i + kt * kys), LDS_PTR(sb + 32768 + i * 8192), 16, 0, 0);
;   };
;   __syncthreads();
;   issue(0, 0);
;   asm volatile("s_waitcnt vmcnt(0)" ::: "memory");
;   __syncthreads();
; #pragma unroll 1
;   for (int kt = 0; kt < nk; ++kt) {
;     const unsigned char* cur = smem + (kt & 1) * 65536;
;     if (kt + 1 < nk) issue(kt + 1, (kt + 1) & 1);
; DI void zero_acc(f32x4 (&acc)[4][8]) {
; #pragma unroll
;   for (int i = 0; i < 4; ++i)
; #pragma unroll
;     for (int j = 0; j < 8; ++j) acc[i][j] = f32x4{0.f, 0.f, 0.f, 0.f};
	global_load_lds_dwordx4 v[0:1], off
	v_lshl_add_u64 v[0:1], v[170:171], 0, s[56:57]
	s_mov_b32 m0, s6
	v_lshl_add_u64 v[172:173], v[166:167], 0, s[60:61]
	v_readfirstlane_b32 s6, v2
	v_add_u32_e32 v2, 0x6000, v130
	global_load_lds_dwordx4 v[0:1], off
	v_lshl_add_u64 v[0:1], v[172:173], 0, s[56:57]
	s_mov_b32 m0, s6
	v_lshl_add_u64 v[174:175], v[166:167], 0, s[62:63]
	v_readfirstlane_b32 s6, v2
	v_add_u32_e32 v2, 0x8000, v130
	global_load_lds_dwordx4 v[0:1], off
	v_lshl_add_u64 v[0:1], v[174:175], 0, s[56:57]
	s_mov_b32 m0, s6
	v_readfirstlane_b32 s6, v2
	v_add_u32_e32 v2, 0xa000, v130
	global_load_lds_dwordx4 v[0:1], off
	v_lshl_add_u64 v[0:1], v[168:169], 0, s[56:57]
	s_mov_b32 m0, s6
	v_lshl_add_u64 v[176:177], v[168:169], 0, s[58:59]
	v_readfirstlane_b32 s6, v2
	v_add_u32_e32 v2, 0xc000, v130
	global_load_lds_dwordx4 v[0:1], off
	v_lshl_add_u64 v[0:1], v[176:177], 0, s[56:57]
	s_mov_b32 m0, s6
	v_lshl_add_u64 v[178:179], v[168:169], 0, s[60:61]
	v_readfirstlane_b32 s6, v2
	v_add_u32_e32 v2, 0xe000, v130
	global_load_lds_dwordx4 v[0:1], off
	v_lshl_add_u64 v[0:1], v[178:179], 0, s[56:57]
	s_mov_b32 m0, s6
	v_lshl_add_u64 v[180:181], v[168:169], 0, s[62:63]
	v_readfirstlane_b32 s6, v2
	global_load_lds_dwordx4 v[0:1], off
	v_lshl_add_u64 v[0:1], v[180:181], 0, s[56:57]
	s_mov_b32 m0, s6
	v_lshlrev_b32_e32 v2, 7, v4
	global_load_lds_dwordx4 v[0:1], off
	v_bfe_u32 v0, v4, 4, 2
	v_bfe_u32 v1, v4, 1, 3
	v_readfirstlane_b32 s10, v4
	s_nop 0
	v_bitop3_b32 v0, v0, v1, 4 bitop3:0x36
	v_and_b32_e32 v2, 0x780, v2
	s_lshl_b32 s6, s10, 8
	s_lshl_b32 s7, s10, 6
	v_lshl_or_b32 v187, v0, 4, v2
	v_bitop3_b32 v0, v5, v1, 3 bitop3:0x6c
	v_mov_b32_e32 v4, 0
	s_and_b32 s6, s6, 0x4000
	s_and_b32 s7, s7, 0xffffe000
	v_lshl_or_b32 v188, v0, 4, v2
	s_mov_b32 s10, 0
	s_mov_b32 s11, 0x10000
	v_mov_b32_e32 v5, v4
	v_mov_b32_e32 v6, v4
	v_mov_b32_e32 v7, v4
	v_mov_b32_e32 v16, v4
	v_mov_b32_e32 v17, v4
	v_mov_b32_e32 v18, v4
	v_mov_b32_e32 v19, v4
	v_mov_b32_e32 v32, v4
	v_mov_b32_e32 v33, v4
	v_mov_b32_e32 v34, v4
	v_mov_b32_e32 v35, v4
	v_mov_b32_e32 v48, v4
	v_mov_b32_e32 v49, v4
	v_mov_b32_e32 v50, v4
	v_mov_b32_e32 v51, v4
	v_mov_b32_e32 v64, v4
	v_mov_b32_e32 v65, v4
	v_mov_b32_e32 v66, v4
	v_mov_b32_e32 v67, v4
	v_mov_b32_e32 v80, v4
	v_mov_b32_e32 v81, v4
	v_mov_b32_e32 v82, v4
	v_mov_b32_e32 v83, v4
	v_mov_b32_e32 v96, v4
	v_mov_b32_e32 v97, v4
	v_mov_b32_e32 v98, v4
	v_mov_b32_e32 v99, v4
	v_mov_b32_e32 v112, v4
	v_mov_b32_e32 v113, v4
	v_mov_b32_e32 v114, v4
	v_mov_b32_e32 v115, v4
	v_mov_b32_e32 v0, v4
	v_mov_b32_e32 v1, v4
	v_mov_b32_e32 v2, v4
	v_mov_b32_e32 v3, v4
	v_mov_b32_e32 v20, v4
	v_mov_b32_e32 v21, v4
	v_mov_b32_e32 v22, v4
	v_mov_b32_e32 v23, v4
	v_mov_b32_e32 v36, v4
	v_mov_b32_e32 v37, v4
	v_mov_b32_e32 v38, v4
	v_mov_b32_e32 v39, v4
	v_mov_b32_e32 v52, v4
	v_mov_b32_e32 v53, v4
	v_mov_b32_e32 v54, v4
	v_mov_b32_e32 v55, v4
	v_mov_b32_e32 v68, v4
	v_mov_b32_e32 v69, v4
	v_mov_b32_e32 v70, v4
	v_mov_b32_e32 v71, v4
	v_mov_b32_e32 v84, v4
	v_mov_b32_e32 v85, v4
	v_mov_b32_e32 v86, v4
	v_mov_b32_e32 v87, v4
	v_mov_b32_e32 v100, v4
	v_mov_b32_e32 v101, v4
	v_mov_b32_e32 v102, v4
	v_mov_b32_e32 v103, v4
	v_mov_b32_e32 v116, v4
	v_mov_b32_e32 v117, v4
	v_mov_b32_e32 v118, v4
	v_mov_b32_e32 v119, v4
	v_mov_b32_e32 v8, v4
	v_mov_b32_e32 v9, v4
	v_mov_b32_e32 v10, v4
	v_mov_b32_e32 v11, v4
	v_mov_b32_e32 v24, v4
	v_mov_b32_e32 v25, v4
	v_mov_b32_e32 v26, v4
	v_mov_b32_e32 v27, v4
	v_mov_b32_e32 v40, v4
	v_mov_b32_e32 v41, v4
	v_mov_b32_e32 v42, v4
	v_mov_b32_e32 v43, v4
	v_mov_b32_e32 v56, v4
	v_mov_b32_e32 v57, v4
	v_mov_b32_e32 v58, v4
	v_mov_b32_e32 v59, v4
	v_mov_b32_e32 v72, v4
	v_mov_b32_e32 v73, v4
	v_mov_b32_e32 v74, v4
	v_mov_b32_e32 v75, v4
	v_mov_b32_e32 v88, v4
	v_mov_b32_e32 v89, v4
	v_mov_b32_e32 v90, v4
	v_mov_b32_e32 v91, v4
	v_mov_b32_e32 v104, v4
	v_mov_b32_e32 v105, v4
	v_mov_b32_e32 v106, v4
	v_mov_b32_e32 v107, v4
	v_mov_b32_e32 v120, v4
	v_mov_b32_e32 v121, v4
	v_mov_b32_e32 v122, v4
	v_mov_b32_e32 v123, v4
	v_mov_b32_e32 v12, v4
	v_mov_b32_e32 v13, v4
	v_mov_b32_e32 v14, v4
	v_mov_b32_e32 v15, v4
	v_mov_b32_e32 v28, v4
	v_mov_b32_e32 v29, v4
	v_mov_b32_e32 v30, v4
	v_mov_b32_e32 v31, v4
	v_mov_b32_e32 v44, v4
	v_mov_b32_e32 v45, v4
	v_mov_b32_e32 v46, v4
	v_mov_b32_e32 v47, v4
	v_mov_b32_e32 v60, v4
	v_mov_b32_e32 v61, v4
	v_mov_b32_e32 v62, v4
	v_mov_b32_e32 v63, v4
	v_mov_b32_e32 v76, v4
	v_mov_b32_e32 v77, v4
	v_mov_b32_e32 v78, v4
	v_mov_b32_e32 v79, v4
	v_mov_b32_e32 v92, v4
	v_mov_b32_e32 v93, v4
	v_mov_b32_e32 v94, v4
	v_mov_b32_e32 v95, v4
	v_mov_b32_e32 v108, v4
	v_mov_b32_e32 v109, v4
	v_mov_b32_e32 v110, v4
	v_mov_b32_e32 v111, v4
	v_mov_b32_e32 v124, v4
	v_mov_b32_e32 v125, v4
	v_mov_b32_e32 v126, v4
	v_mov_b32_e32 v127, v4
	s_add_i32 s8, s68, s10
	s_cmp_lt_u32 s8, 16
	s_cselect_b32 s9, 0, -16
	s_add_i32 s8, s8, s9
	s_and_b32 s9, s11, 0x10000
	v_add_u32_e32 v189, s9, v130
	s_ashr_i32 s9, s8, 31
	s_lshl_b64 s[8:9], s[8:9], 7
	v_readfirstlane_b32 s12, v189
	v_add_u32_e32 v192, 0x2000, v189
	v_lshl_add_u64 v[190:191], v[166:167], 0, s[8:9]
	s_mov_b32 m0, s12
	v_readfirstlane_b32 s12, v192
	v_add_u32_e32 v192, 0x4000, v189
	global_load_lds_dwordx4 v[190:191], off
	v_lshl_add_u64 v[190:191], v[170:171], 0, s[8:9]
	s_mov_b32 m0, s12
	v_readfirstlane_b32 s12, v192
	v_add_u32_e32 v192, 0x6000, v189
	global_load_lds_dwordx4 v[190:191], off
	v_lshl_add_u64 v[190:191], v[172:173], 0, s[8:9]
	s_mov_b32 m0, s12
	v_readfirstlane_b32 s12, v192
	v_add_u32_e32 v192, 0x8000, v189
	global_load_lds_dwordx4 v[190:191], off
	v_lshl_add_u64 v[190:191], v[174:175], 0, s[8:9]
	s_mov_b32 m0, s12
	v_readfirstlane_b32 s12, v192
	v_add_u32_e32 v192, 0xa000, v189
	global_load_lds_dwordx4 v[190:191], off
	v_lshl_add_u64 v[190:191], v[168:169], 0, s[8:9]
	s_mov_b32 m0, s12
	v_readfirstlane_b32 s12, v192
	v_add_u32_e32 v192, 0xc000, v189
	global_load_lds_dwordx4 v[190:191], off
	v_lshl_add_u64 v[190:191], v[176:177], 0, s[8:9]
	s_mov_b32 m0, s12
	v_readfirstlane_b32 s12, v192
	global_load_lds_dwordx4 v[190:191], off
	v_lshl_add_u64 v[190:191], v[178:179], 0, s[8:9]
	s_mov_b32 m0, s12
	v_add_u32_e32 v189, 0xe000, v189
	global_load_lds_dwordx4 v[190:191], off
	v_lshl_add_u64 v[190:191], v[180:181], 0, s[8:9]
	v_readfirstlane_b32 s8, v189
	s_mov_b32 m0, s8
	s_nop 0
	global_load_lds_dwordx4 v[190:191], off
	s_waitcnt vmcnt(8) lgkmcnt(0)
	s_barrier
	s_branch .LBB0_171

; template <int PIPE>
; DI void gemm_loop_g(const u16* __restrict__ Xp, long ldx_l, long ldx_i, long kxs,
;                     const u16* __restrict__ Yp, long ldy_l, long ldy_i, long kys, int K,
;                     f32x4 (&acc)[4][8], unsigned char* smem) {
;   const int t = tid_opaque(), l = t & 63, w = __builtin_amdgcn_readfirstlane(t >> 6), wx = w >> 1, wy = w & 1;
;   const int lrow = t >> 3, gch = (t & 7) ^ ((t >> 4) & 7);
;   const u16* xs = Xp + (long)lrow * ldx_l + gch * 8;
;   const u16* ys = Yp + (long)lrow * ldy_l + gch * 8;
; template <int MODE>
; DI void gemm_phase(const Params& p, const GP& g, unsigned char* smem) {
;     ...
;     int bsel = 0;
;     {
;       const int ml = e / g.ntn;
;       nt = e - ml * g.ntn;
;       mt = xcd + 8 * ml;
;     }
;     if (MODE == M_SEQ) { bsel = mt >> 4; mt &= 15; Wb = g.W + (long)bsel * 1024 * 8192; }
;     const int m0 = mt * 256, n0 = nt * 256;
;     f32x4 acc[4][8];
;     zero_acc(acc);
;     int transposed = 0;
;     if (MODE == M_FN_IN) transposed = nt < 8;
;     if (MODE == M_NA_IN) transposed = (nt >= 8 && nt < 12);
;     if (MODE == M_MLA_UKV) transposed = nt >= 4;
;     if (MODE == M_HG_IN) transposed = nt >= 12;
;     if (MODE == M_PLE) {
;       const u16* pb = (const u16*)g.d1;
;       gemm_loop(g.W2 + (long)n0 * 256, 256, pb + (long)m0 * 256, 256, 256, acc, smem);
;       u16* xb = (u16*)g.d0;
;       EPI_STD_BEGIN
;         *(u32x2*)(xb + (long)m * 1024 + n4) = pack4(v[0], v[1], v[2], v[3]);
;       EPI_END
;       zero_acc(acc);
;     }
;     if (MODE == M_FFT1) {
;       const int bt = mt >> 8, cg = mt & 255;
;       gemm_loop_g<0>(Ab + ((long)(bt * 1024 + cg * 4)) * 8192, 64, 8192, 4096, Wb, 128, 64 * 128, 64, 128, acc, smem);
;     } else if (MODE == M_FFT3) {
;       const int bt = mt >> 8, v = (mt >> 2) & 63, cq = mt & 3;
;       gemm_loop(Ab + (((long)(bt * 64 + v)) * 1024 + cq * 256) * 128, 128, Wb, 128, 128, acc, smem);
;     } else if (MODE == M_FN_IN && transposed) {
;       const u16* Ap = Ab + ((long)(mt >> 4) * 4096 + (mt & 15) * 4) * g.lda;
;       gemm_loop_g<1>(Ap, 64 * g.lda, g.lda, 64, Wb + (long)n0 * g.K, g.K, 64L * g.K, 64, g.K, acc, smem);
;     } else {
;       const u16* Ap = Ab + (long)m0 * g.lda; const u16* Wp = Wb + (long)n0 * g.K;
;       if (transposed) gemm_loop(Ap, g.lda, Wp, g.K, g.K, acc, smem);
;       else gemm_loop(Wp, g.K, Ap, g.lda, g.K, acc, smem);
.LBB0_203:
	s_lshl_b32 s6, s90, 7
	s_and_b32 s6, s6, 0xfffff800
	s_and_b32 s91, s90, 15
	s_or_b32 s12, s6, s59
	s_and_b32 s6, s90, 12
	s_cmp_lg_u32 s6, 8
	s_cselect_b64 s[14:15], -1, 0
	s_ashr_i32 s13, s12, 31
	s_lshl_b64 s[6:7], s[12:13], 11
	s_add_u32 s80, s18, s6
	s_addc_u32 s81, s19, s7
	s_lshl_b32 s6, s91, 19
	s_add_u32 s16, s24, s6
	s_addc_u32 s17, s25, 0
	s_mov_b64 s[82:83], -1
	s_and_b64 vcc, exec, s[14:15]
	s_cbranch_vccz .LBB0_209
	v_mov_b32_e32 v4, v182
	s_nop 0
	v_ashrrev_i32_e32 v0, 3, v4
	v_lshrrev_b32_e32 v5, 4, v4
	v_xor_b32_e32 v6, v5, v4
	v_ashrrev_i32_e32 v1, 31, v0
	v_lshlrev_b64 v[0:1], 11, v[0:1]
	v_lshlrev_b32_e32 v6, 4, v6
	v_lshl_add_u64 v[2:3], s[16:17], 0, v[0:1]
	v_and_b32_e32 v128, 0x70, v6
	v_lshl_add_u64 v[0:1], s[80:81], 0, v[0:1]
	v_lshl_add_u64 v[130:131], v[2:3], 0, v[128:129]
	v_lshl_add_u64 v[132:133], v[0:1], 0, v[128:129]
	v_lshlrev_b32_e32 v128, 4, v4
	v_add_u32_e32 v2, 0x2000, v128
	v_readfirstlane_b32 s6, v128
	v_lshl_add_u64 v[0:1], v[130:131], 0, s[28:29]
	s_mov_b32 m0, s6
	v_lshl_add_u64 v[134:135], v[130:131], 0, s[30:31]
	v_readfirstlane_b32 s6, v2
	v_add_u32_e32 v2, 0x4000, v128
	s_barrier
; #define LDS_PTR(p) ((__attribute__((address_space(3))) unsigned*)(p))
; template <int PIPE>
; DI void gemm_loop_g(const u16* __restrict__ Xp, long ldx_l, long ldx_i, long kxs,
;                     const u16* __restrict__ Yp, long ldy_l, long ldy_i, long kys, int K,
;                     f32x4 (&acc)[4][8], unsigned char* smem) {
;     ...
;   auto issue = [&](int kt0, int stage) {
;     int kt = kt0 + rot; if (kt >= nk) kt -= nk;
;     unsigned char* sb = smem + stage * 65536 + t * 16;
; #pragma unroll
;     for (int i = 0; i < 4; ++i)
;       __builtin_amdgcn_global_load_lds((const unsigned*)(xs + i * ldx_i + kt * kxs), LDS_PTR(sb + i * 8192), 16, 0, 0);
; #pragma unroll
;     for (int i = 0; i < 4; ++i)
;       __builtin_amdgcn_global_load_lds((const unsigned*)(ys + i * ldy_i + kt * kys), LDS_PTR(sb + 32768 + i * 8192), 16, 0, 0);
;   };
;   __syncthreads();
;   issue(0, 0);
;   asm volatile("s_waitcnt vmcnt(0)" ::: "memory");
;   __syncthreads();
; #pragma unroll 1
;   for (int kt = 0; kt < nk; ++kt) {
;     const unsigned char* cur = smem + (kt & 1) * 65536;
;     if (kt + 1 < nk) issue(kt + 1, (kt + 1) & 1);
; DI void zero_acc(f32x4 (&acc)[4][8]) {
; #pragma unroll
;   for (int i = 0; i < 4; ++i)
; #pragma unroll
;     for (int j = 0; j < 8; ++j) acc[i][j] = f32x4{0.f, 0.f, 0.f, 0.f};
	global_load_lds_dwordx4 v[0:1], off
	v_lshl_add_u64 v[0:1], v[134:135], 0, s[28:29]
	s_mov_b32 m0, s6
	v_lshl_add_u64 v[136:137], v[130:131], 0, s[54:55]
	v_readfirstlane_b32 s6, v2
	v_add_u32_e32 v2, 0x6000, v128
	global_load_lds_dwordx4 v[0:1], off
	v_lshl_add_u64 v[0:1], v[136:137], 0, s[28:29]
	s_mov_b32 m0, s6
	v_lshl_add_u64 v[138:139], v[130:131], 0, s[56:57]
	v_readfirstlane_b32 s6, v2
	v_add_u32_e32 v2, 0x8000, v128
	global_load_lds_dwordx4 v[0:1], off
	v_lshl_add_u64 v[0:1], v[138:139], 0, s[28:29]
	s_mov_b32 m0, s6
	v_readfirstlane_b32 s6, v2
	v_add_u32_e32 v2, 0xa000, v128
	global_load_lds_dwordx4 v[0:1], off
	v_lshl_add_u64 v[0:1], v[132:133], 0, s[28:29]
	s_mov_b32 m0, s6
	v_lshl_add_u64 v[140:141], v[132:133], 0, s[30:31]
	v_readfirstlane_b32 s6, v2
	v_add_u32_e32 v2, 0xc000, v128
	global_load_lds_dwordx4 v[0:1], off
	v_lshl_add_u64 v[0:1], v[140:141], 0, s[28:29]
	s_mov_b32 m0, s6
	v_lshl_add_u64 v[142:143], v[132:133], 0, s[54:55]
	v_readfirstlane_b32 s6, v2
	v_add_u32_e32 v2, 0xe000, v128
	global_load_lds_dwordx4 v[0:1], off
	v_lshl_add_u64 v[0:1], v[142:143], 0, s[28:29]
	s_mov_b32 m0, s6
	v_lshl_add_u64 v[144:145], v[132:133], 0, s[56:57]
	v_readfirstlane_b32 s6, v2
	global_load_lds_dwordx4 v[0:1], off
	v_lshl_add_u64 v[0:1], v[144:145], 0, s[28:29]
	s_mov_b32 m0, s6
	v_lshlrev_b32_e32 v2, 7, v4
	global_load_lds_dwordx4 v[0:1], off
	v_bfe_u32 v0, v4, 4, 2
	v_bfe_u32 v1, v4, 1, 3
	v_readfirstlane_b32 s7, v4
	s_nop 0
	v_bitop3_b32 v0, v0, v1, 4 bitop3:0x36
	v_and_b32_e32 v2, 0x780, v2
	s_lshl_b32 s6, s7, 8
	s_lshl_b32 s7, s7, 6
	v_lshl_or_b32 v151, v0, 4, v2
	v_bitop3_b32 v0, v5, v1, 3 bitop3:0x6c
	v_mov_b32_e32 v8, 0
	s_and_b32 s6, s6, 0x4000
	s_and_b32 s7, s7, 0xffffe000
	v_lshl_or_b32 v152, v0, 4, v2
	s_mov_b32 s10, 0
	s_mov_b32 s11, 0x10000
	v_mov_b32_e32 v9, v8
	v_mov_b32_e32 v10, v8
	v_mov_b32_e32 v11, v8
	v_mov_b32_e32 v12, v8
	v_mov_b32_e32 v13, v8
	v_mov_b32_e32 v14, v8
	v_mov_b32_e32 v15, v8
	v_mov_b32_e32 v28, v8
	v_mov_b32_e32 v29, v8
	v_mov_b32_e32 v30, v8
	v_mov_b32_e32 v31, v8
	v_mov_b32_e32 v44, v8
	v_mov_b32_e32 v45, v8
	v_mov_b32_e32 v46, v8
	v_mov_b32_e32 v47, v8
	v_mov_b32_e32 v60, v8
	v_mov_b32_e32 v61, v8
	v_mov_b32_e32 v62, v8
	v_mov_b32_e32 v63, v8
	v_mov_b32_e32 v76, v8
	v_mov_b32_e32 v77, v8
	v_mov_b32_e32 v78, v8
	v_mov_b32_e32 v79, v8
	v_mov_b32_e32 v92, v8
	v_mov_b32_e32 v93, v8
	v_mov_b32_e32 v94, v8
	v_mov_b32_e32 v95, v8
	v_mov_b32_e32 v108, v8
	v_mov_b32_e32 v109, v8
	v_mov_b32_e32 v110, v8
	v_mov_b32_e32 v111, v8
	v_mov_b32_e32 v0, v8
	v_mov_b32_e32 v1, v8
	v_mov_b32_e32 v2, v8
	v_mov_b32_e32 v3, v8
	v_mov_b32_e32 v20, v8
	v_mov_b32_e32 v21, v8
	v_mov_b32_e32 v22, v8
	v_mov_b32_e32 v23, v8
	v_mov_b32_e32 v36, v8
	v_mov_b32_e32 v37, v8
	v_mov_b32_e32 v38, v8
	v_mov_b32_e32 v39, v8
	v_mov_b32_e32 v52, v8
	v_mov_b32_e32 v53, v8
	v_mov_b32_e32 v54, v8
	v_mov_b32_e32 v55, v8
	v_mov_b32_e32 v68, v8
	v_mov_b32_e32 v69, v8
	v_mov_b32_e32 v70, v8
	v_mov_b32_e32 v71, v8
	v_mov_b32_e32 v84, v8
	v_mov_b32_e32 v85, v8
	v_mov_b32_e32 v86, v8
	v_mov_b32_e32 v87, v8
	v_mov_b32_e32 v100, v8
	v_mov_b32_e32 v101, v8
	v_mov_b32_e32 v102, v8
	v_mov_b32_e32 v103, v8
	v_mov_b32_e32 v116, v8
	v_mov_b32_e32 v117, v8
	v_mov_b32_e32 v118, v8
	v_mov_b32_e32 v119, v8
	v_mov_b32_e32 v4, v8
	v_mov_b32_e32 v5, v8
	v_mov_b32_e32 v6, v8
	v_mov_b32_e32 v7, v8
	v_mov_b32_e32 v24, v8
	v_mov_b32_e32 v25, v8
	v_mov_b32_e32 v26, v8
	v_mov_b32_e32 v27, v8
	v_mov_b32_e32 v40, v8
	v_mov_b32_e32 v41, v8
	v_mov_b32_e32 v42, v8
	v_mov_b32_e32 v43, v8
	v_mov_b32_e32 v56, v8
	v_mov_b32_e32 v57, v8
	v_mov_b32_e32 v58, v8
	v_mov_b32_e32 v59, v8
	v_mov_b32_e32 v72, v8
	v_mov_b32_e32 v73, v8
	v_mov_b32_e32 v74, v8
	v_mov_b32_e32 v75, v8
	v_mov_b32_e32 v88, v8
	v_mov_b32_e32 v89, v8
	v_mov_b32_e32 v90, v8
	v_mov_b32_e32 v91, v8
	v_mov_b32_e32 v104, v8
	v_mov_b32_e32 v105, v8
	v_mov_b32_e32 v106, v8
	v_mov_b32_e32 v107, v8
	v_mov_b32_e32 v120, v8
	v_mov_b32_e32 v121, v8
	v_mov_b32_e32 v122, v8
	v_mov_b32_e32 v123, v8
	v_mov_b32_e32 v16, v8
	v_mov_b32_e32 v17, v8
	v_mov_b32_e32 v18, v8
	v_mov_b32_e32 v19, v8
	v_mov_b32_e32 v32, v8
	v_mov_b32_e32 v33, v8
	v_mov_b32_e32 v34, v8
	v_mov_b32_e32 v35, v8
	v_mov_b32_e32 v48, v8
	v_mov_b32_e32 v49, v8
	v_mov_b32_e32 v50, v8
	v_mov_b32_e32 v51, v8
	v_mov_b32_e32 v64, v8
	v_mov_b32_e32 v65, v8
	v_mov_b32_e32 v66, v8
	v_mov_b32_e32 v67, v8
	v_mov_b32_e32 v80, v8
	v_mov_b32_e32 v81, v8
	v_mov_b32_e32 v82, v8
	v_mov_b32_e32 v83, v8
	v_mov_b32_e32 v96, v8
	v_mov_b32_e32 v97, v8
	v_mov_b32_e32 v98, v8
	v_mov_b32_e32 v99, v8
	v_mov_b32_e32 v112, v8
	v_mov_b32_e32 v113, v8
	v_mov_b32_e32 v114, v8
	v_mov_b32_e32 v115, v8
	v_mov_b32_e32 v124, v8
	v_mov_b32_e32 v125, v8
	v_mov_b32_e32 v126, v8
	v_mov_b32_e32 v127, v8
	s_add_i32 s8, s65, s10
	s_cmp_lt_u32 s8, 16
	s_cselect_b32 s9, 0, -16
	s_add_i32 s8, s8, s9
	s_and_b32 s9, s11, 0x10000
	v_add_u32_e32 v153, s9, v128
	s_ashr_i32 s9, s8, 31
	s_lshl_b64 s[8:9], s[8:9], 7
	v_readfirstlane_b32 s13, v153
	v_add_u32_e32 v156, 0x2000, v153
	v_lshl_add_u64 v[154:155], v[130:131], 0, s[8:9]
	s_mov_b32 m0, s13
	v_readfirstlane_b32 s13, v156
	v_add_u32_e32 v156, 0x4000, v153
	global_load_lds_dwordx4 v[154:155], off
	v_lshl_add_u64 v[154:155], v[134:135], 0, s[8:9]
	s_mov_b32 m0, s13
	v_readfirstlane_b32 s13, v156
	v_add_u32_e32 v156, 0x6000, v153
	global_load_lds_dwordx4 v[154:155], off
	v_lshl_add_u64 v[154:155], v[136:137], 0, s[8:9]
	s_mov_b32 m0, s13
	v_readfirstlane_b32 s13, v156
	v_add_u32_e32 v156, 0x8000, v153
	global_load_lds_dwordx4 v[154:155], off
	v_lshl_add_u64 v[154:155], v[138:139], 0, s[8:9]
	s_mov_b32 m0, s13
	v_readfirstlane_b32 s13, v156
	v_add_u32_e32 v156, 0xa000, v153
	global_load_lds_dwordx4 v[154:155], off
	v_lshl_add_u64 v[154:155], v[132:133], 0, s[8:9]
	s_mov_b32 m0, s13
	v_readfirstlane_b32 s13, v156
	v_add_u32_e32 v156, 0xc000, v153
	global_load_lds_dwordx4 v[154:155], off
	v_lshl_add_u64 v[154:155], v[140:141], 0, s[8:9]
	s_mov_b32 m0, s13
	v_readfirstlane_b32 s13, v156
	global_load_lds_dwordx4 v[154:155], off
	v_lshl_add_u64 v[154:155], v[142:143], 0, s[8:9]
	s_mov_b32 m0, s13
	v_add_u32_e32 v153, 0xe000, v153
	global_load_lds_dwordx4 v[154:155], off
	v_lshl_add_u64 v[154:155], v[144:145], 0, s[8:9]
	v_readfirstlane_b32 s8, v153
	s_mov_b32 m0, s8
	s_nop 0
	global_load_lds_dwordx4 v[154:155], off
	s_waitcnt vmcnt(8) lgkmcnt(0)
	s_barrier
	s_branch .LBB0_205

; DI int tid_opaque() { int t = threadIdx.x; asm volatile("" : "+v"(t)); return t; }
; #define LDS_PTR(p) ((__attribute__((address_space(3))) unsigned*)(p))
; template <int PIPE>
; DI void gemm_loop_g(const u16* __restrict__ Xp, long ldx_l, long ldx_i, long kxs,
;                     const u16* __restrict__ Yp, long ldy_l, long ldy_i, long kys, int K,
;                     f32x4 (&acc)[4][8], unsigned char* smem) {
;   const int t = tid_opaque(), l = t & 63, w = __builtin_amdgcn_readfirstlane(t >> 6), wx = w >> 1, wy = w & 1;
;   const int lrow = t >> 3, gch = (t & 7) ^ ((t >> 4) & 7);
;   const u16* xs = Xp + (long)lrow * ldx_l + gch * 8;
;   const u16* ys = Yp + (long)lrow * ldy_l + gch * 8;
;   const int fsw = (l >> 1) & 7, lg = l >> 4;
;   const unsigned fr0 = (l & 15) * 128 + ((lg ^ fsw) << 4);
;   const unsigned fr1 = (l & 15) * 128 + (((lg + 4) ^ fsw) << 4);
;   const unsigned ub = wx * 8192, vb = 32768 + wy * 16384;
;   const int nk = K >> 6;
;   const int rot = (int)((blockIdx.x >> 3) + (blockIdx.x & 7) * 5) % nk;
;   auto issue = [&](int kt0, int stage) {
;     int kt = kt0 + rot; if (kt >= nk) kt -= nk;
;     unsigned char* sb = smem + stage * 65536 + t * 16;
; #pragma unroll
;     for (int i = 0; i < 4; ++i)
;       __builtin_amdgcn_global_load_lds((const unsigned*)(xs + i * ldx_i + kt * kxs), LDS_PTR(sb + i * 8192), 16, 0, 0);
; #pragma unroll
;     for (int i = 0; i < 4; ++i)
;       __builtin_amdgcn_global_load_lds((const unsigned*)(ys + i * ldy_i + kt * kys), LDS_PTR(sb + 32768 + i * 8192), 16, 0, 0);
;   };
;   __syncthreads();
; template <int MODE>
; DI void gemm_phase(const Params& p, const GP& g, unsigned char* smem) {
;     ...
;       const u16* Ap = Ab + (long)m0 * g.lda; const u16* Wp = Wb + (long)n0 * g.K;
;       if (transposed) gemm_loop(Ap, g.lda, Wp, g.K, g.K, acc, smem);
.LBB0_209:
	s_and_b64 vcc, exec, s[82:83]
	s_cbranch_vccz .LBB0_214
	s_nop 1
	v_mov_b32_e32 v4, v182
	s_nop 0
	v_ashrrev_i32_e32 v0, 3, v4
	v_lshrrev_b32_e32 v5, 4, v4
	v_xor_b32_e32 v6, v5, v4
	v_ashrrev_i32_e32 v1, 31, v0
	v_lshlrev_b64 v[0:1], 11, v[0:1]
	v_lshlrev_b32_e32 v6, 4, v6
	v_lshl_add_u64 v[2:3], s[80:81], 0, v[0:1]
	v_and_b32_e32 v128, 0x70, v6
	v_lshl_add_u64 v[0:1], s[16:17], 0, v[0:1]
	v_lshl_add_u64 v[130:131], v[2:3], 0, v[128:129]
	v_lshl_add_u64 v[132:133], v[0:1], 0, v[128:129]
	v_lshlrev_b32_e32 v128, 4, v4
	v_add_u32_e32 v2, 0x2000, v128
	v_readfirstlane_b32 s6, v128
	v_lshl_add_u64 v[0:1], v[130:131], 0, s[28:29]
	s_mov_b32 m0, s6
	v_lshl_add_u64 v[134:135], v[130:131], 0, s[30:31]
	v_readfirstlane_b32 s6, v2
	v_add_u32_e32 v2, 0x4000, v128
	s_barrier
; #define LDS_PTR(p) ((__attribute__((address_space(3))) unsigned*)(p))
; template <int PIPE>
; DI void gemm_loop_g(const u16* __restrict__ Xp, long ldx_l, long ldx_i, long kxs,
;                     const u16* __restrict__ Yp, long ldy_l, long ldy_i, long kys, int K,
;                     f32x4 (&acc)[4][8], unsigned char* smem) {
;     ...
;   auto issue = [&](int kt0, int stage) {
;     int kt = kt0 + rot; if (kt >= nk) kt -= nk;
;     unsigned char* sb = smem + stage * 65536 + t * 16;
; #pragma unroll
;     for (int i = 0; i < 4; ++i)
;       __builtin_amdgcn_global_load_lds((const unsigned*)(xs + i * ldx_i + kt * kxs), LDS_PTR(sb + i * 8192), 16, 0, 0);
; #pragma unroll
;     for (int i = 0; i < 4; ++i)
;       __builtin_amdgcn_global_load_lds((const unsigned*)(ys + i * ldy_i + kt * kys), LDS_PTR(sb + 32768 + i * 8192), 16, 0, 0);
;   };
;   __syncthreads();
;   issue(0, 0);
;   asm volatile("s_waitcnt vmcnt(0)" ::: "memory");
;   __syncthreads();
; #pragma unroll 1
;   for (int kt = 0; kt < nk; ++kt) {
;     const unsigned char* cur = smem + (kt & 1) * 65536;
;     if (kt + 1 < nk) issue(kt + 1, (kt + 1) & 1);
; DI void zero_acc(f32x4 (&acc)[4][8]) {
; #pragma unroll
;   for (int i = 0; i < 4; ++i)
; #pragma unroll
;     for (int j = 0; j < 8; ++j) acc[i][j] = f32x4{0.f, 0.f, 0.f, 0.f};
	global_load_lds_dwordx4 v[0:1], off
	v_lshl_add_u64 v[0:1], v[134:135], 0, s[28:29]
	s_mov_b32 m0, s6
	v_lshl_add_u64 v[136:137], v[130:131], 0, s[54:55]
	v_readfirstlane_b32 s6, v2
	v_add_u32_e32 v2, 0x6000, v128
	global_load_lds_dwordx4 v[0:1], off
	v_lshl_add_u64 v[0:1], v[136:137], 0, s[28:29]
	s_mov_b32 m0, s6
	v_lshl_add_u64 v[138:139], v[130:131], 0, s[56:57]
	v_readfirstlane_b32 s6, v2
	v_add_u32_e32 v2, 0x8000, v128
	global_load_lds_dwordx4 v[0:1], off
	v_lshl_add_u64 v[0:1], v[138:139], 0, s[28:29]
	s_mov_b32 m0, s6
	v_readfirstlane_b32 s6, v2
	v_add_u32_e32 v2, 0xa000, v128
	global_load_lds_dwordx4 v[0:1], off
	v_lshl_add_u64 v[0:1], v[132:133], 0, s[28:29]
	s_mov_b32 m0, s6
	v_lshl_add_u64 v[140:141], v[132:133], 0, s[30:31]
	v_readfirstlane_b32 s6, v2
	v_add_u32_e32 v2, 0xc000, v128
	global_load_lds_dwordx4 v[0:1], off
	v_lshl_add_u64 v[0:1], v[140:141], 0, s[28:29]
	s_mov_b32 m0, s6
	v_lshl_add_u64 v[142:143], v[132:133], 0, s[54:55]
	v_readfirstlane_b32 s6, v2
	v_add_u32_e32 v2, 0xe000, v128
	global_load_lds_dwordx4 v[0:1], off
	v_lshl_add_u64 v[0:1], v[142:143], 0, s[28:29]
	s_mov_b32 m0, s6
	v_lshl_add_u64 v[144:145], v[132:133], 0, s[56:57]
	v_readfirstlane_b32 s6, v2
	global_load_lds_dwordx4 v[0:1], off
	v_lshl_add_u64 v[0:1], v[144:145], 0, s[28:29]
	s_mov_b32 m0, s6
	v_lshlrev_b32_e32 v2, 7, v4
	global_load_lds_dwordx4 v[0:1], off
	v_bfe_u32 v0, v4, 4, 2
	v_bfe_u32 v1, v4, 1, 3
	v_readfirstlane_b32 s7, v4
	s_nop 0
	v_bitop3_b32 v0, v0, v1, 4 bitop3:0x36
	v_and_b32_e32 v2, 0x780, v2
	s_lshl_b32 s6, s7, 8
	s_lshl_b32 s7, s7, 6
	v_lshl_or_b32 v151, v0, 4, v2
	v_bitop3_b32 v0, v5, v1, 3 bitop3:0x6c
	v_mov_b32_e32 v8, 0
	s_and_b32 s6, s6, 0x4000
	s_and_b32 s7, s7, 0xffffe000
	v_lshl_or_b32 v152, v0, 4, v2
	s_mov_b32 s10, 0
	s_mov_b32 s11, 0x10000
	v_mov_b32_e32 v9, v8
	v_mov_b32_e32 v10, v8
	v_mov_b32_e32 v11, v8
	v_mov_b32_e32 v12, v8
	v_mov_b32_e32 v13, v8
	v_mov_b32_e32 v14, v8
	v_mov_b32_e32 v15, v8
	v_mov_b32_e32 v28, v8
	v_mov_b32_e32 v29, v8
	v_mov_b32_e32 v30, v8
	v_mov_b32_e32 v31, v8
	v_mov_b32_e32 v44, v8
	v_mov_b32_e32 v45, v8
	v_mov_b32_e32 v46, v8
	v_mov_b32_e32 v47, v8
	v_mov_b32_e32 v60, v8
	v_mov_b32_e32 v61, v8
	v_mov_b32_e32 v62, v8
	v_mov_b32_e32 v63, v8
	v_mov_b32_e32 v76, v8
	v_mov_b32_e32 v77, v8
	v_mov_b32_e32 v78, v8
	v_mov_b32_e32 v79, v8
	v_mov_b32_e32 v92, v8
	v_mov_b32_e32 v93, v8
	v_mov_b32_e32 v94, v8
	v_mov_b32_e32 v95, v8
	v_mov_b32_e32 v108, v8
	v_mov_b32_e32 v109, v8
	v_mov_b32_e32 v110, v8
	v_mov_b32_e32 v111, v8
	v_mov_b32_e32 v0, v8
	v_mov_b32_e32 v1, v8
	v_mov_b32_e32 v2, v8
	v_mov_b32_e32 v3, v8
	v_mov_b32_e32 v20, v8
	v_mov_b32_e32 v21, v8
	v_mov_b32_e32 v22, v8
	v_mov_b32_e32 v23, v8
	v_mov_b32_e32 v36, v8
	v_mov_b32_e32 v37, v8
	v_mov_b32_e32 v38, v8
	v_mov_b32_e32 v39, v8
	v_mov_b32_e32 v52, v8
	v_mov_b32_e32 v53, v8
	v_mov_b32_e32 v54, v8
	v_mov_b32_e32 v55, v8
	v_mov_b32_e32 v68, v8
	v_mov_b32_e32 v69, v8
	v_mov_b32_e32 v70, v8
	v_mov_b32_e32 v71, v8
	v_mov_b32_e32 v84, v8
	v_mov_b32_e32 v85, v8
	v_mov_b32_e32 v86, v8
	v_mov_b32_e32 v87, v8
	v_mov_b32_e32 v100, v8
	v_mov_b32_e32 v101, v8
	v_mov_b32_e32 v102, v8
	v_mov_b32_e32 v103, v8
	v_mov_b32_e32 v116, v8
	v_mov_b32_e32 v117, v8
	v_mov_b32_e32 v118, v8
	v_mov_b32_e32 v119, v8
	v_mov_b32_e32 v4, v8
	v_mov_b32_e32 v5, v8
	v_mov_b32_e32 v6, v8
	v_mov_b32_e32 v7, v8
	v_mov_b32_e32 v24, v8
	v_mov_b32_e32 v25, v8
	v_mov_b32_e32 v26, v8
	v_mov_b32_e32 v27, v8
	v_mov_b32_e32 v40, v8
	v_mov_b32_e32 v41, v8
	v_mov_b32_e32 v42, v8
	v_mov_b32_e32 v43, v8
	v_mov_b32_e32 v56, v8
	v_mov_b32_e32 v57, v8
	v_mov_b32_e32 v58, v8
	v_mov_b32_e32 v59, v8
	v_mov_b32_e32 v72, v8
	v_mov_b32_e32 v73, v8
	v_mov_b32_e32 v74, v8
	v_mov_b32_e32 v75, v8
	v_mov_b32_e32 v88, v8
	v_mov_b32_e32 v89, v8
	v_mov_b32_e32 v90, v8
	v_mov_b32_e32 v91, v8
	v_mov_b32_e32 v104, v8
	v_mov_b32_e32 v105, v8
	v_mov_b32_e32 v106, v8
	v_mov_b32_e32 v107, v8
	v_mov_b32_e32 v120, v8
	v_mov_b32_e32 v121, v8
	v_mov_b32_e32 v122, v8
	v_mov_b32_e32 v123, v8
	v_mov_b32_e32 v16, v8
	v_mov_b32_e32 v17, v8
	v_mov_b32_e32 v18, v8
	v_mov_b32_e32 v19, v8
	v_mov_b32_e32 v32, v8
	v_mov_b32_e32 v33, v8
	v_mov_b32_e32 v34, v8
	v_mov_b32_e32 v35, v8
	v_mov_b32_e32 v48, v8
	v_mov_b32_e32 v49, v8
	v_mov_b32_e32 v50, v8
	v_mov_b32_e32 v51, v8
	v_mov_b32_e32 v64, v8
	v_mov_b32_e32 v65, v8
	v_mov_b32_e32 v66, v8
	v_mov_b32_e32 v67, v8
	v_mov_b32_e32 v80, v8
	v_mov_b32_e32 v81, v8
	v_mov_b32_e32 v82, v8
	v_mov_b32_e32 v83, v8
	v_mov_b32_e32 v96, v8
	v_mov_b32_e32 v97, v8
	v_mov_b32_e32 v98, v8
	v_mov_b32_e32 v99, v8
	v_mov_b32_e32 v112, v8
	v_mov_b32_e32 v113, v8
	v_mov_b32_e32 v114, v8
	v_mov_b32_e32 v115, v8
	v_mov_b32_e32 v124, v8
	v_mov_b32_e32 v125, v8
	v_mov_b32_e32 v126, v8
	v_mov_b32_e32 v127, v8
	s_add_i32 s8, s65, s10
	s_cmp_lt_u32 s8, 16
	s_cselect_b32 s9, 0, -16
	s_add_i32 s8, s8, s9
	s_and_b32 s9, s11, 0x10000
	v_add_u32_e32 v153, s9, v128
	s_ashr_i32 s9, s8, 31
	s_lshl_b64 s[8:9], s[8:9], 7
	v_readfirstlane_b32 s13, v153
	v_add_u32_e32 v156, 0x2000, v153
	v_lshl_add_u64 v[154:155], v[130:131], 0, s[8:9]
	s_mov_b32 m0, s13
	v_readfirstlane_b32 s13, v156
	v_add_u32_e32 v156, 0x4000, v153
	global_load_lds_dwordx4 v[154:155], off
	v_lshl_add_u64 v[154:155], v[134:135], 0, s[8:9]
	s_mov_b32 m0, s13
	v_readfirstlane_b32 s13, v156
	v_add_u32_e32 v156, 0x6000, v153
	global_load_lds_dwordx4 v[154:155], off
	v_lshl_add_u64 v[154:155], v[136:137], 0, s[8:9]
	s_mov_b32 m0, s13
	v_readfirstlane_b32 s13, v156
	v_add_u32_e32 v156, 0x8000, v153
	global_load_lds_dwordx4 v[154:155], off
	v_lshl_add_u64 v[154:155], v[138:139], 0, s[8:9]
	s_mov_b32 m0, s13
	v_readfirstlane_b32 s13, v156
	v_add_u32_e32 v156, 0xa000, v153
	global_load_lds_dwordx4 v[154:155], off
	v_lshl_add_u64 v[154:155], v[132:133], 0, s[8:9]
	s_mov_b32 m0, s13
	v_readfirstlane_b32 s13, v156
	v_add_u32_e32 v156, 0xc000, v153
	global_load_lds_dwordx4 v[154:155], off
	v_lshl_add_u64 v[154:155], v[140:141], 0, s[8:9]
	s_mov_b32 m0, s13
	v_readfirstlane_b32 s13, v156
	global_load_lds_dwordx4 v[154:155], off
	v_lshl_add_u64 v[154:155], v[142:143], 0, s[8:9]
	s_mov_b32 m0, s13
	v_add_u32_e32 v153, 0xe000, v153
	global_load_lds_dwordx4 v[154:155], off
	v_lshl_add_u64 v[154:155], v[144:145], 0, s[8:9]
	v_readfirstlane_b32 s8, v153
	s_mov_b32 m0, s8
	s_nop 0
	global_load_lds_dwordx4 v[154:155], off
	s_waitcnt vmcnt(8) lgkmcnt(0)
	s_barrier
	s_branch .LBB0_211

; template <int PIPE>
; DI void gemm_loop_g(const u16* __restrict__ Xp, long ldx_l, long ldx_i, long kxs,
;                     const u16* __restrict__ Yp, long ldy_l, long ldy_i, long kys, int K,
;                     f32x4 (&acc)[4][8], unsigned char* smem) {
;   const int t = tid_opaque(), l = t & 63, w = __builtin_amdgcn_readfirstlane(t >> 6), wx = w >> 1, wy = w & 1;
;   const int lrow = t >> 3, gch = (t & 7) ^ ((t >> 4) & 7);
;   const u16* xs = Xp + (long)lrow * ldx_l + gch * 8;
;   const u16* ys = Yp + (long)lrow * ldy_l + gch * 8;
; template <int MODE>
; DI void gemm_phase(const Params& p, const GP& g, unsigned char* smem) {
;     ...
;     int bsel = 0;
;     {
;       const int ml = e / g.ntn;
;       nt = e - ml * g.ntn;
;       mt = xcd + 8 * ml;
;     }
;     if (MODE == M_SEQ) { bsel = mt >> 4; mt &= 15; Wb = g.W + (long)bsel * 1024 * 8192; }
;     const int m0 = mt * 256, n0 = nt * 256;
;     f32x4 acc[4][8];
;     zero_acc(acc);
;     int transposed = 0;
;     if (MODE == M_FN_IN) transposed = nt < 8;
;     if (MODE == M_NA_IN) transposed = (nt >= 8 && nt < 12);
;     if (MODE == M_MLA_UKV) transposed = nt >= 4;
;     if (MODE == M_HG_IN) transposed = nt >= 12;
;     if (MODE == M_PLE) {
;       const u16* pb = (const u16*)g.d1;
;       gemm_loop(g.W2 + (long)n0 * 256, 256, pb + (long)m0 * 256, 256, 256, acc, smem);
;       u16* xb = (u16*)g.d0;
;       EPI_STD_BEGIN
;         *(u32x2*)(xb + (long)m * 1024 + n4) = pack4(v[0], v[1], v[2], v[3]);
;       EPI_END
;       zero_acc(acc);
;     }
;     if (MODE == M_FFT1) {
;       const int bt = mt >> 8, cg = mt & 255;
;       gemm_loop_g<0>(Ab + ((long)(bt * 1024 + cg * 4)) * 8192, 64, 8192, 4096, Wb, 128, 64 * 128, 64, 128, acc, smem);
;     } else if (MODE == M_FFT3) {
;       const int bt = mt >> 8, v = (mt >> 2) & 63, cq = mt & 3;
;       gemm_loop(Ab + (((long)(bt * 64 + v)) * 1024 + cq * 256) * 128, 128, Wb, 128, 128, acc, smem);
;     } else if (MODE == M_FN_IN && transposed) {
;       const u16* Ap = Ab + ((long)(mt >> 4) * 4096 + (mt & 15) * 4) * g.lda;
;       gemm_loop_g<1>(Ap, 64 * g.lda, g.lda, 64, Wb + (long)n0 * g.K, g.K, 64L * g.K, 64, g.K, acc, smem);
;     } else {
;       const u16* Ap = Ab + (long)m0 * g.lda; const u16* Wp = Wb + (long)n0 * g.K;
;       if (transposed) gemm_loop(Ap, g.lda, Wp, g.K, g.K, acc, smem);
;       else gemm_loop(Wp, g.K, Ap, g.lda, g.K, acc, smem);
.LBB0_294:
	s_lshl_b32 s6, s11, 9
	s_and_b32 s6, s6, 0xfffff800
	s_or_b32 s28, s6, s30
	s_lshl_b32 s6, s11, 8
	s_and_b32 s6, s6, 0x300
	s_lshl_b32 s7, s6, 11
	s_waitcnt lgkmcnt(0)
	s_add_u32 s8, s14, s7
	s_addc_u32 s9, s15, 0
	s_ashr_i32 s29, s28, 31
	v_mov_b32_e32 v4, v182
	s_lshl_b64 s[40:41], s[28:29], 11
	s_add_u32 s40, s36, s40
	v_ashrrev_i32_e32 v0, 3, v4
	v_lshrrev_b32_e32 v5, 4, v4
	v_xor_b32_e32 v6, v5, v4
	v_ashrrev_i32_e32 v1, 31, v0
	s_addc_u32 s41, s37, s41
	v_lshlrev_b64 v[0:1], 11, v[0:1]
	v_lshlrev_b32_e32 v6, 4, v6
	v_lshl_add_u64 v[2:3], s[8:9], 0, v[0:1]
	v_and_b32_e32 v128, 0x70, v6
	v_lshl_add_u64 v[0:1], s[40:41], 0, v[0:1]
	v_lshl_add_u64 v[130:131], v[2:3], 0, v[128:129]
	v_lshl_add_u64 v[132:133], v[0:1], 0, v[128:129]
	v_lshlrev_b32_e32 v128, 4, v4
	v_add_u32_e32 v2, 0x2000, v128
	v_readfirstlane_b32 s7, v128
	v_lshl_add_u64 v[0:1], v[130:131], 0, s[16:17]
	s_mov_b32 m0, s7
	v_lshl_add_u64 v[134:135], v[130:131], 0, s[18:19]
	v_readfirstlane_b32 s7, v2
	v_add_u32_e32 v2, 0x4000, v128
	s_barrier
; #define LDS_PTR(p) ((__attribute__((address_space(3))) unsigned*)(p))
; template <int PIPE>
; DI void gemm_loop_g(const u16* __restrict__ Xp, long ldx_l, long ldx_i, long kxs,
;                     const u16* __restrict__ Yp, long ldy_l, long ldy_i, long kys, int K,
;                     f32x4 (&acc)[4][8], unsigned char* smem) {
;     ...
;   auto issue = [&](int kt0, int stage) {
;     int kt = kt0 + rot; if (kt >= nk) kt -= nk;
;     unsigned char* sb = smem + stage * 65536 + t * 16;
; #pragma unroll
;     for (int i = 0; i < 4; ++i)
;       __builtin_amdgcn_global_load_lds((const unsigned*)(xs + i * ldx_i + kt * kxs), LDS_PTR(sb + i * 8192), 16, 0, 0);
; #pragma unroll
;     for (int i = 0; i < 4; ++i)
;       __builtin_amdgcn_global_load_lds((const unsigned*)(ys + i * ldy_i + kt * kys), LDS_PTR(sb + 32768 + i * 8192), 16, 0, 0);
;   };
;   __syncthreads();
;   issue(0, 0);
;   asm volatile("s_waitcnt vmcnt(0)" ::: "memory");
;   __syncthreads();
; #pragma unroll 1
;   for (int kt = 0; kt < nk; ++kt) {
;     const unsigned char* cur = smem + (kt & 1) * 65536;
;     if (kt + 1 < nk) issue(kt + 1, (kt + 1) & 1);
; DI void zero_acc(f32x4 (&acc)[4][8]) {
; #pragma unroll
;   for (int i = 0; i < 4; ++i)
; #pragma unroll
;     for (int j = 0; j < 8; ++j) acc[i][j] = f32x4{0.f, 0.f, 0.f, 0.f};
	global_load_lds_dwordx4 v[0:1], off
	v_lshl_add_u64 v[0:1], v[134:135], 0, s[16:17]
	s_mov_b32 m0, s7
	v_lshl_add_u64 v[136:137], v[130:131], 0, s[24:25]
	v_readfirstlane_b32 s7, v2
	v_add_u32_e32 v2, 0x6000, v128
	global_load_lds_dwordx4 v[0:1], off
	v_lshl_add_u64 v[0:1], v[136:137], 0, s[16:17]
	s_mov_b32 m0, s7
	v_lshl_add_u64 v[138:139], v[130:131], 0, s[26:27]
	v_readfirstlane_b32 s7, v2
	v_add_u32_e32 v2, 0x8000, v128
	global_load_lds_dwordx4 v[0:1], off
	v_lshl_add_u64 v[0:1], v[138:139], 0, s[16:17]
	s_mov_b32 m0, s7
	v_readfirstlane_b32 s7, v2
	v_add_u32_e32 v2, 0xa000, v128
	global_load_lds_dwordx4 v[0:1], off
	v_lshl_add_u64 v[0:1], v[132:133], 0, s[16:17]
	s_mov_b32 m0, s7
	v_lshl_add_u64 v[140:141], v[132:133], 0, s[18:19]
	v_readfirstlane_b32 s7, v2
	v_add_u32_e32 v2, 0xc000, v128
	global_load_lds_dwordx4 v[0:1], off
	v_lshl_add_u64 v[0:1], v[140:141], 0, s[16:17]
	s_mov_b32 m0, s7
	v_lshl_add_u64 v[142:143], v[132:133], 0, s[24:25]
	v_readfirstlane_b32 s7, v2
	v_add_u32_e32 v2, 0xe000, v128
	global_load_lds_dwordx4 v[0:1], off
	v_lshl_add_u64 v[0:1], v[142:143], 0, s[16:17]
	s_mov_b32 m0, s7
	v_lshl_add_u64 v[144:145], v[132:133], 0, s[26:27]
	v_readfirstlane_b32 s7, v2
	global_load_lds_dwordx4 v[0:1], off
	v_lshl_add_u64 v[0:1], v[144:145], 0, s[16:17]
	s_mov_b32 m0, s7
	v_lshlrev_b32_e32 v2, 7, v4
	global_load_lds_dwordx4 v[0:1], off
	v_bfe_u32 v0, v4, 4, 2
	v_bfe_u32 v1, v4, 1, 3
	v_readfirstlane_b32 s29, v4
	s_nop 0
	v_bitop3_b32 v0, v0, v1, 4 bitop3:0x36
	v_and_b32_e32 v2, 0x780, v2
	s_lshl_b32 s7, s29, 8
	s_lshl_b32 s8, s29, 6
	v_lshl_or_b32 v148, v0, 4, v2
	v_bitop3_b32 v0, v5, v1, 3 bitop3:0x6c
	s_and_b32 s7, s7, 0x4000
	s_and_b32 s29, s8, 0xffffe000
	v_lshl_or_b32 v149, v0, 4, v2
	s_mov_b32 s31, 0x10000
	s_mov_b32 s33, 0
	v_mov_b32_e32 v12, 0
	v_mov_b32_e32 v13, v129
	v_mov_b32_e32 v14, v129
	v_mov_b32_e32 v15, v129
	v_mov_b32_e32 v4, 0
	v_mov_b32_e32 v5, v129
	v_mov_b32_e32 v6, v129
	v_mov_b32_e32 v7, v129
	v_mov_b32_e32 v24, 0
	v_mov_b32_e32 v25, v129
	v_mov_b32_e32 v26, v129
	v_mov_b32_e32 v27, v129
	v_mov_b32_e32 v40, 0
	v_mov_b32_e32 v41, v129
	v_mov_b32_e32 v42, v129
	v_mov_b32_e32 v43, v129
	v_mov_b32_e32 v56, 0
	v_mov_b32_e32 v57, v129
	v_mov_b32_e32 v58, v129
	v_mov_b32_e32 v59, v129
	v_mov_b32_e32 v72, 0
	v_mov_b32_e32 v73, v129
	v_mov_b32_e32 v74, v129
	v_mov_b32_e32 v75, v129
	v_mov_b32_e32 v88, 0
	v_mov_b32_e32 v89, v129
	v_mov_b32_e32 v90, v129
	v_mov_b32_e32 v91, v129
	v_mov_b32_e32 v104, 0
	v_mov_b32_e32 v105, v129
	v_mov_b32_e32 v106, v129
	v_mov_b32_e32 v107, v129
	v_mov_b32_e32 v0, 0
	v_mov_b32_e32 v1, v129
	v_mov_b32_e32 v2, v129
	v_mov_b32_e32 v3, v129
	v_mov_b32_e32 v20, 0
	v_mov_b32_e32 v21, v129
	v_mov_b32_e32 v22, v129
	v_mov_b32_e32 v23, v129
	v_mov_b32_e32 v36, 0
	v_mov_b32_e32 v37, v129
	v_mov_b32_e32 v38, v129
	v_mov_b32_e32 v39, v129
	v_mov_b32_e32 v52, 0
	v_mov_b32_e32 v53, v129
	v_mov_b32_e32 v54, v129
	v_mov_b32_e32 v55, v129
	v_mov_b32_e32 v68, 0
	v_mov_b32_e32 v69, v129
	v_mov_b32_e32 v70, v129
	v_mov_b32_e32 v71, v129
	v_mov_b32_e32 v84, 0
	v_mov_b32_e32 v85, v129
	v_mov_b32_e32 v86, v129
	v_mov_b32_e32 v87, v129
	v_mov_b32_e32 v100, 0
	v_mov_b32_e32 v101, v129
	v_mov_b32_e32 v102, v129
	v_mov_b32_e32 v103, v129
	v_mov_b32_e32 v116, 0
	v_mov_b32_e32 v117, v129
	v_mov_b32_e32 v118, v129
	v_mov_b32_e32 v119, v129
	v_mov_b32_e32 v8, 0
	v_mov_b32_e32 v9, v129
	v_mov_b32_e32 v10, v129
	v_mov_b32_e32 v11, v129
	v_mov_b32_e32 v28, 0
	v_mov_b32_e32 v29, v129
	v_mov_b32_e32 v30, v129
	v_mov_b32_e32 v31, v129
	v_mov_b32_e32 v44, 0
	v_mov_b32_e32 v45, v129
	v_mov_b32_e32 v46, v129
	v_mov_b32_e32 v47, v129
	v_mov_b32_e32 v60, 0
	v_mov_b32_e32 v61, v129
	v_mov_b32_e32 v62, v129
	v_mov_b32_e32 v63, v129
	v_mov_b32_e32 v76, 0
	v_mov_b32_e32 v77, v129
	v_mov_b32_e32 v78, v129
	v_mov_b32_e32 v79, v129
	v_mov_b32_e32 v92, 0
	v_mov_b32_e32 v93, v129
	v_mov_b32_e32 v94, v129
	v_mov_b32_e32 v95, v129
	v_mov_b32_e32 v108, 0
	v_mov_b32_e32 v109, v129
	v_mov_b32_e32 v110, v129
	v_mov_b32_e32 v111, v129
	v_mov_b32_e32 v120, 0
	v_mov_b32_e32 v121, v129
	v_mov_b32_e32 v122, v129
	v_mov_b32_e32 v123, v129
	v_mov_b32_e32 v16, 0
	v_mov_b32_e32 v17, v129
	v_mov_b32_e32 v18, v129
	v_mov_b32_e32 v19, v129
	v_mov_b32_e32 v32, 0
	v_mov_b32_e32 v33, v129
	v_mov_b32_e32 v34, v129
	v_mov_b32_e32 v35, v129
	v_mov_b32_e32 v48, 0
	v_mov_b32_e32 v49, v129
	v_mov_b32_e32 v50, v129
	v_mov_b32_e32 v51, v129
	v_mov_b32_e32 v64, 0
	v_mov_b32_e32 v65, v129
	v_mov_b32_e32 v66, v129
	v_mov_b32_e32 v67, v129
	v_mov_b32_e32 v80, 0
	v_mov_b32_e32 v81, v129
	v_mov_b32_e32 v82, v129
	v_mov_b32_e32 v83, v129
	v_mov_b32_e32 v96, 0
	v_mov_b32_e32 v97, v129
	v_mov_b32_e32 v98, v129
	v_mov_b32_e32 v99, v129
	v_mov_b32_e32 v112, 0
	v_mov_b32_e32 v113, v129
	v_mov_b32_e32 v114, v129
	v_mov_b32_e32 v115, v129
	v_mov_b32_e32 v124, 0
	v_mov_b32_e32 v125, v129
	v_mov_b32_e32 v126, v129
	v_mov_b32_e32 v127, v129
	s_add_i32 s8, s10, s33
	s_cmp_lt_u32 s8, 16
	s_cselect_b32 s9, 0, -16
	s_add_i32 s8, s8, s9
	s_and_b32 s9, s31, 0x10000
	v_add_u32_e32 v152, s9, v128
	s_ashr_i32 s9, s8, 31
	s_lshl_b64 s[8:9], s[8:9], 7
	v_readfirstlane_b32 s40, v152
	v_add_u32_e32 v153, 0x2000, v152
	v_lshl_add_u64 v[150:151], v[130:131], 0, s[8:9]
	s_mov_b32 m0, s40
	v_readfirstlane_b32 s40, v153
	v_add_u32_e32 v153, 0x4000, v152
	global_load_lds_dwordx4 v[150:151], off
	v_lshl_add_u64 v[150:151], v[134:135], 0, s[8:9]
	s_mov_b32 m0, s40
	v_readfirstlane_b32 s40, v153
	v_add_u32_e32 v153, 0x6000, v152
	global_load_lds_dwordx4 v[150:151], off
	v_lshl_add_u64 v[150:151], v[136:137], 0, s[8:9]
	s_mov_b32 m0, s40
	v_readfirstlane_b32 s40, v153
	v_add_u32_e32 v153, 0x8000, v152
	global_load_lds_dwordx4 v[150:151], off
	v_lshl_add_u64 v[150:151], v[138:139], 0, s[8:9]
	s_mov_b32 m0, s40
	v_readfirstlane_b32 s40, v153
	v_add_u32_e32 v153, 0xa000, v152
	global_load_lds_dwordx4 v[150:151], off
	v_lshl_add_u64 v[150:151], v[132:133], 0, s[8:9]
	s_mov_b32 m0, s40
	v_readfirstlane_b32 s40, v153
	v_add_u32_e32 v153, 0xc000, v152
	global_load_lds_dwordx4 v[150:151], off
	v_lshl_add_u64 v[150:151], v[140:141], 0, s[8:9]
	s_mov_b32 m0, s40
	v_readfirstlane_b32 s40, v153
	global_load_lds_dwordx4 v[150:151], off
	v_lshl_add_u64 v[150:151], v[142:143], 0, s[8:9]
	s_mov_b32 m0, s40
	v_add_u32_e32 v152, 0xe000, v152
	global_load_lds_dwordx4 v[150:151], off
	v_lshl_add_u64 v[150:151], v[144:145], 0, s[8:9]
	v_readfirstlane_b32 s8, v152
	s_mov_b32 m0, s8
	s_nop 0
	global_load_lds_dwordx4 v[150:151], off
	s_waitcnt vmcnt(8) lgkmcnt(0)
	s_barrier
	s_branch .LBB0_295

; DI int tid_opaque() { int t = threadIdx.x; asm volatile("" : "+v"(t)); return t; }
; #define LDS_PTR(p) ((__attribute__((address_space(3))) unsigned*)(p))
; template <int PIPE>
; DI void gemm_loop_g(const u16* __restrict__ Xp, long ldx_l, long ldx_i, long kxs,
;                     const u16* __restrict__ Yp, long ldy_l, long ldy_i, long kys, int K,
;                     f32x4 (&acc)[4][8], unsigned char* smem) {
;   const int t = tid_opaque(), l = t & 63, w = __builtin_amdgcn_readfirstlane(t >> 6), wx = w >> 1, wy = w & 1;
;   const int lrow = t >> 3, gch = (t & 7) ^ ((t >> 4) & 7);
;   const u16* xs = Xp + (long)lrow * ldx_l + gch * 8;
;   const u16* ys = Yp + (long)lrow * ldy_l + gch * 8;
;   const int fsw = (l >> 1) & 7, lg = l >> 4;
;   const unsigned fr0 = (l & 15) * 128 + ((lg ^ fsw) << 4);
;   const unsigned fr1 = (l & 15) * 128 + (((lg + 4) ^ fsw) << 4);
;   const unsigned ub = wx * 8192, vb = 32768 + wy * 16384;
;   const int nk = K >> 6;
;   const int rot = (int)((blockIdx.x >> 3) + (blockIdx.x & 7) * 5) % nk;
;   auto issue = [&](int kt0, int stage) {
;     int kt = kt0 + rot; if (kt >= nk) kt -= nk;
;     unsigned char* sb = smem + stage * 65536 + t * 16;
; #pragma unroll
;     for (int i = 0; i < 4; ++i)
;       __builtin_amdgcn_global_load_lds((const unsigned*)(xs + i * ldx_i + kt * kxs), LDS_PTR(sb + i * 8192), 16, 0, 0);
; #pragma unroll
;     for (int i = 0; i < 4; ++i)
;       __builtin_amdgcn_global_load_lds((const unsigned*)(ys + i * ldy_i + kt * kys), LDS_PTR(sb + 32768 + i * 8192), 16, 0, 0);
;   };
;   __syncthreads();
; template <int MODE>
; DI void gemm_phase(const Params& p, const GP& g, unsigned char* smem) {
;     ...
;       const u16* pb = (const u16*)g.d1;
;       gemm_loop(g.W2 + (long)n0 * 256, 256, pb + (long)m0 * 256, 256, 256, acc, smem);
.LBB0_314:
	s_lshl_b32 s6, s69, 9
	s_and_b32 s6, s6, 0xfffff800
	s_or_b32 s12, s6, s66
	s_lshl_b32 s6, s69, 8
	s_and_b32 s6, s6, 0x300
	s_lshl_b32 s7, s6, 9
	s_add_u32 s8, s64, s7
	v_mov_b32_e32 v6, v182
	s_addc_u32 s9, s65, 0
	s_ashr_i32 s13, s12, 31
	s_lshl_b64 s[10:11], s[12:13], 9
	v_ashrrev_i32_e32 v2, 3, v6
	v_lshrrev_b32_e32 v7, 4, v6
	v_xor_b32_e32 v8, v7, v6
	v_ashrrev_i32_e32 v3, 31, v2
	s_waitcnt lgkmcnt(0)
	v_lshl_add_u64 v[0:1], v[128:129], 0, s[10:11]
	v_lshlrev_b64 v[2:3], 9, v[2:3]
	v_lshlrev_b32_e32 v8, 4, v8
	v_lshl_add_u64 v[4:5], s[8:9], 0, v[2:3]
	v_and_b32_e32 v130, 0x70, v8
	v_lshl_add_u64 v[0:1], v[0:1], 0, v[2:3]
	v_lshl_add_u64 v[132:133], v[4:5], 0, v[130:131]
	v_lshl_add_u64 v[134:135], v[0:1], 0, v[130:131]
	v_lshlrev_b32_e32 v130, 4, v6
	v_add_u32_e32 v2, 0x2000, v130
	v_readfirstlane_b32 s7, v130
	v_lshl_add_u64 v[0:1], v[132:133], 0, s[18:19]
	s_mov_b32 m0, s7
	v_lshl_add_u64 v[136:137], v[132:133], 0, s[24:25]
	v_readfirstlane_b32 s7, v2
	v_add_u32_e32 v2, 0x4000, v130
	s_barrier
; #define LDS_PTR(p) ((__attribute__((address_space(3))) unsigned*)(p))
; template <int PIPE>
; DI void gemm_loop_g(const u16* __restrict__ Xp, long ldx_l, long ldx_i, long kxs,
;                     const u16* __restrict__ Yp, long ldy_l, long ldy_i, long kys, int K,
;                     f32x4 (&acc)[4][8], unsigned char* smem) {
;     ...
;   auto issue = [&](int kt0, int stage) {
;     int kt = kt0 + rot; if (kt >= nk) kt -= nk;
;     unsigned char* sb = smem + stage * 65536 + t * 16;
; #pragma unroll
;     for (int i = 0; i < 4; ++i)
;       __builtin_amdgcn_global_load_lds((const unsigned*)(xs + i * ldx_i + kt * kxs), LDS_PTR(sb + i * 8192), 16, 0, 0);
; #pragma unroll
;     for (int i = 0; i < 4; ++i)
;       __builtin_amdgcn_global_load_lds((const unsigned*)(ys + i * ldy_i + kt * kys), LDS_PTR(sb + 32768 + i * 8192), 16, 0, 0);
;   };
;   __syncthreads();
;   issue(0, 0);
;   asm volatile("s_waitcnt vmcnt(0)" ::: "memory");
;   __syncthreads();
; #pragma unroll 1
;   for (int kt = 0; kt < nk; ++kt) {
;     const unsigned char* cur = smem + (kt & 1) * 65536;
;     if (kt + 1 < nk) issue(kt + 1, (kt + 1) & 1);
; DI void zero_acc(f32x4 (&acc)[4][8]) {
; #pragma unroll
;   for (int i = 0; i < 4; ++i)
; #pragma unroll
;     for (int j = 0; j < 8; ++j) acc[i][j] = f32x4{0.f, 0.f, 0.f, 0.f};
	global_load_lds_dwordx4 v[0:1], off
	v_lshl_add_u64 v[0:1], v[136:137], 0, s[18:19]
	s_mov_b32 m0, s7
	v_lshl_add_u64 v[138:139], v[132:133], 0, s[26:27]
	v_readfirstlane_b32 s7, v2
	v_add_u32_e32 v2, 0x6000, v130
	global_load_lds_dwordx4 v[0:1], off
	v_lshl_add_u64 v[0:1], v[138:139], 0, s[18:19]
	s_mov_b32 m0, s7
	v_lshl_add_u64 v[140:141], v[132:133], 0, s[28:29]
	v_readfirstlane_b32 s7, v2
	v_add_u32_e32 v2, 0x8000, v130
	global_load_lds_dwordx4 v[0:1], off
	v_lshl_add_u64 v[0:1], v[140:141], 0, s[18:19]
	s_mov_b32 m0, s7
	v_readfirstlane_b32 s7, v2
	v_add_u32_e32 v2, 0xa000, v130
	global_load_lds_dwordx4 v[0:1], off
	v_lshl_add_u64 v[0:1], v[134:135], 0, s[18:19]
	s_mov_b32 m0, s7
	v_lshl_add_u64 v[142:143], v[134:135], 0, s[24:25]
	v_readfirstlane_b32 s7, v2
	v_add_u32_e32 v2, 0xc000, v130
	global_load_lds_dwordx4 v[0:1], off
	v_lshl_add_u64 v[0:1], v[142:143], 0, s[18:19]
	s_mov_b32 m0, s7
	v_lshl_add_u64 v[144:145], v[134:135], 0, s[26:27]
	v_readfirstlane_b32 s7, v2
	v_add_u32_e32 v2, 0xe000, v130
	global_load_lds_dwordx4 v[0:1], off
	v_lshl_add_u64 v[0:1], v[144:145], 0, s[18:19]
	s_mov_b32 m0, s7
	v_lshl_add_u64 v[146:147], v[134:135], 0, s[28:29]
	v_readfirstlane_b32 s7, v2
	global_load_lds_dwordx4 v[0:1], off
	v_lshl_add_u64 v[0:1], v[146:147], 0, s[18:19]
	s_mov_b32 m0, s7
	v_lshlrev_b32_e32 v2, 7, v6
	global_load_lds_dwordx4 v[0:1], off
	v_bfe_u32 v0, v6, 4, 2
	v_bfe_u32 v1, v6, 1, 3
	v_readfirstlane_b32 s10, v6
	s_nop 0
	v_bitop3_b32 v0, v0, v1, 4 bitop3:0x36
	v_and_b32_e32 v2, 0x780, v2
	s_lshl_b32 s7, s10, 8
	s_lshl_b32 s8, s10, 6
	v_lshl_or_b32 v148, v0, 4, v2
	v_bitop3_b32 v0, v7, v1, 3 bitop3:0x6c
	s_and_b32 s7, s7, 0x4000
	s_and_b32 s10, s8, 0xffffe000
	v_lshl_or_b32 v149, v0, 4, v2
	s_mov_b32 s11, 0x10000
	s_mov_b32 s33, 0
	v_mov_b32_e32 v40, 0
	v_mov_b32_e32 v41, v131
	v_mov_b32_e32 v42, v131
	v_mov_b32_e32 v43, v131
	v_mov_b32_e32 v0, 0
	v_mov_b32_e32 v1, v131
	v_mov_b32_e32 v2, v131
	v_mov_b32_e32 v3, v131
	v_mov_b32_e32 v8, 0
	v_mov_b32_e32 v9, v131
	v_mov_b32_e32 v10, v131
	v_mov_b32_e32 v11, v131
	v_mov_b32_e32 v20, 0
	v_mov_b32_e32 v21, v131
	v_mov_b32_e32 v22, v131
	v_mov_b32_e32 v23, v131
	v_mov_b32_e32 v36, 0
	v_mov_b32_e32 v37, v131
	v_mov_b32_e32 v38, v131
	v_mov_b32_e32 v39, v131
	v_mov_b32_e32 v56, 0
	v_mov_b32_e32 v57, v131
	v_mov_b32_e32 v58, v131
	v_mov_b32_e32 v59, v131
	v_mov_b32_e32 v72, 0
	v_mov_b32_e32 v73, v131
	v_mov_b32_e32 v74, v131
	v_mov_b32_e32 v75, v131
	v_mov_b32_e32 v96, 0
	v_mov_b32_e32 v97, v131
	v_mov_b32_e32 v98, v131
	v_mov_b32_e32 v99, v131
	v_mov_b32_e32 v4, 0
	v_mov_b32_e32 v5, v131
	v_mov_b32_e32 v6, v131
	v_mov_b32_e32 v7, v131
	v_mov_b32_e32 v12, 0
	v_mov_b32_e32 v13, v131
	v_mov_b32_e32 v14, v131
	v_mov_b32_e32 v15, v131
	v_mov_b32_e32 v24, 0
	v_mov_b32_e32 v25, v131
	v_mov_b32_e32 v26, v131
	v_mov_b32_e32 v27, v131
	v_mov_b32_e32 v44, 0
	v_mov_b32_e32 v45, v131
	v_mov_b32_e32 v46, v131
	v_mov_b32_e32 v47, v131
	v_mov_b32_e32 v64, 0
	v_mov_b32_e32 v65, v131
	v_mov_b32_e32 v66, v131
	v_mov_b32_e32 v67, v131
	v_mov_b32_e32 v76, 0
	v_mov_b32_e32 v77, v131
	v_mov_b32_e32 v78, v131
	v_mov_b32_e32 v79, v131
	v_mov_b32_e32 v88, 0
	v_mov_b32_e32 v89, v131
	v_mov_b32_e32 v90, v131
	v_mov_b32_e32 v91, v131
	v_mov_b32_e32 v112, 0
	v_mov_b32_e32 v113, v131
	v_mov_b32_e32 v114, v131
	v_mov_b32_e32 v115, v131
	v_mov_b32_e32 v16, 0
	v_mov_b32_e32 v17, v131
	v_mov_b32_e32 v18, v131
	v_mov_b32_e32 v19, v131
	v_mov_b32_e32 v28, 0
	v_mov_b32_e32 v29, v131
	v_mov_b32_e32 v30, v131
	v_mov_b32_e32 v31, v131
	v_mov_b32_e32 v48, 0
	v_mov_b32_e32 v49, v131
	v_mov_b32_e32 v50, v131
	v_mov_b32_e32 v51, v131
	v_mov_b32_e32 v60, 0
	v_mov_b32_e32 v61, v131
	v_mov_b32_e32 v62, v131
	v_mov_b32_e32 v63, v131
	v_mov_b32_e32 v80, 0
	v_mov_b32_e32 v81, v131
	v_mov_b32_e32 v82, v131
	v_mov_b32_e32 v83, v131
	v_mov_b32_e32 v92, 0
	v_mov_b32_e32 v93, v131
	v_mov_b32_e32 v94, v131
	v_mov_b32_e32 v95, v131
	v_mov_b32_e32 v108, 0
	v_mov_b32_e32 v109, v131
	v_mov_b32_e32 v110, v131
	v_mov_b32_e32 v111, v131
	v_mov_b32_e32 v116, 0
	v_mov_b32_e32 v117, v131
	v_mov_b32_e32 v118, v131
	v_mov_b32_e32 v119, v131
	v_mov_b32_e32 v32, 0
	v_mov_b32_e32 v33, v131
	v_mov_b32_e32 v34, v131
	v_mov_b32_e32 v35, v131
	v_mov_b32_e32 v52, 0
	v_mov_b32_e32 v53, v131
	v_mov_b32_e32 v54, v131
	v_mov_b32_e32 v55, v131
	v_mov_b32_e32 v68, 0
	v_mov_b32_e32 v69, v131
	v_mov_b32_e32 v70, v131
	v_mov_b32_e32 v71, v131
	v_mov_b32_e32 v84, 0
	v_mov_b32_e32 v85, v131
	v_mov_b32_e32 v86, v131
	v_mov_b32_e32 v87, v131
	v_mov_b32_e32 v100, 0
	v_mov_b32_e32 v101, v131
	v_mov_b32_e32 v102, v131
	v_mov_b32_e32 v103, v131
	v_mov_b32_e32 v104, 0
	v_mov_b32_e32 v105, v131
	v_mov_b32_e32 v106, v131
	v_mov_b32_e32 v107, v131
	v_mov_b32_e32 v120, 0
	v_mov_b32_e32 v121, v131
	v_mov_b32_e32 v122, v131
	v_mov_b32_e32 v123, v131
	v_mov_b32_e32 v124, 0
	v_mov_b32_e32 v125, v131
	v_mov_b32_e32 v126, v131
	v_mov_b32_e32 v127, v131
	s_add_i32 s8, s67, s33
	s_cmp_lt_u32 s8, 4
	s_cselect_b32 s9, 0, -4
	s_add_i32 s8, s8, s9
	s_and_b32 s9, s11, 0x10000
	v_add_u32_e32 v152, s9, v130
	s_ashr_i32 s9, s8, 31
	s_lshl_b64 s[8:9], s[8:9], 7
	v_readfirstlane_b32 s40, v152
	v_add_u32_e32 v153, 0x2000, v152
	v_lshl_add_u64 v[150:151], v[132:133], 0, s[8:9]
	s_mov_b32 m0, s40
	v_readfirstlane_b32 s40, v153
	v_add_u32_e32 v153, 0x4000, v152
	global_load_lds_dwordx4 v[150:151], off
	v_lshl_add_u64 v[150:151], v[136:137], 0, s[8:9]
	s_mov_b32 m0, s40
	v_readfirstlane_b32 s40, v153
	v_add_u32_e32 v153, 0x6000, v152
	global_load_lds_dwordx4 v[150:151], off
	v_lshl_add_u64 v[150:151], v[138:139], 0, s[8:9]
	s_mov_b32 m0, s40
	v_readfirstlane_b32 s40, v153
	v_add_u32_e32 v153, 0x8000, v152
	global_load_lds_dwordx4 v[150:151], off
	v_lshl_add_u64 v[150:151], v[140:141], 0, s[8:9]
	s_mov_b32 m0, s40
	v_readfirstlane_b32 s40, v153
	v_add_u32_e32 v153, 0xa000, v152
	global_load_lds_dwordx4 v[150:151], off
	v_lshl_add_u64 v[150:151], v[134:135], 0, s[8:9]
	s_mov_b32 m0, s40
	v_readfirstlane_b32 s40, v153
	v_add_u32_e32 v153, 0xc000, v152
	global_load_lds_dwordx4 v[150:151], off
	v_lshl_add_u64 v[150:151], v[142:143], 0, s[8:9]
	s_mov_b32 m0, s40
	v_readfirstlane_b32 s40, v153
	global_load_lds_dwordx4 v[150:151], off
	v_lshl_add_u64 v[150:151], v[144:145], 0, s[8:9]
	s_mov_b32 m0, s40
	v_add_u32_e32 v152, 0xe000, v152
	global_load_lds_dwordx4 v[150:151], off
	v_lshl_add_u64 v[150:151], v[146:147], 0, s[8:9]
	v_readfirstlane_b32 s8, v152
	s_mov_b32 m0, s8
	s_nop 0
	global_load_lds_dwordx4 v[150:151], off
	s_waitcnt vmcnt(8) lgkmcnt(0)
	s_barrier
	s_branch .LBB0_315

; template <int PIPE>
; DI void gemm_loop_g(const u16* __restrict__ Xp, long ldx_l, long ldx_i, long kxs,
;                     const u16* __restrict__ Yp, long ldy_l, long ldy_i, long kys, int K,
;                     f32x4 (&acc)[4][8], unsigned char* smem) {
;   const int t = tid_opaque(), l = t & 63, w = __builtin_amdgcn_readfirstlane(t >> 6), wx = w >> 1, wy = w & 1;
;   const int lrow = t >> 3, gch = (t & 7) ^ ((t >> 4) & 7);
;   const u16* xs = Xp + (long)lrow * ldx_l + gch * 8;
;   const u16* ys = Yp + (long)lrow * ldy_l + gch * 8;
;   const int fsw = (l >> 1) & 7, lg = l >> 4;
;   const unsigned fr0 = (l & 15) * 128 + ((lg ^ fsw) << 4);
;   const unsigned fr1 = (l & 15) * 128 + (((lg + 4) ^ fsw) << 4);
;   const unsigned ub = wx * 8192, vb = 32768 + wy * 16384;
;   const int nk = K >> 6;
;   const int rot = (int)((blockIdx.x >> 3) + (blockIdx.x & 7) * 5) % nk;
;   auto issue = [&](int kt0, int stage) {
;     int kt = kt0 + rot; if (kt >= nk) kt -= nk;
;     unsigned char* sb = smem + stage * 65536 + t * 16;
; #pragma unroll
;     for (int i = 0; i < 4; ++i)
;       __builtin_amdgcn_global_load_lds((const unsigned*)(xs + i * ldx_i + kt * kxs), LDS_PTR(sb + i * 8192), 16, 0, 0);
; #pragma unroll
;     for (int i = 0; i < 4; ++i)
; template <int MODE>
; DI void gemm_phase(const Params& p, const GP& g, unsigned char* smem) {
;     ...
;       u16* xb = (u16*)g.d0;
;       EPI_STD_BEGIN
;         *(u32x2*)(xb + (long)m * 1024 + n4) = pack4(v[0], v[1], v[2], v[3]);
;       EPI_END
;       zero_acc(acc);
;     }
;     if (MODE == M_FFT1) {
;       const int bt = mt >> 8, cg = mt & 255;
;       gemm_loop_g<0>(Ab + ((long)(bt * 1024 + cg * 4)) * 8192, 64, 8192, 4096, Wb, 128, 64 * 128, 64, 128, acc, smem);
;     } else if (MODE == M_FFT3) {
;       const int bt = mt >> 8, v = (mt >> 2) & 63, cq = mt & 3;
;       gemm_loop(Ab + (((long)(bt * 64 + v)) * 1024 + cq * 256) * 128, 128, Wb, 128, 128, acc, smem);
;     } else if (MODE == M_FN_IN && transposed) {
;       const u16* Ap = Ab + ((long)(mt >> 4) * 4096 + (mt & 15) * 4) * g.lda;
;       gemm_loop_g<1>(Ap, 64 * g.lda, g.lda, 64, Wb + (long)n0 * g.K, g.K, 64L * g.K, 64, g.K, acc, smem);
;     } else {
;       const u16* Ap = Ab + (long)m0 * g.lda; const u16* Wp = Wb + (long)n0 * g.K;
;       if (transposed) gemm_loop(Ap, g.lda, Wp, g.K, g.K, acc, smem);
;       else gemm_loop(Wp, g.K, Ap, g.lda, g.K, acc, smem);
.LBB0_318:
	v_or_b32_e32 v160, s12, v185
	v_add_u32_e32 v134, s6, v184
	v_ashrrev_i32_e32 v161, 31, v160
	v_lshlrev_b64 v[164:165], 11, v[160:161]
	v_ashrrev_i32_e32 v135, 31, v134
	v_or_b32_e32 v156, 16, v160
	v_lshl_add_u64 v[132:133], s[36:37], 0, v[164:165]
	v_cvt_pk_bf16_f32 v124, v124, v125
	v_cvt_pk_bf16_f32 v125, v126, v127
	v_lshlrev_b64 v[126:127], 1, v[134:135]
	v_ashrrev_i32_e32 v157, 31, v156
	v_lshl_add_u64 v[132:133], v[132:133], 0, v[126:127]
	v_cvt_pk_bf16_f32 v96, v96, v97
	v_cvt_pk_bf16_f32 v97, v98, v99
	v_lshlrev_b64 v[162:163], 11, v[156:157]
	v_or_b32_e32 v152, 32, v160
	global_store_dwordx2 v[132:133], v[96:97], off offset:96
	v_lshl_add_u64 v[96:97], s[36:37], 0, v[162:163]
	v_ashrrev_i32_e32 v153, 31, v152
	v_lshl_add_u64 v[96:97], v[96:97], 0, v[126:127]
	v_cvt_pk_bf16_f32 v72, v72, v73
	v_cvt_pk_bf16_f32 v73, v74, v75
	v_lshlrev_b64 v[158:159], 11, v[152:153]
	v_or_b32_e32 v148, 48, v160
	global_store_dwordx2 v[96:97], v[72:73], off offset:96
	v_lshl_add_u64 v[72:73], s[36:37], 0, v[158:159]
	v_ashrrev_i32_e32 v149, 31, v148
	v_lshl_add_u64 v[72:73], v[72:73], 0, v[126:127]
	v_cvt_pk_bf16_f32 v56, v56, v57
	v_cvt_pk_bf16_f32 v57, v58, v59
	v_lshlrev_b64 v[154:155], 11, v[148:149]
	global_store_dwordx2 v[72:73], v[56:57], off offset:96
	v_lshl_add_u64 v[56:57], s[36:37], 0, v[154:155]
	v_cvt_pk_bf16_f32 v74, v104, v105
	v_cvt_pk_bf16_f32 v75, v106, v107
	v_cvt_pk_bf16_f32 v58, v100, v101
	v_cvt_pk_bf16_f32 v59, v102, v103
	v_lshl_add_u64 v[56:57], v[56:57], 0, v[126:127]
	v_cvt_pk_bf16_f32 v98, v120, v121
	v_cvt_pk_bf16_f32 v99, v122, v123
	global_store_dwordx2 v[72:73], v[74:75], off
	v_cvt_pk_bf16_f32 v74, v92, v93
	v_cvt_pk_bf16_f32 v75, v94, v95
	global_store_dwordx2 v[56:57], v[58:59], off
	v_cvt_pk_bf16_f32 v58, v80, v81
	v_cvt_pk_bf16_f32 v59, v82, v83
	v_cvt_pk_bf16_f32 v116, v116, v117
	v_cvt_pk_bf16_f32 v117, v118, v119
	v_cvt_pk_bf16_f32 v112, v112, v113
	v_cvt_pk_bf16_f32 v113, v114, v115
	global_store_dwordx2 v[96:97], v[98:99], off
	v_cvt_pk_bf16_f32 v98, v108, v109
	v_cvt_pk_bf16_f32 v99, v110, v111
	v_cvt_pk_bf16_f32 v88, v88, v89
	v_cvt_pk_bf16_f32 v89, v90, v91
	global_store_dwordx2 v[72:73], v[74:75], off offset:32
	v_cvt_pk_bf16_f32 v74, v76, v77
	v_cvt_pk_bf16_f32 v75, v78, v79
	global_store_dwordx2 v[56:57], v[58:59], off offset:32
	v_cvt_pk_bf16_f32 v58, v64, v65
	v_cvt_pk_bf16_f32 v59, v66, v67
	v_cvt_pk_bf16_f32 v36, v36, v37
	v_cvt_pk_bf16_f32 v37, v38, v39
	global_store_dwordx2 v[132:133], v[124:125], off
	global_store_dwordx2 v[132:133], v[116:117], off offset:32
	global_store_dwordx2 v[132:133], v[112:113], off offset:64
	global_store_dwordx2 v[96:97], v[98:99], off offset:32
	global_store_dwordx2 v[96:97], v[88:89], off offset:64
	global_store_dwordx2 v[72:73], v[74:75], off offset:64
	global_store_dwordx2 v[56:57], v[58:59], off offset:64
	global_store_dwordx2 v[56:57], v[36:37], off offset:96
	v_or_b32_e32 v144, 64, v160
	v_ashrrev_i32_e32 v145, 31, v144
	v_lshlrev_b64 v[150:151], 11, v[144:145]
	v_or_b32_e32 v140, 0x50, v160
	v_lshl_add_u64 v[36:37], s[36:37], 0, v[150:151]
	v_ashrrev_i32_e32 v141, 31, v140
	v_lshl_add_u64 v[36:37], v[36:37], 0, v[126:127]
	v_cvt_pk_bf16_f32 v20, v20, v21
	v_cvt_pk_bf16_f32 v21, v22, v23
	v_lshlrev_b64 v[146:147], 11, v[140:141]
	v_or_b32_e32 v136, 0x60, v160
	global_store_dwordx2 v[36:37], v[20:21], off offset:96
	v_lshl_add_u64 v[20:21], s[36:37], 0, v[146:147]
	v_ashrrev_i32_e32 v137, 31, v136
	v_lshl_add_u64 v[20:21], v[20:21], 0, v[126:127]
	v_cvt_pk_bf16_f32 v8, v8, v9
	v_cvt_pk_bf16_f32 v9, v10, v11
	v_lshlrev_b64 v[142:143], 11, v[136:137]
	v_or_b32_e32 v132, 0x70, v160
	global_store_dwordx2 v[20:21], v[8:9], off offset:96
	v_lshl_add_u64 v[8:9], s[36:37], 0, v[142:143]
	v_ashrrev_i32_e32 v133, 31, v132
	v_lshl_add_u64 v[8:9], v[8:9], 0, v[126:127]
	v_cvt_pk_bf16_f32 v0, v0, v1
	v_cvt_pk_bf16_f32 v1, v2, v3
	v_lshlrev_b64 v[138:139], 11, v[132:133]
	global_store_dwordx2 v[8:9], v[0:1], off offset:96
	v_lshl_add_u64 v[0:1], s[36:37], 0, v[138:139]
	v_cvt_pk_bf16_f32 v2, v32, v33
	v_cvt_pk_bf16_f32 v3, v34, v35
	v_lshl_add_u64 v[0:1], v[0:1], 0, v[126:127]
	v_cvt_pk_bf16_f32 v38, v84, v85
	v_cvt_pk_bf16_f32 v39, v86, v87
	v_cvt_pk_bf16_f32 v22, v68, v69
	v_cvt_pk_bf16_f32 v23, v70, v71
	v_cvt_pk_bf16_f32 v10, v52, v53
	v_cvt_pk_bf16_f32 v11, v54, v55
	global_store_dwordx2 v[0:1], v[2:3], off
	v_cvt_pk_bf16_f32 v2, v16, v17
	v_cvt_pk_bf16_f32 v3, v18, v19
	global_store_dwordx2 v[36:37], v[38:39], off
	v_cvt_pk_bf16_f32 v38, v60, v61
	v_cvt_pk_bf16_f32 v39, v62, v63
	global_store_dwordx2 v[20:21], v[22:23], off
	v_cvt_pk_bf16_f32 v22, v48, v49
	v_cvt_pk_bf16_f32 v23, v50, v51
	global_store_dwordx2 v[8:9], v[10:11], off
	v_cvt_pk_bf16_f32 v10, v28, v29
	v_cvt_pk_bf16_f32 v11, v30, v31
	global_store_dwordx2 v[0:1], v[2:3], off offset:32
	v_cvt_pk_bf16_f32 v2, v4, v5
	v_cvt_pk_bf16_f32 v3, v6, v7
	global_store_dwordx2 v[36:37], v[38:39], off offset:32
	v_cvt_pk_bf16_f32 v38, v44, v45
	v_cvt_pk_bf16_f32 v39, v46, v47
	global_store_dwordx2 v[20:21], v[22:23], off offset:32
	v_cvt_pk_bf16_f32 v22, v24, v25
	v_cvt_pk_bf16_f32 v23, v26, v27
	global_store_dwordx2 v[8:9], v[10:11], off offset:32
	v_cvt_pk_bf16_f32 v10, v12, v13
	v_cvt_pk_bf16_f32 v11, v14, v15
	global_store_dwordx2 v[0:1], v[2:3], off offset:64
	v_cvt_pk_bf16_f32 v2, v40, v41
	v_cvt_pk_bf16_f32 v3, v42, v43
	global_store_dwordx2 v[36:37], v[38:39], off offset:64
	global_store_dwordx2 v[20:21], v[22:23], off offset:64
	global_store_dwordx2 v[8:9], v[10:11], off offset:64
	global_store_dwordx2 v[0:1], v[2:3], off offset:96
	s_lshl_b32 s6, s6, 11
	s_add_u32 s6, s62, s6
	v_mov_b32_e32 v4, v182
	s_addc_u32 s7, s63, 0
	s_lshl_b64 s[8:9], s[12:13], 11
	s_add_u32 s8, s38, s8
	v_ashrrev_i32_e32 v0, 3, v4
	v_lshrrev_b32_e32 v5, 4, v4
	v_xor_b32_e32 v6, v5, v4
	v_ashrrev_i32_e32 v1, 31, v0
	s_addc_u32 s9, s39, s9
	v_lshlrev_b64 v[0:1], 11, v[0:1]
	v_lshlrev_b32_e32 v6, 4, v6
	v_lshl_add_u64 v[2:3], s[6:7], 0, v[0:1]
	v_and_b32_e32 v130, 0x70, v6
	v_lshl_add_u64 v[0:1], s[8:9], 0, v[0:1]
	v_lshl_add_u64 v[166:167], v[2:3], 0, v[130:131]
	v_lshl_add_u64 v[168:169], v[0:1], 0, v[130:131]
	v_lshlrev_b32_e32 v130, 4, v4
	v_add_u32_e32 v2, 0x2000, v130
	v_readfirstlane_b32 s6, v130
	v_lshl_add_u64 v[0:1], v[166:167], 0, s[30:31]
	s_mov_b32 m0, s6
	v_lshl_add_u64 v[170:171], v[166:167], 0, s[54:55]
	v_readfirstlane_b32 s6, v2
	v_add_u32_e32 v2, 0x4000, v130
	s_barrier
; #define LDS_PTR(p) ((__attribute__((address_space(3))) unsigned*)(p))
; template <int PIPE>
; DI void gemm_loop_g(const u16* __restrict__ Xp, long ldx_l, long ldx_i, long kxs,
;                     const u16* __restrict__ Yp, long ldy_l, long ldy_i, long kys, int K,
;                     f32x4 (&acc)[4][8], unsigned char* smem) {
;     ...
;   auto issue = [&](int kt0, int stage) {
;     int kt = kt0 + rot; if (kt >= nk) kt -= nk;
;     unsigned char* sb = smem + stage * 65536 + t * 16;
; #pragma unroll
;     for (int i = 0; i < 4; ++i)
;       __builtin_amdgcn_global_load_lds((const unsigned*)(xs + i * ldx_i + kt * kxs), LDS_PTR(sb + i * 8192), 16, 0, 0);
; #pragma unroll
;     for (int i = 0; i < 4; ++i)
;       __builtin_amdgcn_global_load_lds((const unsigned*)(ys + i * ldy_i + kt * kys), LDS_PTR(sb + 32768 + i * 8192), 16, 0, 0);
;   };
;   __syncthreads();
;   issue(0, 0);
;   asm volatile("s_waitcnt vmcnt(0)" ::: "memory");
;   __syncthreads();
; #pragma unroll 1
;   for (int kt = 0; kt < nk; ++kt) {
;     const unsigned char* cur = smem + (kt & 1) * 65536;
;     if (kt + 1 < nk) issue(kt + 1, (kt + 1) & 1);
; DI void zero_acc(f32x4 (&acc)[4][8]) {
; #pragma unroll
;   for (int i = 0; i < 4; ++i)
; #pragma unroll
;     for (int j = 0; j < 8; ++j) acc[i][j] = f32x4{0.f, 0.f, 0.f, 0.f};
	global_load_lds_dwordx4 v[0:1], off
	v_lshl_add_u64 v[0:1], v[170:171], 0, s[30:31]
	s_mov_b32 m0, s6
	v_lshl_add_u64 v[172:173], v[166:167], 0, s[56:57]
	v_readfirstlane_b32 s6, v2
	v_add_u32_e32 v2, 0x6000, v130
	global_load_lds_dwordx4 v[0:1], off
	v_lshl_add_u64 v[0:1], v[172:173], 0, s[30:31]
	s_mov_b32 m0, s6
	v_lshl_add_u64 v[174:175], v[166:167], 0, s[58:59]
	v_readfirstlane_b32 s6, v2
	v_add_u32_e32 v2, 0x8000, v130
	global_load_lds_dwordx4 v[0:1], off
	v_lshl_add_u64 v[0:1], v[174:175], 0, s[30:31]
	s_mov_b32 m0, s6
	v_readfirstlane_b32 s6, v2
	v_add_u32_e32 v2, 0xa000, v130
	global_load_lds_dwordx4 v[0:1], off
	v_lshl_add_u64 v[0:1], v[168:169], 0, s[30:31]
	s_mov_b32 m0, s6
	v_lshl_add_u64 v[176:177], v[168:169], 0, s[54:55]
	v_readfirstlane_b32 s6, v2
	v_add_u32_e32 v2, 0xc000, v130
	global_load_lds_dwordx4 v[0:1], off
	v_lshl_add_u64 v[0:1], v[176:177], 0, s[30:31]
	s_mov_b32 m0, s6
	v_lshl_add_u64 v[178:179], v[168:169], 0, s[56:57]
	v_readfirstlane_b32 s6, v2
	v_add_u32_e32 v2, 0xe000, v130
	global_load_lds_dwordx4 v[0:1], off
	v_lshl_add_u64 v[0:1], v[178:179], 0, s[30:31]
	s_mov_b32 m0, s6
	v_lshl_add_u64 v[180:181], v[168:169], 0, s[58:59]
	v_readfirstlane_b32 s6, v2
	global_load_lds_dwordx4 v[0:1], off
	v_lshl_add_u64 v[0:1], v[180:181], 0, s[30:31]
	s_mov_b32 m0, s6
	v_lshlrev_b32_e32 v2, 7, v4
	global_load_lds_dwordx4 v[0:1], off
	v_bfe_u32 v0, v4, 4, 2
	v_bfe_u32 v1, v4, 1, 3
	v_readfirstlane_b32 s10, v4
	s_nop 0
	v_bitop3_b32 v0, v0, v1, 4 bitop3:0x36
	v_and_b32_e32 v2, 0x780, v2
	s_lshl_b32 s6, s10, 8
	s_lshl_b32 s7, s10, 6
	v_lshl_or_b32 v187, v0, 4, v2
	v_bitop3_b32 v0, v5, v1, 3 bitop3:0x6c
	v_mov_b32_e32 v4, 0
	s_and_b32 s6, s6, 0x4000
	s_and_b32 s7, s7, 0xffffe000
	v_lshl_or_b32 v188, v0, 4, v2
	s_mov_b32 s10, 0
	s_mov_b32 s11, 0x10000
	v_mov_b32_e32 v5, v4
	v_mov_b32_e32 v6, v4
	v_mov_b32_e32 v7, v4
	v_mov_b32_e32 v16, v4
	v_mov_b32_e32 v17, v4
	v_mov_b32_e32 v18, v4
	v_mov_b32_e32 v19, v4
	v_mov_b32_e32 v32, v4
	v_mov_b32_e32 v33, v4
	v_mov_b32_e32 v34, v4
	v_mov_b32_e32 v35, v4
	v_mov_b32_e32 v48, v4
	v_mov_b32_e32 v49, v4
	v_mov_b32_e32 v50, v4
	v_mov_b32_e32 v51, v4
	v_mov_b32_e32 v64, v4
	v_mov_b32_e32 v65, v4
	v_mov_b32_e32 v66, v4
	v_mov_b32_e32 v67, v4
	v_mov_b32_e32 v80, v4
	v_mov_b32_e32 v81, v4
	v_mov_b32_e32 v82, v4
	v_mov_b32_e32 v83, v4
	v_mov_b32_e32 v96, v4
	v_mov_b32_e32 v97, v4
	v_mov_b32_e32 v98, v4
	v_mov_b32_e32 v99, v4
	v_mov_b32_e32 v112, v4
	v_mov_b32_e32 v113, v4
	v_mov_b32_e32 v114, v4
	v_mov_b32_e32 v115, v4
	v_mov_b32_e32 v0, v4
	v_mov_b32_e32 v1, v4
	v_mov_b32_e32 v2, v4
	v_mov_b32_e32 v3, v4
	v_mov_b32_e32 v20, v4
	v_mov_b32_e32 v21, v4
	v_mov_b32_e32 v22, v4
	v_mov_b32_e32 v23, v4
	v_mov_b32_e32 v36, v4
	v_mov_b32_e32 v37, v4
	v_mov_b32_e32 v38, v4
	v_mov_b32_e32 v39, v4
	v_mov_b32_e32 v52, v4
	v_mov_b32_e32 v53, v4
	v_mov_b32_e32 v54, v4
	v_mov_b32_e32 v55, v4
	v_mov_b32_e32 v68, v4
	v_mov_b32_e32 v69, v4
	v_mov_b32_e32 v70, v4
	v_mov_b32_e32 v71, v4
	v_mov_b32_e32 v84, v4
	v_mov_b32_e32 v85, v4
	v_mov_b32_e32 v86, v4
	v_mov_b32_e32 v87, v4
	v_mov_b32_e32 v100, v4
	v_mov_b32_e32 v101, v4
	v_mov_b32_e32 v102, v4
	v_mov_b32_e32 v103, v4
	v_mov_b32_e32 v116, v4
	v_mov_b32_e32 v117, v4
	v_mov_b32_e32 v118, v4
	v_mov_b32_e32 v119, v4
	v_mov_b32_e32 v8, v4
	v_mov_b32_e32 v9, v4
	v_mov_b32_e32 v10, v4
	v_mov_b32_e32 v11, v4
	v_mov_b32_e32 v24, v4
	v_mov_b32_e32 v25, v4
	v_mov_b32_e32 v26, v4
	v_mov_b32_e32 v27, v4
	v_mov_b32_e32 v40, v4
	v_mov_b32_e32 v41, v4
	v_mov_b32_e32 v42, v4
	v_mov_b32_e32 v43, v4
	v_mov_b32_e32 v56, v4
	v_mov_b32_e32 v57, v4
	v_mov_b32_e32 v58, v4
	v_mov_b32_e32 v59, v4
	v_mov_b32_e32 v72, v4
	v_mov_b32_e32 v73, v4
	v_mov_b32_e32 v74, v4
	v_mov_b32_e32 v75, v4
	v_mov_b32_e32 v88, v4
	v_mov_b32_e32 v89, v4
	v_mov_b32_e32 v90, v4
	v_mov_b32_e32 v91, v4
	v_mov_b32_e32 v104, v4
	v_mov_b32_e32 v105, v4
	v_mov_b32_e32 v106, v4
	v_mov_b32_e32 v107, v4
	v_mov_b32_e32 v120, v4
	v_mov_b32_e32 v121, v4
	v_mov_b32_e32 v122, v4
	v_mov_b32_e32 v123, v4
	v_mov_b32_e32 v12, v4
	v_mov_b32_e32 v13, v4
	v_mov_b32_e32 v14, v4
	v_mov_b32_e32 v15, v4
	v_mov_b32_e32 v28, v4
	v_mov_b32_e32 v29, v4
	v_mov_b32_e32 v30, v4
	v_mov_b32_e32 v31, v4
	v_mov_b32_e32 v44, v4
	v_mov_b32_e32 v45, v4
	v_mov_b32_e32 v46, v4
	v_mov_b32_e32 v47, v4
	v_mov_b32_e32 v60, v4
	v_mov_b32_e32 v61, v4
	v_mov_b32_e32 v62, v4
	v_mov_b32_e32 v63, v4
	v_mov_b32_e32 v76, v4
	v_mov_b32_e32 v77, v4
	v_mov_b32_e32 v78, v4
	v_mov_b32_e32 v79, v4
	v_mov_b32_e32 v92, v4
	v_mov_b32_e32 v93, v4
	v_mov_b32_e32 v94, v4
	v_mov_b32_e32 v95, v4
	v_mov_b32_e32 v108, v4
	v_mov_b32_e32 v109, v4
	v_mov_b32_e32 v110, v4
	v_mov_b32_e32 v111, v4
	v_mov_b32_e32 v124, v4
	v_mov_b32_e32 v125, v4
	v_mov_b32_e32 v126, v4
	v_mov_b32_e32 v127, v4
	s_add_i32 s8, s68, s10
	s_cmp_lt_u32 s8, 16
	s_cselect_b32 s9, 0, -16
	s_add_i32 s8, s8, s9
	s_and_b32 s9, s11, 0x10000
	v_add_u32_e32 v189, s9, v130
	s_ashr_i32 s9, s8, 31
	s_lshl_b64 s[8:9], s[8:9], 7
	v_readfirstlane_b32 s12, v189
	v_add_u32_e32 v192, 0x2000, v189
	v_lshl_add_u64 v[190:191], v[166:167], 0, s[8:9]
	s_mov_b32 m0, s12
	v_readfirstlane_b32 s12, v192
	v_add_u32_e32 v192, 0x4000, v189
	global_load_lds_dwordx4 v[190:191], off
	v_lshl_add_u64 v[190:191], v[170:171], 0, s[8:9]
	s_mov_b32 m0, s12
	v_readfirstlane_b32 s12, v192
	v_add_u32_e32 v192, 0x6000, v189
	global_load_lds_dwordx4 v[190:191], off
	v_lshl_add_u64 v[190:191], v[172:173], 0, s[8:9]
	s_mov_b32 m0, s12
	v_readfirstlane_b32 s12, v192
	v_add_u32_e32 v192, 0x8000, v189
	global_load_lds_dwordx4 v[190:191], off
	v_lshl_add_u64 v[190:191], v[174:175], 0, s[8:9]
	s_mov_b32 m0, s12
	v_readfirstlane_b32 s12, v192
	v_add_u32_e32 v192, 0xa000, v189
	global_load_lds_dwordx4 v[190:191], off
	v_lshl_add_u64 v[190:191], v[168:169], 0, s[8:9]
	s_mov_b32 m0, s12
	v_readfirstlane_b32 s12, v192
	v_add_u32_e32 v192, 0xc000, v189
	global_load_lds_dwordx4 v[190:191], off
	v_lshl_add_u64 v[190:191], v[176:177], 0, s[8:9]
	s_mov_b32 m0, s12
	v_readfirstlane_b32 s12, v192
	global_load_lds_dwordx4 v[190:191], off
	v_lshl_add_u64 v[190:191], v[178:179], 0, s[8:9]
	s_mov_b32 m0, s12
	v_add_u32_e32 v189, 0xe000, v189
	global_load_lds_dwordx4 v[190:191], off
	v_lshl_add_u64 v[190:191], v[180:181], 0, s[8:9]
	v_readfirstlane_b32 s8, v189
	s_mov_b32 m0, s8
	s_nop 0
	global_load_lds_dwordx4 v[190:191], off
	s_waitcnt vmcnt(8) lgkmcnt(0)
	s_barrier
	s_branch .LBB0_319

; template <int PIPE>
; DI void gemm_loop_g(const u16* __restrict__ Xp, long ldx_l, long ldx_i, long kxs,
;                     const u16* __restrict__ Yp, long ldy_l, long ldy_i, long kys, int K,
;                     f32x4 (&acc)[4][8], unsigned char* smem) {
;   const int t = tid_opaque(), l = t & 63, w = __builtin_amdgcn_readfirstlane(t >> 6), wx = w >> 1, wy = w & 1;
;   const int lrow = t >> 3, gch = (t & 7) ^ ((t >> 4) & 7);
;   const u16* xs = Xp + (long)lrow * ldx_l + gch * 8;
;   const u16* ys = Yp + (long)lrow * ldy_l + gch * 8;
; template <int MODE>
; DI void gemm_phase(const Params& p, const GP& g, unsigned char* smem) {
;     ...
;     int bsel = 0;
;     {
;       const int ml = e / g.ntn;
;       nt = e - ml * g.ntn;
;       mt = xcd + 8 * ml;
;     }
;     if (MODE == M_SEQ) { bsel = mt >> 4; mt &= 15; Wb = g.W + (long)bsel * 1024 * 8192; }
;     const int m0 = mt * 256, n0 = nt * 256;
;     f32x4 acc[4][8];
;     zero_acc(acc);
;     int transposed = 0;
;     if (MODE == M_FN_IN) transposed = nt < 8;
;     if (MODE == M_NA_IN) transposed = (nt >= 8 && nt < 12);
;     if (MODE == M_MLA_UKV) transposed = nt >= 4;
;     if (MODE == M_HG_IN) transposed = nt >= 12;
;     if (MODE == M_PLE) {
;       const u16* pb = (const u16*)g.d1;
;       gemm_loop(g.W2 + (long)n0 * 256, 256, pb + (long)m0 * 256, 256, 256, acc, smem);
;       u16* xb = (u16*)g.d0;
;       EPI_STD_BEGIN
;         *(u32x2*)(xb + (long)m * 1024 + n4) = pack4(v[0], v[1], v[2], v[3]);
;       EPI_END
;       zero_acc(acc);
;     }
;     if (MODE == M_FFT1) {
;       const int bt = mt >> 8, cg = mt & 255;
;       gemm_loop_g<0>(Ab + ((long)(bt * 1024 + cg * 4)) * 8192, 64, 8192, 4096, Wb, 128, 64 * 128, 64, 128, acc, smem);
;     } else if (MODE == M_FFT3) {
;       const int bt = mt >> 8, v = (mt >> 2) & 63, cq = mt & 3;
;       gemm_loop(Ab + (((long)(bt * 64 + v)) * 1024 + cq * 256) * 128, 128, Wb, 128, 128, acc, smem);
;     } else if (MODE == M_FN_IN && transposed) {
;       const u16* Ap = Ab + ((long)(mt >> 4) * 4096 + (mt & 15) * 4) * g.lda;
;       gemm_loop_g<1>(Ap, 64 * g.lda, g.lda, 64, Wb + (long)n0 * g.K, g.K, 64L * g.K, 64, g.K, acc, smem);
;     } else {
;       const u16* Ap = Ab + (long)m0 * g.lda; const u16* Wp = Wb + (long)n0 * g.K;
;       if (transposed) gemm_loop(Ap, g.lda, Wp, g.K, g.K, acc, smem);
;       else gemm_loop(Wp, g.K, Ap, g.lda, g.K, acc, smem);
.LBB0_352:
	s_mul_hi_u32 s6, s69, 0xaaaaaaab
	s_lshr_b32 s7, s6, 1
	s_mul_i32 s6, s7, -3
	s_add_i32 s6, s6, s69
	s_lshl_b32 s58, s6, 8
	s_lshl_b32 s7, s7, 11
	s_ashr_i32 s59, s58, 31
	s_or_b32 s60, s7, s65
	s_lshl_b64 s[8:9], s[58:59], 11
	s_add_u32 s8, s26, s8
	s_addc_u32 s9, s27, s9
	s_ashr_i32 s61, s60, 31
	v_mov_b32_e32 v4, v182
	s_lshl_b64 s[10:11], s[60:61], 11
	s_add_u32 s10, s36, s10
	v_ashrrev_i32_e32 v0, 3, v4
	v_lshrrev_b32_e32 v5, 4, v4
	v_xor_b32_e32 v6, v5, v4
	s_waitcnt lgkmcnt(0)
	v_ashrrev_i32_e32 v1, 31, v0
	s_addc_u32 s11, s37, s11
	v_lshlrev_b64 v[0:1], 11, v[0:1]
	v_lshlrev_b32_e32 v6, 4, v6
	v_lshl_add_u64 v[2:3], s[8:9], 0, v[0:1]
	v_and_b32_e32 v128, 0x70, v6
	v_lshl_add_u64 v[0:1], s[10:11], 0, v[0:1]
	v_lshl_add_u64 v[132:133], v[2:3], 0, v[128:129]
	v_lshl_add_u64 v[134:135], v[0:1], 0, v[128:129]
	v_lshlrev_b32_e32 v128, 4, v4
	v_add_u32_e32 v2, 0x2000, v128
	v_readfirstlane_b32 s7, v128
	v_lshl_add_u64 v[0:1], v[132:133], 0, s[24:25]
	s_mov_b32 m0, s7
	v_lshl_add_u64 v[136:137], v[132:133], 0, s[30:31]
	v_readfirstlane_b32 s7, v2
	v_add_u32_e32 v2, 0x4000, v128
	s_barrier
; #define LDS_PTR(p) ((__attribute__((address_space(3))) unsigned*)(p))
; template <int PIPE>
; DI void gemm_loop_g(const u16* __restrict__ Xp, long ldx_l, long ldx_i, long kxs,
;                     const u16* __restrict__ Yp, long ldy_l, long ldy_i, long kys, int K,
;                     f32x4 (&acc)[4][8], unsigned char* smem) {
;     ...
;   auto issue = [&](int kt0, int stage) {
;     int kt = kt0 + rot; if (kt >= nk) kt -= nk;
;     unsigned char* sb = smem + stage * 65536 + t * 16;
; #pragma unroll
;     for (int i = 0; i < 4; ++i)
;       __builtin_amdgcn_global_load_lds((const unsigned*)(xs + i * ldx_i + kt * kxs), LDS_PTR(sb + i * 8192), 16, 0, 0);
; #pragma unroll
;     for (int i = 0; i < 4; ++i)
;       __builtin_amdgcn_global_load_lds((const unsigned*)(ys + i * ldy_i + kt * kys), LDS_PTR(sb + 32768 + i * 8192), 16, 0, 0);
;   };
;   __syncthreads();
;   issue(0, 0);
;   asm volatile("s_waitcnt vmcnt(0)" ::: "memory");
;   __syncthreads();
; #pragma unroll 1
;   for (int kt = 0; kt < nk; ++kt) {
;     const unsigned char* cur = smem + (kt & 1) * 65536;
;     if (kt + 1 < nk) issue(kt + 1, (kt + 1) & 1);
; DI void zero_acc(f32x4 (&acc)[4][8]) {
; #pragma unroll
;   for (int i = 0; i < 4; ++i)
; #pragma unroll
;     for (int j = 0; j < 8; ++j) acc[i][j] = f32x4{0.f, 0.f, 0.f, 0.f};
	global_load_lds_dwordx4 v[0:1], off
	v_lshl_add_u64 v[0:1], v[136:137], 0, s[24:25]
	s_mov_b32 m0, s7
	v_lshl_add_u64 v[138:139], v[132:133], 0, s[54:55]
	v_readfirstlane_b32 s7, v2
	v_add_u32_e32 v2, 0x6000, v128
	global_load_lds_dwordx4 v[0:1], off
	v_lshl_add_u64 v[0:1], v[138:139], 0, s[24:25]
	s_mov_b32 m0, s7
	v_lshl_add_u64 v[140:141], v[132:133], 0, s[56:57]
	v_readfirstlane_b32 s7, v2
	v_add_u32_e32 v2, 0x8000, v128
	global_load_lds_dwordx4 v[0:1], off
	v_lshl_add_u64 v[0:1], v[140:141], 0, s[24:25]
	s_mov_b32 m0, s7
	v_readfirstlane_b32 s7, v2
	v_add_u32_e32 v2, 0xa000, v128
	global_load_lds_dwordx4 v[0:1], off
	v_lshl_add_u64 v[0:1], v[134:135], 0, s[24:25]
	s_mov_b32 m0, s7
	v_lshl_add_u64 v[142:143], v[134:135], 0, s[30:31]
	v_readfirstlane_b32 s7, v2
	v_add_u32_e32 v2, 0xc000, v128
	global_load_lds_dwordx4 v[0:1], off
	v_lshl_add_u64 v[0:1], v[142:143], 0, s[24:25]
	s_mov_b32 m0, s7
	v_lshl_add_u64 v[144:145], v[134:135], 0, s[54:55]
	v_readfirstlane_b32 s7, v2
	v_add_u32_e32 v2, 0xe000, v128
	global_load_lds_dwordx4 v[0:1], off
	v_lshl_add_u64 v[0:1], v[144:145], 0, s[24:25]
	s_mov_b32 m0, s7
	v_lshl_add_u64 v[146:147], v[134:135], 0, s[56:57]
	v_readfirstlane_b32 s7, v2
	global_load_lds_dwordx4 v[0:1], off
	v_lshl_add_u64 v[0:1], v[146:147], 0, s[24:25]
	s_mov_b32 m0, s7
	v_lshlrev_b32_e32 v2, 7, v4
	global_load_lds_dwordx4 v[0:1], off
	v_bfe_u32 v0, v4, 4, 2
	v_bfe_u32 v1, v4, 1, 3
	v_readfirstlane_b32 s33, v4
	s_nop 0
	v_bitop3_b32 v0, v0, v1, 4 bitop3:0x36
	v_and_b32_e32 v2, 0x780, v2
	s_lshl_b32 s7, s33, 8
	s_lshl_b32 s8, s33, 6
	v_lshl_or_b32 v154, v0, 4, v2
	v_bitop3_b32 v0, v5, v1, 3 bitop3:0x6c
	s_and_b32 s7, s7, 0x4000
	s_and_b32 s10, s8, 0xffffe000
	v_lshl_or_b32 v155, v0, 4, v2
	s_mov_b32 s11, 0x10000
	s_mov_b32 s33, 0
	v_mov_b32_e32 v8, 0
	v_mov_b32_e32 v9, v129
	v_mov_b32_e32 v10, v129
	v_mov_b32_e32 v11, v129
	v_mov_b32_e32 v12, 0
	v_mov_b32_e32 v13, v129
	v_mov_b32_e32 v14, v129
	v_mov_b32_e32 v15, v129
	v_mov_b32_e32 v28, 0
	v_mov_b32_e32 v29, v129
	v_mov_b32_e32 v30, v129
	v_mov_b32_e32 v31, v129
	v_mov_b32_e32 v44, 0
	v_mov_b32_e32 v45, v129
	v_mov_b32_e32 v46, v129
	v_mov_b32_e32 v47, v129
	v_mov_b32_e32 v60, 0
	v_mov_b32_e32 v61, v129
	v_mov_b32_e32 v62, v129
	v_mov_b32_e32 v63, v129
	v_mov_b32_e32 v76, 0
	v_mov_b32_e32 v77, v129
	v_mov_b32_e32 v78, v129
	v_mov_b32_e32 v79, v129
	v_mov_b32_e32 v92, 0
	v_mov_b32_e32 v93, v129
	v_mov_b32_e32 v94, v129
	v_mov_b32_e32 v95, v129
	v_mov_b32_e32 v108, 0
	v_mov_b32_e32 v109, v129
	v_mov_b32_e32 v110, v129
	v_mov_b32_e32 v111, v129
	v_mov_b32_e32 v0, 0
	v_mov_b32_e32 v1, v129
	v_mov_b32_e32 v2, v129
	v_mov_b32_e32 v3, v129
	v_mov_b32_e32 v20, 0
	v_mov_b32_e32 v21, v129
	v_mov_b32_e32 v22, v129
	v_mov_b32_e32 v23, v129
	v_mov_b32_e32 v36, 0
	v_mov_b32_e32 v37, v129
	v_mov_b32_e32 v38, v129
	v_mov_b32_e32 v39, v129
	v_mov_b32_e32 v52, 0
	v_mov_b32_e32 v53, v129
	v_mov_b32_e32 v54, v129
	v_mov_b32_e32 v55, v129
	v_mov_b32_e32 v68, 0
	v_mov_b32_e32 v69, v129
	v_mov_b32_e32 v70, v129
	v_mov_b32_e32 v71, v129
	v_mov_b32_e32 v84, 0
	v_mov_b32_e32 v85, v129
	v_mov_b32_e32 v86, v129
	v_mov_b32_e32 v87, v129
	v_mov_b32_e32 v100, 0
	v_mov_b32_e32 v101, v129
	v_mov_b32_e32 v102, v129
	v_mov_b32_e32 v103, v129
	v_mov_b32_e32 v116, 0
	v_mov_b32_e32 v117, v129
	v_mov_b32_e32 v118, v129
	v_mov_b32_e32 v119, v129
	v_mov_b32_e32 v4, 0
	v_mov_b32_e32 v5, v129
	v_mov_b32_e32 v6, v129
	v_mov_b32_e32 v7, v129
	v_mov_b32_e32 v24, 0
	v_mov_b32_e32 v25, v129
	v_mov_b32_e32 v26, v129
	v_mov_b32_e32 v27, v129
	v_mov_b32_e32 v40, 0
	v_mov_b32_e32 v41, v129
	v_mov_b32_e32 v42, v129
	v_mov_b32_e32 v43, v129
	v_mov_b32_e32 v56, 0
	v_mov_b32_e32 v57, v129
	v_mov_b32_e32 v58, v129
	v_mov_b32_e32 v59, v129
	v_mov_b32_e32 v72, 0
	v_mov_b32_e32 v73, v129
	v_mov_b32_e32 v74, v129
	v_mov_b32_e32 v75, v129
	v_mov_b32_e32 v88, 0
	v_mov_b32_e32 v89, v129
	v_mov_b32_e32 v90, v129
	v_mov_b32_e32 v91, v129
	v_mov_b32_e32 v104, 0
	v_mov_b32_e32 v105, v129
	v_mov_b32_e32 v106, v129
	v_mov_b32_e32 v107, v129
	v_mov_b32_e32 v120, 0
	v_mov_b32_e32 v121, v129
	v_mov_b32_e32 v122, v129
	v_mov_b32_e32 v123, v129
	v_mov_b32_e32 v16, 0
	v_mov_b32_e32 v17, v129
	v_mov_b32_e32 v18, v129
	v_mov_b32_e32 v19, v129
	v_mov_b32_e32 v32, 0
	v_mov_b32_e32 v33, v129
	v_mov_b32_e32 v34, v129
	v_mov_b32_e32 v35, v129
	v_mov_b32_e32 v48, 0
	v_mov_b32_e32 v49, v129
	v_mov_b32_e32 v50, v129
	v_mov_b32_e32 v51, v129
	v_mov_b32_e32 v64, 0
	v_mov_b32_e32 v65, v129
	v_mov_b32_e32 v66, v129
	v_mov_b32_e32 v67, v129
	v_mov_b32_e32 v80, 0
	v_mov_b32_e32 v81, v129
	v_mov_b32_e32 v82, v129
	v_mov_b32_e32 v83, v129
	v_mov_b32_e32 v96, 0
	v_mov_b32_e32 v97, v129
	v_mov_b32_e32 v98, v129
	v_mov_b32_e32 v99, v129
	v_mov_b32_e32 v112, 0
	v_mov_b32_e32 v113, v129
	v_mov_b32_e32 v114, v129
	v_mov_b32_e32 v115, v129
	v_mov_b32_e32 v124, 0
	v_mov_b32_e32 v125, v129
	v_mov_b32_e32 v126, v129
	v_mov_b32_e32 v127, v129
	s_add_i32 s8, s66, s33
	s_cmp_lt_u32 s8, 16
	s_cselect_b32 s9, 0, -16
	s_add_i32 s8, s8, s9
	s_and_b32 s9, s11, 0x10000
	v_add_u32_e32 v158, s9, v128
	s_ashr_i32 s9, s8, 31
	s_lshl_b64 s[8:9], s[8:9], 7
	v_readfirstlane_b32 s40, v158
	v_add_u32_e32 v159, 0x2000, v158
	v_lshl_add_u64 v[156:157], v[132:133], 0, s[8:9]
	s_mov_b32 m0, s40
	v_readfirstlane_b32 s40, v159
	v_add_u32_e32 v159, 0x4000, v158
	global_load_lds_dwordx4 v[156:157], off
	v_lshl_add_u64 v[156:157], v[136:137], 0, s[8:9]
	s_mov_b32 m0, s40
	v_readfirstlane_b32 s40, v159
	v_add_u32_e32 v159, 0x6000, v158
	global_load_lds_dwordx4 v[156:157], off
	v_lshl_add_u64 v[156:157], v[138:139], 0, s[8:9]
	s_mov_b32 m0, s40
	v_readfirstlane_b32 s40, v159
	v_add_u32_e32 v159, 0x8000, v158
	global_load_lds_dwordx4 v[156:157], off
	v_lshl_add_u64 v[156:157], v[140:141], 0, s[8:9]
	s_mov_b32 m0, s40
	v_readfirstlane_b32 s40, v159
	v_add_u32_e32 v159, 0xa000, v158
	global_load_lds_dwordx4 v[156:157], off
	v_lshl_add_u64 v[156:157], v[134:135], 0, s[8:9]
	s_mov_b32 m0, s40
	v_readfirstlane_b32 s40, v159
	v_add_u32_e32 v159, 0xc000, v158
	global_load_lds_dwordx4 v[156:157], off
	v_lshl_add_u64 v[156:157], v[142:143], 0, s[8:9]
	s_mov_b32 m0, s40
	v_readfirstlane_b32 s40, v159
	global_load_lds_dwordx4 v[156:157], off
	v_lshl_add_u64 v[156:157], v[144:145], 0, s[8:9]
	s_mov_b32 m0, s40
	v_add_u32_e32 v158, 0xe000, v158
	global_load_lds_dwordx4 v[156:157], off
	v_lshl_add_u64 v[156:157], v[146:147], 0, s[8:9]
	v_readfirstlane_b32 s8, v158
	s_mov_b32 m0, s8
	s_nop 0
	global_load_lds_dwordx4 v[156:157], off
	s_waitcnt vmcnt(8) lgkmcnt(0)
	s_barrier
	s_branch .LBB0_353

; template <int PIPE>
; DI void gemm_loop_g(const u16* __restrict__ Xp, long ldx_l, long ldx_i, long kxs,
;                     const u16* __restrict__ Yp, long ldy_l, long ldy_i, long kys, int K,
;                     f32x4 (&acc)[4][8], unsigned char* smem) {
;   const int t = tid_opaque(), l = t & 63, w = __builtin_amdgcn_readfirstlane(t >> 6), wx = w >> 1, wy = w & 1;
;   const int lrow = t >> 3, gch = (t & 7) ^ ((t >> 4) & 7);
;   const u16* xs = Xp + (long)lrow * ldx_l + gch * 8;
;   const u16* ys = Yp + (long)lrow * ldy_l + gch * 8;
; template <int MODE>
; DI void gemm_phase(const Params& p, const GP& g, unsigned char* smem) {
;     ...
;     int bsel = 0;
;     {
;       const int ml = e / g.ntn;
;       nt = e - ml * g.ntn;
;       mt = xcd + 8 * ml;
;     }
;     if (MODE == M_SEQ) { bsel = mt >> 4; mt &= 15; Wb = g.W + (long)bsel * 1024 * 8192; }
;     const int m0 = mt * 256, n0 = nt * 256;
;     f32x4 acc[4][8];
;     zero_acc(acc);
;     int transposed = 0;
;     if (MODE == M_FN_IN) transposed = nt < 8;
;     if (MODE == M_NA_IN) transposed = (nt >= 8 && nt < 12);
;     if (MODE == M_MLA_UKV) transposed = nt >= 4;
;     if (MODE == M_HG_IN) transposed = nt >= 12;
;     if (MODE == M_PLE) {
;       const u16* pb = (const u16*)g.d1;
;       gemm_loop(g.W2 + (long)n0 * 256, 256, pb + (long)m0 * 256, 256, 256, acc, smem);
;       u16* xb = (u16*)g.d0;
;       EPI_STD_BEGIN
;         *(u32x2*)(xb + (long)m * 1024 + n4) = pack4(v[0], v[1], v[2], v[3]);
;       EPI_END
;       zero_acc(acc);
;     }
;     if (MODE == M_FFT1) {
;       const int bt = mt >> 8, cg = mt & 255;
;       gemm_loop_g<0>(Ab + ((long)(bt * 1024 + cg * 4)) * 8192, 64, 8192, 4096, Wb, 128, 64 * 128, 64, 128, acc, smem);
;     } else if (MODE == M_FFT3) {
;       const int bt = mt >> 8, v = (mt >> 2) & 63, cq = mt & 3;
;       gemm_loop(Ab + (((long)(bt * 64 + v)) * 1024 + cq * 256) * 128, 128, Wb, 128, 128, acc, smem);
;     } else if (MODE == M_FN_IN && transposed) {
;       const u16* Ap = Ab + ((long)(mt >> 4) * 4096 + (mt & 15) * 4) * g.lda;
;       gemm_loop_g<1>(Ap, 64 * g.lda, g.lda, 64, Wb + (long)n0 * g.K, g.K, 64L * g.K, 64, g.K, acc, smem);
;     } else {
;       const u16* Ap = Ab + (long)m0 * g.lda; const u16* Wp = Wb + (long)n0 * g.K;
;       if (transposed) gemm_loop(Ap, g.lda, Wp, g.K, g.K, acc, smem);
;       else gemm_loop(Wp, g.K, Ap, g.lda, g.K, acc, smem);
.LBB0_390:
	s_mul_hi_u32 s6, s62, 0xaaaaaaab
	s_lshr_b32 s6, s6, 2
	s_mul_i32 s10, s6, -6
	s_add_i32 s10, s10, s62
	s_lshl_b32 s6, s6, 11
	s_or_b32 s7, s6, s57
	s_lshl_b32 s6, s10, 8
	s_mul_i32 s8, s10, 0x30000
	v_mov_b32_e32 v2, v182
	s_mul_hi_i32 s9, s6, 0x300
	s_waitcnt lgkmcnt(0)
	s_add_u32 s8, s14, s8
	s_addc_u32 s9, s15, s9
	v_lshrrev_b32_e32 v4, 4, v2
	s_mul_i32 s33, s7, 0x300
	v_xor_b32_e32 v5, v4, v2
	s_mul_hi_i32 s11, s7, 0x300
	s_add_u32 s40, s38, s33
	v_ashrrev_i32_e32 v3, 3, v2
	v_mov_b64_e32 v[0:1], s[8:9]
	v_lshlrev_b32_e32 v5, 4, v5
	s_addc_u32 s41, s39, s11
	v_mad_i64_i32 v[0:1], s[8:9], v3, s59, v[0:1]
	v_and_b32_e32 v130, 0x70, v5
	v_lshl_add_u64 v[132:133], v[0:1], 0, v[130:131]
	v_mov_b64_e32 v[0:1], s[40:41]
	v_mad_i64_i32 v[0:1], s[8:9], v3, s59, v[0:1]
	v_lshl_add_u64 v[134:135], v[0:1], 0, v[130:131]
	v_lshlrev_b32_e32 v130, 4, v2
	v_add_u32_e32 v3, 0x2000, v130
	v_readfirstlane_b32 s8, v130
	v_lshl_add_u64 v[0:1], v[132:133], 0, s[12:13]
	s_mov_b32 m0, s8
	v_lshl_add_u64 v[136:137], v[132:133], 0, s[26:27]
	v_readfirstlane_b32 s8, v3
	v_add_u32_e32 v3, 0x4000, v130
	s_barrier
; #define LDS_PTR(p) ((__attribute__((address_space(3))) unsigned*)(p))
; template <int PIPE>
; DI void gemm_loop_g(const u16* __restrict__ Xp, long ldx_l, long ldx_i, long kxs,
;                     const u16* __restrict__ Yp, long ldy_l, long ldy_i, long kys, int K,
;                     f32x4 (&acc)[4][8], unsigned char* smem) {
;     ...
;   auto issue = [&](int kt0, int stage) {
;     int kt = kt0 + rot; if (kt >= nk) kt -= nk;
;     unsigned char* sb = smem + stage * 65536 + t * 16;
; #pragma unroll
;     for (int i = 0; i < 4; ++i)
;       __builtin_amdgcn_global_load_lds((const unsigned*)(xs + i * ldx_i + kt * kxs), LDS_PTR(sb + i * 8192), 16, 0, 0);
; #pragma unroll
;     for (int i = 0; i < 4; ++i)
;       __builtin_amdgcn_global_load_lds((const unsigned*)(ys + i * ldy_i + kt * kys), LDS_PTR(sb + 32768 + i * 8192), 16, 0, 0);
;   };
;   __syncthreads();
;   issue(0, 0);
;   asm volatile("s_waitcnt vmcnt(0)" ::: "memory");
;   __syncthreads();
; DI void zero_acc(f32x4 (&acc)[4][8]) {
; #pragma unroll
;   for (int i = 0; i < 4; ++i)
; #pragma unroll
;     for (int j = 0; j < 8; ++j) acc[i][j] = f32x4{0.f, 0.f, 0.f, 0.f};
	global_load_lds_dwordx4 v[0:1], off
	v_lshl_add_u64 v[0:1], v[136:137], 0, s[12:13]
	s_mov_b32 m0, s8
	v_lshl_add_u64 v[138:139], v[132:133], 0, s[28:29]
	v_readfirstlane_b32 s8, v3
	v_add_u32_e32 v3, 0x6000, v130
	global_load_lds_dwordx4 v[0:1], off
	v_lshl_add_u64 v[0:1], v[138:139], 0, s[12:13]
	s_mov_b32 m0, s8
	v_lshl_add_u64 v[140:141], v[132:133], 0, s[30:31]
	v_readfirstlane_b32 s8, v3
	v_add_u32_e32 v3, 0x8000, v130
	global_load_lds_dwordx4 v[0:1], off
	v_lshl_add_u64 v[0:1], v[140:141], 0, s[12:13]
	s_mov_b32 m0, s8
	v_readfirstlane_b32 s8, v3
	v_add_u32_e32 v3, 0xa000, v130
	global_load_lds_dwordx4 v[0:1], off
	v_lshl_add_u64 v[0:1], v[134:135], 0, s[12:13]
	s_mov_b32 m0, s8
	v_lshl_add_u64 v[142:143], v[134:135], 0, s[26:27]
	v_readfirstlane_b32 s8, v3
	v_add_u32_e32 v3, 0xc000, v130
	global_load_lds_dwordx4 v[0:1], off
	v_lshl_add_u64 v[0:1], v[142:143], 0, s[12:13]
	s_mov_b32 m0, s8
	v_lshl_add_u64 v[144:145], v[134:135], 0, s[28:29]
	v_readfirstlane_b32 s8, v3
	v_add_u32_e32 v3, 0xe000, v130
	global_load_lds_dwordx4 v[0:1], off
	v_lshl_add_u64 v[0:1], v[144:145], 0, s[12:13]
	s_mov_b32 m0, s8
	v_lshl_add_u64 v[146:147], v[134:135], 0, s[30:31]
	v_readfirstlane_b32 s8, v3
	global_load_lds_dwordx4 v[0:1], off
	v_lshl_add_u64 v[0:1], v[146:147], 0, s[12:13]
	s_mov_b32 m0, s8
	v_readfirstlane_b32 s33, v2
	global_load_lds_dwordx4 v[0:1], off
	v_bfe_u32 v0, v2, 4, 2
	v_bfe_u32 v1, v2, 1, 3
	v_lshlrev_b32_e32 v2, 7, v2
	s_nop 0
	s_lshl_b32 s8, s33, 8
	v_bitop3_b32 v0, v0, v1, 4 bitop3:0x36
	v_and_b32_e32 v2, 0x780, v2
	s_and_b32 s11, s8, 0x4000
	s_lshl_b32 s8, s33, 6
	v_lshl_or_b32 v151, v0, 4, v2
	v_bitop3_b32 v0, v4, v1, 3 bitop3:0x6c
	s_and_b32 s33, s8, 0xffffe000
	v_lshl_or_b32 v152, v0, 4, v2
	s_mov_b32 s48, 0x10000
	s_mov_b32 s49, 0
	v_mov_b32_e32 v8, 0
	v_mov_b32_e32 v9, v131
	v_mov_b32_e32 v10, v131
	v_mov_b32_e32 v11, v131
	v_mov_b32_e32 v12, 0
	v_mov_b32_e32 v13, v131
	v_mov_b32_e32 v14, v131
	v_mov_b32_e32 v15, v131
	v_mov_b32_e32 v28, 0
	v_mov_b32_e32 v29, v131
	v_mov_b32_e32 v30, v131
	v_mov_b32_e32 v31, v131
	v_mov_b32_e32 v44, 0
	v_mov_b32_e32 v45, v131
	v_mov_b32_e32 v46, v131
	v_mov_b32_e32 v47, v131
	v_mov_b32_e32 v60, 0
	v_mov_b32_e32 v61, v131
	v_mov_b32_e32 v62, v131
	v_mov_b32_e32 v63, v131
	v_mov_b32_e32 v76, 0
	v_mov_b32_e32 v77, v131
	v_mov_b32_e32 v78, v131
	v_mov_b32_e32 v79, v131
	v_mov_b32_e32 v92, 0
	v_mov_b32_e32 v93, v131
	v_mov_b32_e32 v94, v131
	v_mov_b32_e32 v95, v131
	v_mov_b32_e32 v108, 0
	v_mov_b32_e32 v109, v131
	v_mov_b32_e32 v110, v131
	v_mov_b32_e32 v111, v131
	v_mov_b32_e32 v4, 0
	v_mov_b32_e32 v5, v131
	v_mov_b32_e32 v6, v131
	v_mov_b32_e32 v7, v131
	v_mov_b32_e32 v24, 0
	v_mov_b32_e32 v25, v131
	v_mov_b32_e32 v26, v131
	v_mov_b32_e32 v27, v131
	v_mov_b32_e32 v40, 0
	v_mov_b32_e32 v41, v131
	v_mov_b32_e32 v42, v131
	v_mov_b32_e32 v43, v131
	v_mov_b32_e32 v56, 0
	v_mov_b32_e32 v57, v131
	v_mov_b32_e32 v58, v131
	v_mov_b32_e32 v59, v131
	v_mov_b32_e32 v72, 0
	v_mov_b32_e32 v73, v131
	v_mov_b32_e32 v74, v131
	v_mov_b32_e32 v75, v131
	v_mov_b32_e32 v88, 0
	v_mov_b32_e32 v89, v131
	v_mov_b32_e32 v90, v131
	v_mov_b32_e32 v91, v131
	v_mov_b32_e32 v104, 0
	v_mov_b32_e32 v105, v131
	v_mov_b32_e32 v106, v131
	v_mov_b32_e32 v107, v131
	v_mov_b32_e32 v120, 0
	v_mov_b32_e32 v121, v131
	v_mov_b32_e32 v122, v131
	v_mov_b32_e32 v123, v131
	v_mov_b32_e32 v0, 0
	v_mov_b32_e32 v1, v131
	v_mov_b32_e32 v2, v131
	v_mov_b32_e32 v3, v131
	v_mov_b32_e32 v20, 0
	v_mov_b32_e32 v21, v131
	v_mov_b32_e32 v22, v131
	v_mov_b32_e32 v23, v131
	v_mov_b32_e32 v36, 0
	v_mov_b32_e32 v37, v131
	v_mov_b32_e32 v38, v131
	v_mov_b32_e32 v39, v131
	v_mov_b32_e32 v52, 0
	v_mov_b32_e32 v53, v131
	v_mov_b32_e32 v54, v131
	v_mov_b32_e32 v55, v131
	v_mov_b32_e32 v68, 0
	v_mov_b32_e32 v69, v131
	v_mov_b32_e32 v70, v131
	v_mov_b32_e32 v71, v131
	v_mov_b32_e32 v84, 0
	v_mov_b32_e32 v85, v131
	v_mov_b32_e32 v86, v131
	v_mov_b32_e32 v87, v131
	v_mov_b32_e32 v100, 0
	v_mov_b32_e32 v101, v131
	v_mov_b32_e32 v102, v131
	v_mov_b32_e32 v103, v131
	v_mov_b32_e32 v116, 0
	v_mov_b32_e32 v117, v131
	v_mov_b32_e32 v118, v131
	v_mov_b32_e32 v119, v131
	v_mov_b32_e32 v16, 0
	v_mov_b32_e32 v17, v131
	v_mov_b32_e32 v18, v131
	v_mov_b32_e32 v19, v131
	v_mov_b32_e32 v32, 0
	v_mov_b32_e32 v33, v131
	v_mov_b32_e32 v34, v131
	v_mov_b32_e32 v35, v131
	v_mov_b32_e32 v48, 0
	v_mov_b32_e32 v49, v131
	v_mov_b32_e32 v50, v131
	v_mov_b32_e32 v51, v131
	v_mov_b32_e32 v64, 0
	v_mov_b32_e32 v65, v131
	v_mov_b32_e32 v66, v131
	v_mov_b32_e32 v67, v131
	v_mov_b32_e32 v80, 0
	v_mov_b32_e32 v81, v131
	v_mov_b32_e32 v82, v131
	v_mov_b32_e32 v83, v131
	v_mov_b32_e32 v96, 0
	v_mov_b32_e32 v97, v131
	v_mov_b32_e32 v98, v131
	v_mov_b32_e32 v99, v131
	v_mov_b32_e32 v112, 0
	v_mov_b32_e32 v113, v131
	v_mov_b32_e32 v114, v131
	v_mov_b32_e32 v115, v131
	v_mov_b32_e32 v124, 0
	v_mov_b32_e32 v125, v131
	v_mov_b32_e32 v126, v131
	v_mov_b32_e32 v127, v131
	s_add_i32 s8, s58, s49
	s_cmp_lt_u32 s8, 6
	s_cselect_b32 s9, 0, -6
	s_add_i32 s8, s8, s9
	s_and_b32 s9, s48, 0x10000
	v_add_u32_e32 v153, s9, v130
	s_ashr_i32 s9, s8, 31
	s_lshl_b64 s[8:9], s[8:9], 7
	v_readfirstlane_b32 s40, v153
	v_add_u32_e32 v156, 0x2000, v153
	v_lshl_add_u64 v[154:155], v[132:133], 0, s[8:9]
	s_mov_b32 m0, s40
	v_readfirstlane_b32 s40, v156
	v_add_u32_e32 v156, 0x4000, v153
	global_load_lds_dwordx4 v[154:155], off
	v_lshl_add_u64 v[154:155], v[136:137], 0, s[8:9]
	s_mov_b32 m0, s40
	v_readfirstlane_b32 s40, v156
	v_add_u32_e32 v156, 0x6000, v153
	global_load_lds_dwordx4 v[154:155], off
	v_lshl_add_u64 v[154:155], v[138:139], 0, s[8:9]
	s_mov_b32 m0, s40
	v_readfirstlane_b32 s40, v156
	v_add_u32_e32 v156, 0x8000, v153
	global_load_lds_dwordx4 v[154:155], off
	v_lshl_add_u64 v[154:155], v[140:141], 0, s[8:9]
	s_mov_b32 m0, s40
	v_readfirstlane_b32 s40, v156
	v_add_u32_e32 v156, 0xa000, v153
	global_load_lds_dwordx4 v[154:155], off
	v_lshl_add_u64 v[154:155], v[134:135], 0, s[8:9]
	s_mov_b32 m0, s40
	v_readfirstlane_b32 s40, v156
	v_add_u32_e32 v156, 0xc000, v153
	global_load_lds_dwordx4 v[154:155], off
	v_lshl_add_u64 v[154:155], v[142:143], 0, s[8:9]
	s_mov_b32 m0, s40
	v_readfirstlane_b32 s40, v156
	global_load_lds_dwordx4 v[154:155], off
	v_lshl_add_u64 v[154:155], v[144:145], 0, s[8:9]
	s_mov_b32 m0, s40
	v_add_u32_e32 v153, 0xe000, v153
	global_load_lds_dwordx4 v[154:155], off
	v_lshl_add_u64 v[154:155], v[146:147], 0, s[8:9]
	v_readfirstlane_b32 s8, v153
	s_mov_b32 m0, s8
	s_nop 0
	global_load_lds_dwordx4 v[154:155], off
	s_waitcnt vmcnt(8) lgkmcnt(0)
	s_barrier
	s_branch .LBB0_391

; template <int MODE>
; DI void gemm_phase(const Params& p, const GP& g, unsigned char* smem) {
;     ...
;       const int ml = e / g.ntn;
;       nt = e - ml * g.ntn;
;       mt = xcd + 8 * ml;
;     }
;     if (MODE == M_SEQ) { bsel = mt >> 4; mt &= 15; Wb = g.W + (long)bsel * 1024 * 8192; }
;     const int m0 = mt * 256, n0 = nt * 256;
;     f32x4 acc[4][8];
;     zero_acc(acc);
;     int transposed = 0;
;     if (MODE == M_FN_IN) transposed = nt < 8;
;     if (MODE == M_NA_IN) transposed = (nt >= 8 && nt < 12);
;     if (MODE == M_MLA_UKV) transposed = nt >= 4;
;     ...
;       const u16* Ap = Ab + (long)m0 * g.lda; const u16* Wp = Wb + (long)n0 * g.K;
;       if (transposed) gemm_loop(Ap, g.lda, Wp, g.K, g.K, acc, smem);
;       else gemm_loop(Wp, g.K, Ap, g.lda, g.K, acc, smem);
.LBB0_401:
	s_lshl_b32 s6, s78, 8
	s_and_b32 s6, s6, 0xfffff800
	s_and_b32 s79, s78, 7
	s_or_b32 s12, s6, s67
	s_cmp_lt_u32 s79, 4
	s_cselect_b64 s[14:15], -1, 0
	s_ashr_i32 s13, s12, 31
	s_lshl_b64 s[6:7], s[12:13], 9
	s_add_u32 s68, s63, s6
	s_addc_u32 s69, s65, s7
	s_lshl_b32 s6, s79, 17
	s_waitcnt lgkmcnt(0)
	s_add_u32 s16, s28, s6
	s_addc_u32 s17, s29, 0
	s_mov_b64 s[70:71], -1
	s_and_b64 vcc, exec, s[14:15]
	s_cbranch_vccz .LBB0_407
	v_mov_b32_e32 v4, v182
	s_nop 0
	v_ashrrev_i32_e32 v0, 3, v4
	v_lshrrev_b32_e32 v5, 4, v4
	v_xor_b32_e32 v6, v5, v4
	v_ashrrev_i32_e32 v1, 31, v0
	v_lshlrev_b64 v[0:1], 9, v[0:1]
	v_lshlrev_b32_e32 v6, 4, v6
	v_lshl_add_u64 v[2:3], s[16:17], 0, v[0:1]
	v_and_b32_e32 v128, 0x70, v6
	v_lshl_add_u64 v[0:1], s[68:69], 0, v[0:1]
	v_lshl_add_u64 v[130:131], v[2:3], 0, v[128:129]
	v_lshl_add_u64 v[132:133], v[0:1], 0, v[128:129]
	v_lshlrev_b32_e32 v128, 4, v4
	v_add_u32_e32 v2, 0x2000, v128
	v_readfirstlane_b32 s6, v128
	v_lshl_add_u64 v[0:1], v[130:131], 0, s[54:55]
	s_mov_b32 m0, s6
	v_lshl_add_u64 v[134:135], v[130:131], 0, s[56:57]
	v_readfirstlane_b32 s6, v2
	v_add_u32_e32 v2, 0x4000, v128
	s_barrier
; #define LDS_PTR(p) ((__attribute__((address_space(3))) unsigned*)(p))
; template <int PIPE>
; DI void gemm_loop_g(const u16* __restrict__ Xp, long ldx_l, long ldx_i, long kxs,
;                     const u16* __restrict__ Yp, long ldy_l, long ldy_i, long kys, int K,
;                     f32x4 (&acc)[4][8], unsigned char* smem) {
;     ...
;   auto issue = [&](int kt0, int stage) {
;     int kt = kt0 + rot; if (kt >= nk) kt -= nk;
;     unsigned char* sb = smem + stage * 65536 + t * 16;
; #pragma unroll
;     for (int i = 0; i < 4; ++i)
;       __builtin_amdgcn_global_load_lds((const unsigned*)(xs + i * ldx_i + kt * kxs), LDS_PTR(sb + i * 8192), 16, 0, 0);
; #pragma unroll
;     for (int i = 0; i < 4; ++i)
;       __builtin_amdgcn_global_load_lds((const unsigned*)(ys + i * ldy_i + kt * kys), LDS_PTR(sb + 32768 + i * 8192), 16, 0, 0);
;   };
;   __syncthreads();
;   issue(0, 0);
;   asm volatile("s_waitcnt vmcnt(0)" ::: "memory");
;   __syncthreads();
; DI void zero_acc(f32x4 (&acc)[4][8]) {
; #pragma unroll
;   for (int i = 0; i < 4; ++i)
; #pragma unroll
;     for (int j = 0; j < 8; ++j) acc[i][j] = f32x4{0.f, 0.f, 0.f, 0.f};
	global_load_lds_dwordx4 v[0:1], off
	v_lshl_add_u64 v[0:1], v[134:135], 0, s[54:55]
	s_mov_b32 m0, s6
	v_lshl_add_u64 v[136:137], v[130:131], 0, s[58:59]
	v_readfirstlane_b32 s6, v2
	v_add_u32_e32 v2, 0x6000, v128
	global_load_lds_dwordx4 v[0:1], off
	v_lshl_add_u64 v[0:1], v[136:137], 0, s[54:55]
	s_mov_b32 m0, s6
	v_lshl_add_u64 v[138:139], v[130:131], 0, s[60:61]
	v_readfirstlane_b32 s6, v2
	v_add_u32_e32 v2, 0x8000, v128
	global_load_lds_dwordx4 v[0:1], off
	v_lshl_add_u64 v[0:1], v[138:139], 0, s[54:55]
	s_mov_b32 m0, s6
	v_readfirstlane_b32 s6, v2
	v_add_u32_e32 v2, 0xa000, v128
	global_load_lds_dwordx4 v[0:1], off
	v_lshl_add_u64 v[0:1], v[132:133], 0, s[54:55]
	s_mov_b32 m0, s6
	v_lshl_add_u64 v[140:141], v[132:133], 0, s[56:57]
	v_readfirstlane_b32 s6, v2
	v_add_u32_e32 v2, 0xc000, v128
	global_load_lds_dwordx4 v[0:1], off
	v_lshl_add_u64 v[0:1], v[140:141], 0, s[54:55]
	s_mov_b32 m0, s6
	v_lshl_add_u64 v[142:143], v[132:133], 0, s[58:59]
	v_readfirstlane_b32 s6, v2
	v_add_u32_e32 v2, 0xe000, v128
	global_load_lds_dwordx4 v[0:1], off
	v_lshl_add_u64 v[0:1], v[142:143], 0, s[54:55]
	s_mov_b32 m0, s6
	v_lshl_add_u64 v[144:145], v[132:133], 0, s[60:61]
	v_readfirstlane_b32 s6, v2
	global_load_lds_dwordx4 v[0:1], off
	v_lshl_add_u64 v[0:1], v[144:145], 0, s[54:55]
	s_mov_b32 m0, s6
	v_lshlrev_b32_e32 v2, 7, v4
	global_load_lds_dwordx4 v[0:1], off
	v_bfe_u32 v0, v4, 4, 2
	v_bfe_u32 v1, v4, 1, 3
	v_readfirstlane_b32 s7, v4
	s_nop 0
	v_bitop3_b32 v0, v0, v1, 4 bitop3:0x36
	v_and_b32_e32 v2, 0x780, v2
	s_lshl_b32 s6, s7, 8
	s_lshl_b32 s7, s7, 6
	v_lshl_or_b32 v152, v0, 4, v2
	v_bitop3_b32 v0, v5, v1, 3 bitop3:0x6c
	v_mov_b32_e32 v8, 0
	s_and_b32 s6, s6, 0x4000
	s_and_b32 s7, s7, 0xffffe000
	v_lshl_or_b32 v153, v0, 4, v2
	s_mov_b32 s10, 0
	s_mov_b32 s11, 0x10000
	v_mov_b32_e32 v9, v8
	v_mov_b32_e32 v10, v8
	v_mov_b32_e32 v11, v8
	v_mov_b32_e32 v12, v8
	v_mov_b32_e32 v13, v8
	v_mov_b32_e32 v14, v8
	v_mov_b32_e32 v15, v8
	v_mov_b32_e32 v28, v8
	v_mov_b32_e32 v29, v8
	v_mov_b32_e32 v30, v8
	v_mov_b32_e32 v31, v8
	v_mov_b32_e32 v44, v8
	v_mov_b32_e32 v45, v8
	v_mov_b32_e32 v46, v8
	v_mov_b32_e32 v47, v8
	v_mov_b32_e32 v60, v8
	v_mov_b32_e32 v61, v8
	v_mov_b32_e32 v62, v8
	v_mov_b32_e32 v63, v8
	v_mov_b32_e32 v76, v8
	v_mov_b32_e32 v77, v8
	v_mov_b32_e32 v78, v8
	v_mov_b32_e32 v79, v8
	v_mov_b32_e32 v92, v8
	v_mov_b32_e32 v93, v8
	v_mov_b32_e32 v94, v8
	v_mov_b32_e32 v95, v8
	v_mov_b32_e32 v108, v8
	v_mov_b32_e32 v109, v8
	v_mov_b32_e32 v110, v8
	v_mov_b32_e32 v111, v8
	v_mov_b32_e32 v0, v8
	v_mov_b32_e32 v1, v8
	v_mov_b32_e32 v2, v8
	v_mov_b32_e32 v3, v8
	v_mov_b32_e32 v20, v8
	v_mov_b32_e32 v21, v8
	v_mov_b32_e32 v22, v8
	v_mov_b32_e32 v23, v8
	v_mov_b32_e32 v36, v8
	v_mov_b32_e32 v37, v8
	v_mov_b32_e32 v38, v8
	v_mov_b32_e32 v39, v8
	v_mov_b32_e32 v52, v8
	v_mov_b32_e32 v53, v8
	v_mov_b32_e32 v54, v8
	v_mov_b32_e32 v55, v8
	v_mov_b32_e32 v68, v8
	v_mov_b32_e32 v69, v8
	v_mov_b32_e32 v70, v8
	v_mov_b32_e32 v71, v8
	v_mov_b32_e32 v84, v8
	v_mov_b32_e32 v85, v8
	v_mov_b32_e32 v86, v8
	v_mov_b32_e32 v87, v8
	v_mov_b32_e32 v100, v8
	v_mov_b32_e32 v101, v8
	v_mov_b32_e32 v102, v8
	v_mov_b32_e32 v103, v8
	v_mov_b32_e32 v116, v8
	v_mov_b32_e32 v117, v8
	v_mov_b32_e32 v118, v8
	v_mov_b32_e32 v119, v8
	v_mov_b32_e32 v4, v8
	v_mov_b32_e32 v5, v8
	v_mov_b32_e32 v6, v8
	v_mov_b32_e32 v7, v8
	v_mov_b32_e32 v24, v8
	v_mov_b32_e32 v25, v8
	v_mov_b32_e32 v26, v8
	v_mov_b32_e32 v27, v8
	v_mov_b32_e32 v40, v8
	v_mov_b32_e32 v41, v8
	v_mov_b32_e32 v42, v8
	v_mov_b32_e32 v43, v8
	v_mov_b32_e32 v56, v8
	v_mov_b32_e32 v57, v8
	v_mov_b32_e32 v58, v8
	v_mov_b32_e32 v59, v8
	v_mov_b32_e32 v72, v8
	v_mov_b32_e32 v73, v8
	v_mov_b32_e32 v74, v8
	v_mov_b32_e32 v75, v8
	v_mov_b32_e32 v88, v8
	v_mov_b32_e32 v89, v8
	v_mov_b32_e32 v90, v8
	v_mov_b32_e32 v91, v8
	v_mov_b32_e32 v104, v8
	v_mov_b32_e32 v105, v8
	v_mov_b32_e32 v106, v8
	v_mov_b32_e32 v107, v8
	v_mov_b32_e32 v120, v8
	v_mov_b32_e32 v121, v8
	v_mov_b32_e32 v122, v8
	v_mov_b32_e32 v123, v8
	v_mov_b32_e32 v16, v8
	v_mov_b32_e32 v17, v8
	v_mov_b32_e32 v18, v8
	v_mov_b32_e32 v19, v8
	v_mov_b32_e32 v32, v8
	v_mov_b32_e32 v33, v8
	v_mov_b32_e32 v34, v8
	v_mov_b32_e32 v35, v8
	v_mov_b32_e32 v48, v8
	v_mov_b32_e32 v49, v8
	v_mov_b32_e32 v50, v8
	v_mov_b32_e32 v51, v8
	v_mov_b32_e32 v64, v8
	v_mov_b32_e32 v65, v8
	v_mov_b32_e32 v66, v8
	v_mov_b32_e32 v67, v8
	v_mov_b32_e32 v80, v8
	v_mov_b32_e32 v81, v8
	v_mov_b32_e32 v82, v8
	v_mov_b32_e32 v83, v8
	v_mov_b32_e32 v96, v8
	v_mov_b32_e32 v97, v8
	v_mov_b32_e32 v98, v8
	v_mov_b32_e32 v99, v8
	v_mov_b32_e32 v112, v8
	v_mov_b32_e32 v113, v8
	v_mov_b32_e32 v114, v8
	v_mov_b32_e32 v115, v8
	v_mov_b32_e32 v124, v8
	v_mov_b32_e32 v125, v8
	v_mov_b32_e32 v126, v8
	v_mov_b32_e32 v127, v8
	s_add_i32 s8, s73, s10
	s_cmp_lt_u32 s8, 4
	s_cselect_b32 s9, 0, -4
	s_add_i32 s8, s8, s9
	s_and_b32 s9, s11, 0x10000
	v_add_u32_e32 v156, s9, v128
	s_ashr_i32 s9, s8, 31
	s_lshl_b64 s[8:9], s[8:9], 7
	v_readfirstlane_b32 s13, v156
	v_add_u32_e32 v157, 0x2000, v156
	v_lshl_add_u64 v[154:155], v[130:131], 0, s[8:9]
	s_mov_b32 m0, s13
	v_readfirstlane_b32 s13, v157
	v_add_u32_e32 v157, 0x4000, v156
	global_load_lds_dwordx4 v[154:155], off
	v_lshl_add_u64 v[154:155], v[134:135], 0, s[8:9]
	s_mov_b32 m0, s13
	v_readfirstlane_b32 s13, v157
	v_add_u32_e32 v157, 0x6000, v156
	global_load_lds_dwordx4 v[154:155], off
	v_lshl_add_u64 v[154:155], v[136:137], 0, s[8:9]
	s_mov_b32 m0, s13
	v_readfirstlane_b32 s13, v157
	v_add_u32_e32 v157, 0x8000, v156
	global_load_lds_dwordx4 v[154:155], off
	v_lshl_add_u64 v[154:155], v[138:139], 0, s[8:9]
	s_mov_b32 m0, s13
	v_readfirstlane_b32 s13, v157
	v_add_u32_e32 v157, 0xa000, v156
	global_load_lds_dwordx4 v[154:155], off
	v_lshl_add_u64 v[154:155], v[132:133], 0, s[8:9]
	s_mov_b32 m0, s13
	v_readfirstlane_b32 s13, v157
	v_add_u32_e32 v157, 0xc000, v156
	global_load_lds_dwordx4 v[154:155], off
	v_lshl_add_u64 v[154:155], v[140:141], 0, s[8:9]
	s_mov_b32 m0, s13
	v_readfirstlane_b32 s13, v157
	global_load_lds_dwordx4 v[154:155], off
	v_lshl_add_u64 v[154:155], v[142:143], 0, s[8:9]
	s_mov_b32 m0, s13
	v_add_u32_e32 v156, 0xe000, v156
	global_load_lds_dwordx4 v[154:155], off
	v_lshl_add_u64 v[154:155], v[144:145], 0, s[8:9]
	v_readfirstlane_b32 s8, v156
	s_mov_b32 m0, s8
	s_nop 0
	global_load_lds_dwordx4 v[154:155], off
	s_waitcnt vmcnt(8) lgkmcnt(0)
	s_barrier
	s_branch .LBB0_403

; template <int MODE>
; DI void gemm_phase(const Params& p, const GP& g, unsigned char* smem) {
;     ...
;     if (MODE == M_NA_IN) transposed = (nt >= 8 && nt < 12);
;     if (MODE == M_MLA_UKV) transposed = nt >= 4;
;     ...
;       const u16* Ap = Ab + (long)m0 * g.lda; const u16* Wp = Wb + (long)n0 * g.K;
;       if (transposed) gemm_loop(Ap, g.lda, Wp, g.K, g.K, acc, smem);
.LBB0_407:
	s_and_b64 vcc, exec, s[70:71]
	s_cbranch_vccz .LBB0_412
	s_nop 1
	v_mov_b32_e32 v4, v182
	s_nop 0
	v_ashrrev_i32_e32 v0, 3, v4
	v_lshrrev_b32_e32 v5, 4, v4
	v_xor_b32_e32 v6, v5, v4
	v_ashrrev_i32_e32 v1, 31, v0
	v_lshlrev_b64 v[0:1], 9, v[0:1]
	v_lshlrev_b32_e32 v6, 4, v6
	v_lshl_add_u64 v[2:3], s[68:69], 0, v[0:1]
	v_and_b32_e32 v128, 0x70, v6
	v_lshl_add_u64 v[0:1], s[16:17], 0, v[0:1]
	v_lshl_add_u64 v[130:131], v[2:3], 0, v[128:129]
	v_lshl_add_u64 v[132:133], v[0:1], 0, v[128:129]
	v_lshlrev_b32_e32 v128, 4, v4
	v_add_u32_e32 v2, 0x2000, v128
	v_readfirstlane_b32 s6, v128
	v_lshl_add_u64 v[0:1], v[130:131], 0, s[54:55]
	s_mov_b32 m0, s6
	v_lshl_add_u64 v[134:135], v[130:131], 0, s[56:57]
	v_readfirstlane_b32 s6, v2
	v_add_u32_e32 v2, 0x4000, v128
	s_barrier
; #define LDS_PTR(p) ((__attribute__((address_space(3))) unsigned*)(p))
; template <int PIPE>
; DI void gemm_loop_g(const u16* __restrict__ Xp, long ldx_l, long ldx_i, long kxs,
;                     const u16* __restrict__ Yp, long ldy_l, long ldy_i, long kys, int K,
;                     f32x4 (&acc)[4][8], unsigned char* smem) {
;     ...
;   auto issue = [&](int kt0, int stage) {
;     int kt = kt0 + rot; if (kt >= nk) kt -= nk;
;     unsigned char* sb = smem + stage * 65536 + t * 16;
; #pragma unroll
;     for (int i = 0; i < 4; ++i)
;       __builtin_amdgcn_global_load_lds((const unsigned*)(xs + i * ldx_i + kt * kxs), LDS_PTR(sb + i * 8192), 16, 0, 0);
; #pragma unroll
;     for (int i = 0; i < 4; ++i)
;       __builtin_amdgcn_global_load_lds((const unsigned*)(ys + i * ldy_i + kt * kys), LDS_PTR(sb + 32768 + i * 8192), 16, 0, 0);
;   };
;   __syncthreads();
;   issue(0, 0);
;   asm volatile("s_waitcnt vmcnt(0)" ::: "memory");
;   __syncthreads();
; DI void zero_acc(f32x4 (&acc)[4][8]) {
; #pragma unroll
;   for (int i = 0; i < 4; ++i)
; #pragma unroll
;     for (int j = 0; j < 8; ++j) acc[i][j] = f32x4{0.f, 0.f, 0.f, 0.f};
	global_load_lds_dwordx4 v[0:1], off
	v_lshl_add_u64 v[0:1], v[134:135], 0, s[54:55]
	s_mov_b32 m0, s6
	v_lshl_add_u64 v[136:137], v[130:131], 0, s[58:59]
	v_readfirstlane_b32 s6, v2
	v_add_u32_e32 v2, 0x6000, v128
	global_load_lds_dwordx4 v[0:1], off
	v_lshl_add_u64 v[0:1], v[136:137], 0, s[54:55]
	s_mov_b32 m0, s6
	v_lshl_add_u64 v[138:139], v[130:131], 0, s[60:61]
	v_readfirstlane_b32 s6, v2
	v_add_u32_e32 v2, 0x8000, v128
	global_load_lds_dwordx4 v[0:1], off
	v_lshl_add_u64 v[0:1], v[138:139], 0, s[54:55]
	s_mov_b32 m0, s6
	v_readfirstlane_b32 s6, v2
	v_add_u32_e32 v2, 0xa000, v128
	global_load_lds_dwordx4 v[0:1], off
	v_lshl_add_u64 v[0:1], v[132:133], 0, s[54:55]
	s_mov_b32 m0, s6
	v_lshl_add_u64 v[140:141], v[132:133], 0, s[56:57]
	v_readfirstlane_b32 s6, v2
	v_add_u32_e32 v2, 0xc000, v128
	global_load_lds_dwordx4 v[0:1], off
	v_lshl_add_u64 v[0:1], v[140:141], 0, s[54:55]
	s_mov_b32 m0, s6
	v_lshl_add_u64 v[142:143], v[132:133], 0, s[58:59]
	v_readfirstlane_b32 s6, v2
	v_add_u32_e32 v2, 0xe000, v128
	global_load_lds_dwordx4 v[0:1], off
	v_lshl_add_u64 v[0:1], v[142:143], 0, s[54:55]
	s_mov_b32 m0, s6
	v_lshl_add_u64 v[144:145], v[132:133], 0, s[60:61]
	v_readfirstlane_b32 s6, v2
	global_load_lds_dwordx4 v[0:1], off
	v_lshl_add_u64 v[0:1], v[144:145], 0, s[54:55]
	s_mov_b32 m0, s6
	v_lshlrev_b32_e32 v2, 7, v4
	global_load_lds_dwordx4 v[0:1], off
	v_bfe_u32 v0, v4, 4, 2
	v_bfe_u32 v1, v4, 1, 3
	v_readfirstlane_b32 s7, v4
	s_nop 0
	v_bitop3_b32 v0, v0, v1, 4 bitop3:0x36
	v_and_b32_e32 v2, 0x780, v2
	s_lshl_b32 s6, s7, 8
	s_lshl_b32 s7, s7, 6
	v_lshl_or_b32 v152, v0, 4, v2
	v_bitop3_b32 v0, v5, v1, 3 bitop3:0x6c
	v_mov_b32_e32 v8, 0
	s_and_b32 s6, s6, 0x4000
	s_and_b32 s7, s7, 0xffffe000
	v_lshl_or_b32 v153, v0, 4, v2
	s_mov_b32 s10, 0
	s_mov_b32 s11, 0x10000
	v_mov_b32_e32 v9, v8
	v_mov_b32_e32 v10, v8
	v_mov_b32_e32 v11, v8
	v_mov_b32_e32 v12, v8
	v_mov_b32_e32 v13, v8
	v_mov_b32_e32 v14, v8
	v_mov_b32_e32 v15, v8
	v_mov_b32_e32 v28, v8
	v_mov_b32_e32 v29, v8
	v_mov_b32_e32 v30, v8
	v_mov_b32_e32 v31, v8
	v_mov_b32_e32 v44, v8
	v_mov_b32_e32 v45, v8
	v_mov_b32_e32 v46, v8
	v_mov_b32_e32 v47, v8
	v_mov_b32_e32 v60, v8
	v_mov_b32_e32 v61, v8
	v_mov_b32_e32 v62, v8
	v_mov_b32_e32 v63, v8
	v_mov_b32_e32 v76, v8
	v_mov_b32_e32 v77, v8
	v_mov_b32_e32 v78, v8
	v_mov_b32_e32 v79, v8
	v_mov_b32_e32 v92, v8
	v_mov_b32_e32 v93, v8
	v_mov_b32_e32 v94, v8
	v_mov_b32_e32 v95, v8
	v_mov_b32_e32 v108, v8
	v_mov_b32_e32 v109, v8
	v_mov_b32_e32 v110, v8
	v_mov_b32_e32 v111, v8
	v_mov_b32_e32 v0, v8
	v_mov_b32_e32 v1, v8
	v_mov_b32_e32 v2, v8
	v_mov_b32_e32 v3, v8
	v_mov_b32_e32 v20, v8
	v_mov_b32_e32 v21, v8
	v_mov_b32_e32 v22, v8
	v_mov_b32_e32 v23, v8
	v_mov_b32_e32 v36, v8
	v_mov_b32_e32 v37, v8
	v_mov_b32_e32 v38, v8
	v_mov_b32_e32 v39, v8
	v_mov_b32_e32 v52, v8
	v_mov_b32_e32 v53, v8
	v_mov_b32_e32 v54, v8
	v_mov_b32_e32 v55, v8
	v_mov_b32_e32 v68, v8
	v_mov_b32_e32 v69, v8
	v_mov_b32_e32 v70, v8
	v_mov_b32_e32 v71, v8
	v_mov_b32_e32 v84, v8
	v_mov_b32_e32 v85, v8
	v_mov_b32_e32 v86, v8
	v_mov_b32_e32 v87, v8
	v_mov_b32_e32 v100, v8
	v_mov_b32_e32 v101, v8
	v_mov_b32_e32 v102, v8
	v_mov_b32_e32 v103, v8
	v_mov_b32_e32 v116, v8
	v_mov_b32_e32 v117, v8
	v_mov_b32_e32 v118, v8
	v_mov_b32_e32 v119, v8
	v_mov_b32_e32 v4, v8
	v_mov_b32_e32 v5, v8
	v_mov_b32_e32 v6, v8
	v_mov_b32_e32 v7, v8
	v_mov_b32_e32 v24, v8
	v_mov_b32_e32 v25, v8
	v_mov_b32_e32 v26, v8
	v_mov_b32_e32 v27, v8
	v_mov_b32_e32 v40, v8
	v_mov_b32_e32 v41, v8
	v_mov_b32_e32 v42, v8
	v_mov_b32_e32 v43, v8
	v_mov_b32_e32 v56, v8
	v_mov_b32_e32 v57, v8
	v_mov_b32_e32 v58, v8
	v_mov_b32_e32 v59, v8
	v_mov_b32_e32 v72, v8
	v_mov_b32_e32 v73, v8
	v_mov_b32_e32 v74, v8
	v_mov_b32_e32 v75, v8
	v_mov_b32_e32 v88, v8
	v_mov_b32_e32 v89, v8
	v_mov_b32_e32 v90, v8
	v_mov_b32_e32 v91, v8
	v_mov_b32_e32 v104, v8
	v_mov_b32_e32 v105, v8
	v_mov_b32_e32 v106, v8
	v_mov_b32_e32 v107, v8
	v_mov_b32_e32 v120, v8
	v_mov_b32_e32 v121, v8
	v_mov_b32_e32 v122, v8
	v_mov_b32_e32 v123, v8
	v_mov_b32_e32 v16, v8
	v_mov_b32_e32 v17, v8
	v_mov_b32_e32 v18, v8
	v_mov_b32_e32 v19, v8
	v_mov_b32_e32 v32, v8
	v_mov_b32_e32 v33, v8
	v_mov_b32_e32 v34, v8
	v_mov_b32_e32 v35, v8
	v_mov_b32_e32 v48, v8
	v_mov_b32_e32 v49, v8
	v_mov_b32_e32 v50, v8
	v_mov_b32_e32 v51, v8
	v_mov_b32_e32 v64, v8
	v_mov_b32_e32 v65, v8
	v_mov_b32_e32 v66, v8
	v_mov_b32_e32 v67, v8
	v_mov_b32_e32 v80, v8
	v_mov_b32_e32 v81, v8
	v_mov_b32_e32 v82, v8
	v_mov_b32_e32 v83, v8
	v_mov_b32_e32 v96, v8
	v_mov_b32_e32 v97, v8
	v_mov_b32_e32 v98, v8
	v_mov_b32_e32 v99, v8
	v_mov_b32_e32 v112, v8
	v_mov_b32_e32 v113, v8
	v_mov_b32_e32 v114, v8
	v_mov_b32_e32 v115, v8
	v_mov_b32_e32 v124, v8
	v_mov_b32_e32 v125, v8
	v_mov_b32_e32 v126, v8
	v_mov_b32_e32 v127, v8
	s_add_i32 s8, s73, s10
	s_cmp_lt_u32 s8, 4
	s_cselect_b32 s9, 0, -4
	s_add_i32 s8, s8, s9
	s_and_b32 s9, s11, 0x10000
	v_add_u32_e32 v156, s9, v128
	s_ashr_i32 s9, s8, 31
	s_lshl_b64 s[8:9], s[8:9], 7
	v_readfirstlane_b32 s13, v156
	v_add_u32_e32 v157, 0x2000, v156
	v_lshl_add_u64 v[154:155], v[130:131], 0, s[8:9]
	s_mov_b32 m0, s13
	v_readfirstlane_b32 s13, v157
	v_add_u32_e32 v157, 0x4000, v156
	global_load_lds_dwordx4 v[154:155], off
	v_lshl_add_u64 v[154:155], v[134:135], 0, s[8:9]
	s_mov_b32 m0, s13
	v_readfirstlane_b32 s13, v157
	v_add_u32_e32 v157, 0x6000, v156
	global_load_lds_dwordx4 v[154:155], off
	v_lshl_add_u64 v[154:155], v[136:137], 0, s[8:9]
	s_mov_b32 m0, s13
	v_readfirstlane_b32 s13, v157
	v_add_u32_e32 v157, 0x8000, v156
	global_load_lds_dwordx4 v[154:155], off
	v_lshl_add_u64 v[154:155], v[138:139], 0, s[8:9]
	s_mov_b32 m0, s13
	v_readfirstlane_b32 s13, v157
	v_add_u32_e32 v157, 0xa000, v156
	global_load_lds_dwordx4 v[154:155], off
	v_lshl_add_u64 v[154:155], v[132:133], 0, s[8:9]
	s_mov_b32 m0, s13
	v_readfirstlane_b32 s13, v157
	v_add_u32_e32 v157, 0xc000, v156
	global_load_lds_dwordx4 v[154:155], off
	v_lshl_add_u64 v[154:155], v[140:141], 0, s[8:9]
	s_mov_b32 m0, s13
	v_readfirstlane_b32 s13, v157
	global_load_lds_dwordx4 v[154:155], off
	v_lshl_add_u64 v[154:155], v[142:143], 0, s[8:9]
	s_mov_b32 m0, s13
	v_add_u32_e32 v156, 0xe000, v156
	global_load_lds_dwordx4 v[154:155], off
	v_lshl_add_u64 v[154:155], v[144:145], 0, s[8:9]
	v_readfirstlane_b32 s8, v156
	s_mov_b32 m0, s8
	s_nop 0
	global_load_lds_dwordx4 v[154:155], off
	s_waitcnt vmcnt(8) lgkmcnt(0)
	s_barrier
	s_branch .LBB0_409

; DI u32x2 pack4(float a, float b, float c, float d) { u32x2 r; r.x = pack2(a, b); r.y = pack2(c, d); return r; }
; #define EPI_END if (i == 3 && (j & 3) == 3) __builtin_amdgcn_sched_barrier(0); }
; template <int MODE>
; DI void gemm_phase(const Params& p, const GP& g, unsigned char* smem) {
;     ...
;   for (int e = slot; e < nent; e += nslot) {
;     int mt, nt;
;     const u16* Ab = g.A; const u16* Wb = g.W;
;     int bsel = 0;
;     {
;       const int ml = e / g.ntn;
;       nt = e - ml * g.ntn;
;       mt = xcd + 8 * ml;
;     }
;     if (MODE == M_SEQ) { bsel = mt >> 4; mt &= 15; Wb = g.W + (long)bsel * 1024 * 8192; }
;     const int m0 = mt * 256, n0 = nt * 256;
;     f32x4 acc[4][8];
;     zero_acc(acc);
;     int transposed = 0;
;     if (MODE == M_FN_IN) transposed = nt < 8;
;     if (MODE == M_NA_IN) transposed = (nt >= 8 && nt < 12);
;     if (MODE == M_MLA_UKV) transposed = nt >= 4;
;     if (MODE == M_HG_IN) transposed = nt >= 12;
;     if (MODE == M_PLE) {
;       const u16* pb = (const u16*)g.d1;
;       gemm_loop(g.W2 + (long)n0 * 256, 256, pb + (long)m0 * 256, 256, 256, acc, smem);
;       u16* xb = (u16*)g.d0;
;       EPI_STD_BEGIN
;         *(u32x2*)(xb + (long)m * 1024 + n4) = pack4(v[0], v[1], v[2], v[3]);
;       EPI_END
;       zero_acc(acc);
;     }
;     if (MODE == M_FFT1) {
;       const int bt = mt >> 8, cg = mt & 255;
;       gemm_loop_g<0>(Ab + ((long)(bt * 1024 + cg * 4)) * 8192, 64, 8192, 4096, Wb, 128, 64 * 128, 64, 128, acc, smem);
;     } else if (MODE == M_FFT3) {
;       const int bt = mt >> 8, v = (mt >> 2) & 63, cq = mt & 3;
;       gemm_loop(Ab + (((long)(bt * 64 + v)) * 1024 + cq * 256) * 128, 128, Wb, 128, 128, acc, smem);
;     } else if (MODE == M_FN_IN && transposed) {
;       const u16* Ap = Ab + ((long)(mt >> 4) * 4096 + (mt & 15) * 4) * g.lda;
;       gemm_loop_g<1>(Ap, 64 * g.lda, g.lda, 64, Wb + (long)n0 * g.K, g.K, 64L * g.K, 64, g.K, acc, smem);
;     } else {
;       const u16* Ap = Ab + (long)m0 * g.lda; const u16* Wp = Wb + (long)n0 * g.K;
;       if (transposed) gemm_loop(Ap, g.lda, Wp, g.K, g.K, acc, smem);
;       else gemm_loop(Wp, g.K, Ap, g.lda, g.K, acc, smem);
.LBB0_486:
	s_lshl_b32 s6, s55, 9
	s_and_b32 s6, s6, 0xfffff800
	s_or_b32 s28, s6, s30
	s_lshl_b32 s6, s55, 8
	s_and_b32 s6, s6, 0x300
	s_lshl_b32 s7, s6, 11
	s_add_u32 s8, s12, s7
	s_addc_u32 s9, s13, 0
	s_ashr_i32 s29, s28, 31
	v_mov_b32_e32 v4, v182
	s_lshl_b64 s[10:11], s[28:29], 11
	s_add_u32 s10, s36, s10
	v_ashrrev_i32_e32 v0, 3, v4
	v_lshrrev_b32_e32 v5, 4, v4
	v_xor_b32_e32 v6, v5, v4
	v_ashrrev_i32_e32 v1, 31, v0
	s_addc_u32 s11, s37, s11
	v_lshlrev_b64 v[0:1], 11, v[0:1]
	v_lshlrev_b32_e32 v6, 4, v6
	v_lshl_add_u64 v[2:3], s[8:9], 0, v[0:1]
	v_and_b32_e32 v128, 0x70, v6
	v_lshl_add_u64 v[0:1], s[10:11], 0, v[0:1]
	v_lshl_add_u64 v[130:131], v[2:3], 0, v[128:129]
	v_lshl_add_u64 v[132:133], v[0:1], 0, v[128:129]
	v_lshlrev_b32_e32 v128, 4, v4
	v_add_u32_e32 v2, 0x2000, v128
	v_readfirstlane_b32 s7, v128
	v_lshl_add_u64 v[0:1], v[130:131], 0, s[16:17]
	s_mov_b32 m0, s7
	v_lshl_add_u64 v[134:135], v[130:131], 0, s[18:19]
	v_readfirstlane_b32 s7, v2
	v_add_u32_e32 v2, 0x4000, v128
	s_barrier
; #define LDS_PTR(p) ((__attribute__((address_space(3))) unsigned*)(p))
; template <int PIPE>
; DI void gemm_loop_g(const u16* __restrict__ Xp, long ldx_l, long ldx_i, long kxs,
;                     const u16* __restrict__ Yp, long ldy_l, long ldy_i, long kys, int K,
;                     f32x4 (&acc)[4][8], unsigned char* smem) {
;     ...
;   auto issue = [&](int kt0, int stage) {
;     int kt = kt0 + rot; if (kt >= nk) kt -= nk;
;     unsigned char* sb = smem + stage * 65536 + t * 16;
; #pragma unroll
;     for (int i = 0; i < 4; ++i)
;       __builtin_amdgcn_global_load_lds((const unsigned*)(xs + i * ldx_i + kt * kxs), LDS_PTR(sb + i * 8192), 16, 0, 0);
; #pragma unroll
;     for (int i = 0; i < 4; ++i)
;       __builtin_amdgcn_global_load_lds((const unsigned*)(ys + i * ldy_i + kt * kys), LDS_PTR(sb + 32768 + i * 8192), 16, 0, 0);
;   };
;   __syncthreads();
;   issue(0, 0);
;   asm volatile("s_waitcnt vmcnt(0)" ::: "memory");
;   __syncthreads();
; DI void zero_acc(f32x4 (&acc)[4][8]) {
; #pragma unroll
;   for (int i = 0; i < 4; ++i)
; #pragma unroll
;     for (int j = 0; j < 8; ++j) acc[i][j] = f32x4{0.f, 0.f, 0.f, 0.f};
	global_load_lds_dwordx4 v[0:1], off
	v_lshl_add_u64 v[0:1], v[134:135], 0, s[16:17]
	s_mov_b32 m0, s7
	v_lshl_add_u64 v[136:137], v[130:131], 0, s[24:25]
	v_readfirstlane_b32 s7, v2
	v_add_u32_e32 v2, 0x6000, v128
	global_load_lds_dwordx4 v[0:1], off
	v_lshl_add_u64 v[0:1], v[136:137], 0, s[16:17]
	s_mov_b32 m0, s7
	v_lshl_add_u64 v[138:139], v[130:131], 0, s[26:27]
	v_readfirstlane_b32 s7, v2
	v_add_u32_e32 v2, 0x8000, v128
	global_load_lds_dwordx4 v[0:1], off
	v_lshl_add_u64 v[0:1], v[138:139], 0, s[16:17]
	s_mov_b32 m0, s7
	v_readfirstlane_b32 s7, v2
	v_add_u32_e32 v2, 0xa000, v128
	global_load_lds_dwordx4 v[0:1], off
	v_lshl_add_u64 v[0:1], v[132:133], 0, s[16:17]
	s_mov_b32 m0, s7
	v_lshl_add_u64 v[140:141], v[132:133], 0, s[18:19]
	v_readfirstlane_b32 s7, v2
	v_add_u32_e32 v2, 0xc000, v128
	global_load_lds_dwordx4 v[0:1], off
	v_lshl_add_u64 v[0:1], v[140:141], 0, s[16:17]
	s_mov_b32 m0, s7
	v_lshl_add_u64 v[142:143], v[132:133], 0, s[24:25]
	v_readfirstlane_b32 s7, v2
	v_add_u32_e32 v2, 0xe000, v128
	global_load_lds_dwordx4 v[0:1], off
	v_lshl_add_u64 v[0:1], v[142:143], 0, s[16:17]
	s_mov_b32 m0, s7
	v_lshl_add_u64 v[144:145], v[132:133], 0, s[26:27]
	v_readfirstlane_b32 s7, v2
	global_load_lds_dwordx4 v[0:1], off
	v_lshl_add_u64 v[0:1], v[144:145], 0, s[16:17]
	s_mov_b32 m0, s7
	v_lshlrev_b32_e32 v2, 7, v4
	global_load_lds_dwordx4 v[0:1], off
	v_bfe_u32 v0, v4, 4, 2
	v_bfe_u32 v1, v4, 1, 3
	v_readfirstlane_b32 s29, v4
	s_nop 0
	v_bitop3_b32 v0, v0, v1, 4 bitop3:0x36
	v_and_b32_e32 v2, 0x780, v2
	s_lshl_b32 s7, s29, 8
	s_lshl_b32 s8, s29, 6
	v_lshl_or_b32 v149, v0, 4, v2
	v_bitop3_b32 v0, v5, v1, 3 bitop3:0x6c
	s_and_b32 s7, s7, 0x4000
	s_and_b32 s10, s8, 0xffffe000
	v_lshl_or_b32 v150, v0, 4, v2
	s_mov_b32 s11, 0x10000
	s_mov_b32 s29, 0
	v_mov_b32_e32 v4, 0
	v_mov_b32_e32 v5, v129
	v_mov_b32_e32 v6, v129
	v_mov_b32_e32 v7, v129
	v_mov_b32_e32 v16, 0
	v_mov_b32_e32 v17, v129
	v_mov_b32_e32 v18, v129
	v_mov_b32_e32 v19, v129
	v_mov_b32_e32 v32, 0
	v_mov_b32_e32 v33, v129
	v_mov_b32_e32 v34, v129
	v_mov_b32_e32 v35, v129
	v_mov_b32_e32 v48, 0
	v_mov_b32_e32 v49, v129
	v_mov_b32_e32 v50, v129
	v_mov_b32_e32 v51, v129
	v_mov_b32_e32 v64, 0
	v_mov_b32_e32 v65, v129
	v_mov_b32_e32 v66, v129
	v_mov_b32_e32 v67, v129
	v_mov_b32_e32 v80, 0
	v_mov_b32_e32 v81, v129
	v_mov_b32_e32 v82, v129
	v_mov_b32_e32 v83, v129
	v_mov_b32_e32 v96, 0
	v_mov_b32_e32 v97, v129
	v_mov_b32_e32 v98, v129
	v_mov_b32_e32 v99, v129
	v_mov_b32_e32 v112, 0
	v_mov_b32_e32 v113, v129
	v_mov_b32_e32 v114, v129
	v_mov_b32_e32 v115, v129
	v_mov_b32_e32 v0, 0
	v_mov_b32_e32 v1, v129
	v_mov_b32_e32 v2, v129
	v_mov_b32_e32 v3, v129
	v_mov_b32_e32 v20, 0
	v_mov_b32_e32 v21, v129
	v_mov_b32_e32 v22, v129
	v_mov_b32_e32 v23, v129
	v_mov_b32_e32 v36, 0
	v_mov_b32_e32 v37, v129
	v_mov_b32_e32 v38, v129
	v_mov_b32_e32 v39, v129
	v_mov_b32_e32 v52, 0
	v_mov_b32_e32 v53, v129
	v_mov_b32_e32 v54, v129
	v_mov_b32_e32 v55, v129
	v_mov_b32_e32 v68, 0
	v_mov_b32_e32 v69, v129
	v_mov_b32_e32 v70, v129
	v_mov_b32_e32 v71, v129
	v_mov_b32_e32 v84, 0
	v_mov_b32_e32 v85, v129
	v_mov_b32_e32 v86, v129
	v_mov_b32_e32 v87, v129
	v_mov_b32_e32 v100, 0
	v_mov_b32_e32 v101, v129
	v_mov_b32_e32 v102, v129
	v_mov_b32_e32 v103, v129
	v_mov_b32_e32 v116, 0
	v_mov_b32_e32 v117, v129
	v_mov_b32_e32 v118, v129
	v_mov_b32_e32 v119, v129
	v_mov_b32_e32 v8, 0
	v_mov_b32_e32 v9, v129
	v_mov_b32_e32 v10, v129
	v_mov_b32_e32 v11, v129
	v_mov_b32_e32 v24, 0
	v_mov_b32_e32 v25, v129
	v_mov_b32_e32 v26, v129
	v_mov_b32_e32 v27, v129
	v_mov_b32_e32 v40, 0
	v_mov_b32_e32 v41, v129
	v_mov_b32_e32 v42, v129
	v_mov_b32_e32 v43, v129
	v_mov_b32_e32 v56, 0
	v_mov_b32_e32 v57, v129
	v_mov_b32_e32 v58, v129
	v_mov_b32_e32 v59, v129
	v_mov_b32_e32 v72, 0
	v_mov_b32_e32 v73, v129
	v_mov_b32_e32 v74, v129
	v_mov_b32_e32 v75, v129
	v_mov_b32_e32 v88, 0
	v_mov_b32_e32 v89, v129
	v_mov_b32_e32 v90, v129
	v_mov_b32_e32 v91, v129
	v_mov_b32_e32 v104, 0
	v_mov_b32_e32 v105, v129
	v_mov_b32_e32 v106, v129
	v_mov_b32_e32 v107, v129
	v_mov_b32_e32 v120, 0
	v_mov_b32_e32 v121, v129
	v_mov_b32_e32 v122, v129
	v_mov_b32_e32 v123, v129
	v_mov_b32_e32 v12, 0
	v_mov_b32_e32 v13, v129
	v_mov_b32_e32 v14, v129
	v_mov_b32_e32 v15, v129
	v_mov_b32_e32 v28, 0
	v_mov_b32_e32 v29, v129
	v_mov_b32_e32 v30, v129
	v_mov_b32_e32 v31, v129
	v_mov_b32_e32 v44, 0
	v_mov_b32_e32 v45, v129
	v_mov_b32_e32 v46, v129
	v_mov_b32_e32 v47, v129
	v_mov_b32_e32 v60, 0
	v_mov_b32_e32 v61, v129
	v_mov_b32_e32 v62, v129
	v_mov_b32_e32 v63, v129
	v_mov_b32_e32 v76, 0
	v_mov_b32_e32 v77, v129
	v_mov_b32_e32 v78, v129
	v_mov_b32_e32 v79, v129
	v_mov_b32_e32 v92, 0
	v_mov_b32_e32 v93, v129
	v_mov_b32_e32 v94, v129
	v_mov_b32_e32 v95, v129
	v_mov_b32_e32 v108, 0
	v_mov_b32_e32 v109, v129
	v_mov_b32_e32 v110, v129
	v_mov_b32_e32 v111, v129
	v_mov_b32_e32 v124, 0
	v_mov_b32_e32 v125, v129
	v_mov_b32_e32 v126, v129
	v_mov_b32_e32 v127, v129
	s_add_i32 s8, s31, s29
	s_cmp_lt_u32 s8, 16
	s_cselect_b32 s9, 0, -16
	s_add_i32 s8, s8, s9
	s_and_b32 s9, s11, 0x10000
	v_add_u32_e32 v151, s9, v128
	s_ashr_i32 s9, s8, 31
	s_lshl_b64 s[8:9], s[8:9], 7
	v_readfirstlane_b32 s33, v151
	v_add_u32_e32 v154, 0x2000, v151
	v_lshl_add_u64 v[152:153], v[130:131], 0, s[8:9]
	s_mov_b32 m0, s33
	v_readfirstlane_b32 s33, v154
	v_add_u32_e32 v154, 0x4000, v151
	global_load_lds_dwordx4 v[152:153], off
	v_lshl_add_u64 v[152:153], v[134:135], 0, s[8:9]
	s_mov_b32 m0, s33
	v_readfirstlane_b32 s33, v154
	v_add_u32_e32 v154, 0x6000, v151
	global_load_lds_dwordx4 v[152:153], off
	v_lshl_add_u64 v[152:153], v[136:137], 0, s[8:9]
	s_mov_b32 m0, s33
	v_readfirstlane_b32 s33, v154
	v_add_u32_e32 v154, 0x8000, v151
	global_load_lds_dwordx4 v[152:153], off
	v_lshl_add_u64 v[152:153], v[138:139], 0, s[8:9]
	s_mov_b32 m0, s33
	v_readfirstlane_b32 s33, v154
	v_add_u32_e32 v154, 0xa000, v151
	global_load_lds_dwordx4 v[152:153], off
	v_lshl_add_u64 v[152:153], v[132:133], 0, s[8:9]
	s_mov_b32 m0, s33
	v_readfirstlane_b32 s33, v154
	v_add_u32_e32 v154, 0xc000, v151
	global_load_lds_dwordx4 v[152:153], off
	v_lshl_add_u64 v[152:153], v[140:141], 0, s[8:9]
	s_mov_b32 m0, s33
	v_readfirstlane_b32 s33, v154
	global_load_lds_dwordx4 v[152:153], off
	v_lshl_add_u64 v[152:153], v[142:143], 0, s[8:9]
	s_mov_b32 m0, s33
	v_add_u32_e32 v151, 0xe000, v151
	global_load_lds_dwordx4 v[152:153], off
	v_lshl_add_u64 v[152:153], v[144:145], 0, s[8:9]
	v_readfirstlane_b32 s8, v151
	s_mov_b32 m0, s8
	s_nop 0
	global_load_lds_dwordx4 v[152:153], off
	s_waitcnt vmcnt(8) lgkmcnt(0)
	s_barrier
	s_branch .LBB0_487

; DI u32x2 pack4(float a, float b, float c, float d) { u32x2 r; r.x = pack2(a, b); r.y = pack2(c, d); return r; }
; #define EPI_END if (i == 3 && (j & 3) == 3) __builtin_amdgcn_sched_barrier(0); }
; template <int MODE>
; DI void gemm_phase(const Params& p, const GP& g, unsigned char* smem) {
;     ...
;   for (int e = slot; e < nent; e += nslot) {
;     int mt, nt;
;     const u16* Ab = g.A; const u16* Wb = g.W;
;     int bsel = 0;
;     {
;       const int ml = e / g.ntn;
;       nt = e - ml * g.ntn;
;       mt = xcd + 8 * ml;
;     }
;     if (MODE == M_SEQ) { bsel = mt >> 4; mt &= 15; Wb = g.W + (long)bsel * 1024 * 8192; }
;     const int m0 = mt * 256, n0 = nt * 256;
;     f32x4 acc[4][8];
;     zero_acc(acc);
;     int transposed = 0;
;     if (MODE == M_FN_IN) transposed = nt < 8;
;     if (MODE == M_NA_IN) transposed = (nt >= 8 && nt < 12);
;     if (MODE == M_MLA_UKV) transposed = nt >= 4;
;     if (MODE == M_HG_IN) transposed = nt >= 12;
;     if (MODE == M_PLE) {
;       const u16* pb = (const u16*)g.d1;
;       gemm_loop(g.W2 + (long)n0 * 256, 256, pb + (long)m0 * 256, 256, 256, acc, smem);
;       u16* xb = (u16*)g.d0;
;       EPI_STD_BEGIN
;         *(u32x2*)(xb + (long)m * 1024 + n4) = pack4(v[0], v[1], v[2], v[3]);
;       EPI_END
;       zero_acc(acc);
;     }
;     if (MODE == M_FFT1) {
;       const int bt = mt >> 8, cg = mt & 255;
;       gemm_loop_g<0>(Ab + ((long)(bt * 1024 + cg * 4)) * 8192, 64, 8192, 4096, Wb, 128, 64 * 128, 64, 128, acc, smem);
;     } else if (MODE == M_FFT3) {
;       const int bt = mt >> 8, v = (mt >> 2) & 63, cq = mt & 3;
;       gemm_loop(Ab + (((long)(bt * 64 + v)) * 1024 + cq * 256) * 128, 128, Wb, 128, 128, acc, smem);
;     } else if (MODE == M_FN_IN && transposed) {
;       const u16* Ap = Ab + ((long)(mt >> 4) * 4096 + (mt & 15) * 4) * g.lda;
;       gemm_loop_g<1>(Ap, 64 * g.lda, g.lda, 64, Wb + (long)n0 * g.K, g.K, 64L * g.K, 64, g.K, acc, smem);
;     } else {
;       const u16* Ap = Ab + (long)m0 * g.lda; const u16* Wp = Wb + (long)n0 * g.K;
;       if (transposed) gemm_loop(Ap, g.lda, Wp, g.K, g.K, acc, smem);
;       else gemm_loop(Wp, g.K, Ap, g.lda, g.K, acc, smem);
.LBB0_503:
	s_lshl_b32 s6, s11, 9
	s_and_b32 s6, s6, 0xfffff800
	s_or_b32 s28, s6, s30
	s_lshl_b32 s6, s11, 8
	s_and_b32 s6, s6, 0x300
	s_lshl_b32 s7, s6, 11
	s_waitcnt lgkmcnt(0)
	s_add_u32 s8, s14, s7
	s_addc_u32 s9, s15, 0
	s_ashr_i32 s29, s28, 31
	v_mov_b32_e32 v4, v182
	s_lshl_b64 s[40:41], s[28:29], 11
	s_add_u32 s40, s38, s40
	v_ashrrev_i32_e32 v0, 3, v4
	v_lshrrev_b32_e32 v5, 4, v4
	v_xor_b32_e32 v6, v5, v4
	v_ashrrev_i32_e32 v1, 31, v0
	s_addc_u32 s41, s39, s41
	v_lshlrev_b64 v[0:1], 11, v[0:1]
	v_lshlrev_b32_e32 v6, 4, v6
	v_lshl_add_u64 v[2:3], s[8:9], 0, v[0:1]
	v_and_b32_e32 v128, 0x70, v6
	v_lshl_add_u64 v[0:1], s[40:41], 0, v[0:1]
	v_lshl_add_u64 v[130:131], v[2:3], 0, v[128:129]
	v_lshl_add_u64 v[132:133], v[0:1], 0, v[128:129]
	v_lshlrev_b32_e32 v128, 4, v4
	v_add_u32_e32 v2, 0x2000, v128
	v_readfirstlane_b32 s7, v128
	v_lshl_add_u64 v[0:1], v[130:131], 0, s[12:13]
	s_mov_b32 m0, s7
	v_lshl_add_u64 v[134:135], v[130:131], 0, s[18:19]
	v_readfirstlane_b32 s7, v2
	v_add_u32_e32 v2, 0x4000, v128
	s_barrier
; #define LDS_PTR(p) ((__attribute__((address_space(3))) unsigned*)(p))
; template <int PIPE>
; DI void gemm_loop_g(const u16* __restrict__ Xp, long ldx_l, long ldx_i, long kxs,
;                     const u16* __restrict__ Yp, long ldy_l, long ldy_i, long kys, int K,
;                     f32x4 (&acc)[4][8], unsigned char* smem) {
;     ...
;   auto issue = [&](int kt0, int stage) {
;     int kt = kt0 + rot; if (kt >= nk) kt -= nk;
;     unsigned char* sb = smem + stage * 65536 + t * 16;
; #pragma unroll
;     for (int i = 0; i < 4; ++i)
;       __builtin_amdgcn_global_load_lds((const unsigned*)(xs + i * ldx_i + kt * kxs), LDS_PTR(sb + i * 8192), 16, 0, 0);
; #pragma unroll
;     for (int i = 0; i < 4; ++i)
;       __builtin_amdgcn_global_load_lds((const unsigned*)(ys + i * ldy_i + kt * kys), LDS_PTR(sb + 32768 + i * 8192), 16, 0, 0);
;   };
;   __syncthreads();
;   issue(0, 0);
;   asm volatile("s_waitcnt vmcnt(0)" ::: "memory");
;   __syncthreads();
; DI void zero_acc(f32x4 (&acc)[4][8]) {
; #pragma unroll
;   for (int i = 0; i < 4; ++i)
; #pragma unroll
;     for (int j = 0; j < 8; ++j) acc[i][j] = f32x4{0.f, 0.f, 0.f, 0.f};
	global_load_lds_dwordx4 v[0:1], off
	v_lshl_add_u64 v[0:1], v[134:135], 0, s[12:13]
	s_mov_b32 m0, s7
	v_lshl_add_u64 v[136:137], v[130:131], 0, s[24:25]
	v_readfirstlane_b32 s7, v2
	v_add_u32_e32 v2, 0x6000, v128
	global_load_lds_dwordx4 v[0:1], off
	v_lshl_add_u64 v[0:1], v[136:137], 0, s[12:13]
	s_mov_b32 m0, s7
	v_lshl_add_u64 v[138:139], v[130:131], 0, s[26:27]
	v_readfirstlane_b32 s7, v2
	v_add_u32_e32 v2, 0x8000, v128
	global_load_lds_dwordx4 v[0:1], off
	v_lshl_add_u64 v[0:1], v[138:139], 0, s[12:13]
	s_mov_b32 m0, s7
	v_readfirstlane_b32 s7, v2
	v_add_u32_e32 v2, 0xa000, v128
	global_load_lds_dwordx4 v[0:1], off
	v_lshl_add_u64 v[0:1], v[132:133], 0, s[12:13]
	s_mov_b32 m0, s7
	v_lshl_add_u64 v[140:141], v[132:133], 0, s[18:19]
	v_readfirstlane_b32 s7, v2
	v_add_u32_e32 v2, 0xc000, v128
	global_load_lds_dwordx4 v[0:1], off
	v_lshl_add_u64 v[0:1], v[140:141], 0, s[12:13]
	s_mov_b32 m0, s7
	v_lshl_add_u64 v[142:143], v[132:133], 0, s[24:25]
	v_readfirstlane_b32 s7, v2
	v_add_u32_e32 v2, 0xe000, v128
	global_load_lds_dwordx4 v[0:1], off
	v_lshl_add_u64 v[0:1], v[142:143], 0, s[12:13]
	s_mov_b32 m0, s7
	v_lshl_add_u64 v[144:145], v[132:133], 0, s[26:27]
	v_readfirstlane_b32 s7, v2
	global_load_lds_dwordx4 v[0:1], off
	v_lshl_add_u64 v[0:1], v[144:145], 0, s[12:13]
	s_mov_b32 m0, s7
	v_lshlrev_b32_e32 v2, 7, v4
	global_load_lds_dwordx4 v[0:1], off
	v_bfe_u32 v0, v4, 4, 2
	v_bfe_u32 v1, v4, 1, 3
	v_readfirstlane_b32 s29, v4
	s_nop 0
	v_bitop3_b32 v0, v0, v1, 4 bitop3:0x36
	v_and_b32_e32 v2, 0x780, v2
	s_lshl_b32 s7, s29, 8
	s_lshl_b32 s8, s29, 6
	v_lshl_or_b32 v148, v0, 4, v2
	v_bitop3_b32 v0, v5, v1, 3 bitop3:0x6c
	s_and_b32 s7, s7, 0x4000
	s_and_b32 s29, s8, 0xffffe000
	v_lshl_or_b32 v149, v0, 4, v2
	s_mov_b32 s31, 0x10000
	s_mov_b32 s33, 0
	v_mov_b32_e32 v12, 0
	v_mov_b32_e32 v13, v129
	v_mov_b32_e32 v14, v129
	v_mov_b32_e32 v15, v129
	v_mov_b32_e32 v4, 0
	v_mov_b32_e32 v5, v129
	v_mov_b32_e32 v6, v129
	v_mov_b32_e32 v7, v129
	v_mov_b32_e32 v24, 0
	v_mov_b32_e32 v25, v129
	v_mov_b32_e32 v26, v129
	v_mov_b32_e32 v27, v129
	v_mov_b32_e32 v40, 0
	v_mov_b32_e32 v41, v129
	v_mov_b32_e32 v42, v129
	v_mov_b32_e32 v43, v129
	v_mov_b32_e32 v56, 0
	v_mov_b32_e32 v57, v129
	v_mov_b32_e32 v58, v129
	v_mov_b32_e32 v59, v129
	v_mov_b32_e32 v72, 0
	v_mov_b32_e32 v73, v129
	v_mov_b32_e32 v74, v129
	v_mov_b32_e32 v75, v129
	v_mov_b32_e32 v88, 0
	v_mov_b32_e32 v89, v129
	v_mov_b32_e32 v90, v129
	v_mov_b32_e32 v91, v129
	v_mov_b32_e32 v104, 0
	v_mov_b32_e32 v105, v129
	v_mov_b32_e32 v106, v129
	v_mov_b32_e32 v107, v129
	v_mov_b32_e32 v0, 0
	v_mov_b32_e32 v1, v129
	v_mov_b32_e32 v2, v129
	v_mov_b32_e32 v3, v129
	v_mov_b32_e32 v20, 0
	v_mov_b32_e32 v21, v129
	v_mov_b32_e32 v22, v129
	v_mov_b32_e32 v23, v129
	v_mov_b32_e32 v36, 0
	v_mov_b32_e32 v37, v129
	v_mov_b32_e32 v38, v129
	v_mov_b32_e32 v39, v129
	v_mov_b32_e32 v52, 0
	v_mov_b32_e32 v53, v129
	v_mov_b32_e32 v54, v129
	v_mov_b32_e32 v55, v129
	v_mov_b32_e32 v68, 0
	v_mov_b32_e32 v69, v129
	v_mov_b32_e32 v70, v129
	v_mov_b32_e32 v71, v129
	v_mov_b32_e32 v84, 0
	v_mov_b32_e32 v85, v129
	v_mov_b32_e32 v86, v129
	v_mov_b32_e32 v87, v129
	v_mov_b32_e32 v100, 0
	v_mov_b32_e32 v101, v129
	v_mov_b32_e32 v102, v129
	v_mov_b32_e32 v103, v129
	v_mov_b32_e32 v116, 0
	v_mov_b32_e32 v117, v129
	v_mov_b32_e32 v118, v129
	v_mov_b32_e32 v119, v129
	v_mov_b32_e32 v8, 0
	v_mov_b32_e32 v9, v129
	v_mov_b32_e32 v10, v129
	v_mov_b32_e32 v11, v129
	v_mov_b32_e32 v28, 0
	v_mov_b32_e32 v29, v129
	v_mov_b32_e32 v30, v129
	v_mov_b32_e32 v31, v129
	v_mov_b32_e32 v44, 0
	v_mov_b32_e32 v45, v129
	v_mov_b32_e32 v46, v129
	v_mov_b32_e32 v47, v129
	v_mov_b32_e32 v60, 0
	v_mov_b32_e32 v61, v129
	v_mov_b32_e32 v62, v129
	v_mov_b32_e32 v63, v129
	v_mov_b32_e32 v76, 0
	v_mov_b32_e32 v77, v129
	v_mov_b32_e32 v78, v129
	v_mov_b32_e32 v79, v129
	v_mov_b32_e32 v92, 0
	v_mov_b32_e32 v93, v129
	v_mov_b32_e32 v94, v129
	v_mov_b32_e32 v95, v129
	v_mov_b32_e32 v108, 0
	v_mov_b32_e32 v109, v129
	v_mov_b32_e32 v110, v129
	v_mov_b32_e32 v111, v129
	v_mov_b32_e32 v120, 0
	v_mov_b32_e32 v121, v129
	v_mov_b32_e32 v122, v129
	v_mov_b32_e32 v123, v129
	v_mov_b32_e32 v16, 0
	v_mov_b32_e32 v17, v129
	v_mov_b32_e32 v18, v129
	v_mov_b32_e32 v19, v129
	v_mov_b32_e32 v32, 0
	v_mov_b32_e32 v33, v129
	v_mov_b32_e32 v34, v129
	v_mov_b32_e32 v35, v129
	v_mov_b32_e32 v48, 0
	v_mov_b32_e32 v49, v129
	v_mov_b32_e32 v50, v129
	v_mov_b32_e32 v51, v129
	v_mov_b32_e32 v64, 0
	v_mov_b32_e32 v65, v129
	v_mov_b32_e32 v66, v129
	v_mov_b32_e32 v67, v129
	v_mov_b32_e32 v80, 0
	v_mov_b32_e32 v81, v129
	v_mov_b32_e32 v82, v129
	v_mov_b32_e32 v83, v129
	v_mov_b32_e32 v96, 0
	v_mov_b32_e32 v97, v129
	v_mov_b32_e32 v98, v129
	v_mov_b32_e32 v99, v129
	v_mov_b32_e32 v112, 0
	v_mov_b32_e32 v113, v129
	v_mov_b32_e32 v114, v129
	v_mov_b32_e32 v115, v129
	v_mov_b32_e32 v124, 0
	v_mov_b32_e32 v125, v129
	v_mov_b32_e32 v126, v129
	v_mov_b32_e32 v127, v129
	s_add_i32 s8, s10, s33
	s_cmp_lt_u32 s8, 16
	s_cselect_b32 s9, 0, -16
	s_add_i32 s8, s8, s9
	s_and_b32 s9, s31, 0x10000
	v_add_u32_e32 v152, s9, v128
	s_ashr_i32 s9, s8, 31
	s_lshl_b64 s[8:9], s[8:9], 7
	v_readfirstlane_b32 s40, v152
	v_add_u32_e32 v153, 0x2000, v152
	v_lshl_add_u64 v[150:151], v[130:131], 0, s[8:9]
	s_mov_b32 m0, s40
	v_readfirstlane_b32 s40, v153
	v_add_u32_e32 v153, 0x4000, v152
	global_load_lds_dwordx4 v[150:151], off
	v_lshl_add_u64 v[150:151], v[134:135], 0, s[8:9]
	s_mov_b32 m0, s40
	v_readfirstlane_b32 s40, v153
	v_add_u32_e32 v153, 0x6000, v152
	global_load_lds_dwordx4 v[150:151], off
	v_lshl_add_u64 v[150:151], v[136:137], 0, s[8:9]
	s_mov_b32 m0, s40
	v_readfirstlane_b32 s40, v153
	v_add_u32_e32 v153, 0x8000, v152
	global_load_lds_dwordx4 v[150:151], off
	v_lshl_add_u64 v[150:151], v[138:139], 0, s[8:9]
	s_mov_b32 m0, s40
	v_readfirstlane_b32 s40, v153
	v_add_u32_e32 v153, 0xa000, v152
	global_load_lds_dwordx4 v[150:151], off
	v_lshl_add_u64 v[150:151], v[132:133], 0, s[8:9]
	s_mov_b32 m0, s40
	v_readfirstlane_b32 s40, v153
	v_add_u32_e32 v153, 0xc000, v152
	global_load_lds_dwordx4 v[150:151], off
	v_lshl_add_u64 v[150:151], v[140:141], 0, s[8:9]
	s_mov_b32 m0, s40
	v_readfirstlane_b32 s40, v153
	global_load_lds_dwordx4 v[150:151], off
	v_lshl_add_u64 v[150:151], v[142:143], 0, s[8:9]
	s_mov_b32 m0, s40
	v_add_u32_e32 v152, 0xe000, v152
	global_load_lds_dwordx4 v[150:151], off
	v_lshl_add_u64 v[150:151], v[144:145], 0, s[8:9]
	v_readfirstlane_b32 s8, v152
	s_mov_b32 m0, s8
	s_nop 0
	global_load_lds_dwordx4 v[150:151], off
	s_waitcnt vmcnt(8) lgkmcnt(0)
	s_barrier
	s_branch .LBB0_504

; DI u32x2 pack4(float a, float b, float c, float d) { u32x2 r; r.x = pack2(a, b); r.y = pack2(c, d); return r; }
; #define EPI_END if (i == 3 && (j & 3) == 3) __builtin_amdgcn_sched_barrier(0); }
; template <int MODE>
; DI void gemm_phase(const Params& p, const GP& g, unsigned char* smem) {
;     ...
;       EPI_STD_BEGIN
;         *(u32x2*)(xb + (long)m * 1024 + n4) = pack4(v[0], v[1], v[2], v[3]);
;       EPI_END
;       zero_acc(acc);
;     ...
;       const u16* Ap = Ab + (long)m0 * g.lda; const u16* Wp = Wb + (long)n0 * g.K;
;       if (transposed) gemm_loop(Ap, g.lda, Wp, g.K, g.K, acc, smem);
;       else gemm_loop(Wp, g.K, Ap, g.lda, g.K, acc, smem);
.LBB0_527:
	v_or_b32_e32 v160, s12, v185
	v_add_u32_e32 v134, s6, v184
	v_ashrrev_i32_e32 v161, 31, v160
	v_lshlrev_b64 v[164:165], 11, v[160:161]
	v_ashrrev_i32_e32 v135, 31, v134
	v_or_b32_e32 v156, 16, v160
	v_lshl_add_u64 v[132:133], s[38:39], 0, v[164:165]
	v_cvt_pk_bf16_f32 v124, v124, v125
	v_cvt_pk_bf16_f32 v125, v126, v127
	v_lshlrev_b64 v[126:127], 1, v[134:135]
	v_ashrrev_i32_e32 v157, 31, v156
	v_lshl_add_u64 v[132:133], v[132:133], 0, v[126:127]
	v_cvt_pk_bf16_f32 v96, v96, v97
	v_cvt_pk_bf16_f32 v97, v98, v99
	v_lshlrev_b64 v[162:163], 11, v[156:157]
	v_or_b32_e32 v152, 32, v160
	global_store_dwordx2 v[132:133], v[96:97], off offset:96
	v_lshl_add_u64 v[96:97], s[38:39], 0, v[162:163]
	v_ashrrev_i32_e32 v153, 31, v152
	v_lshl_add_u64 v[96:97], v[96:97], 0, v[126:127]
	v_cvt_pk_bf16_f32 v72, v72, v73
	v_cvt_pk_bf16_f32 v73, v74, v75
	v_lshlrev_b64 v[158:159], 11, v[152:153]
	v_or_b32_e32 v148, 48, v160
	global_store_dwordx2 v[96:97], v[72:73], off offset:96
	v_lshl_add_u64 v[72:73], s[38:39], 0, v[158:159]
	v_ashrrev_i32_e32 v149, 31, v148
	v_lshl_add_u64 v[72:73], v[72:73], 0, v[126:127]
	v_cvt_pk_bf16_f32 v56, v56, v57
	v_cvt_pk_bf16_f32 v57, v58, v59
	v_lshlrev_b64 v[154:155], 11, v[148:149]
	global_store_dwordx2 v[72:73], v[56:57], off offset:96
	v_lshl_add_u64 v[56:57], s[38:39], 0, v[154:155]
	v_cvt_pk_bf16_f32 v74, v104, v105
	v_cvt_pk_bf16_f32 v75, v106, v107
	v_cvt_pk_bf16_f32 v58, v100, v101
	v_cvt_pk_bf16_f32 v59, v102, v103
	v_lshl_add_u64 v[56:57], v[56:57], 0, v[126:127]
	v_cvt_pk_bf16_f32 v98, v120, v121
	v_cvt_pk_bf16_f32 v99, v122, v123
	global_store_dwordx2 v[72:73], v[74:75], off
	v_cvt_pk_bf16_f32 v74, v92, v93
	v_cvt_pk_bf16_f32 v75, v94, v95
	global_store_dwordx2 v[56:57], v[58:59], off
	v_cvt_pk_bf16_f32 v58, v80, v81
	v_cvt_pk_bf16_f32 v59, v82, v83
	v_cvt_pk_bf16_f32 v116, v116, v117
	v_cvt_pk_bf16_f32 v117, v118, v119
	v_cvt_pk_bf16_f32 v112, v112, v113
	v_cvt_pk_bf16_f32 v113, v114, v115
	global_store_dwordx2 v[96:97], v[98:99], off
	v_cvt_pk_bf16_f32 v98, v108, v109
	v_cvt_pk_bf16_f32 v99, v110, v111
	v_cvt_pk_bf16_f32 v88, v88, v89
	v_cvt_pk_bf16_f32 v89, v90, v91
	global_store_dwordx2 v[72:73], v[74:75], off offset:32
	v_cvt_pk_bf16_f32 v74, v76, v77
	v_cvt_pk_bf16_f32 v75, v78, v79
	global_store_dwordx2 v[56:57], v[58:59], off offset:32
	v_cvt_pk_bf16_f32 v58, v64, v65
	v_cvt_pk_bf16_f32 v59, v66, v67
	v_cvt_pk_bf16_f32 v36, v36, v37
	v_cvt_pk_bf16_f32 v37, v38, v39
	global_store_dwordx2 v[132:133], v[124:125], off
	global_store_dwordx2 v[132:133], v[116:117], off offset:32
	global_store_dwordx2 v[132:133], v[112:113], off offset:64
	global_store_dwordx2 v[96:97], v[98:99], off offset:32
	global_store_dwordx2 v[96:97], v[88:89], off offset:64
	global_store_dwordx2 v[72:73], v[74:75], off offset:64
	global_store_dwordx2 v[56:57], v[58:59], off offset:64
	global_store_dwordx2 v[56:57], v[36:37], off offset:96
	v_or_b32_e32 v144, 64, v160
	v_ashrrev_i32_e32 v145, 31, v144
	v_lshlrev_b64 v[150:151], 11, v[144:145]
	v_or_b32_e32 v140, 0x50, v160
	v_lshl_add_u64 v[36:37], s[38:39], 0, v[150:151]
	v_ashrrev_i32_e32 v141, 31, v140
	v_lshl_add_u64 v[36:37], v[36:37], 0, v[126:127]
	v_cvt_pk_bf16_f32 v20, v20, v21
	v_cvt_pk_bf16_f32 v21, v22, v23
	v_lshlrev_b64 v[146:147], 11, v[140:141]
	v_or_b32_e32 v136, 0x60, v160
	global_store_dwordx2 v[36:37], v[20:21], off offset:96
	v_lshl_add_u64 v[20:21], s[38:39], 0, v[146:147]
	v_ashrrev_i32_e32 v137, 31, v136
	v_lshl_add_u64 v[20:21], v[20:21], 0, v[126:127]
	v_cvt_pk_bf16_f32 v8, v8, v9
	v_cvt_pk_bf16_f32 v9, v10, v11
	v_lshlrev_b64 v[142:143], 11, v[136:137]
	v_or_b32_e32 v132, 0x70, v160
	global_store_dwordx2 v[20:21], v[8:9], off offset:96
	v_lshl_add_u64 v[8:9], s[38:39], 0, v[142:143]
	v_ashrrev_i32_e32 v133, 31, v132
	v_lshl_add_u64 v[8:9], v[8:9], 0, v[126:127]
	v_cvt_pk_bf16_f32 v0, v0, v1
	v_cvt_pk_bf16_f32 v1, v2, v3
	v_lshlrev_b64 v[138:139], 11, v[132:133]
	global_store_dwordx2 v[8:9], v[0:1], off offset:96
	v_lshl_add_u64 v[0:1], s[38:39], 0, v[138:139]
	v_cvt_pk_bf16_f32 v2, v32, v33
	v_cvt_pk_bf16_f32 v3, v34, v35
	v_lshl_add_u64 v[0:1], v[0:1], 0, v[126:127]
	v_cvt_pk_bf16_f32 v38, v84, v85
	v_cvt_pk_bf16_f32 v39, v86, v87
	v_cvt_pk_bf16_f32 v22, v68, v69
	v_cvt_pk_bf16_f32 v23, v70, v71
	v_cvt_pk_bf16_f32 v10, v52, v53
	v_cvt_pk_bf16_f32 v11, v54, v55
	global_store_dwordx2 v[0:1], v[2:3], off
	v_cvt_pk_bf16_f32 v2, v16, v17
	v_cvt_pk_bf16_f32 v3, v18, v19
	global_store_dwordx2 v[36:37], v[38:39], off
	v_cvt_pk_bf16_f32 v38, v60, v61
	v_cvt_pk_bf16_f32 v39, v62, v63
	global_store_dwordx2 v[20:21], v[22:23], off
	v_cvt_pk_bf16_f32 v22, v48, v49
	v_cvt_pk_bf16_f32 v23, v50, v51
	global_store_dwordx2 v[8:9], v[10:11], off
	v_cvt_pk_bf16_f32 v10, v28, v29
	v_cvt_pk_bf16_f32 v11, v30, v31
	global_store_dwordx2 v[0:1], v[2:3], off offset:32
	v_cvt_pk_bf16_f32 v2, v4, v5
	v_cvt_pk_bf16_f32 v3, v6, v7
	global_store_dwordx2 v[36:37], v[38:39], off offset:32
	v_cvt_pk_bf16_f32 v38, v44, v45
	v_cvt_pk_bf16_f32 v39, v46, v47
	global_store_dwordx2 v[20:21], v[22:23], off offset:32
	v_cvt_pk_bf16_f32 v22, v24, v25
	v_cvt_pk_bf16_f32 v23, v26, v27
	global_store_dwordx2 v[8:9], v[10:11], off offset:32
	v_cvt_pk_bf16_f32 v10, v12, v13
	v_cvt_pk_bf16_f32 v11, v14, v15
	global_store_dwordx2 v[0:1], v[2:3], off offset:64
	v_cvt_pk_bf16_f32 v2, v40, v41
	v_cvt_pk_bf16_f32 v3, v42, v43
	global_store_dwordx2 v[36:37], v[38:39], off offset:64
	global_store_dwordx2 v[20:21], v[22:23], off offset:64
	global_store_dwordx2 v[8:9], v[10:11], off offset:64
	global_store_dwordx2 v[0:1], v[2:3], off offset:96
	s_lshl_b32 s6, s6, 11
	s_add_u32 s6, s62, s6
	v_mov_b32_e32 v4, v182
	s_addc_u32 s7, s63, 0
	s_lshl_b64 s[8:9], s[12:13], 11
	s_add_u32 s8, s36, s8
	v_ashrrev_i32_e32 v0, 3, v4
	v_lshrrev_b32_e32 v5, 4, v4
	v_xor_b32_e32 v6, v5, v4
	v_ashrrev_i32_e32 v1, 31, v0
	s_addc_u32 s9, s37, s9
	v_lshlrev_b64 v[0:1], 11, v[0:1]
	v_lshlrev_b32_e32 v6, 4, v6
	v_lshl_add_u64 v[2:3], s[6:7], 0, v[0:1]
	v_and_b32_e32 v130, 0x70, v6
	v_lshl_add_u64 v[0:1], s[8:9], 0, v[0:1]
	v_lshl_add_u64 v[166:167], v[2:3], 0, v[130:131]
	v_lshl_add_u64 v[168:169], v[0:1], 0, v[130:131]
	v_lshlrev_b32_e32 v130, 4, v4
	v_add_u32_e32 v2, 0x2000, v130
	v_readfirstlane_b32 s6, v130
	v_lshl_add_u64 v[0:1], v[166:167], 0, s[30:31]
	s_mov_b32 m0, s6
	v_lshl_add_u64 v[170:171], v[166:167], 0, s[54:55]
	v_readfirstlane_b32 s6, v2
	v_add_u32_e32 v2, 0x4000, v130
	s_barrier
; #define LDS_PTR(p) ((__attribute__((address_space(3))) unsigned*)(p))
; template <int PIPE>
; DI void gemm_loop_g(const u16* __restrict__ Xp, long ldx_l, long ldx_i, long kxs,
;                     const u16* __restrict__ Yp, long ldy_l, long ldy_i, long kys, int K,
;                     f32x4 (&acc)[4][8], unsigned char* smem) {
;     ...
;   auto issue = [&](int kt0, int stage) {
;     int kt = kt0 + rot; if (kt >= nk) kt -= nk;
;     unsigned char* sb = smem + stage * 65536 + t * 16;
; #pragma unroll
;     for (int i = 0; i < 4; ++i)
;       __builtin_amdgcn_global_load_lds((const unsigned*)(xs + i * ldx_i + kt * kxs), LDS_PTR(sb + i * 8192), 16, 0, 0);
; #pragma unroll
;     for (int i = 0; i < 4; ++i)
;       __builtin_amdgcn_global_load_lds((const unsigned*)(ys + i * ldy_i + kt * kys), LDS_PTR(sb + 32768 + i * 8192), 16, 0, 0);
;   };
;   __syncthreads();
;   issue(0, 0);
;   asm volatile("s_waitcnt vmcnt(0)" ::: "memory");
;   __syncthreads();
; DI void zero_acc(f32x4 (&acc)[4][8]) {
; #pragma unroll
;   for (int i = 0; i < 4; ++i)
; #pragma unroll
;     for (int j = 0; j < 8; ++j) acc[i][j] = f32x4{0.f, 0.f, 0.f, 0.f};
	global_load_lds_dwordx4 v[0:1], off
	v_lshl_add_u64 v[0:1], v[170:171], 0, s[30:31]
	s_mov_b32 m0, s6
	v_lshl_add_u64 v[172:173], v[166:167], 0, s[56:57]
	v_readfirstlane_b32 s6, v2
	v_add_u32_e32 v2, 0x6000, v130
	global_load_lds_dwordx4 v[0:1], off
	v_lshl_add_u64 v[0:1], v[172:173], 0, s[30:31]
	s_mov_b32 m0, s6
	v_lshl_add_u64 v[174:175], v[166:167], 0, s[58:59]
	v_readfirstlane_b32 s6, v2
	v_add_u32_e32 v2, 0x8000, v130
	global_load_lds_dwordx4 v[0:1], off
	v_lshl_add_u64 v[0:1], v[174:175], 0, s[30:31]
	s_mov_b32 m0, s6
	v_readfirstlane_b32 s6, v2
	v_add_u32_e32 v2, 0xa000, v130
	global_load_lds_dwordx4 v[0:1], off
	v_lshl_add_u64 v[0:1], v[168:169], 0, s[30:31]
	s_mov_b32 m0, s6
	v_lshl_add_u64 v[176:177], v[168:169], 0, s[54:55]
	v_readfirstlane_b32 s6, v2
	v_add_u32_e32 v2, 0xc000, v130
	global_load_lds_dwordx4 v[0:1], off
	v_lshl_add_u64 v[0:1], v[176:177], 0, s[30:31]
	s_mov_b32 m0, s6
	v_lshl_add_u64 v[178:179], v[168:169], 0, s[56:57]
	v_readfirstlane_b32 s6, v2
	v_add_u32_e32 v2, 0xe000, v130
	global_load_lds_dwordx4 v[0:1], off
	v_lshl_add_u64 v[0:1], v[178:179], 0, s[30:31]
	s_mov_b32 m0, s6
	v_lshl_add_u64 v[180:181], v[168:169], 0, s[58:59]
	v_readfirstlane_b32 s6, v2
	global_load_lds_dwordx4 v[0:1], off
	v_lshl_add_u64 v[0:1], v[180:181], 0, s[30:31]
	s_mov_b32 m0, s6
	v_lshlrev_b32_e32 v2, 7, v4
	global_load_lds_dwordx4 v[0:1], off
	v_bfe_u32 v0, v4, 4, 2
	v_bfe_u32 v1, v4, 1, 3
	v_readfirstlane_b32 s10, v4
	s_nop 0
	v_bitop3_b32 v0, v0, v1, 4 bitop3:0x36
	v_and_b32_e32 v2, 0x780, v2
	s_lshl_b32 s6, s10, 8
	s_lshl_b32 s7, s10, 6
	v_lshl_or_b32 v187, v0, 4, v2
	v_bitop3_b32 v0, v5, v1, 3 bitop3:0x6c
	v_mov_b32_e32 v4, 0
	s_and_b32 s6, s6, 0x4000
	s_and_b32 s7, s7, 0xffffe000
	v_lshl_or_b32 v188, v0, 4, v2
	s_mov_b32 s10, 0
	s_mov_b32 s11, 0x10000
	v_mov_b32_e32 v5, v4
	v_mov_b32_e32 v6, v4
	v_mov_b32_e32 v7, v4
	v_mov_b32_e32 v16, v4
	v_mov_b32_e32 v17, v4
	v_mov_b32_e32 v18, v4
	v_mov_b32_e32 v19, v4
	v_mov_b32_e32 v32, v4
	v_mov_b32_e32 v33, v4
	v_mov_b32_e32 v34, v4
	v_mov_b32_e32 v35, v4
	v_mov_b32_e32 v48, v4
	v_mov_b32_e32 v49, v4
	v_mov_b32_e32 v50, v4
	v_mov_b32_e32 v51, v4
	v_mov_b32_e32 v64, v4
	v_mov_b32_e32 v65, v4
	v_mov_b32_e32 v66, v4
	v_mov_b32_e32 v67, v4
	v_mov_b32_e32 v80, v4
	v_mov_b32_e32 v81, v4
	v_mov_b32_e32 v82, v4
	v_mov_b32_e32 v83, v4
	v_mov_b32_e32 v96, v4
	v_mov_b32_e32 v97, v4
	v_mov_b32_e32 v98, v4
	v_mov_b32_e32 v99, v4
	v_mov_b32_e32 v112, v4
	v_mov_b32_e32 v113, v4
	v_mov_b32_e32 v114, v4
	v_mov_b32_e32 v115, v4
	v_mov_b32_e32 v0, v4
	v_mov_b32_e32 v1, v4
	v_mov_b32_e32 v2, v4
	v_mov_b32_e32 v3, v4
	v_mov_b32_e32 v20, v4
	v_mov_b32_e32 v21, v4
	v_mov_b32_e32 v22, v4
	v_mov_b32_e32 v23, v4
	v_mov_b32_e32 v36, v4
	v_mov_b32_e32 v37, v4
	v_mov_b32_e32 v38, v4
	v_mov_b32_e32 v39, v4
	v_mov_b32_e32 v52, v4
	v_mov_b32_e32 v53, v4
	v_mov_b32_e32 v54, v4
	v_mov_b32_e32 v55, v4
	v_mov_b32_e32 v68, v4
	v_mov_b32_e32 v69, v4
	v_mov_b32_e32 v70, v4
	v_mov_b32_e32 v71, v4
	v_mov_b32_e32 v84, v4
	v_mov_b32_e32 v85, v4
	v_mov_b32_e32 v86, v4
	v_mov_b32_e32 v87, v4
	v_mov_b32_e32 v100, v4
	v_mov_b32_e32 v101, v4
	v_mov_b32_e32 v102, v4
	v_mov_b32_e32 v103, v4
	v_mov_b32_e32 v116, v4
	v_mov_b32_e32 v117, v4
	v_mov_b32_e32 v118, v4
	v_mov_b32_e32 v119, v4
	v_mov_b32_e32 v8, v4
	v_mov_b32_e32 v9, v4
	v_mov_b32_e32 v10, v4
	v_mov_b32_e32 v11, v4
	v_mov_b32_e32 v24, v4
	v_mov_b32_e32 v25, v4
	v_mov_b32_e32 v26, v4
	v_mov_b32_e32 v27, v4
	v_mov_b32_e32 v40, v4
	v_mov_b32_e32 v41, v4
	v_mov_b32_e32 v42, v4
	v_mov_b32_e32 v43, v4
	v_mov_b32_e32 v56, v4
	v_mov_b32_e32 v57, v4
	v_mov_b32_e32 v58, v4
	v_mov_b32_e32 v59, v4
	v_mov_b32_e32 v72, v4
	v_mov_b32_e32 v73, v4
	v_mov_b32_e32 v74, v4
	v_mov_b32_e32 v75, v4
	v_mov_b32_e32 v88, v4
	v_mov_b32_e32 v89, v4
	v_mov_b32_e32 v90, v4
	v_mov_b32_e32 v91, v4
	v_mov_b32_e32 v104, v4
	v_mov_b32_e32 v105, v4
	v_mov_b32_e32 v106, v4
	v_mov_b32_e32 v107, v4
	v_mov_b32_e32 v120, v4
	v_mov_b32_e32 v121, v4
	v_mov_b32_e32 v122, v4
	v_mov_b32_e32 v123, v4
	v_mov_b32_e32 v12, v4
	v_mov_b32_e32 v13, v4
	v_mov_b32_e32 v14, v4
	v_mov_b32_e32 v15, v4
	v_mov_b32_e32 v28, v4
	v_mov_b32_e32 v29, v4
	v_mov_b32_e32 v30, v4
	v_mov_b32_e32 v31, v4
	v_mov_b32_e32 v44, v4
	v_mov_b32_e32 v45, v4
	v_mov_b32_e32 v46, v4
	v_mov_b32_e32 v47, v4
	v_mov_b32_e32 v60, v4
	v_mov_b32_e32 v61, v4
	v_mov_b32_e32 v62, v4
	v_mov_b32_e32 v63, v4
	v_mov_b32_e32 v76, v4
	v_mov_b32_e32 v77, v4
	v_mov_b32_e32 v78, v4
	v_mov_b32_e32 v79, v4
	v_mov_b32_e32 v92, v4
	v_mov_b32_e32 v93, v4
	v_mov_b32_e32 v94, v4
	v_mov_b32_e32 v95, v4
	v_mov_b32_e32 v108, v4
	v_mov_b32_e32 v109, v4
	v_mov_b32_e32 v110, v4
	v_mov_b32_e32 v111, v4
	v_mov_b32_e32 v124, v4
	v_mov_b32_e32 v125, v4
	v_mov_b32_e32 v126, v4
	v_mov_b32_e32 v127, v4
	s_add_i32 s8, s68, s10
	s_cmp_lt_u32 s8, 16
	s_cselect_b32 s9, 0, -16
	s_add_i32 s8, s8, s9
	s_and_b32 s9, s11, 0x10000
	v_add_u32_e32 v189, s9, v130
	s_ashr_i32 s9, s8, 31
	s_lshl_b64 s[8:9], s[8:9], 7
	v_readfirstlane_b32 s12, v189
	v_add_u32_e32 v192, 0x2000, v189
	v_lshl_add_u64 v[190:191], v[166:167], 0, s[8:9]
	s_mov_b32 m0, s12
	v_readfirstlane_b32 s12, v192
	v_add_u32_e32 v192, 0x4000, v189
	global_load_lds_dwordx4 v[190:191], off
	v_lshl_add_u64 v[190:191], v[170:171], 0, s[8:9]
	s_mov_b32 m0, s12
	v_readfirstlane_b32 s12, v192
	v_add_u32_e32 v192, 0x6000, v189
	global_load_lds_dwordx4 v[190:191], off
	v_lshl_add_u64 v[190:191], v[172:173], 0, s[8:9]
	s_mov_b32 m0, s12
	v_readfirstlane_b32 s12, v192
	v_add_u32_e32 v192, 0x8000, v189
	global_load_lds_dwordx4 v[190:191], off
	v_lshl_add_u64 v[190:191], v[174:175], 0, s[8:9]
	s_mov_b32 m0, s12
	v_readfirstlane_b32 s12, v192
	v_add_u32_e32 v192, 0xa000, v189
	global_load_lds_dwordx4 v[190:191], off
	v_lshl_add_u64 v[190:191], v[168:169], 0, s[8:9]
	s_mov_b32 m0, s12
	v_readfirstlane_b32 s12, v192
	v_add_u32_e32 v192, 0xc000, v189
	global_load_lds_dwordx4 v[190:191], off
	v_lshl_add_u64 v[190:191], v[176:177], 0, s[8:9]
	s_mov_b32 m0, s12
	v_readfirstlane_b32 s12, v192
	global_load_lds_dwordx4 v[190:191], off
	v_lshl_add_u64 v[190:191], v[178:179], 0, s[8:9]
	s_mov_b32 m0, s12
	v_add_u32_e32 v189, 0xe000, v189
	global_load_lds_dwordx4 v[190:191], off
	v_lshl_add_u64 v[190:191], v[180:181], 0, s[8:9]
	v_readfirstlane_b32 s8, v189
	s_mov_b32 m0, s8
	s_nop 0
	global_load_lds_dwordx4 v[190:191], off
	s_waitcnt vmcnt(8) lgkmcnt(0)
	s_barrier
	s_branch .LBB0_528

; template <int MODE>
; DI void gemm_phase(const Params& p, const GP& g, unsigned char* smem) {
;     ...
;       const int ml = e / g.ntn;
;       nt = e - ml * g.ntn;
;       mt = xcd + 8 * ml;
;     }
;     if (MODE == M_SEQ) { bsel = mt >> 4; mt &= 15; Wb = g.W + (long)bsel * 1024 * 8192; }
;     const int m0 = mt * 256, n0 = nt * 256;
;     f32x4 acc[4][8];
;     zero_acc(acc);
;     int transposed = 0;
;     if (MODE == M_FN_IN) transposed = nt < 8;
;     if (MODE == M_NA_IN) transposed = (nt >= 8 && nt < 12);
;     if (MODE == M_MLA_UKV) transposed = nt >= 4;
;     if (MODE == M_HG_IN) transposed = nt >= 12;
;     ...
;       const u16* Ap = Ab + (long)m0 * g.lda; const u16* Wp = Wb + (long)n0 * g.K;
;       if (transposed) gemm_loop(Ap, g.lda, Wp, g.K, g.K, acc, smem);
;       else gemm_loop(Wp, g.K, Ap, g.lda, g.K, acc, smem);
.LBB0_560:
	s_lshl_b32 s6, s74, 7
	s_and_b32 s6, s6, 0xfffff800
	s_and_b32 s75, s74, 15
	s_or_b32 s64, s6, s59
	s_cmp_lt_u32 s75, 12
	s_cselect_b64 s[10:11], -1, 0
	s_ashr_i32 s65, s64, 31
	s_lshl_b64 s[6:7], s[64:65], 11
	s_add_u32 s14, s16, s6
	s_addc_u32 s15, s17, s7
	s_lshl_b32 s6, s75, 19
	s_add_u32 s12, s18, s6
	s_addc_u32 s13, s19, 0
	s_mov_b64 s[66:67], -1
	s_and_b64 vcc, exec, s[10:11]
	s_cbranch_vccz .LBB0_566
	v_mov_b32_e32 v4, v182
	s_nop 0
	v_ashrrev_i32_e32 v0, 3, v4
	v_lshrrev_b32_e32 v5, 4, v4
	v_xor_b32_e32 v6, v5, v4
	v_ashrrev_i32_e32 v1, 31, v0
	v_lshlrev_b64 v[0:1], 11, v[0:1]
	v_lshlrev_b32_e32 v6, 4, v6
	v_lshl_add_u64 v[2:3], s[12:13], 0, v[0:1]
	v_and_b32_e32 v128, 0x70, v6
	v_lshl_add_u64 v[0:1], s[14:15], 0, v[0:1]
	v_lshl_add_u64 v[130:131], v[2:3], 0, v[128:129]
	v_lshl_add_u64 v[132:133], v[0:1], 0, v[128:129]
	v_lshlrev_b32_e32 v128, 4, v4
	v_add_u32_e32 v2, 0x2000, v128
	v_readfirstlane_b32 s6, v128
	v_lshl_add_u64 v[0:1], v[130:131], 0, s[28:29]
	s_mov_b32 m0, s6
	v_lshl_add_u64 v[134:135], v[130:131], 0, s[30:31]
	v_readfirstlane_b32 s6, v2
	v_add_u32_e32 v2, 0x4000, v128
	s_barrier
; #define LDS_PTR(p) ((__attribute__((address_space(3))) unsigned*)(p))
; template <int PIPE>
; DI void gemm_loop_g(const u16* __restrict__ Xp, long ldx_l, long ldx_i, long kxs,
;                     const u16* __restrict__ Yp, long ldy_l, long ldy_i, long kys, int K,
;                     f32x4 (&acc)[4][8], unsigned char* smem) {
;     ...
;   auto issue = [&](int kt0, int stage) {
;     int kt = kt0 + rot; if (kt >= nk) kt -= nk;
;     unsigned char* sb = smem + stage * 65536 + t * 16;
; #pragma unroll
;     for (int i = 0; i < 4; ++i)
;       __builtin_amdgcn_global_load_lds((const unsigned*)(xs + i * ldx_i + kt * kxs), LDS_PTR(sb + i * 8192), 16, 0, 0);
; #pragma unroll
;     for (int i = 0; i < 4; ++i)
;       __builtin_amdgcn_global_load_lds((const unsigned*)(ys + i * ldy_i + kt * kys), LDS_PTR(sb + 32768 + i * 8192), 16, 0, 0);
;   };
;   __syncthreads();
;   issue(0, 0);
;   asm volatile("s_waitcnt vmcnt(0)" ::: "memory");
;   __syncthreads();
; DI void zero_acc(f32x4 (&acc)[4][8]) {
; #pragma unroll
;   for (int i = 0; i < 4; ++i)
; #pragma unroll
;     for (int j = 0; j < 8; ++j) acc[i][j] = f32x4{0.f, 0.f, 0.f, 0.f};
	global_load_lds_dwordx4 v[0:1], off
	v_lshl_add_u64 v[0:1], v[134:135], 0, s[28:29]
	s_mov_b32 m0, s6
	v_lshl_add_u64 v[136:137], v[130:131], 0, s[54:55]
	v_readfirstlane_b32 s6, v2
	v_add_u32_e32 v2, 0x6000, v128
	global_load_lds_dwordx4 v[0:1], off
	v_lshl_add_u64 v[0:1], v[136:137], 0, s[28:29]
	s_mov_b32 m0, s6
	v_lshl_add_u64 v[138:139], v[130:131], 0, s[56:57]
	v_readfirstlane_b32 s6, v2
	v_add_u32_e32 v2, 0x8000, v128
	global_load_lds_dwordx4 v[0:1], off
	v_lshl_add_u64 v[0:1], v[138:139], 0, s[28:29]
	s_mov_b32 m0, s6
	v_readfirstlane_b32 s6, v2
	v_add_u32_e32 v2, 0xa000, v128
	global_load_lds_dwordx4 v[0:1], off
	v_lshl_add_u64 v[0:1], v[132:133], 0, s[28:29]
	s_mov_b32 m0, s6
	v_lshl_add_u64 v[140:141], v[132:133], 0, s[30:31]
	v_readfirstlane_b32 s6, v2
	v_add_u32_e32 v2, 0xc000, v128
	global_load_lds_dwordx4 v[0:1], off
	v_lshl_add_u64 v[0:1], v[140:141], 0, s[28:29]
	s_mov_b32 m0, s6
	v_lshl_add_u64 v[142:143], v[132:133], 0, s[54:55]
	v_readfirstlane_b32 s6, v2
	v_add_u32_e32 v2, 0xe000, v128
	global_load_lds_dwordx4 v[0:1], off
	v_lshl_add_u64 v[0:1], v[142:143], 0, s[28:29]
	s_mov_b32 m0, s6
	v_lshl_add_u64 v[144:145], v[132:133], 0, s[56:57]
	v_readfirstlane_b32 s6, v2
	global_load_lds_dwordx4 v[0:1], off
	v_lshl_add_u64 v[0:1], v[144:145], 0, s[28:29]
	s_mov_b32 m0, s6
	v_lshlrev_b32_e32 v2, 7, v4
	global_load_lds_dwordx4 v[0:1], off
	v_bfe_u32 v0, v4, 4, 2
	v_bfe_u32 v1, v4, 1, 3
	v_readfirstlane_b32 s7, v4
	s_nop 0
	v_bitop3_b32 v0, v0, v1, 4 bitop3:0x36
	v_and_b32_e32 v2, 0x780, v2
	s_lshl_b32 s6, s7, 8
	s_lshl_b32 s7, s7, 6
	v_lshl_or_b32 v154, v0, 4, v2
	v_bitop3_b32 v0, v5, v1, 3 bitop3:0x6c
	v_mov_b32_e32 v8, 0
	s_and_b32 s6, s6, 0x4000
	s_and_b32 s7, s7, 0xffffe000
	v_lshl_or_b32 v155, v0, 4, v2
	s_mov_b32 s33, 0
	s_mov_b32 s48, 0x10000
	v_mov_b32_e32 v9, v8
	v_mov_b32_e32 v10, v8
	v_mov_b32_e32 v11, v8
	v_mov_b32_e32 v12, v8
	v_mov_b32_e32 v13, v8
	v_mov_b32_e32 v14, v8
	v_mov_b32_e32 v15, v8
	v_mov_b32_e32 v28, v8
	v_mov_b32_e32 v29, v8
	v_mov_b32_e32 v30, v8
	v_mov_b32_e32 v31, v8
	v_mov_b32_e32 v44, v8
	v_mov_b32_e32 v45, v8
	v_mov_b32_e32 v46, v8
	v_mov_b32_e32 v47, v8
	v_mov_b32_e32 v60, v8
	v_mov_b32_e32 v61, v8
	v_mov_b32_e32 v62, v8
	v_mov_b32_e32 v63, v8
	v_mov_b32_e32 v76, v8
	v_mov_b32_e32 v77, v8
	v_mov_b32_e32 v78, v8
	v_mov_b32_e32 v79, v8
	v_mov_b32_e32 v92, v8
	v_mov_b32_e32 v93, v8
	v_mov_b32_e32 v94, v8
	v_mov_b32_e32 v95, v8
	v_mov_b32_e32 v108, v8
	v_mov_b32_e32 v109, v8
	v_mov_b32_e32 v110, v8
	v_mov_b32_e32 v111, v8
	v_mov_b32_e32 v0, v8
	v_mov_b32_e32 v1, v8
	v_mov_b32_e32 v2, v8
	v_mov_b32_e32 v3, v8
	v_mov_b32_e32 v20, v8
	v_mov_b32_e32 v21, v8
	v_mov_b32_e32 v22, v8
	v_mov_b32_e32 v23, v8
	v_mov_b32_e32 v36, v8
	v_mov_b32_e32 v37, v8
	v_mov_b32_e32 v38, v8
	v_mov_b32_e32 v39, v8
	v_mov_b32_e32 v52, v8
	v_mov_b32_e32 v53, v8
	v_mov_b32_e32 v54, v8
	v_mov_b32_e32 v55, v8
	v_mov_b32_e32 v68, v8
	v_mov_b32_e32 v69, v8
	v_mov_b32_e32 v70, v8
	v_mov_b32_e32 v71, v8
	v_mov_b32_e32 v84, v8
	v_mov_b32_e32 v85, v8
	v_mov_b32_e32 v86, v8
	v_mov_b32_e32 v87, v8
	v_mov_b32_e32 v100, v8
	v_mov_b32_e32 v101, v8
	v_mov_b32_e32 v102, v8
	v_mov_b32_e32 v103, v8
	v_mov_b32_e32 v116, v8
	v_mov_b32_e32 v117, v8
	v_mov_b32_e32 v118, v8
	v_mov_b32_e32 v119, v8
	v_mov_b32_e32 v4, v8
	v_mov_b32_e32 v5, v8
	v_mov_b32_e32 v6, v8
	v_mov_b32_e32 v7, v8
	v_mov_b32_e32 v24, v8
	v_mov_b32_e32 v25, v8
	v_mov_b32_e32 v26, v8
	v_mov_b32_e32 v27, v8
	v_mov_b32_e32 v40, v8
	v_mov_b32_e32 v41, v8
	v_mov_b32_e32 v42, v8
	v_mov_b32_e32 v43, v8
	v_mov_b32_e32 v56, v8
	v_mov_b32_e32 v57, v8
	v_mov_b32_e32 v58, v8
	v_mov_b32_e32 v59, v8
	v_mov_b32_e32 v72, v8
	v_mov_b32_e32 v73, v8
	v_mov_b32_e32 v74, v8
	v_mov_b32_e32 v75, v8
	v_mov_b32_e32 v88, v8
	v_mov_b32_e32 v89, v8
	v_mov_b32_e32 v90, v8
	v_mov_b32_e32 v91, v8
	v_mov_b32_e32 v104, v8
	v_mov_b32_e32 v105, v8
	v_mov_b32_e32 v106, v8
	v_mov_b32_e32 v107, v8
	v_mov_b32_e32 v120, v8
	v_mov_b32_e32 v121, v8
	v_mov_b32_e32 v122, v8
	v_mov_b32_e32 v123, v8
	v_mov_b32_e32 v16, v8
	v_mov_b32_e32 v17, v8
	v_mov_b32_e32 v18, v8
	v_mov_b32_e32 v19, v8
	v_mov_b32_e32 v32, v8
	v_mov_b32_e32 v33, v8
	v_mov_b32_e32 v34, v8
	v_mov_b32_e32 v35, v8
	v_mov_b32_e32 v48, v8
	v_mov_b32_e32 v49, v8
	v_mov_b32_e32 v50, v8
	v_mov_b32_e32 v51, v8
	v_mov_b32_e32 v64, v8
	v_mov_b32_e32 v65, v8
	v_mov_b32_e32 v66, v8
	v_mov_b32_e32 v67, v8
	v_mov_b32_e32 v80, v8
	v_mov_b32_e32 v81, v8
	v_mov_b32_e32 v82, v8
	v_mov_b32_e32 v83, v8
	v_mov_b32_e32 v96, v8
	v_mov_b32_e32 v97, v8
	v_mov_b32_e32 v98, v8
	v_mov_b32_e32 v99, v8
	v_mov_b32_e32 v112, v8
	v_mov_b32_e32 v113, v8
	v_mov_b32_e32 v114, v8
	v_mov_b32_e32 v115, v8
	v_mov_b32_e32 v124, v8
	v_mov_b32_e32 v125, v8
	v_mov_b32_e32 v126, v8
	v_mov_b32_e32 v127, v8
	s_add_i32 s8, s63, s33
	s_cmp_lt_u32 s8, 16
	s_cselect_b32 s9, 0, -16
	s_add_i32 s8, s8, s9
	s_and_b32 s9, s48, 0x10000
	v_add_u32_e32 v158, s9, v128
	s_ashr_i32 s9, s8, 31
	s_lshl_b64 s[8:9], s[8:9], 7
	v_readfirstlane_b32 s40, v158
	v_add_u32_e32 v159, 0x2000, v158
	v_lshl_add_u64 v[156:157], v[130:131], 0, s[8:9]
	s_mov_b32 m0, s40
	v_readfirstlane_b32 s40, v159
	v_add_u32_e32 v159, 0x4000, v158
	global_load_lds_dwordx4 v[156:157], off
	v_lshl_add_u64 v[156:157], v[134:135], 0, s[8:9]
	s_mov_b32 m0, s40
	v_readfirstlane_b32 s40, v159
	v_add_u32_e32 v159, 0x6000, v158
	global_load_lds_dwordx4 v[156:157], off
	v_lshl_add_u64 v[156:157], v[136:137], 0, s[8:9]
	s_mov_b32 m0, s40
	v_readfirstlane_b32 s40, v159
	v_add_u32_e32 v159, 0x8000, v158
	global_load_lds_dwordx4 v[156:157], off
	v_lshl_add_u64 v[156:157], v[138:139], 0, s[8:9]
	s_mov_b32 m0, s40
	v_readfirstlane_b32 s40, v159
	v_add_u32_e32 v159, 0xa000, v158
	global_load_lds_dwordx4 v[156:157], off
	v_lshl_add_u64 v[156:157], v[132:133], 0, s[8:9]
	s_mov_b32 m0, s40
	v_readfirstlane_b32 s40, v159
	v_add_u32_e32 v159, 0xc000, v158
	global_load_lds_dwordx4 v[156:157], off
	v_lshl_add_u64 v[156:157], v[140:141], 0, s[8:9]
	s_mov_b32 m0, s40
	v_readfirstlane_b32 s40, v159
	global_load_lds_dwordx4 v[156:157], off
	v_lshl_add_u64 v[156:157], v[142:143], 0, s[8:9]
	s_mov_b32 m0, s40
	v_add_u32_e32 v158, 0xe000, v158
	global_load_lds_dwordx4 v[156:157], off
	v_lshl_add_u64 v[156:157], v[144:145], 0, s[8:9]
	v_readfirstlane_b32 s8, v158
	s_mov_b32 m0, s8
	s_nop 0
	global_load_lds_dwordx4 v[156:157], off
	s_waitcnt vmcnt(8) lgkmcnt(0)
	s_barrier
	s_branch .LBB0_562

; template <int MODE>
; DI void gemm_phase(const Params& p, const GP& g, unsigned char* smem) {
;     ...
;     if (MODE == M_HG_IN) transposed = nt >= 12;
;     ...
;       const u16* Ap = Ab + (long)m0 * g.lda; const u16* Wp = Wb + (long)n0 * g.K;
;       if (transposed) gemm_loop(Ap, g.lda, Wp, g.K, g.K, acc, smem);
.LBB0_566:
	s_and_b64 vcc, exec, s[66:67]
	s_cbranch_vccz .LBB0_571
	s_nop 1
	v_mov_b32_e32 v4, v182
	s_nop 0
	v_ashrrev_i32_e32 v0, 3, v4
	v_lshrrev_b32_e32 v5, 4, v4
	v_xor_b32_e32 v6, v5, v4
	v_ashrrev_i32_e32 v1, 31, v0
	v_lshlrev_b64 v[0:1], 11, v[0:1]
	v_lshlrev_b32_e32 v6, 4, v6
	v_lshl_add_u64 v[2:3], s[14:15], 0, v[0:1]
	v_and_b32_e32 v128, 0x70, v6
	v_lshl_add_u64 v[0:1], s[12:13], 0, v[0:1]
	v_lshl_add_u64 v[130:131], v[2:3], 0, v[128:129]
	v_lshl_add_u64 v[132:133], v[0:1], 0, v[128:129]
	v_lshlrev_b32_e32 v128, 4, v4
	v_add_u32_e32 v2, 0x2000, v128
	v_readfirstlane_b32 s6, v128
	v_lshl_add_u64 v[0:1], v[130:131], 0, s[28:29]
	s_mov_b32 m0, s6
	v_lshl_add_u64 v[134:135], v[130:131], 0, s[30:31]
	v_readfirstlane_b32 s6, v2
	v_add_u32_e32 v2, 0x4000, v128
	s_barrier
; #define LDS_PTR(p) ((__attribute__((address_space(3))) unsigned*)(p))
; template <int PIPE>
; DI void gemm_loop_g(const u16* __restrict__ Xp, long ldx_l, long ldx_i, long kxs,
;                     const u16* __restrict__ Yp, long ldy_l, long ldy_i, long kys, int K,
;                     f32x4 (&acc)[4][8], unsigned char* smem) {
;     ...
;   auto issue = [&](int kt0, int stage) {
;     int kt = kt0 + rot; if (kt >= nk) kt -= nk;
;     unsigned char* sb = smem + stage * 65536 + t * 16;
; #pragma unroll
;     for (int i = 0; i < 4; ++i)
;       __builtin_amdgcn_global_load_lds((const unsigned*)(xs + i * ldx_i + kt * kxs), LDS_PTR(sb + i * 8192), 16, 0, 0);
; #pragma unroll
;     for (int i = 0; i < 4; ++i)
;       __builtin_amdgcn_global_load_lds((const unsigned*)(ys + i * ldy_i + kt * kys), LDS_PTR(sb + 32768 + i * 8192), 16, 0, 0);
;   };
;   __syncthreads();
;   issue(0, 0);
;   asm volatile("s_waitcnt vmcnt(0)" ::: "memory");
;   __syncthreads();
; DI void zero_acc(f32x4 (&acc)[4][8]) {
; #pragma unroll
;   for (int i = 0; i < 4; ++i)
; #pragma unroll
;     for (int j = 0; j < 8; ++j) acc[i][j] = f32x4{0.f, 0.f, 0.f, 0.f};
	global_load_lds_dwordx4 v[0:1], off
	v_lshl_add_u64 v[0:1], v[134:135], 0, s[28:29]
	s_mov_b32 m0, s6
	v_lshl_add_u64 v[136:137], v[130:131], 0, s[54:55]
	v_readfirstlane_b32 s6, v2
	v_add_u32_e32 v2, 0x6000, v128
	global_load_lds_dwordx4 v[0:1], off
	v_lshl_add_u64 v[0:1], v[136:137], 0, s[28:29]
	s_mov_b32 m0, s6
	v_lshl_add_u64 v[138:139], v[130:131], 0, s[56:57]
	v_readfirstlane_b32 s6, v2
	v_add_u32_e32 v2, 0x8000, v128
	global_load_lds_dwordx4 v[0:1], off
	v_lshl_add_u64 v[0:1], v[138:139], 0, s[28:29]
	s_mov_b32 m0, s6
	v_readfirstlane_b32 s6, v2
	v_add_u32_e32 v2, 0xa000, v128
	global_load_lds_dwordx4 v[0:1], off
	v_lshl_add_u64 v[0:1], v[132:133], 0, s[28:29]
	s_mov_b32 m0, s6
	v_lshl_add_u64 v[140:141], v[132:133], 0, s[30:31]
	v_readfirstlane_b32 s6, v2
	v_add_u32_e32 v2, 0xc000, v128
	global_load_lds_dwordx4 v[0:1], off
	v_lshl_add_u64 v[0:1], v[140:141], 0, s[28:29]
	s_mov_b32 m0, s6
	v_lshl_add_u64 v[142:143], v[132:133], 0, s[54:55]
	v_readfirstlane_b32 s6, v2
	v_add_u32_e32 v2, 0xe000, v128
	global_load_lds_dwordx4 v[0:1], off
	v_lshl_add_u64 v[0:1], v[142:143], 0, s[28:29]
	s_mov_b32 m0, s6
	v_lshl_add_u64 v[144:145], v[132:133], 0, s[56:57]
	v_readfirstlane_b32 s6, v2
	global_load_lds_dwordx4 v[0:1], off
	v_lshl_add_u64 v[0:1], v[144:145], 0, s[28:29]
	s_mov_b32 m0, s6
	v_lshlrev_b32_e32 v2, 7, v4
	global_load_lds_dwordx4 v[0:1], off
	v_bfe_u32 v0, v4, 4, 2
	v_bfe_u32 v1, v4, 1, 3
	v_readfirstlane_b32 s7, v4
	s_nop 0
	v_bitop3_b32 v0, v0, v1, 4 bitop3:0x36
	v_and_b32_e32 v2, 0x780, v2
	s_lshl_b32 s6, s7, 8
	s_lshl_b32 s7, s7, 6
	v_lshl_or_b32 v154, v0, 4, v2
	v_bitop3_b32 v0, v5, v1, 3 bitop3:0x6c
	v_mov_b32_e32 v8, 0
	s_and_b32 s6, s6, 0x4000
	s_and_b32 s7, s7, 0xffffe000
	v_lshl_or_b32 v155, v0, 4, v2
	s_mov_b32 s12, 0
	s_mov_b32 s13, 0x10000
	v_mov_b32_e32 v9, v8
	v_mov_b32_e32 v10, v8
	v_mov_b32_e32 v11, v8
	v_mov_b32_e32 v12, v8
	v_mov_b32_e32 v13, v8
	v_mov_b32_e32 v14, v8
	v_mov_b32_e32 v15, v8
	v_mov_b32_e32 v28, v8
	v_mov_b32_e32 v29, v8
	v_mov_b32_e32 v30, v8
	v_mov_b32_e32 v31, v8
	v_mov_b32_e32 v44, v8
	v_mov_b32_e32 v45, v8
	v_mov_b32_e32 v46, v8
	v_mov_b32_e32 v47, v8
	v_mov_b32_e32 v60, v8
	v_mov_b32_e32 v61, v8
	v_mov_b32_e32 v62, v8
	v_mov_b32_e32 v63, v8
	v_mov_b32_e32 v76, v8
	v_mov_b32_e32 v77, v8
	v_mov_b32_e32 v78, v8
	v_mov_b32_e32 v79, v8
	v_mov_b32_e32 v92, v8
	v_mov_b32_e32 v93, v8
	v_mov_b32_e32 v94, v8
	v_mov_b32_e32 v95, v8
	v_mov_b32_e32 v108, v8
	v_mov_b32_e32 v109, v8
	v_mov_b32_e32 v110, v8
	v_mov_b32_e32 v111, v8
	v_mov_b32_e32 v0, v8
	v_mov_b32_e32 v1, v8
	v_mov_b32_e32 v2, v8
	v_mov_b32_e32 v3, v8
	v_mov_b32_e32 v20, v8
	v_mov_b32_e32 v21, v8
	v_mov_b32_e32 v22, v8
	v_mov_b32_e32 v23, v8
	v_mov_b32_e32 v36, v8
	v_mov_b32_e32 v37, v8
	v_mov_b32_e32 v38, v8
	v_mov_b32_e32 v39, v8
	v_mov_b32_e32 v52, v8
	v_mov_b32_e32 v53, v8
	v_mov_b32_e32 v54, v8
	v_mov_b32_e32 v55, v8
	v_mov_b32_e32 v68, v8
	v_mov_b32_e32 v69, v8
	v_mov_b32_e32 v70, v8
	v_mov_b32_e32 v71, v8
	v_mov_b32_e32 v84, v8
	v_mov_b32_e32 v85, v8
	v_mov_b32_e32 v86, v8
	v_mov_b32_e32 v87, v8
	v_mov_b32_e32 v100, v8
	v_mov_b32_e32 v101, v8
	v_mov_b32_e32 v102, v8
	v_mov_b32_e32 v103, v8
	v_mov_b32_e32 v116, v8
	v_mov_b32_e32 v117, v8
	v_mov_b32_e32 v118, v8
	v_mov_b32_e32 v119, v8
	v_mov_b32_e32 v4, v8
	v_mov_b32_e32 v5, v8
	v_mov_b32_e32 v6, v8
	v_mov_b32_e32 v7, v8
	v_mov_b32_e32 v24, v8
	v_mov_b32_e32 v25, v8
	v_mov_b32_e32 v26, v8
	v_mov_b32_e32 v27, v8
	v_mov_b32_e32 v40, v8
	v_mov_b32_e32 v41, v8
	v_mov_b32_e32 v42, v8
	v_mov_b32_e32 v43, v8
	v_mov_b32_e32 v56, v8
	v_mov_b32_e32 v57, v8
	v_mov_b32_e32 v58, v8
	v_mov_b32_e32 v59, v8
	v_mov_b32_e32 v72, v8
	v_mov_b32_e32 v73, v8
	v_mov_b32_e32 v74, v8
	v_mov_b32_e32 v75, v8
	v_mov_b32_e32 v88, v8
	v_mov_b32_e32 v89, v8
	v_mov_b32_e32 v90, v8
	v_mov_b32_e32 v91, v8
	v_mov_b32_e32 v104, v8
	v_mov_b32_e32 v105, v8
	v_mov_b32_e32 v106, v8
	v_mov_b32_e32 v107, v8
	v_mov_b32_e32 v120, v8
	v_mov_b32_e32 v121, v8
	v_mov_b32_e32 v122, v8
	v_mov_b32_e32 v123, v8
	v_mov_b32_e32 v16, v8
	v_mov_b32_e32 v17, v8
	v_mov_b32_e32 v18, v8
	v_mov_b32_e32 v19, v8
	v_mov_b32_e32 v32, v8
	v_mov_b32_e32 v33, v8
	v_mov_b32_e32 v34, v8
	v_mov_b32_e32 v35, v8
	v_mov_b32_e32 v48, v8
	v_mov_b32_e32 v49, v8
	v_mov_b32_e32 v50, v8
	v_mov_b32_e32 v51, v8
	v_mov_b32_e32 v64, v8
	v_mov_b32_e32 v65, v8
	v_mov_b32_e32 v66, v8
	v_mov_b32_e32 v67, v8
	v_mov_b32_e32 v80, v8
	v_mov_b32_e32 v81, v8
	v_mov_b32_e32 v82, v8
	v_mov_b32_e32 v83, v8
	v_mov_b32_e32 v96, v8
	v_mov_b32_e32 v97, v8
	v_mov_b32_e32 v98, v8
	v_mov_b32_e32 v99, v8
	v_mov_b32_e32 v112, v8
	v_mov_b32_e32 v113, v8
	v_mov_b32_e32 v114, v8
	v_mov_b32_e32 v115, v8
	v_mov_b32_e32 v124, v8
	v_mov_b32_e32 v125, v8
	v_mov_b32_e32 v126, v8
	v_mov_b32_e32 v127, v8
	s_add_i32 s8, s63, s12
	s_cmp_lt_u32 s8, 16
	s_cselect_b32 s9, 0, -16
	s_add_i32 s8, s8, s9
	s_and_b32 s9, s13, 0x10000
	v_add_u32_e32 v158, s9, v128
	s_ashr_i32 s9, s8, 31
	s_lshl_b64 s[8:9], s[8:9], 7
	v_readfirstlane_b32 s14, v158
	v_add_u32_e32 v159, 0x2000, v158
	v_lshl_add_u64 v[156:157], v[130:131], 0, s[8:9]
	s_mov_b32 m0, s14
	v_readfirstlane_b32 s14, v159
	v_add_u32_e32 v159, 0x4000, v158
	global_load_lds_dwordx4 v[156:157], off
	v_lshl_add_u64 v[156:157], v[134:135], 0, s[8:9]
	s_mov_b32 m0, s14
	v_readfirstlane_b32 s14, v159
	v_add_u32_e32 v159, 0x6000, v158
	global_load_lds_dwordx4 v[156:157], off
	v_lshl_add_u64 v[156:157], v[136:137], 0, s[8:9]
	s_mov_b32 m0, s14
	v_readfirstlane_b32 s14, v159
	v_add_u32_e32 v159, 0x8000, v158
	global_load_lds_dwordx4 v[156:157], off
	v_lshl_add_u64 v[156:157], v[138:139], 0, s[8:9]
	s_mov_b32 m0, s14
	v_readfirstlane_b32 s14, v159
	v_add_u32_e32 v159, 0xa000, v158
	global_load_lds_dwordx4 v[156:157], off
	v_lshl_add_u64 v[156:157], v[132:133], 0, s[8:9]
	s_mov_b32 m0, s14
	v_readfirstlane_b32 s14, v159
	v_add_u32_e32 v159, 0xc000, v158
	global_load_lds_dwordx4 v[156:157], off
	v_lshl_add_u64 v[156:157], v[140:141], 0, s[8:9]
	s_mov_b32 m0, s14
	v_readfirstlane_b32 s14, v159
	global_load_lds_dwordx4 v[156:157], off
	v_lshl_add_u64 v[156:157], v[142:143], 0, s[8:9]
	s_mov_b32 m0, s14
	v_add_u32_e32 v158, 0xe000, v158
	global_load_lds_dwordx4 v[156:157], off
	v_lshl_add_u64 v[156:157], v[144:145], 0, s[8:9]
	v_readfirstlane_b32 s8, v158
	s_mov_b32 m0, s8
	s_nop 0
	global_load_lds_dwordx4 v[156:157], off
	s_waitcnt vmcnt(8) lgkmcnt(0)
	s_barrier
	s_branch .LBB0_568

; DI u32x2 pack4(float a, float b, float c, float d) { u32x2 r; r.x = pack2(a, b); r.y = pack2(c, d); return r; }
; #define EPI_END if (i == 3 && (j & 3) == 3) __builtin_amdgcn_sched_barrier(0); }
; template <int MODE>
; DI void gemm_phase(const Params& p, const GP& g, unsigned char* smem) {
;     ...
;   for (int e = slot; e < nent; e += nslot) {
;     int mt, nt;
;     const u16* Ab = g.A; const u16* Wb = g.W;
;     int bsel = 0;
;     {
;       const int ml = e / g.ntn;
;       nt = e - ml * g.ntn;
;       mt = xcd + 8 * ml;
;     }
;     if (MODE == M_SEQ) { bsel = mt >> 4; mt &= 15; Wb = g.W + (long)bsel * 1024 * 8192; }
;     const int m0 = mt * 256, n0 = nt * 256;
;     f32x4 acc[4][8];
;     zero_acc(acc);
;     int transposed = 0;
;     if (MODE == M_FN_IN) transposed = nt < 8;
;     if (MODE == M_NA_IN) transposed = (nt >= 8 && nt < 12);
;     if (MODE == M_MLA_UKV) transposed = nt >= 4;
;     if (MODE == M_HG_IN) transposed = nt >= 12;
;     if (MODE == M_PLE) {
;       const u16* pb = (const u16*)g.d1;
;       gemm_loop(g.W2 + (long)n0 * 256, 256, pb + (long)m0 * 256, 256, 256, acc, smem);
;       u16* xb = (u16*)g.d0;
;       EPI_STD_BEGIN
;         *(u32x2*)(xb + (long)m * 1024 + n4) = pack4(v[0], v[1], v[2], v[3]);
;       EPI_END
;       zero_acc(acc);
;     }
;     if (MODE == M_FFT1) {
;       const int bt = mt >> 8, cg = mt & 255;
;       gemm_loop_g<0>(Ab + ((long)(bt * 1024 + cg * 4)) * 8192, 64, 8192, 4096, Wb, 128, 64 * 128, 64, 128, acc, smem);
;     } else if (MODE == M_FFT3) {
;       const int bt = mt >> 8, v = (mt >> 2) & 63, cq = mt & 3;
;       gemm_loop(Ab + (((long)(bt * 64 + v)) * 1024 + cq * 256) * 128, 128, Wb, 128, 128, acc, smem);
;     } else if (MODE == M_FN_IN && transposed) {
;       const u16* Ap = Ab + ((long)(mt >> 4) * 4096 + (mt & 15) * 4) * g.lda;
;       gemm_loop_g<1>(Ap, 64 * g.lda, g.lda, 64, Wb + (long)n0 * g.K, g.K, 64L * g.K, 64, g.K, acc, smem);
;     } else {
;       const u16* Ap = Ab + (long)m0 * g.lda; const u16* Wp = Wb + (long)n0 * g.K;
;       if (transposed) gemm_loop(Ap, g.lda, Wp, g.K, g.K, acc, smem);
;       else gemm_loop(Wp, g.K, Ap, g.lda, g.K, acc, smem);
.LBB0_639:
	s_lshl_b32 s6, s27, 9
	s_and_b32 s6, s6, 0xfffff800
	s_or_b32 s22, s6, s24
	s_lshl_b32 s6, s27, 8
	s_and_b32 s6, s6, 0x300
	s_lshl_b32 s7, s6, 11
	s_add_u32 s8, s10, s7
	s_addc_u32 s9, s11, 0
	s_ashr_i32 s23, s22, 31
	s_waitcnt vmcnt(0)
	v_mov_b32_e32 v4, v182
	s_lshl_b64 s[28:29], s[22:23], 11
	s_add_u32 s28, s38, s28
	v_ashrrev_i32_e32 v0, 3, v4
	v_lshrrev_b32_e32 v5, 4, v4
	v_xor_b32_e32 v6, v5, v4
	v_ashrrev_i32_e32 v1, 31, v0
	s_addc_u32 s29, s39, s29
	v_lshlrev_b64 v[0:1], 11, v[0:1]
	v_lshlrev_b32_e32 v6, 4, v6
	v_lshl_add_u64 v[2:3], s[8:9], 0, v[0:1]
	v_and_b32_e32 v128, 0x70, v6
	v_lshl_add_u64 v[0:1], s[28:29], 0, v[0:1]
	v_lshl_add_u64 v[130:131], v[2:3], 0, v[128:129]
	v_lshl_add_u64 v[132:133], v[0:1], 0, v[128:129]
	v_lshlrev_b32_e32 v128, 4, v4
	v_add_u32_e32 v2, 0x2000, v128
	v_readfirstlane_b32 s7, v128
	v_lshl_add_u64 v[0:1], v[130:131], 0, s[14:15]
	s_mov_b32 m0, s7
	v_lshl_add_u64 v[134:135], v[130:131], 0, s[16:17]
	v_readfirstlane_b32 s7, v2
	v_add_u32_e32 v2, 0x4000, v128
	s_barrier
; #define LDS_PTR(p) ((__attribute__((address_space(3))) unsigned*)(p))
; template <int PIPE>
; DI void gemm_loop_g(const u16* __restrict__ Xp, long ldx_l, long ldx_i, long kxs,
;                     const u16* __restrict__ Yp, long ldy_l, long ldy_i, long kys, int K,
;                     f32x4 (&acc)[4][8], unsigned char* smem) {
;     ...
;   auto issue = [&](int kt0, int stage) {
;     int kt = kt0 + rot; if (kt >= nk) kt -= nk;
;     unsigned char* sb = smem + stage * 65536 + t * 16;
; #pragma unroll
;     for (int i = 0; i < 4; ++i)
;       __builtin_amdgcn_global_load_lds((const unsigned*)(xs + i * ldx_i + kt * kxs), LDS_PTR(sb + i * 8192), 16, 0, 0);
; #pragma unroll
;     for (int i = 0; i < 4; ++i)
;       __builtin_amdgcn_global_load_lds((const unsigned*)(ys + i * ldy_i + kt * kys), LDS_PTR(sb + 32768 + i * 8192), 16, 0, 0);
;   };
;   __syncthreads();
;   issue(0, 0);
;   asm volatile("s_waitcnt vmcnt(0)" ::: "memory");
;   __syncthreads();
; DI void zero_acc(f32x4 (&acc)[4][8]) {
; #pragma unroll
;   for (int i = 0; i < 4; ++i)
; #pragma unroll
;     for (int j = 0; j < 8; ++j) acc[i][j] = f32x4{0.f, 0.f, 0.f, 0.f};
	global_load_lds_dwordx4 v[0:1], off
	v_lshl_add_u64 v[0:1], v[134:135], 0, s[14:15]
	s_mov_b32 m0, s7
	v_lshl_add_u64 v[136:137], v[130:131], 0, s[18:19]
	v_readfirstlane_b32 s7, v2
	v_add_u32_e32 v2, 0x6000, v128
	global_load_lds_dwordx4 v[0:1], off
	v_lshl_add_u64 v[0:1], v[136:137], 0, s[14:15]
	s_mov_b32 m0, s7
	v_lshl_add_u64 v[138:139], v[130:131], 0, s[20:21]
	v_readfirstlane_b32 s7, v2
	v_add_u32_e32 v2, 0x8000, v128
	global_load_lds_dwordx4 v[0:1], off
	v_lshl_add_u64 v[0:1], v[138:139], 0, s[14:15]
	s_mov_b32 m0, s7
	v_readfirstlane_b32 s7, v2
	v_add_u32_e32 v2, 0xa000, v128
	global_load_lds_dwordx4 v[0:1], off
	v_lshl_add_u64 v[0:1], v[132:133], 0, s[14:15]
	s_mov_b32 m0, s7
	v_lshl_add_u64 v[140:141], v[132:133], 0, s[16:17]
	v_readfirstlane_b32 s7, v2
	v_add_u32_e32 v2, 0xc000, v128
	global_load_lds_dwordx4 v[0:1], off
	v_lshl_add_u64 v[0:1], v[140:141], 0, s[14:15]
	s_mov_b32 m0, s7
	v_lshl_add_u64 v[142:143], v[132:133], 0, s[18:19]
	v_readfirstlane_b32 s7, v2
	v_add_u32_e32 v2, 0xe000, v128
	global_load_lds_dwordx4 v[0:1], off
	v_lshl_add_u64 v[0:1], v[142:143], 0, s[14:15]
	s_mov_b32 m0, s7
	v_lshl_add_u64 v[144:145], v[132:133], 0, s[20:21]
	v_readfirstlane_b32 s7, v2
	global_load_lds_dwordx4 v[0:1], off
	v_lshl_add_u64 v[0:1], v[144:145], 0, s[14:15]
	s_mov_b32 m0, s7
	v_lshlrev_b32_e32 v2, 7, v4
	global_load_lds_dwordx4 v[0:1], off
	v_bfe_u32 v0, v4, 4, 2
	v_bfe_u32 v1, v4, 1, 3
	v_readfirstlane_b32 s23, v4
	s_nop 0
	v_bitop3_b32 v0, v0, v1, 4 bitop3:0x36
	v_and_b32_e32 v2, 0x780, v2
	s_lshl_b32 s7, s23, 8
	s_lshl_b32 s8, s23, 6
	v_lshl_or_b32 v149, v0, 4, v2
	v_bitop3_b32 v0, v5, v1, 3 bitop3:0x6c
	s_and_b32 s7, s7, 0x4000
	s_and_b32 s23, s8, 0xffffe000
	v_lshl_or_b32 v150, v0, 4, v2
	s_mov_b32 s28, 0x10000
	s_mov_b32 s29, 0
	v_mov_b32_e32 v4, 0
	v_mov_b32_e32 v5, v129
	v_mov_b32_e32 v6, v129
	v_mov_b32_e32 v7, v129
	v_mov_b32_e32 v16, 0
	v_mov_b32_e32 v17, v129
	v_mov_b32_e32 v18, v129
	v_mov_b32_e32 v19, v129
	v_mov_b32_e32 v32, 0
	v_mov_b32_e32 v33, v129
	v_mov_b32_e32 v34, v129
	v_mov_b32_e32 v35, v129
	v_mov_b32_e32 v48, 0
	v_mov_b32_e32 v49, v129
	v_mov_b32_e32 v50, v129
	v_mov_b32_e32 v51, v129
	v_mov_b32_e32 v64, 0
	v_mov_b32_e32 v65, v129
	v_mov_b32_e32 v66, v129
	v_mov_b32_e32 v67, v129
	v_mov_b32_e32 v80, 0
	v_mov_b32_e32 v81, v129
	v_mov_b32_e32 v82, v129
	v_mov_b32_e32 v83, v129
	v_mov_b32_e32 v96, 0
	v_mov_b32_e32 v97, v129
	v_mov_b32_e32 v98, v129
	v_mov_b32_e32 v99, v129
	v_mov_b32_e32 v112, 0
	v_mov_b32_e32 v113, v129
	v_mov_b32_e32 v114, v129
	v_mov_b32_e32 v115, v129
	v_mov_b32_e32 v0, 0
	v_mov_b32_e32 v1, v129
	v_mov_b32_e32 v2, v129
	v_mov_b32_e32 v3, v129
	v_mov_b32_e32 v20, 0
	v_mov_b32_e32 v21, v129
	v_mov_b32_e32 v22, v129
	v_mov_b32_e32 v23, v129
	v_mov_b32_e32 v36, 0
	v_mov_b32_e32 v37, v129
	v_mov_b32_e32 v38, v129
	v_mov_b32_e32 v39, v129
	v_mov_b32_e32 v52, 0
	v_mov_b32_e32 v53, v129
	v_mov_b32_e32 v54, v129
	v_mov_b32_e32 v55, v129
	v_mov_b32_e32 v68, 0
	v_mov_b32_e32 v69, v129
	v_mov_b32_e32 v70, v129
	v_mov_b32_e32 v71, v129
	v_mov_b32_e32 v84, 0
	v_mov_b32_e32 v85, v129
	v_mov_b32_e32 v86, v129
	v_mov_b32_e32 v87, v129
	v_mov_b32_e32 v100, 0
	v_mov_b32_e32 v101, v129
	v_mov_b32_e32 v102, v129
	v_mov_b32_e32 v103, v129
	v_mov_b32_e32 v116, 0
	v_mov_b32_e32 v117, v129
	v_mov_b32_e32 v118, v129
	v_mov_b32_e32 v119, v129
	v_mov_b32_e32 v8, 0
	v_mov_b32_e32 v9, v129
	v_mov_b32_e32 v10, v129
	v_mov_b32_e32 v11, v129
	v_mov_b32_e32 v24, 0
	v_mov_b32_e32 v25, v129
	v_mov_b32_e32 v26, v129
	v_mov_b32_e32 v27, v129
	v_mov_b32_e32 v40, 0
	v_mov_b32_e32 v41, v129
	v_mov_b32_e32 v42, v129
	v_mov_b32_e32 v43, v129
	v_mov_b32_e32 v56, 0
	v_mov_b32_e32 v57, v129
	v_mov_b32_e32 v58, v129
	v_mov_b32_e32 v59, v129
	v_mov_b32_e32 v72, 0
	v_mov_b32_e32 v73, v129
	v_mov_b32_e32 v74, v129
	v_mov_b32_e32 v75, v129
	v_mov_b32_e32 v88, 0
	v_mov_b32_e32 v89, v129
	v_mov_b32_e32 v90, v129
	v_mov_b32_e32 v91, v129
	v_mov_b32_e32 v104, 0
	v_mov_b32_e32 v105, v129
	v_mov_b32_e32 v106, v129
	v_mov_b32_e32 v107, v129
	v_mov_b32_e32 v120, 0
	v_mov_b32_e32 v121, v129
	v_mov_b32_e32 v122, v129
	v_mov_b32_e32 v123, v129
	v_mov_b32_e32 v12, 0
	v_mov_b32_e32 v13, v129
	v_mov_b32_e32 v14, v129
	v_mov_b32_e32 v15, v129
	v_mov_b32_e32 v28, 0
	v_mov_b32_e32 v29, v129
	v_mov_b32_e32 v30, v129
	v_mov_b32_e32 v31, v129
	v_mov_b32_e32 v44, 0
	v_mov_b32_e32 v45, v129
	v_mov_b32_e32 v46, v129
	v_mov_b32_e32 v47, v129
	v_mov_b32_e32 v60, 0
	v_mov_b32_e32 v61, v129
	v_mov_b32_e32 v62, v129
	v_mov_b32_e32 v63, v129
	v_mov_b32_e32 v76, 0
	v_mov_b32_e32 v77, v129
	v_mov_b32_e32 v78, v129
	v_mov_b32_e32 v79, v129
	v_mov_b32_e32 v92, 0
	v_mov_b32_e32 v93, v129
	v_mov_b32_e32 v94, v129
	v_mov_b32_e32 v95, v129
	v_mov_b32_e32 v108, 0
	v_mov_b32_e32 v109, v129
	v_mov_b32_e32 v110, v129
	v_mov_b32_e32 v111, v129
	v_mov_b32_e32 v124, 0
	v_mov_b32_e32 v125, v129
	v_mov_b32_e32 v126, v129
	v_mov_b32_e32 v127, v129
	s_add_i32 s8, s25, s29
	s_cmp_lt_u32 s8, 16
	s_cselect_b32 s9, 0, -16
	s_add_i32 s8, s8, s9
	s_and_b32 s9, s28, 0x10000
	v_add_u32_e32 v151, s9, v128
	s_ashr_i32 s9, s8, 31
	s_lshl_b64 s[8:9], s[8:9], 7
	v_readfirstlane_b32 s30, v151
	v_add_u32_e32 v154, 0x2000, v151
	v_lshl_add_u64 v[152:153], v[130:131], 0, s[8:9]
	s_mov_b32 m0, s30
	v_readfirstlane_b32 s30, v154
	v_add_u32_e32 v154, 0x4000, v151
	global_load_lds_dwordx4 v[152:153], off
	v_lshl_add_u64 v[152:153], v[134:135], 0, s[8:9]
	s_mov_b32 m0, s30
	v_readfirstlane_b32 s30, v154
	v_add_u32_e32 v154, 0x6000, v151
	global_load_lds_dwordx4 v[152:153], off
	v_lshl_add_u64 v[152:153], v[136:137], 0, s[8:9]
	s_mov_b32 m0, s30
	v_readfirstlane_b32 s30, v154
	v_add_u32_e32 v154, 0x8000, v151
	global_load_lds_dwordx4 v[152:153], off
	v_lshl_add_u64 v[152:153], v[138:139], 0, s[8:9]
	s_mov_b32 m0, s30
	v_readfirstlane_b32 s30, v154
	v_add_u32_e32 v154, 0xa000, v151
	global_load_lds_dwordx4 v[152:153], off
	v_lshl_add_u64 v[152:153], v[132:133], 0, s[8:9]
	s_mov_b32 m0, s30
	v_readfirstlane_b32 s30, v154
	v_add_u32_e32 v154, 0xc000, v151
	global_load_lds_dwordx4 v[152:153], off
	v_lshl_add_u64 v[152:153], v[140:141], 0, s[8:9]
	s_mov_b32 m0, s30
	v_readfirstlane_b32 s30, v154
	global_load_lds_dwordx4 v[152:153], off
	v_lshl_add_u64 v[152:153], v[142:143], 0, s[8:9]
	s_mov_b32 m0, s30
	v_add_u32_e32 v151, 0xe000, v151
	global_load_lds_dwordx4 v[152:153], off
	v_lshl_add_u64 v[152:153], v[144:145], 0, s[8:9]
	v_readfirstlane_b32 s8, v151
	s_mov_b32 m0, s8
	s_nop 0
	global_load_lds_dwordx4 v[152:153], off
	s_waitcnt vmcnt(8) lgkmcnt(0)
	s_barrier
	s_branch .LBB0_640

; DI u32x2 pack4(float a, float b, float c, float d) { u32x2 r; r.x = pack2(a, b); r.y = pack2(c, d); return r; }
; #define EPI_END if (i == 3 && (j & 3) == 3) __builtin_amdgcn_sched_barrier(0); }
; template <int MODE>
; DI void gemm_phase(const Params& p, const GP& g, unsigned char* smem) {
;     ...
;   for (int e = slot; e < nent; e += nslot) {
;     int mt, nt;
;     const u16* Ab = g.A; const u16* Wb = g.W;
;     int bsel = 0;
;     {
;       const int ml = e / g.ntn;
;       nt = e - ml * g.ntn;
;       mt = xcd + 8 * ml;
;     }
;     if (MODE == M_SEQ) { bsel = mt >> 4; mt &= 15; Wb = g.W + (long)bsel * 1024 * 8192; }
;     const int m0 = mt * 256, n0 = nt * 256;
;     f32x4 acc[4][8];
;     zero_acc(acc);
;     int transposed = 0;
;     if (MODE == M_FN_IN) transposed = nt < 8;
;     if (MODE == M_NA_IN) transposed = (nt >= 8 && nt < 12);
;     if (MODE == M_MLA_UKV) transposed = nt >= 4;
;     if (MODE == M_HG_IN) transposed = nt >= 12;
;     if (MODE == M_PLE) {
;       const u16* pb = (const u16*)g.d1;
;       gemm_loop(g.W2 + (long)n0 * 256, 256, pb + (long)m0 * 256, 256, 256, acc, smem);
;       u16* xb = (u16*)g.d0;
;       EPI_STD_BEGIN
;         *(u32x2*)(xb + (long)m * 1024 + n4) = pack4(v[0], v[1], v[2], v[3]);
;       EPI_END
;       zero_acc(acc);
;     }
;     if (MODE == M_FFT1) {
;       const int bt = mt >> 8, cg = mt & 255;
;       gemm_loop_g<0>(Ab + ((long)(bt * 1024 + cg * 4)) * 8192, 64, 8192, 4096, Wb, 128, 64 * 128, 64, 128, acc, smem);
;     } else if (MODE == M_FFT3) {
;       const int bt = mt >> 8, v = (mt >> 2) & 63, cq = mt & 3;
;       gemm_loop(Ab + (((long)(bt * 64 + v)) * 1024 + cq * 256) * 128, 128, Wb, 128, 128, acc, smem);
;     } else if (MODE == M_FN_IN && transposed) {
;       const u16* Ap = Ab + ((long)(mt >> 4) * 4096 + (mt & 15) * 4) * g.lda;
;       gemm_loop_g<1>(Ap, 64 * g.lda, g.lda, 64, Wb + (long)n0 * g.K, g.K, 64L * g.K, 64, g.K, acc, smem);
;     } else {
;       const u16* Ap = Ab + (long)m0 * g.lda; const u16* Wp = Wb + (long)n0 * g.K;
;       if (transposed) gemm_loop(Ap, g.lda, Wp, g.K, g.K, acc, smem);
;       else gemm_loop(Wp, g.K, Ap, g.lda, g.K, acc, smem);
.LBB0_656:
	s_lshl_b32 s6, s24, 9
	s_and_b32 s6, s6, 0xfffff800
	s_or_b32 s20, s6, s22
	s_lshl_b32 s6, s24, 8
	s_and_b32 s6, s6, 0x300
	s_lshl_b32 s7, s6, 11
	s_waitcnt lgkmcnt(0)
	s_add_u32 s8, s10, s7
	s_addc_u32 s9, s11, 0
	s_ashr_i32 s21, s20, 31
	s_waitcnt vmcnt(0)
	v_mov_b32_e32 v4, v182
	s_lshl_b64 s[26:27], s[20:21], 11
	s_add_u32 s26, s36, s26
	v_ashrrev_i32_e32 v0, 3, v4
	v_lshrrev_b32_e32 v5, 4, v4
	v_xor_b32_e32 v6, v5, v4
	v_ashrrev_i32_e32 v1, 31, v0
	s_addc_u32 s27, s37, s27
	v_lshlrev_b64 v[0:1], 11, v[0:1]
	v_lshlrev_b32_e32 v6, 4, v6
	v_lshl_add_u64 v[2:3], s[8:9], 0, v[0:1]
	v_and_b32_e32 v128, 0x70, v6
	v_lshl_add_u64 v[0:1], s[26:27], 0, v[0:1]
	v_lshl_add_u64 v[130:131], v[2:3], 0, v[128:129]
	v_lshl_add_u64 v[132:133], v[0:1], 0, v[128:129]
	v_lshlrev_b32_e32 v128, 4, v4
	v_add_u32_e32 v2, 0x2000, v128
	v_readfirstlane_b32 s7, v128
	v_lshl_add_u64 v[0:1], v[130:131], 0, s[4:5]
	s_mov_b32 m0, s7
	v_lshl_add_u64 v[134:135], v[130:131], 0, s[14:15]
	v_readfirstlane_b32 s7, v2
	v_add_u32_e32 v2, 0x4000, v128
	s_barrier
; #define LDS_PTR(p) ((__attribute__((address_space(3))) unsigned*)(p))
; template <int PIPE>
; DI void gemm_loop_g(const u16* __restrict__ Xp, long ldx_l, long ldx_i, long kxs,
;                     const u16* __restrict__ Yp, long ldy_l, long ldy_i, long kys, int K,
;                     f32x4 (&acc)[4][8], unsigned char* smem) {
;     ...
;   auto issue = [&](int kt0, int stage) {
;     int kt = kt0 + rot; if (kt >= nk) kt -= nk;
;     unsigned char* sb = smem + stage * 65536 + t * 16;
; #pragma unroll
;     for (int i = 0; i < 4; ++i)
;       __builtin_amdgcn_global_load_lds((const unsigned*)(xs + i * ldx_i + kt * kxs), LDS_PTR(sb + i * 8192), 16, 0, 0);
; #pragma unroll
;     for (int i = 0; i < 4; ++i)
;       __builtin_amdgcn_global_load_lds((const unsigned*)(ys + i * ldy_i + kt * kys), LDS_PTR(sb + 32768 + i * 8192), 16, 0, 0);
;   };
;   __syncthreads();
;   issue(0, 0);
;   asm volatile("s_waitcnt vmcnt(0)" ::: "memory");
;   __syncthreads();
; DI void zero_acc(f32x4 (&acc)[4][8]) {
; #pragma unroll
;   for (int i = 0; i < 4; ++i)
; #pragma unroll
;     for (int j = 0; j < 8; ++j) acc[i][j] = f32x4{0.f, 0.f, 0.f, 0.f};
	global_load_lds_dwordx4 v[0:1], off
	v_lshl_add_u64 v[0:1], v[134:135], 0, s[4:5]
	s_mov_b32 m0, s7
	v_lshl_add_u64 v[136:137], v[130:131], 0, s[16:17]
	v_readfirstlane_b32 s7, v2
	v_add_u32_e32 v2, 0x6000, v128
	global_load_lds_dwordx4 v[0:1], off
	v_lshl_add_u64 v[0:1], v[136:137], 0, s[4:5]
	s_mov_b32 m0, s7
	v_lshl_add_u64 v[138:139], v[130:131], 0, s[18:19]
	v_readfirstlane_b32 s7, v2
	v_add_u32_e32 v2, 0x8000, v128
	global_load_lds_dwordx4 v[0:1], off
	v_lshl_add_u64 v[0:1], v[138:139], 0, s[4:5]
	s_mov_b32 m0, s7
	v_readfirstlane_b32 s7, v2
	v_add_u32_e32 v2, 0xa000, v128
	global_load_lds_dwordx4 v[0:1], off
	v_lshl_add_u64 v[0:1], v[132:133], 0, s[4:5]
	s_mov_b32 m0, s7
	v_lshl_add_u64 v[140:141], v[132:133], 0, s[14:15]
	v_readfirstlane_b32 s7, v2
	v_add_u32_e32 v2, 0xc000, v128
	global_load_lds_dwordx4 v[0:1], off
	v_lshl_add_u64 v[0:1], v[140:141], 0, s[4:5]
	s_mov_b32 m0, s7
	v_lshl_add_u64 v[142:143], v[132:133], 0, s[16:17]
	v_readfirstlane_b32 s7, v2
	v_add_u32_e32 v2, 0xe000, v128
	global_load_lds_dwordx4 v[0:1], off
	v_lshl_add_u64 v[0:1], v[142:143], 0, s[4:5]
	s_mov_b32 m0, s7
	v_lshl_add_u64 v[144:145], v[132:133], 0, s[18:19]
	v_readfirstlane_b32 s7, v2
	global_load_lds_dwordx4 v[0:1], off
	v_lshl_add_u64 v[0:1], v[144:145], 0, s[4:5]
	s_mov_b32 m0, s7
	v_lshlrev_b32_e32 v2, 7, v4
	global_load_lds_dwordx4 v[0:1], off
	v_bfe_u32 v0, v4, 4, 2
	v_bfe_u32 v1, v4, 1, 3
	v_readfirstlane_b32 s21, v4
	s_nop 0
	v_bitop3_b32 v0, v0, v1, 4 bitop3:0x36
	v_and_b32_e32 v2, 0x780, v2
	s_lshl_b32 s7, s21, 8
	s_lshl_b32 s8, s21, 6
	v_lshl_or_b32 v148, v0, 4, v2
	v_bitop3_b32 v0, v5, v1, 3 bitop3:0x6c
	s_and_b32 s7, s7, 0x4000
	s_and_b32 s21, s8, 0xffffe000
	v_lshl_or_b32 v149, v0, 4, v2
	s_mov_b32 s25, 0x10000
	s_mov_b32 s26, 0
	v_mov_b32_e32 v12, 0
	v_mov_b32_e32 v13, v129
	v_mov_b32_e32 v14, v129
	v_mov_b32_e32 v15, v129
	v_mov_b32_e32 v4, 0
	v_mov_b32_e32 v5, v129
	v_mov_b32_e32 v6, v129
	v_mov_b32_e32 v7, v129
	v_mov_b32_e32 v24, 0
	v_mov_b32_e32 v25, v129
	v_mov_b32_e32 v26, v129
	v_mov_b32_e32 v27, v129
	v_mov_b32_e32 v40, 0
	v_mov_b32_e32 v41, v129
	v_mov_b32_e32 v42, v129
	v_mov_b32_e32 v43, v129
	v_mov_b32_e32 v56, 0
	v_mov_b32_e32 v57, v129
	v_mov_b32_e32 v58, v129
	v_mov_b32_e32 v59, v129
	v_mov_b32_e32 v72, 0
	v_mov_b32_e32 v73, v129
	v_mov_b32_e32 v74, v129
	v_mov_b32_e32 v75, v129
	v_mov_b32_e32 v88, 0
	v_mov_b32_e32 v89, v129
	v_mov_b32_e32 v90, v129
	v_mov_b32_e32 v91, v129
	v_mov_b32_e32 v104, 0
	v_mov_b32_e32 v105, v129
	v_mov_b32_e32 v106, v129
	v_mov_b32_e32 v107, v129
	v_mov_b32_e32 v0, 0
	v_mov_b32_e32 v1, v129
	v_mov_b32_e32 v2, v129
	v_mov_b32_e32 v3, v129
	v_mov_b32_e32 v20, 0
	v_mov_b32_e32 v21, v129
	v_mov_b32_e32 v22, v129
	v_mov_b32_e32 v23, v129
	v_mov_b32_e32 v36, 0
	v_mov_b32_e32 v37, v129
	v_mov_b32_e32 v38, v129
	v_mov_b32_e32 v39, v129
	v_mov_b32_e32 v52, 0
	v_mov_b32_e32 v53, v129
	v_mov_b32_e32 v54, v129
	v_mov_b32_e32 v55, v129
	v_mov_b32_e32 v68, 0
	v_mov_b32_e32 v69, v129
	v_mov_b32_e32 v70, v129
	v_mov_b32_e32 v71, v129
	v_mov_b32_e32 v84, 0
	v_mov_b32_e32 v85, v129
	v_mov_b32_e32 v86, v129
	v_mov_b32_e32 v87, v129
	v_mov_b32_e32 v100, 0
	v_mov_b32_e32 v101, v129
	v_mov_b32_e32 v102, v129
	v_mov_b32_e32 v103, v129
	v_mov_b32_e32 v116, 0
	v_mov_b32_e32 v117, v129
	v_mov_b32_e32 v118, v129
	v_mov_b32_e32 v119, v129
	v_mov_b32_e32 v8, 0
	v_mov_b32_e32 v9, v129
	v_mov_b32_e32 v10, v129
	v_mov_b32_e32 v11, v129
	v_mov_b32_e32 v28, 0
	v_mov_b32_e32 v29, v129
	v_mov_b32_e32 v30, v129
	v_mov_b32_e32 v31, v129
	v_mov_b32_e32 v44, 0
	v_mov_b32_e32 v45, v129
	v_mov_b32_e32 v46, v129
	v_mov_b32_e32 v47, v129
	v_mov_b32_e32 v60, 0
	v_mov_b32_e32 v61, v129
	v_mov_b32_e32 v62, v129
	v_mov_b32_e32 v63, v129
	v_mov_b32_e32 v76, 0
	v_mov_b32_e32 v77, v129
	v_mov_b32_e32 v78, v129
	v_mov_b32_e32 v79, v129
	v_mov_b32_e32 v92, 0
	v_mov_b32_e32 v93, v129
	v_mov_b32_e32 v94, v129
	v_mov_b32_e32 v95, v129
	v_mov_b32_e32 v108, 0
	v_mov_b32_e32 v109, v129
	v_mov_b32_e32 v110, v129
	v_mov_b32_e32 v111, v129
	v_mov_b32_e32 v120, 0
	v_mov_b32_e32 v121, v129
	v_mov_b32_e32 v122, v129
	v_mov_b32_e32 v123, v129
	v_mov_b32_e32 v16, 0
	v_mov_b32_e32 v17, v129
	v_mov_b32_e32 v18, v129
	v_mov_b32_e32 v19, v129
	v_mov_b32_e32 v32, 0
	v_mov_b32_e32 v33, v129
	v_mov_b32_e32 v34, v129
	v_mov_b32_e32 v35, v129
	v_mov_b32_e32 v48, 0
	v_mov_b32_e32 v49, v129
	v_mov_b32_e32 v50, v129
	v_mov_b32_e32 v51, v129
	v_mov_b32_e32 v64, 0
	v_mov_b32_e32 v65, v129
	v_mov_b32_e32 v66, v129
	v_mov_b32_e32 v67, v129
	v_mov_b32_e32 v80, 0
	v_mov_b32_e32 v81, v129
	v_mov_b32_e32 v82, v129
	v_mov_b32_e32 v83, v129
	v_mov_b32_e32 v96, 0
	v_mov_b32_e32 v97, v129
	v_mov_b32_e32 v98, v129
	v_mov_b32_e32 v99, v129
	v_mov_b32_e32 v112, 0
	v_mov_b32_e32 v113, v129
	v_mov_b32_e32 v114, v129
	v_mov_b32_e32 v115, v129
	v_mov_b32_e32 v124, 0
	v_mov_b32_e32 v125, v129
	v_mov_b32_e32 v126, v129
	v_mov_b32_e32 v127, v129
	s_add_i32 s8, s23, s26
	s_cmp_lt_u32 s8, 16
	s_cselect_b32 s9, 0, -16
	s_add_i32 s8, s8, s9
	s_and_b32 s9, s25, 0x10000
	v_add_u32_e32 v152, s9, v128
	s_ashr_i32 s9, s8, 31
	s_lshl_b64 s[8:9], s[8:9], 7
	v_readfirstlane_b32 s27, v152
	v_add_u32_e32 v153, 0x2000, v152
	v_lshl_add_u64 v[150:151], v[130:131], 0, s[8:9]
	s_mov_b32 m0, s27
	v_readfirstlane_b32 s27, v153
	v_add_u32_e32 v153, 0x4000, v152
	global_load_lds_dwordx4 v[150:151], off
	v_lshl_add_u64 v[150:151], v[134:135], 0, s[8:9]
	s_mov_b32 m0, s27
	v_readfirstlane_b32 s27, v153
	v_add_u32_e32 v153, 0x6000, v152
	global_load_lds_dwordx4 v[150:151], off
	v_lshl_add_u64 v[150:151], v[136:137], 0, s[8:9]
	s_mov_b32 m0, s27
	v_readfirstlane_b32 s27, v153
	v_add_u32_e32 v153, 0x8000, v152
	global_load_lds_dwordx4 v[150:151], off
	v_lshl_add_u64 v[150:151], v[138:139], 0, s[8:9]
	s_mov_b32 m0, s27
	v_readfirstlane_b32 s27, v153
	v_add_u32_e32 v153, 0xa000, v152
	global_load_lds_dwordx4 v[150:151], off
	v_lshl_add_u64 v[150:151], v[132:133], 0, s[8:9]
	s_mov_b32 m0, s27
	v_readfirstlane_b32 s27, v153
	v_add_u32_e32 v153, 0xc000, v152
	global_load_lds_dwordx4 v[150:151], off
	v_lshl_add_u64 v[150:151], v[140:141], 0, s[8:9]
	s_mov_b32 m0, s27
	v_readfirstlane_b32 s27, v153
	global_load_lds_dwordx4 v[150:151], off
	v_lshl_add_u64 v[150:151], v[142:143], 0, s[8:9]
	s_mov_b32 m0, s27
	v_add_u32_e32 v152, 0xe000, v152
	global_load_lds_dwordx4 v[150:151], off
	v_lshl_add_u64 v[150:151], v[144:145], 0, s[8:9]
	v_readfirstlane_b32 s8, v152
	s_mov_b32 m0, s8
	s_nop 0
	global_load_lds_dwordx4 v[150:151], off
	s_waitcnt vmcnt(8) lgkmcnt(0)
	s_barrier
	s_branch .LBB0_657

; DI int tid_opaque() { int t = threadIdx.x; asm volatile("" : "+v"(t)); return t; }
; template <int PIPE>
; DI void gemm_loop_g(const u16* __restrict__ Xp, long ldx_l, long ldx_i, long kxs,
;                     const u16* __restrict__ Yp, long ldy_l, long ldy_i, long kys, int K,
;                     f32x4 (&acc)[4][8], unsigned char* smem) {
;   const int t = tid_opaque(), l = t & 63, w = __builtin_amdgcn_readfirstlane(t >> 6), wx = w >> 1, wy = w & 1;
;   const int lrow = t >> 3, gch = (t & 7) ^ ((t >> 4) & 7);
;   const u16* xs = Xp + (long)lrow * ldx_l + gch * 8;
;   const u16* ys = Yp + (long)lrow * ldy_l + gch * 8;
;   const int fsw = (l >> 1) & 7, lg = l >> 4;
;   const unsigned fr0 = (l & 15) * 128 + ((lg ^ fsw) << 4);
;   const unsigned fr1 = (l & 15) * 128 + (((lg + 4) ^ fsw) << 4);
;   const unsigned ub = wx * 8192, vb = 32768 + wy * 16384;
; template <int MODE>
; DI void gemm_phase(const Params& p, const GP& g, unsigned char* smem) {
;     ...
;     if (MODE == M_PLE) {
;       const u16* pb = (const u16*)g.d1;
;       gemm_loop(g.W2 + (long)n0 * 256, 256, pb + (long)m0 * 256, 256, 256, acc, smem);
.LBB0_676:
	s_lshl_b32 s2, s35, 9
	s_lshl_b32 s3, s35, 8
	s_and_b32 s2, s2, 0xfffff800
	s_and_b32 s6, s3, 0x300
	s_or_b32 s2, s2, s42
	s_lshl_b32 s3, s6, 9
	s_add_u32 s26, s30, s3
	s_waitcnt vmcnt(0)
	v_mov_b32_e32 v6, v182
	s_addc_u32 s27, s31, 0
	s_ashr_i32 s3, s2, 31
	s_lshl_b64 s[40:41], s[2:3], 9
	v_ashrrev_i32_e32 v2, 3, v6
	v_lshrrev_b32_e32 v7, 4, v6
	v_xor_b32_e32 v8, v7, v6
	v_ashrrev_i32_e32 v3, 31, v2
	s_waitcnt lgkmcnt(0)
	v_lshl_add_u64 v[0:1], v[128:129], 0, s[40:41]
	v_lshlrev_b64 v[2:3], 9, v[2:3]
	v_lshlrev_b32_e32 v8, 4, v8
	v_lshl_add_u64 v[4:5], s[26:27], 0, v[2:3]
	v_and_b32_e32 v130, 0x70, v8
	v_lshl_add_u64 v[0:1], v[0:1], 0, v[2:3]
	v_lshl_add_u64 v[132:133], v[4:5], 0, v[130:131]
	v_lshl_add_u64 v[134:135], v[0:1], 0, v[130:131]
	v_lshlrev_b32_e32 v130, 4, v6
	v_add_u32_e32 v2, 0x2000, v130
	v_readfirstlane_b32 s7, v130
	v_lshl_add_u64 v[0:1], v[132:133], 0, s[10:11]
	s_mov_b32 m0, s7
	v_lshl_add_u64 v[136:137], v[132:133], 0, s[12:13]
	v_readfirstlane_b32 s7, v2
	v_add_u32_e32 v2, 0x4000, v130
	s_barrier
; #define LDS_PTR(p) ((__attribute__((address_space(3))) unsigned*)(p))
; template <int PIPE>
; DI void gemm_loop_g(const u16* __restrict__ Xp, long ldx_l, long ldx_i, long kxs,
;                     const u16* __restrict__ Yp, long ldy_l, long ldy_i, long kys, int K,
;                     f32x4 (&acc)[4][8], unsigned char* smem) {
;     ...
;   auto issue = [&](int kt0, int stage) {
;     int kt = kt0 + rot; if (kt >= nk) kt -= nk;
;     unsigned char* sb = smem + stage * 65536 + t * 16;
; #pragma unroll
;     for (int i = 0; i < 4; ++i)
;       __builtin_amdgcn_global_load_lds((const unsigned*)(xs + i * ldx_i + kt * kxs), LDS_PTR(sb + i * 8192), 16, 0, 0);
; #pragma unroll
;     for (int i = 0; i < 4; ++i)
;       __builtin_amdgcn_global_load_lds((const unsigned*)(ys + i * ldy_i + kt * kys), LDS_PTR(sb + 32768 + i * 8192), 16, 0, 0);
;   };
;   __syncthreads();
;   issue(0, 0);
;   asm volatile("s_waitcnt vmcnt(0)" ::: "memory");
;   __syncthreads();
; DI void zero_acc(f32x4 (&acc)[4][8]) {
; #pragma unroll
;   for (int i = 0; i < 4; ++i)
; #pragma unroll
;     for (int j = 0; j < 8; ++j) acc[i][j] = f32x4{0.f, 0.f, 0.f, 0.f};
	global_load_lds_dwordx4 v[0:1], off
	v_lshl_add_u64 v[0:1], v[136:137], 0, s[10:11]
	s_mov_b32 m0, s7
	v_lshl_add_u64 v[138:139], v[132:133], 0, s[14:15]
	v_readfirstlane_b32 s7, v2
	v_add_u32_e32 v2, 0x6000, v130
	global_load_lds_dwordx4 v[0:1], off
	v_lshl_add_u64 v[0:1], v[138:139], 0, s[10:11]
	s_mov_b32 m0, s7
	v_lshl_add_u64 v[140:141], v[132:133], 0, s[16:17]
	v_readfirstlane_b32 s7, v2
	v_add_u32_e32 v2, 0x8000, v130
	global_load_lds_dwordx4 v[0:1], off
	v_lshl_add_u64 v[0:1], v[140:141], 0, s[10:11]
	s_mov_b32 m0, s7
	v_readfirstlane_b32 s7, v2
	v_add_u32_e32 v2, 0xa000, v130
	global_load_lds_dwordx4 v[0:1], off
	v_lshl_add_u64 v[0:1], v[134:135], 0, s[10:11]
	s_mov_b32 m0, s7
	v_lshl_add_u64 v[142:143], v[134:135], 0, s[12:13]
	v_readfirstlane_b32 s7, v2
	v_add_u32_e32 v2, 0xc000, v130
	global_load_lds_dwordx4 v[0:1], off
	v_lshl_add_u64 v[0:1], v[142:143], 0, s[10:11]
	s_mov_b32 m0, s7
	v_lshl_add_u64 v[144:145], v[134:135], 0, s[14:15]
	v_readfirstlane_b32 s7, v2
	v_add_u32_e32 v2, 0xe000, v130
	global_load_lds_dwordx4 v[0:1], off
	v_lshl_add_u64 v[0:1], v[144:145], 0, s[10:11]
	s_mov_b32 m0, s7
	v_lshl_add_u64 v[146:147], v[134:135], 0, s[16:17]
	v_readfirstlane_b32 s7, v2
	global_load_lds_dwordx4 v[0:1], off
	v_lshl_add_u64 v[0:1], v[146:147], 0, s[10:11]
	s_mov_b32 m0, s7
	v_lshlrev_b32_e32 v2, 7, v6
	global_load_lds_dwordx4 v[0:1], off
	v_bfe_u32 v0, v6, 4, 2
	v_bfe_u32 v1, v6, 1, 3
	v_readfirstlane_b32 s33, v6
	s_nop 0
	v_bitop3_b32 v0, v0, v1, 4 bitop3:0x36
	v_and_b32_e32 v2, 0x780, v2
	s_lshl_b32 s7, s33, 8
	s_lshl_b32 s26, s33, 6
	v_lshl_or_b32 v148, v0, 4, v2
	v_bitop3_b32 v0, v7, v1, 3 bitop3:0x6c
	s_and_b32 s7, s7, 0x4000
	s_and_b32 s26, s26, 0xffffe000
	v_lshl_or_b32 v149, v0, 4, v2
	s_mov_b32 s27, 0x10000
	s_mov_b32 s33, 0
	v_mov_b32_e32 v40, 0
	v_mov_b32_e32 v41, v131
	v_mov_b32_e32 v42, v131
	v_mov_b32_e32 v43, v131
	v_mov_b32_e32 v0, 0
	v_mov_b32_e32 v1, v131
	v_mov_b32_e32 v2, v131
	v_mov_b32_e32 v3, v131
	v_mov_b32_e32 v8, 0
	v_mov_b32_e32 v9, v131
	v_mov_b32_e32 v10, v131
	v_mov_b32_e32 v11, v131
	v_mov_b32_e32 v20, 0
	v_mov_b32_e32 v21, v131
	v_mov_b32_e32 v22, v131
	v_mov_b32_e32 v23, v131
	v_mov_b32_e32 v36, 0
	v_mov_b32_e32 v37, v131
	v_mov_b32_e32 v38, v131
	v_mov_b32_e32 v39, v131
	v_mov_b32_e32 v56, 0
	v_mov_b32_e32 v57, v131
	v_mov_b32_e32 v58, v131
	v_mov_b32_e32 v59, v131
	v_mov_b32_e32 v72, 0
	v_mov_b32_e32 v73, v131
	v_mov_b32_e32 v74, v131
	v_mov_b32_e32 v75, v131
	v_mov_b32_e32 v96, 0
	v_mov_b32_e32 v97, v131
	v_mov_b32_e32 v98, v131
	v_mov_b32_e32 v99, v131
	v_mov_b32_e32 v4, 0
	v_mov_b32_e32 v5, v131
	v_mov_b32_e32 v6, v131
	v_mov_b32_e32 v7, v131
	v_mov_b32_e32 v12, 0
	v_mov_b32_e32 v13, v131
	v_mov_b32_e32 v14, v131
	v_mov_b32_e32 v15, v131
	v_mov_b32_e32 v24, 0
	v_mov_b32_e32 v25, v131
	v_mov_b32_e32 v26, v131
	v_mov_b32_e32 v27, v131
	v_mov_b32_e32 v44, 0
	v_mov_b32_e32 v45, v131
	v_mov_b32_e32 v46, v131
	v_mov_b32_e32 v47, v131
	v_mov_b32_e32 v64, 0
	v_mov_b32_e32 v65, v131
	v_mov_b32_e32 v66, v131
	v_mov_b32_e32 v67, v131
	v_mov_b32_e32 v76, 0
	v_mov_b32_e32 v77, v131
	v_mov_b32_e32 v78, v131
	v_mov_b32_e32 v79, v131
	v_mov_b32_e32 v88, 0
	v_mov_b32_e32 v89, v131
	v_mov_b32_e32 v90, v131
	v_mov_b32_e32 v91, v131
	v_mov_b32_e32 v112, 0
	v_mov_b32_e32 v113, v131
	v_mov_b32_e32 v114, v131
	v_mov_b32_e32 v115, v131
	v_mov_b32_e32 v16, 0
	v_mov_b32_e32 v17, v131
	v_mov_b32_e32 v18, v131
	v_mov_b32_e32 v19, v131
	v_mov_b32_e32 v28, 0
	v_mov_b32_e32 v29, v131
	v_mov_b32_e32 v30, v131
	v_mov_b32_e32 v31, v131
	v_mov_b32_e32 v48, 0
	v_mov_b32_e32 v49, v131
	v_mov_b32_e32 v50, v131
	v_mov_b32_e32 v51, v131
	v_mov_b32_e32 v60, 0
	v_mov_b32_e32 v61, v131
	v_mov_b32_e32 v62, v131
	v_mov_b32_e32 v63, v131
	v_mov_b32_e32 v80, 0
	v_mov_b32_e32 v81, v131
	v_mov_b32_e32 v82, v131
	v_mov_b32_e32 v83, v131
	v_mov_b32_e32 v92, 0
	v_mov_b32_e32 v93, v131
	v_mov_b32_e32 v94, v131
	v_mov_b32_e32 v95, v131
	v_mov_b32_e32 v108, 0
	v_mov_b32_e32 v109, v131
	v_mov_b32_e32 v110, v131
	v_mov_b32_e32 v111, v131
	v_mov_b32_e32 v116, 0
	v_mov_b32_e32 v117, v131
	v_mov_b32_e32 v118, v131
	v_mov_b32_e32 v119, v131
	v_mov_b32_e32 v32, 0
	v_mov_b32_e32 v33, v131
	v_mov_b32_e32 v34, v131
	v_mov_b32_e32 v35, v131
	v_mov_b32_e32 v52, 0
	v_mov_b32_e32 v53, v131
	v_mov_b32_e32 v54, v131
	v_mov_b32_e32 v55, v131
	v_mov_b32_e32 v68, 0
	v_mov_b32_e32 v69, v131
	v_mov_b32_e32 v70, v131
	v_mov_b32_e32 v71, v131
	v_mov_b32_e32 v84, 0
	v_mov_b32_e32 v85, v131
	v_mov_b32_e32 v86, v131
	v_mov_b32_e32 v87, v131
	v_mov_b32_e32 v100, 0
	v_mov_b32_e32 v101, v131
	v_mov_b32_e32 v102, v131
	v_mov_b32_e32 v103, v131
	v_mov_b32_e32 v104, 0
	v_mov_b32_e32 v105, v131
	v_mov_b32_e32 v106, v131
	v_mov_b32_e32 v107, v131
	v_mov_b32_e32 v120, 0
	v_mov_b32_e32 v121, v131
	v_mov_b32_e32 v122, v131
	v_mov_b32_e32 v123, v131
	v_mov_b32_e32 v124, 0
	v_mov_b32_e32 v125, v131
	v_mov_b32_e32 v126, v131
	v_mov_b32_e32 v127, v131
	s_add_i32 s40, s43, s33
	s_cmp_lt_u32 s40, 4
	s_cselect_b32 s41, 0, -4
	s_add_i32 s40, s40, s41
	s_and_b32 s41, s27, 0x10000
	v_add_u32_e32 v152, s41, v130
	s_ashr_i32 s41, s40, 31
	s_lshl_b64 s[40:41], s[40:41], 7
	v_readfirstlane_b32 s45, v152
	v_add_u32_e32 v153, 0x2000, v152
	v_lshl_add_u64 v[150:151], v[132:133], 0, s[40:41]
	s_mov_b32 m0, s45
	v_readfirstlane_b32 s45, v153
	v_add_u32_e32 v153, 0x4000, v152
	global_load_lds_dwordx4 v[150:151], off
	v_lshl_add_u64 v[150:151], v[136:137], 0, s[40:41]
	s_mov_b32 m0, s45
	v_readfirstlane_b32 s45, v153
	v_add_u32_e32 v153, 0x6000, v152
	global_load_lds_dwordx4 v[150:151], off
	v_lshl_add_u64 v[150:151], v[138:139], 0, s[40:41]
	s_mov_b32 m0, s45
	v_readfirstlane_b32 s45, v153
	v_add_u32_e32 v153, 0x8000, v152
	global_load_lds_dwordx4 v[150:151], off
	v_lshl_add_u64 v[150:151], v[140:141], 0, s[40:41]
	s_mov_b32 m0, s45
	v_readfirstlane_b32 s45, v153
	v_add_u32_e32 v153, 0xa000, v152
	global_load_lds_dwordx4 v[150:151], off
	v_lshl_add_u64 v[150:151], v[134:135], 0, s[40:41]
	s_mov_b32 m0, s45
	v_readfirstlane_b32 s45, v153
	v_add_u32_e32 v153, 0xc000, v152
	global_load_lds_dwordx4 v[150:151], off
	v_lshl_add_u64 v[150:151], v[142:143], 0, s[40:41]
	s_mov_b32 m0, s45
	v_readfirstlane_b32 s45, v153
	global_load_lds_dwordx4 v[150:151], off
	v_lshl_add_u64 v[150:151], v[144:145], 0, s[40:41]
	s_mov_b32 m0, s45
	v_add_u32_e32 v152, 0xe000, v152
	global_load_lds_dwordx4 v[150:151], off
	v_lshl_add_u64 v[150:151], v[146:147], 0, s[40:41]
	v_readfirstlane_b32 s40, v152
	s_mov_b32 m0, s40
	s_nop 0
	global_load_lds_dwordx4 v[150:151], off
	s_waitcnt vmcnt(8) lgkmcnt(0)
	s_barrier
	s_branch .LBB0_677

; DI u32x2 pack4(float a, float b, float c, float d) { u32x2 r; r.x = pack2(a, b); r.y = pack2(c, d); return r; }
; #define EPI_END if (i == 3 && (j & 3) == 3) __builtin_amdgcn_sched_barrier(0); }
; template <int MODE>
; DI void gemm_phase(const Params& p, const GP& g, unsigned char* smem) {
;     ...
;       EPI_STD_BEGIN
;         *(u32x2*)(xb + (long)m * 1024 + n4) = pack4(v[0], v[1], v[2], v[3]);
;       EPI_END
;       zero_acc(acc);
;     ...
;       const u16* Ap = Ab + (long)m0 * g.lda; const u16* Wp = Wb + (long)n0 * g.K;
;       if (transposed) gemm_loop(Ap, g.lda, Wp, g.K, g.K, acc, smem);
;       else gemm_loop(Wp, g.K, Ap, g.lda, g.K, acc, smem);
.LBB0_680:
	v_or_b32_e32 v160, s2, v185
	v_add_u32_e32 v134, s6, v184
	v_ashrrev_i32_e32 v161, 31, v160
	v_lshlrev_b64 v[164:165], 11, v[160:161]
	v_ashrrev_i32_e32 v135, 31, v134
	v_or_b32_e32 v156, 16, v160
	v_lshl_add_u64 v[132:133], s[36:37], 0, v[164:165]
	v_cvt_pk_bf16_f32 v124, v124, v125
	v_cvt_pk_bf16_f32 v125, v126, v127
	v_lshlrev_b64 v[126:127], 1, v[134:135]
	v_ashrrev_i32_e32 v157, 31, v156
	v_lshl_add_u64 v[132:133], v[132:133], 0, v[126:127]
	v_cvt_pk_bf16_f32 v96, v96, v97
	v_cvt_pk_bf16_f32 v97, v98, v99
	v_lshlrev_b64 v[162:163], 11, v[156:157]
	v_or_b32_e32 v152, 32, v160
	global_store_dwordx2 v[132:133], v[96:97], off offset:96
	v_lshl_add_u64 v[96:97], s[36:37], 0, v[162:163]
	v_ashrrev_i32_e32 v153, 31, v152
	v_lshl_add_u64 v[96:97], v[96:97], 0, v[126:127]
	v_cvt_pk_bf16_f32 v72, v72, v73
	v_cvt_pk_bf16_f32 v73, v74, v75
	v_lshlrev_b64 v[158:159], 11, v[152:153]
	v_or_b32_e32 v148, 48, v160
	global_store_dwordx2 v[96:97], v[72:73], off offset:96
	v_lshl_add_u64 v[72:73], s[36:37], 0, v[158:159]
	v_ashrrev_i32_e32 v149, 31, v148
	v_lshl_add_u64 v[72:73], v[72:73], 0, v[126:127]
	v_cvt_pk_bf16_f32 v56, v56, v57
	v_cvt_pk_bf16_f32 v57, v58, v59
	v_lshlrev_b64 v[154:155], 11, v[148:149]
	global_store_dwordx2 v[72:73], v[56:57], off offset:96
	v_lshl_add_u64 v[56:57], s[36:37], 0, v[154:155]
	v_cvt_pk_bf16_f32 v74, v104, v105
	v_cvt_pk_bf16_f32 v75, v106, v107
	v_cvt_pk_bf16_f32 v58, v100, v101
	v_cvt_pk_bf16_f32 v59, v102, v103
	v_lshl_add_u64 v[56:57], v[56:57], 0, v[126:127]
	v_cvt_pk_bf16_f32 v98, v120, v121
	v_cvt_pk_bf16_f32 v99, v122, v123
	global_store_dwordx2 v[72:73], v[74:75], off
	v_cvt_pk_bf16_f32 v74, v92, v93
	v_cvt_pk_bf16_f32 v75, v94, v95
	global_store_dwordx2 v[56:57], v[58:59], off
	v_cvt_pk_bf16_f32 v58, v80, v81
	v_cvt_pk_bf16_f32 v59, v82, v83
	v_cvt_pk_bf16_f32 v116, v116, v117
	v_cvt_pk_bf16_f32 v117, v118, v119
	v_cvt_pk_bf16_f32 v112, v112, v113
	v_cvt_pk_bf16_f32 v113, v114, v115
	global_store_dwordx2 v[96:97], v[98:99], off
	v_cvt_pk_bf16_f32 v98, v108, v109
	v_cvt_pk_bf16_f32 v99, v110, v111
	v_cvt_pk_bf16_f32 v88, v88, v89
	v_cvt_pk_bf16_f32 v89, v90, v91
	global_store_dwordx2 v[72:73], v[74:75], off offset:32
	v_cvt_pk_bf16_f32 v74, v76, v77
	v_cvt_pk_bf16_f32 v75, v78, v79
	global_store_dwordx2 v[56:57], v[58:59], off offset:32
	v_cvt_pk_bf16_f32 v58, v64, v65
	v_cvt_pk_bf16_f32 v59, v66, v67
	v_cvt_pk_bf16_f32 v36, v36, v37
	v_cvt_pk_bf16_f32 v37, v38, v39
	global_store_dwordx2 v[132:133], v[124:125], off
	global_store_dwordx2 v[132:133], v[116:117], off offset:32
	global_store_dwordx2 v[132:133], v[112:113], off offset:64
	global_store_dwordx2 v[96:97], v[98:99], off offset:32
	global_store_dwordx2 v[96:97], v[88:89], off offset:64
	global_store_dwordx2 v[72:73], v[74:75], off offset:64
	global_store_dwordx2 v[56:57], v[58:59], off offset:64
	global_store_dwordx2 v[56:57], v[36:37], off offset:96
	v_or_b32_e32 v144, 64, v160
	v_ashrrev_i32_e32 v145, 31, v144
	v_lshlrev_b64 v[150:151], 11, v[144:145]
	v_or_b32_e32 v140, 0x50, v160
	v_lshl_add_u64 v[36:37], s[36:37], 0, v[150:151]
	v_ashrrev_i32_e32 v141, 31, v140
	v_lshl_add_u64 v[36:37], v[36:37], 0, v[126:127]
	v_cvt_pk_bf16_f32 v20, v20, v21
	v_cvt_pk_bf16_f32 v21, v22, v23
	v_lshlrev_b64 v[146:147], 11, v[140:141]
	v_or_b32_e32 v136, 0x60, v160
	global_store_dwordx2 v[36:37], v[20:21], off offset:96
	v_lshl_add_u64 v[20:21], s[36:37], 0, v[146:147]
	v_ashrrev_i32_e32 v137, 31, v136
	v_lshl_add_u64 v[20:21], v[20:21], 0, v[126:127]
	v_cvt_pk_bf16_f32 v8, v8, v9
	v_cvt_pk_bf16_f32 v9, v10, v11
	v_lshlrev_b64 v[142:143], 11, v[136:137]
	v_or_b32_e32 v132, 0x70, v160
	global_store_dwordx2 v[20:21], v[8:9], off offset:96
	v_lshl_add_u64 v[8:9], s[36:37], 0, v[142:143]
	v_ashrrev_i32_e32 v133, 31, v132
	v_lshl_add_u64 v[8:9], v[8:9], 0, v[126:127]
	v_cvt_pk_bf16_f32 v0, v0, v1
	v_cvt_pk_bf16_f32 v1, v2, v3
	v_lshlrev_b64 v[138:139], 11, v[132:133]
	global_store_dwordx2 v[8:9], v[0:1], off offset:96
	v_lshl_add_u64 v[0:1], s[36:37], 0, v[138:139]
	v_cvt_pk_bf16_f32 v2, v32, v33
	v_cvt_pk_bf16_f32 v3, v34, v35
	v_lshl_add_u64 v[0:1], v[0:1], 0, v[126:127]
	v_cvt_pk_bf16_f32 v38, v84, v85
	v_cvt_pk_bf16_f32 v39, v86, v87
	v_cvt_pk_bf16_f32 v22, v68, v69
	v_cvt_pk_bf16_f32 v23, v70, v71
	v_cvt_pk_bf16_f32 v10, v52, v53
	v_cvt_pk_bf16_f32 v11, v54, v55
	global_store_dwordx2 v[0:1], v[2:3], off
	v_cvt_pk_bf16_f32 v2, v16, v17
	v_cvt_pk_bf16_f32 v3, v18, v19
	global_store_dwordx2 v[36:37], v[38:39], off
	v_cvt_pk_bf16_f32 v38, v60, v61
	v_cvt_pk_bf16_f32 v39, v62, v63
	global_store_dwordx2 v[20:21], v[22:23], off
	v_cvt_pk_bf16_f32 v22, v48, v49
	v_cvt_pk_bf16_f32 v23, v50, v51
	global_store_dwordx2 v[8:9], v[10:11], off
	v_cvt_pk_bf16_f32 v10, v28, v29
	v_cvt_pk_bf16_f32 v11, v30, v31
	global_store_dwordx2 v[0:1], v[2:3], off offset:32
	v_cvt_pk_bf16_f32 v2, v4, v5
	v_cvt_pk_bf16_f32 v3, v6, v7
	global_store_dwordx2 v[36:37], v[38:39], off offset:32
	v_cvt_pk_bf16_f32 v38, v44, v45
	v_cvt_pk_bf16_f32 v39, v46, v47
	global_store_dwordx2 v[20:21], v[22:23], off offset:32
	v_cvt_pk_bf16_f32 v22, v24, v25
	v_cvt_pk_bf16_f32 v23, v26, v27
	global_store_dwordx2 v[8:9], v[10:11], off offset:32
	v_cvt_pk_bf16_f32 v10, v12, v13
	v_cvt_pk_bf16_f32 v11, v14, v15
	global_store_dwordx2 v[0:1], v[2:3], off offset:64
	v_cvt_pk_bf16_f32 v2, v40, v41
	v_cvt_pk_bf16_f32 v3, v42, v43
	global_store_dwordx2 v[36:37], v[38:39], off offset:64
	global_store_dwordx2 v[20:21], v[22:23], off offset:64
	global_store_dwordx2 v[8:9], v[10:11], off offset:64
	global_store_dwordx2 v[0:1], v[2:3], off offset:96
	s_lshl_b32 s6, s6, 11
	s_add_u32 s6, s28, s6
	v_mov_b32_e32 v4, v182
	s_addc_u32 s7, s29, 0
	s_lshl_b64 s[2:3], s[2:3], 11
	s_add_u32 s2, s38, s2
	v_ashrrev_i32_e32 v0, 3, v4
	v_lshrrev_b32_e32 v5, 4, v4
	v_xor_b32_e32 v6, v5, v4
	v_ashrrev_i32_e32 v1, 31, v0
	s_addc_u32 s3, s39, s3
	v_lshlrev_b64 v[0:1], 11, v[0:1]
	v_lshlrev_b32_e32 v6, 4, v6
	v_lshl_add_u64 v[2:3], s[6:7], 0, v[0:1]
	v_and_b32_e32 v130, 0x70, v6
	v_lshl_add_u64 v[0:1], s[2:3], 0, v[0:1]
	v_lshl_add_u64 v[166:167], v[2:3], 0, v[130:131]
	v_lshl_add_u64 v[168:169], v[0:1], 0, v[130:131]
	v_lshlrev_b32_e32 v130, 4, v4
	v_add_u32_e32 v2, 0x2000, v130
	v_readfirstlane_b32 s2, v130
	v_lshl_add_u64 v[0:1], v[166:167], 0, s[18:19]
	s_mov_b32 m0, s2
	v_lshl_add_u64 v[170:171], v[166:167], 0, s[20:21]
	v_readfirstlane_b32 s2, v2
	v_add_u32_e32 v2, 0x4000, v130
	s_barrier
; #define LDS_PTR(p) ((__attribute__((address_space(3))) unsigned*)(p))
; template <int PIPE>
; DI void gemm_loop_g(const u16* __restrict__ Xp, long ldx_l, long ldx_i, long kxs,
;                     const u16* __restrict__ Yp, long ldy_l, long ldy_i, long kys, int K,
;                     f32x4 (&acc)[4][8], unsigned char* smem) {
;     ...
;   auto issue = [&](int kt0, int stage) {
;     int kt = kt0 + rot; if (kt >= nk) kt -= nk;
;     unsigned char* sb = smem + stage * 65536 + t * 16;
; #pragma unroll
;     for (int i = 0; i < 4; ++i)
;       __builtin_amdgcn_global_load_lds((const unsigned*)(xs + i * ldx_i + kt * kxs), LDS_PTR(sb + i * 8192), 16, 0, 0);
; #pragma unroll
;     for (int i = 0; i < 4; ++i)
;       __builtin_amdgcn_global_load_lds((const unsigned*)(ys + i * ldy_i + kt * kys), LDS_PTR(sb + 32768 + i * 8192), 16, 0, 0);
;   };
;   __syncthreads();
;   issue(0, 0);
;   asm volatile("s_waitcnt vmcnt(0)" ::: "memory");
;   __syncthreads();
; DI void zero_acc(f32x4 (&acc)[4][8]) {
; #pragma unroll
;   for (int i = 0; i < 4; ++i)
; #pragma unroll
;     for (int j = 0; j < 8; ++j) acc[i][j] = f32x4{0.f, 0.f, 0.f, 0.f};
	global_load_lds_dwordx4 v[0:1], off
	v_lshl_add_u64 v[0:1], v[170:171], 0, s[18:19]
	s_mov_b32 m0, s2
	v_lshl_add_u64 v[172:173], v[166:167], 0, s[22:23]
	v_readfirstlane_b32 s2, v2
	v_add_u32_e32 v2, 0x6000, v130
	global_load_lds_dwordx4 v[0:1], off
	v_lshl_add_u64 v[0:1], v[172:173], 0, s[18:19]
	s_mov_b32 m0, s2
	v_lshl_add_u64 v[174:175], v[166:167], 0, s[24:25]
	v_readfirstlane_b32 s2, v2
	v_add_u32_e32 v2, 0x8000, v130
	global_load_lds_dwordx4 v[0:1], off
	v_lshl_add_u64 v[0:1], v[174:175], 0, s[18:19]
	s_mov_b32 m0, s2
	v_readfirstlane_b32 s2, v2
	v_add_u32_e32 v2, 0xa000, v130
	global_load_lds_dwordx4 v[0:1], off
	v_lshl_add_u64 v[0:1], v[168:169], 0, s[18:19]
	s_mov_b32 m0, s2
	v_lshl_add_u64 v[176:177], v[168:169], 0, s[20:21]
	v_readfirstlane_b32 s2, v2
	v_add_u32_e32 v2, 0xc000, v130
	global_load_lds_dwordx4 v[0:1], off
	v_lshl_add_u64 v[0:1], v[176:177], 0, s[18:19]
	s_mov_b32 m0, s2
	v_lshl_add_u64 v[178:179], v[168:169], 0, s[22:23]
	v_readfirstlane_b32 s2, v2
	v_add_u32_e32 v2, 0xe000, v130
	global_load_lds_dwordx4 v[0:1], off
	v_lshl_add_u64 v[0:1], v[178:179], 0, s[18:19]
	s_mov_b32 m0, s2
	v_lshl_add_u64 v[180:181], v[168:169], 0, s[24:25]
	v_readfirstlane_b32 s2, v2
	global_load_lds_dwordx4 v[0:1], off
	v_lshl_add_u64 v[0:1], v[180:181], 0, s[18:19]
	s_mov_b32 m0, s2
	v_lshlrev_b32_e32 v2, 7, v4
	global_load_lds_dwordx4 v[0:1], off
	v_bfe_u32 v0, v4, 4, 2
	v_bfe_u32 v1, v4, 1, 3
	v_readfirstlane_b32 s26, v4
	s_nop 0
	v_bitop3_b32 v0, v0, v1, 4 bitop3:0x36
	v_and_b32_e32 v2, 0x780, v2
	s_lshl_b32 s2, s26, 8
	s_lshl_b32 s3, s26, 6
	v_lshl_or_b32 v187, v0, 4, v2
	v_bitop3_b32 v0, v5, v1, 3 bitop3:0x6c
	v_mov_b32_e32 v4, 0
	s_and_b32 s2, s2, 0x4000
	s_and_b32 s3, s3, 0xffffe000
	v_lshl_or_b32 v188, v0, 4, v2
	s_mov_b32 s6, 0
	s_mov_b32 s7, 0x10000
	v_mov_b32_e32 v5, v4
	v_mov_b32_e32 v6, v4
	v_mov_b32_e32 v7, v4
	v_mov_b32_e32 v16, v4
	v_mov_b32_e32 v17, v4
	v_mov_b32_e32 v18, v4
	v_mov_b32_e32 v19, v4
	v_mov_b32_e32 v32, v4
	v_mov_b32_e32 v33, v4
	v_mov_b32_e32 v34, v4
	v_mov_b32_e32 v35, v4
	v_mov_b32_e32 v48, v4
	v_mov_b32_e32 v49, v4
	v_mov_b32_e32 v50, v4
	v_mov_b32_e32 v51, v4
	v_mov_b32_e32 v64, v4
	v_mov_b32_e32 v65, v4
	v_mov_b32_e32 v66, v4
	v_mov_b32_e32 v67, v4
	v_mov_b32_e32 v80, v4
	v_mov_b32_e32 v81, v4
	v_mov_b32_e32 v82, v4
	v_mov_b32_e32 v83, v4
	v_mov_b32_e32 v96, v4
	v_mov_b32_e32 v97, v4
	v_mov_b32_e32 v98, v4
	v_mov_b32_e32 v99, v4
	v_mov_b32_e32 v112, v4
	v_mov_b32_e32 v113, v4
	v_mov_b32_e32 v114, v4
	v_mov_b32_e32 v115, v4
	v_mov_b32_e32 v0, v4
	v_mov_b32_e32 v1, v4
	v_mov_b32_e32 v2, v4
	v_mov_b32_e32 v3, v4
	v_mov_b32_e32 v20, v4
	v_mov_b32_e32 v21, v4
	v_mov_b32_e32 v22, v4
	v_mov_b32_e32 v23, v4
	v_mov_b32_e32 v36, v4
	v_mov_b32_e32 v37, v4
	v_mov_b32_e32 v38, v4
	v_mov_b32_e32 v39, v4
	v_mov_b32_e32 v52, v4
	v_mov_b32_e32 v53, v4
	v_mov_b32_e32 v54, v4
	v_mov_b32_e32 v55, v4
	v_mov_b32_e32 v68, v4
	v_mov_b32_e32 v69, v4
	v_mov_b32_e32 v70, v4
	v_mov_b32_e32 v71, v4
	v_mov_b32_e32 v84, v4
	v_mov_b32_e32 v85, v4
	v_mov_b32_e32 v86, v4
	v_mov_b32_e32 v87, v4
	v_mov_b32_e32 v100, v4
	v_mov_b32_e32 v101, v4
	v_mov_b32_e32 v102, v4
	v_mov_b32_e32 v103, v4
	v_mov_b32_e32 v116, v4
	v_mov_b32_e32 v117, v4
	v_mov_b32_e32 v118, v4
	v_mov_b32_e32 v119, v4
	v_mov_b32_e32 v8, v4
	v_mov_b32_e32 v9, v4
	v_mov_b32_e32 v10, v4
	v_mov_b32_e32 v11, v4
	v_mov_b32_e32 v24, v4
	v_mov_b32_e32 v25, v4
	v_mov_b32_e32 v26, v4
	v_mov_b32_e32 v27, v4
	v_mov_b32_e32 v40, v4
	v_mov_b32_e32 v41, v4
	v_mov_b32_e32 v42, v4
	v_mov_b32_e32 v43, v4
	v_mov_b32_e32 v56, v4
	v_mov_b32_e32 v57, v4
	v_mov_b32_e32 v58, v4
	v_mov_b32_e32 v59, v4
	v_mov_b32_e32 v72, v4
	v_mov_b32_e32 v73, v4
	v_mov_b32_e32 v74, v4
	v_mov_b32_e32 v75, v4
	v_mov_b32_e32 v88, v4
	v_mov_b32_e32 v89, v4
	v_mov_b32_e32 v90, v4
	v_mov_b32_e32 v91, v4
	v_mov_b32_e32 v104, v4
	v_mov_b32_e32 v105, v4
	v_mov_b32_e32 v106, v4
	v_mov_b32_e32 v107, v4
	v_mov_b32_e32 v120, v4
	v_mov_b32_e32 v121, v4
	v_mov_b32_e32 v122, v4
	v_mov_b32_e32 v123, v4
	v_mov_b32_e32 v12, v4
	v_mov_b32_e32 v13, v4
	v_mov_b32_e32 v14, v4
	v_mov_b32_e32 v15, v4
	v_mov_b32_e32 v28, v4
	v_mov_b32_e32 v29, v4
	v_mov_b32_e32 v30, v4
	v_mov_b32_e32 v31, v4
	v_mov_b32_e32 v44, v4
	v_mov_b32_e32 v45, v4
	v_mov_b32_e32 v46, v4
	v_mov_b32_e32 v47, v4
	v_mov_b32_e32 v60, v4
	v_mov_b32_e32 v61, v4
	v_mov_b32_e32 v62, v4
	v_mov_b32_e32 v63, v4
	v_mov_b32_e32 v76, v4
	v_mov_b32_e32 v77, v4
	v_mov_b32_e32 v78, v4
	v_mov_b32_e32 v79, v4
	v_mov_b32_e32 v92, v4
	v_mov_b32_e32 v93, v4
	v_mov_b32_e32 v94, v4
	v_mov_b32_e32 v95, v4
	v_mov_b32_e32 v108, v4
	v_mov_b32_e32 v109, v4
	v_mov_b32_e32 v110, v4
	v_mov_b32_e32 v111, v4
	v_mov_b32_e32 v124, v4
	v_mov_b32_e32 v125, v4
	v_mov_b32_e32 v126, v4
	v_mov_b32_e32 v127, v4
	s_add_i32 s26, s44, s6
	s_cmp_lt_u32 s26, 16
	s_cselect_b32 s27, 0, -16
	s_add_i32 s26, s26, s27
	s_and_b32 s27, s7, 0x10000
	v_add_u32_e32 v189, s27, v130
	s_ashr_i32 s27, s26, 31
	s_lshl_b64 s[26:27], s[26:27], 7
	v_readfirstlane_b32 s33, v189
	v_add_u32_e32 v192, 0x2000, v189
	v_lshl_add_u64 v[190:191], v[166:167], 0, s[26:27]
	s_mov_b32 m0, s33
	v_readfirstlane_b32 s33, v192
	v_add_u32_e32 v192, 0x4000, v189
	global_load_lds_dwordx4 v[190:191], off
	v_lshl_add_u64 v[190:191], v[170:171], 0, s[26:27]
	s_mov_b32 m0, s33
	v_readfirstlane_b32 s33, v192
	v_add_u32_e32 v192, 0x6000, v189
	global_load_lds_dwordx4 v[190:191], off
	v_lshl_add_u64 v[190:191], v[172:173], 0, s[26:27]
	s_mov_b32 m0, s33
	v_readfirstlane_b32 s33, v192
	v_add_u32_e32 v192, 0x8000, v189
	global_load_lds_dwordx4 v[190:191], off
	v_lshl_add_u64 v[190:191], v[174:175], 0, s[26:27]
	s_mov_b32 m0, s33
	v_readfirstlane_b32 s33, v192
	v_add_u32_e32 v192, 0xa000, v189
	global_load_lds_dwordx4 v[190:191], off
	v_lshl_add_u64 v[190:191], v[168:169], 0, s[26:27]
	s_mov_b32 m0, s33
	v_readfirstlane_b32 s33, v192
	v_add_u32_e32 v192, 0xc000, v189
	global_load_lds_dwordx4 v[190:191], off
	v_lshl_add_u64 v[190:191], v[176:177], 0, s[26:27]
	s_mov_b32 m0, s33
	v_readfirstlane_b32 s33, v192
	global_load_lds_dwordx4 v[190:191], off
	v_lshl_add_u64 v[190:191], v[178:179], 0, s[26:27]
	s_mov_b32 m0, s33
	v_add_u32_e32 v189, 0xe000, v189
	global_load_lds_dwordx4 v[190:191], off
	v_lshl_add_u64 v[190:191], v[180:181], 0, s[26:27]
	v_readfirstlane_b32 s26, v189
	s_mov_b32 m0, s26
	s_nop 0
	global_load_lds_dwordx4 v[190:191], off
	s_waitcnt vmcnt(8) lgkmcnt(0)
	s_barrier
	s_branch .LBB0_681

; DI int tid_opaque() { int t = threadIdx.x; asm volatile("" : "+v"(t)); return t; }
; DI void final_norm(const Params& p) {
;   const int tt_ = tid_opaque();
;   const int l = tt_ & 63, gw = blockIdx.x * 8 + (tt_ >> 6), nw = gridDim.x * 8;
;   for (int row = gw; row < T_TOK; row += nw) {
;     float4* xp = (float4*)(p.out + (long)row * 1024);
;     float4 v[4];
;     float s = 0.f;
; #pragma unroll
;     for (int i = 0; i < 4; ++i) {
;       v[i] = xp[l + 64 * i];
;       s += v[i].x * v[i].x + v[i].y * v[i].y + v[i].z * v[i].z + v[i].w * v[i].w;
;     }
; #pragma unroll
;     for (int o = 1; o < 64; o <<= 1) s += __shfl_xor(s, o);
;     const float rs = rsqrtf(s * (1.f / 1024.f) + 1e-6f);
; #pragma unroll
;     for (int i = 0; i < 4; ++i) {
;       const float4 g = ((const float4*)p.final_g)[l + 64 * i];
;       v[i].x *= rs * g.x; v[i].y *= rs * g.y; v[i].z *= rs * g.z; v[i].w *= rs * g.w;
;       xp[l + 64 * i] = v[i];
;     }
;   }
; }
.LBB0_710:
	s_or_b64 exec, exec, s[2:3]
	s_barrier
	s_mov_b32 s2, 0x14000
	v_ashrrev_i32_e32 v0, 6, v182
	v_add_u32_e32 v0, s92, v0
	v_cmp_gt_i32_e32 vcc, s2, v0
	s_and_saveexec_b64 s[2:3], vcc
	s_cbranch_execz .LBB0_713
	s_load_dwordx4 s[4:7], s[0:1], 0x50
	v_mbcnt_hi_u32_b32 v1, -1, v183
	v_and_b32_e32 v2, 64, v1
	s_waitcnt vmcnt(0)
	v_add_u32_e32 v11, 64, v2
	v_lshlrev_b32_e32 v2, 4, v182
	v_and_b32_e32 v4, 0x3f0, v2
	v_mov_b32_e32 v5, 0
	s_waitcnt lgkmcnt(0)
	v_lshl_add_u64 v[2:3], s[4:5], 0, v[4:5]
	v_xor_b32_e32 v5, 1, v1
	v_cmp_lt_i32_e32 vcc, v5, v11
	s_mov_b64 s[0:1], 0x800
	s_ashr_i32 s35, s34, 31
	v_cndmask_b32_e32 v5, v1, v5, vcc
	v_lshlrev_b32_e32 v6, 2, v5
	v_xor_b32_e32 v5, 2, v1
	v_cmp_lt_i32_e32 vcc, v5, v11
	s_mov_b64 s[2:3], 0
	s_mov_b32 s4, 0x800000
	v_cndmask_b32_e32 v5, v1, v5, vcc
	v_lshlrev_b32_e32 v7, 2, v5
	v_xor_b32_e32 v5, 4, v1
	v_cmp_lt_i32_e32 vcc, v5, v11
	s_mov_b32 s5, 0x13fff
	s_nop 0
	v_cndmask_b32_e32 v5, v1, v5, vcc
	v_lshlrev_b32_e32 v8, 2, v5
	v_xor_b32_e32 v5, 8, v1
	v_cmp_lt_i32_e32 vcc, v5, v11
	s_nop 1
	v_cndmask_b32_e32 v5, v1, v5, vcc
	v_lshlrev_b32_e32 v9, 2, v5
	v_xor_b32_e32 v5, 16, v1
	v_cmp_lt_i32_e32 vcc, v5, v11
	s_nop 1
	v_cndmask_b32_e32 v5, v1, v5, vcc
	v_lshlrev_b32_e32 v10, 2, v5
	v_xor_b32_e32 v5, 32, v1
	v_cmp_lt_i32_e32 vcc, v5, v11
	s_nop 1
	v_cndmask_b32_e32 v1, v1, v5, vcc
	v_lshlrev_b32_e32 v11, 2, v1
	v_ashrrev_i32_e32 v1, 31, v0
	v_lshlrev_b64 v[12:13], 12, v[0:1]
	v_or_b32_e32 v12, v12, v4
	v_lshl_add_u64 v[4:5], s[6:7], 0, v[12:13]
	v_lshl_add_u64 v[4:5], v[4:5], 0, s[0:1]
	s_lshl_b64 s[0:1], s[34:35], 12
	v_mov_b32_e32 v1, 0x358637bd
	global_load_dwordx4 v[48:51], v[2:3], off
	global_load_dwordx4 v[52:55], v[2:3], off offset:1024
	global_load_dwordx4 v[56:59], v[2:3], off offset:2048
	global_load_dwordx4 v[60:63], v[2:3], off offset:3072
	global_load_dwordx4 v[66:69], v[4:5], off offset:-2048
	global_load_dwordx4 v[70:73], v[4:5], off offset:-1024
	global_load_dwordx4 v[74:77], v[4:5], off
	global_load_dwordx4 v[78:81], v[4:5], off offset:1024
	s_waitcnt vmcnt(0)
.LBB0_712:
	v_add_u32_e32 v0, s34, v0
	s_waitcnt vmcnt(4)
	v_mov_b32_e32 v12, v66
	v_mov_b32_e32 v13, v67
	v_mov_b32_e32 v14, v68
	v_mov_b32_e32 v15, v69
	v_mov_b32_e32 v16, v70
	v_mov_b32_e32 v17, v71
	v_mov_b32_e32 v18, v72
	v_mov_b32_e32 v19, v73
	v_mov_b32_e32 v20, v74
	v_mov_b32_e32 v21, v75
	v_mov_b32_e32 v22, v76
	v_mov_b32_e32 v23, v77
	v_mov_b32_e32 v24, v78
	v_mov_b32_e32 v25, v79
	v_mov_b32_e32 v26, v80
	v_mov_b32_e32 v27, v81
	v_cmp_ge_i32_e32 vcc, s5, v0
	v_lshl_add_u64 v[64:65], v[4:5], 0, s[0:1]
	s_and_saveexec_b64 s[6:7], vcc
	global_load_dwordx4 v[66:69], v[64:65], off offset:-2048
	global_load_dwordx4 v[70:73], v[64:65], off offset:-1024
	global_load_dwordx4 v[74:77], v[64:65], off
	global_load_dwordx4 v[78:81], v[64:65], off offset:1024
	s_mov_b64 exec, s[6:7]
	v_mov_b32_e32 v34, v13
	v_mov_b32_e32 v35, v17
	v_mov_b32_e32 v32, v12
	v_mov_b32_e32 v33, v16
	v_mov_b32_e32 v42, v21
	v_mov_b32_e32 v43, v25
	v_pk_mul_f32 v[34:35], v[34:35], v[34:35]
	v_mov_b32_e32 v36, v14
	v_mov_b32_e32 v37, v18
	v_mov_b32_e32 v40, v20
	v_mov_b32_e32 v41, v24
	v_pk_mul_f32 v[42:43], v[42:43], v[42:43]
	v_pk_fma_f32 v[32:33], v[32:33], v[32:33], v[34:35]
	v_mov_b32_e32 v38, v15
	v_mov_b32_e32 v39, v19
	v_mov_b32_e32 v44, v22
	v_mov_b32_e32 v45, v26
	v_pk_fma_f32 v[34:35], v[40:41], v[40:41], v[42:43]
	v_pk_fma_f32 v[32:33], v[36:37], v[36:37], v[32:33]
	v_mov_b32_e32 v46, v23
	v_mov_b32_e32 v47, v27
	v_pk_fma_f32 v[34:35], v[44:45], v[44:45], v[34:35]
	v_pk_fma_f32 v[32:33], v[38:39], v[38:39], v[32:33]
	v_pk_fma_f32 v[34:35], v[46:47], v[46:47], v[34:35]
	v_add_f32_e32 v32, v32, v33
	v_add_f32_e32 v32, v32, v34
	v_add_f32_e32 v32, v32, v35
	ds_bpermute_b32 v33, v6, v32
	s_waitcnt lgkmcnt(0)
	v_add_f32_e32 v32, v32, v33
	ds_bpermute_b32 v33, v7, v32
	s_waitcnt lgkmcnt(0)
	v_add_f32_e32 v32, v32, v33
	ds_bpermute_b32 v33, v8, v32
	s_waitcnt lgkmcnt(0)
	v_add_f32_e32 v32, v32, v33
	ds_bpermute_b32 v33, v9, v32
	s_waitcnt lgkmcnt(0)
	v_add_f32_e32 v32, v32, v33
	ds_bpermute_b32 v33, v10, v32
	s_waitcnt lgkmcnt(0)
	v_add_f32_e32 v32, v32, v33
	ds_bpermute_b32 v33, v11, v32
	s_waitcnt lgkmcnt(0)
	v_add_f32_e32 v32, v32, v33
	v_fmamk_f32 v32, v32, 0x3a800000, v1
	v_mul_f32_e32 v33, 0x4b800000, v32
	v_cmp_gt_f32_e32 vcc, s4, v32
	s_nop 1
	v_cndmask_b32_e32 v32, v32, v33, vcc
	v_rsq_f32_e32 v32, v32
	s_nop 0
	v_mul_f32_e32 v33, 0x45800000, v32
	v_cndmask_b32_e32 v32, v32, v33, vcc
	v_pk_mul_f32 v[28:29], v[48:49], v[32:33] op_sel_hi:[1,0]
	v_pk_mul_f32 v[30:31], v[50:51], v[32:33] op_sel_hi:[1,0]
	v_pk_mul_f32 v[12:13], v[12:13], v[28:29]
	v_pk_mul_f32 v[14:15], v[14:15], v[30:31]
	global_store_dwordx4 v[4:5], v[12:15], off offset:-2048
	v_pk_mul_f32 v[28:29], v[52:53], v[32:33] op_sel_hi:[1,0]
	v_pk_mul_f32 v[30:31], v[54:55], v[32:33] op_sel_hi:[1,0]
	v_pk_mul_f32 v[16:17], v[16:17], v[28:29]
	v_pk_mul_f32 v[18:19], v[18:19], v[30:31]
	global_store_dwordx4 v[4:5], v[16:19], off offset:-1024
	v_pk_mul_f32 v[28:29], v[56:57], v[32:33] op_sel_hi:[1,0]
	v_pk_mul_f32 v[30:31], v[58:59], v[32:33] op_sel_hi:[1,0]
	v_pk_mul_f32 v[20:21], v[20:21], v[28:29]
	v_pk_mul_f32 v[22:23], v[22:23], v[30:31]
	global_store_dwordx4 v[4:5], v[20:23], off
	v_pk_mul_f32 v[28:29], v[60:61], v[32:33] op_sel_hi:[1,0]
	v_pk_mul_f32 v[30:31], v[62:63], v[32:33] op_sel_hi:[1,0]
	v_pk_mul_f32 v[24:25], v[24:25], v[28:29]
	v_pk_mul_f32 v[26:27], v[26:27], v[30:31]
	global_store_dwordx4 v[4:5], v[24:27], off offset:1024
	v_cmp_lt_i32_e32 vcc, s5, v0
	s_or_b64 s[2:3], vcc, s[2:3]
	v_mov_b32_e32 v4, v64
	v_mov_b32_e32 v5, v65
	s_andn2_b64 exec, exec, s[2:3]
	s_cbranch_execnz .LBB0_712
